# NA: loader-wave prefetch + pipelined QK/bias reads; dense attn: counted lgkmcnt in PV, 4 LDS buffers (one barrier per tile), early K/V LDS writes
# speedup vs baseline: 1.0130x; 1.0130x over previous
; __device__ __forceinline__ int opaque_lane() { int z; asm volatile("v_mov_b32 %0, 0" : "=v"(z)); return __builtin_amdgcn_mbcnt_hi(-1, __builtin_amdgcn_mbcnt_lo(-1, z)); }
; __device__ __forceinline__ int launder_s(int v) { asm volatile("" : "+s"(v)); return v; }
; __device__ __forceinline__ int v_st(int k, int c) { const int kk = (k & ~0xC) | ((k & 4) << 1) | ((k & 8) >> 1); return ((kk >> 3) * 4 + (c >> 5)) * 512 + ((kk & 7) * 32 + (c & 31)) * 2; }
;   p0 = f32x16{}; p1 = f32x16{};
; #pragma unroll
;   for (int d0 = DLO; d0 < DHI; ++d0) { int cb = (d0 * 16 + hi * 8) * 2;
;     bf16x8 b0 = *reinterpret_cast<const bf16x8*>((const char*)Ks + KSWZ(r32, cb));
;     bf16x8 b1 = *reinterpret_cast<const bf16x8*>((const char*)Ks + KSWZ(32 + r32, cb));
;     p0 = __builtin_amdgcn_mfma_f32_32x32x16_bf16(b0, qr[d0], p0, 0, 0, 0);
;     p1 = __builtin_amdgcn_mfma_f32_32x32x16_bf16(b1, qr[d0], p1, 0, 0, 0); }
; }
; template <int DLO, int DHI>
; __device__ __forceinline__ void attn_dense_body(const int g_wave, const bf16* __restrict__ Qb, const bf16* __restrict__ Kh, const bf16* __restrict__ Vh,
;                                                 bf16* __restrict__ Ob, int ldo, char* lds) {
;   const int wid = launder_s(g_wave), lane = opaque_lane(), tid = (wid << 6) | lane, r32 = lane & 31, hi = lane >> 5;
;   bf16* V_lds = (bf16*)lds; bf16* K_lds = (bf16*)(lds + 2 * SHM_V);
;   float* ws = (float*)(lds + 2 * SHM_V + 2 * SHM_K) + wid * 64; float* li_l = ws; float* al_l = ws + 32;
;   float m_reg = -1e30f, l_reg = 0; f32x16 o[4] = {}; bf16x8 qr[8];
;   const bf16* Qw = Qb + (long)(wid * QBLK + r32) * LDQ + hi * 8;
; #pragma unroll
;   for (int d0 = DLO; d0 < DHI; ++d0) qr[d0] = ld8(Qw + d0 * 16);
;   const int sr = tid >> 4, sc = (tid & 15) * 8, vst0 = v_st(sr, sc), vst1 = v_st(32 + sr, sc);
;   const int vb0 = (int)(uintptr_t)V_lds + v_rd_base(lane);
;   struct { bf16x8 vs0, vs1, ks0, ks1; } sr_[2];
;     ...
;   f32x16 pA0, pA1, pB0, pB1; float mnA, mnB, alA, alB; bf16x8 pa0, pa1, pa2, pa3; constexpr int NT = SEQ / KVBLK;
;   constexpr int SE = 0, SO = 1;
;   SLOAD(SE, 0); asm volatile("s_waitcnt vmcnt(0)" ::: "memory"); SWRITE(0, SE); __syncthreads();
;   qkt<DLO, DHI>(pA0, pA1, K_lds, qr, r32, hi); partialSM(pA0, pA1, m_reg, mnA, alA);
.LBB0_999:
	s_lshl_b32 s5, s5, 20
	s_lshl_b32 s8, s1, 24
	s_waitcnt lgkmcnt(0)
	s_add_u32 s8, s84, s8
	s_addc_u32 s9, s85, 0
	s_add_u32 s5, s8, s5
	s_addc_u32 s8, s9, 0
	s_lshl_b64 s[6:7], s[6:7], 1
	s_add_u32 s5, s5, s6
	s_addc_u32 s6, s8, s7
	s_add_u32 s90, s5, 0x1d600000
	s_addc_u32 s91, s6, 0
	s_mul_i32 s11, s1, 0x600000
	s_add_u32 s5, s84, s11
	s_addc_u32 s6, s85, 0
	s_lshl_b64 s[86:87], s[16:17], 1
	s_add_u32 s5, s5, s86
	s_addc_u32 s6, s6, s87
	s_add_u32 s92, s5, 0x1f600000
	s_addc_u32 s93, s6, 0
	s_mul_i32 s13, s1, 0x2400000
	s_add_u32 s1, s84, s13
	s_mov_b32 s5, s17
	s_addc_u32 s6, s85, 0
	s_lshl_b64 s[88:89], s[4:5], 1
	s_add_u32 s1, s1, s88
	s_addc_u32 s4, s6, s89
	s_add_u32 s94, s1, 0x18e00000
	s_addc_u32 s95, s4, 0
	s_mov_b64 s[4:5], -1
	s_and_b64 vcc, exec, s[2:3]
	s_cbranch_vccz .LBB0_1041
	s_cmp_lg_u32 s14, 0
	s_cbranch_scc0 .LBB0_1061
	s_mov_b32 s1, s64
	v_mov_b32 v0, 0
	s_lshl_b32 s4, s1, 6
	v_mbcnt_lo_u32_b32 v0, -1, v0
	s_waitcnt vmcnt(0)
	v_mbcnt_hi_u32_b32 v72, -1, v0
	v_or_b32_e32 v0, s4, v72
	v_ashrrev_i32_e32 v73, 4, v0
	v_lshlrev_b32_e32 v54, 3, v72
	v_and_b32_e32 v0, 0x78, v54
	v_add_u32_e32 v22, 32, v73
	v_mov_b64_e32 v[50:51], s[94:95]
	v_mov_b64_e32 v[52:53], s[92:93]
	v_lshlrev_b32_e32 v0, 1, v0
	v_mad_i64_i32 v[2:3], s[2:3], v73, s79, v[50:51]
	v_mad_i64_i32 v[4:5], s[2:3], v22, s79, v[50:51]
	v_mad_i64_i32 v[10:11], s[2:3], v73, s67, v[52:53]
	v_mad_i64_i32 v[12:13], s[2:3], v22, s67, v[52:53]
	v_lshl_add_u64 v[2:3], v[2:3], 0, v[0:1]
	v_lshl_add_u64 v[6:7], v[4:5], 0, v[0:1]
	v_lshl_add_u64 v[10:11], v[10:11], 0, v[0:1]
	v_lshl_add_u64 v[14:15], v[12:13], 0, v[0:1]
	v_and_b32_e32 v170, 31, v72
	s_lshl_b32 s14, s1, 5
	global_load_dwordx4 v[2:5], v[2:3], off
	s_nop 0
	global_load_dwordx4 v[6:9], v[6:7], off
	s_nop 0
	global_load_dwordx4 v[10:13], v[10:11], off
	s_nop 0
	global_load_dwordx4 v[14:17], v[14:15], off
	v_or_b32_e32 v18, s14, v170
	v_ashrrev_i32_e32 v171, 5, v72
	v_ashrrev_i32_e32 v19, 31, v18
	v_lshlrev_b64 v[18:19], 12, v[18:19]
	v_lshlrev_b32_e32 v20, 3, v171
	v_lshl_add_u64 v[18:19], s[90:91], 0, v[18:19]
	v_ashrrev_i32_e32 v21, 31, v20
	v_lshl_add_u64 v[18:19], v[20:21], 1, v[18:19]
	global_load_dwordx4 v[102:105], v[18:19], off offset:128
	global_load_dwordx4 v[98:101], v[18:19], off offset:160
	global_load_dwordx4 v[106:109], v[18:19], off offset:192
	global_load_dwordx4 v[110:113], v[18:19], off offset:224
	v_and_b32_e32 v23, 0xfffff0, v73
	v_lshlrev_b32_e32 v24, 1, v73
	v_lshrrev_b32_e32 v25, 1, v73
	v_and_b32_e32 v26, 3, v73
	v_mov_b32_e32 v20, s4
	v_and_or_b32 v23, v24, 8, v23
	v_and_or_b32 v24, v25, 4, v26
	v_and_b32_e32 v26, 0xfffff0, v22
	v_lshlrev_b32_e32 v29, 1, v22
	v_bitop3_b32 v20, v72, s80, v20 bitop3:0xc8
	v_bfe_u32 v21, v54, 5, 2
	v_lshlrev_b32_e32 v27, 8, v73
	v_lshlrev_b32_e32 v22, 8, v22
	v_lshrrev_b32_e32 v23, 1, v23
	v_and_or_b32 v26, v29, 8, v26
	v_lshlrev_b32_e32 v55, 4, v72
	v_lshlrev_b32_e32 v172, 4, v171
	v_bitop3_b32 v27, v0, v27, v20 bitop3:0xde
	v_bitop3_b32 v18, v22, v0, v20 bitop3:0xf6
	v_or_b32_e32 v19, v23, v21
	v_lshrrev_b32_e32 v20, 1, v26
	v_lshlrev_b32_e32 v56, 8, v170
	v_and_b32_e32 v57, 0x70, v55
	v_add_u32_e32 v28, 0x80, v172
	v_and_b32_e32 v25, 48, v0
	v_lshlrev_b32_e32 v24, 6, v24
	v_add_u32_e32 v191, 0, v18
	v_lshlrev_b32_e32 v18, 9, v19
	v_or_b32_e32 v19, v20, v21
	v_xad_u32 v28, v28, v57, v56
	v_or3_b32 v18, v18, v24, v25
	v_lshlrev_b32_e32 v19, 9, v19
	v_add_u32_e32 v190, 0, v28
	v_or3_b32 v19, v19, v24, v25
	v_add_u32_e32 v192, 0, v18
	v_add_u32_e32 v177, 0, v27
	s_waitcnt vmcnt(0)
	v_add_u32_e32 v193, 0, v19
	v_add_u32_e32 v62, 64, v73
	v_add_u32_e32 v64, 0x60, v73
	v_add_u32_e32 v77, 0x80, v73
	v_add_u32_e32 v78, 0xa0, v73
	s_lshl_b32 s1, s1, 8
	s_add_i32 s15, s1, 0
	s_add_i32 s15, s15, 0x20000
	s_cmp_lg_u32 0, -1
	s_cselect_b32 s1, 0, 0
	s_mov_b32 s16, s17
	s_waitcnt vmcnt(7)
	ds_write_b128 v192, v[2:5]
	s_waitcnt vmcnt(6)
	ds_write_b128 v193, v[6:9]
	s_waitcnt vmcnt(5)
	ds_write_b128 v177, v[10:13] offset:32768
	s_waitcnt vmcnt(4)
	ds_write_b128 v191, v[14:17] offset:32768
	s_waitcnt lgkmcnt(0)
	s_barrier
	ds_read_b128 v[2:5], v190 offset:32768
	ds_read_b128 v[6:9], v190 offset:40960
	s_waitcnt vmcnt(3) lgkmcnt(1)
	v_mfma_f32_32x32x16_bf16 v[34:49], v[2:5], v[102:105], 0
	v_add_u32_e32 v2, 0xa0, v172
	v_xad_u32 v2, v2, v57, v56
	v_add_u32_e32 v194, 0, v2
	ds_read_b128 v[2:5], v194 offset:32768
	v_lshlrev_b32_e32 v10, 1, v72
	s_mov_b32 s18, s17
	s_mov_b32 s19, s17
	s_waitcnt lgkmcnt(1)
	v_mfma_f32_32x32x16_bf16 v[18:33], v[6:9], v[102:105], 0
	ds_read_b128 v[6:9], v194 offset:40960
	s_mov_b32 s20, s17
	s_mov_b32 s21, s17
	s_mov_b32 s22, s17
	s_mov_b32 s23, s17
	s_mov_b32 s24, s17
	s_mov_b32 s25, s17
	s_waitcnt vmcnt(2) lgkmcnt(1)
	v_mfma_f32_32x32x16_bf16 v[34:49], v[2:5], v[98:101], v[34:49]
	v_and_b32_e32 v2, 0xc0, v55
	v_and_or_b32 v11, v54, 24, v2
	v_add_u32_e32 v2, 0xc0, v172
	v_xad_u32 v2, v2, v57, v56
	v_add_u32_e32 v195, 0, v2
	ds_read_b128 v[2:5], v195 offset:32768
	s_mov_b32 s26, s17
	s_waitcnt lgkmcnt(1)
	v_mfma_f32_32x32x16_bf16 v[18:33], v[6:9], v[98:101], v[18:33]
	v_and_b32_e32 v6, 32, v10
	v_and_b32_e32 v7, 0x100, v54
	v_or3_b32 v74, v11, v6, v7
	ds_read_b128 v[6:9], v195 offset:40960
	v_add_u32_e32 v176, s1, v74
	s_mov_b32 s27, s17
	s_mov_b32 s28, s17
	s_waitcnt vmcnt(1) lgkmcnt(1)
	v_mfma_f32_32x32x16_bf16 v[34:49], v[2:5], v[106:109], v[34:49]
	v_add_u32_e32 v2, 0xe0, v172
	v_xad_u32 v2, v2, v57, v56
	v_add_u32_e32 v196, 0, v2
	ds_read_b128 v[2:5], v196 offset:32768
	ds_read_b128 v[54:57], v196 offset:40960
	s_mov_b32 s29, s17
	s_mov_b32 s30, s17
	s_waitcnt lgkmcnt(2)
; #define SLOAD(i, k0) do { sr_[i].vs0 = ld8(&Vh[(long)((k0) + sr) * LDV + sc]); sr_[i].vs1 = ld8(&Vh[(long)((k0) + 32 + sr) * LDV + sc]); \
;     sr_[i].ks0 = ld8(&Kh[(long)((k0) + sr) * LDK + sc]); sr_[i].ks1 = ld8(&Kh[(long)((k0) + 32 + sr) * LDK + sc]); } while (0)
; #define SWRITE(b, i) do { *(bf16x8*)((char*)V_lds + (b) * SHM_V + vst0) = sr_[i].vs0;          \
;     *(bf16x8*)((char*)V_lds + (b) * SHM_V + vst1) = sr_[i].vs1; int kc = sc * 2;               \
;     *(bf16x8*)((char*)K_lds + (b) * SHM_K + KSWZ(sr, kc)) = sr_[i].ks0;                       \
;     *(bf16x8*)((char*)K_lds + (b) * SHM_K + KSWZ(32 + sr, kc)) = sr_[i].ks1; } while (0)
; #define SWAIT() asm volatile("s_waitcnt vmcnt(4)" ::: "memory")
; __device__ __forceinline__ void partialSM(f32x16& p0, f32x16& p1, float& m_reg, float& mn, float& alpha) {
;   constexpr float C = SCALE * 1.4426950408889634f;
;   float pmax = p0[0];
; #pragma unroll
;   for (int r = 1; r < 16; ++r) pmax = fmaxf(pmax, p0[r]);
; #pragma unroll
;   for (int r = 0; r < 16; ++r) pmax = fmaxf(pmax, p1[r]);
;   { auto rr = __builtin_amdgcn_permlane32_swap(__float_as_uint(pmax), __float_as_uint(pmax), false, false);
;     pmax = fmaxf(__uint_as_float(rr[0]), __uint_as_float(rr[1])); }
;   if (__builtin_expect(__all(pmax - m_reg <= THR / SCALE), 1)) { mn = m_reg; alpha = 1.f; }
;   else { mn = fmaxf(m_reg, pmax); alpha = __builtin_amdgcn_exp2f((m_reg - mn) * C); m_reg = mn; }
;   float mnC = -mn * C;
; #pragma unroll
;   for (int r = 0; r < 16; ++r) p0[r] = fmaf(p0[r], C, mnC);
; #pragma unroll
;   for (int r = 0; r < 16; ++r) p1[r] = fmaf(p1[r], C, mnC);
; #pragma unroll
;   for (int r = 0; r < 16; ++r) p0[r] = __builtin_amdgcn_exp2f(p0[r]);
; }
; template <int DLO, int DHI>
; __device__ __forceinline__ void attn_dense_body(const int g_wave, const bf16* __restrict__ Qb, const bf16* __restrict__ Kh, const bf16* __restrict__ Vh,
;                                                 bf16* __restrict__ Ob, int ldo, char* lds) {
;     ...
;   SLOAD(SE, 0); asm volatile("s_waitcnt vmcnt(0)" ::: "memory"); SWRITE(0, SE); __syncthreads();
;   qkt<DLO, DHI>(pA0, pA1, K_lds, qr, r32, hi); partialSM(pA0, pA1, m_reg, mnA, alA);
;   SLOAD(SO, KVBLK); SLOAD(SE, 2 * KVBLK);
;   SWAIT(); SWRITE(1, SO); __syncthreads();
	v_mfma_f32_32x32x16_bf16 v[18:33], v[6:9], v[106:109], v[18:33]
	s_mov_b32 s31, s17
	s_mov_b32 s34, 1
	v_cmp_gt_u32_e64 s[6:7], 32, v72
	v_lshl_add_u32 v173, v170, 2, s15
	v_mov_b32_e32 v174, 0
	s_waitcnt vmcnt(0) lgkmcnt(1)
	v_mfma_f32_32x32x16_bf16 v[34:49], v[2:5], v[110:113], v[34:49]
	v_mov_b64_e32 v[2:3], s[16:17]
	v_mov_b64_e32 v[16:17], s[30:31]
	v_mov_b64_e32 v[4:5], s[18:19]
	v_mov_b64_e32 v[6:7], s[20:21]
	v_mov_b64_e32 v[8:9], s[22:23]
	v_mov_b64_e32 v[10:11], s[24:25]
	v_mov_b64_e32 v[12:13], s[26:27]
	s_waitcnt lgkmcnt(0)
	v_mfma_f32_32x32x16_bf16 v[18:33], v[54:57], v[110:113], v[18:33]
	s_nop 2
	v_max_f32_e32 v54, v35, v35
	v_max_f32_e32 v55, v34, v34
	v_max_f32_e32 v54, v55, v54
	v_max3_f32 v54, v54, v36, v37
	v_max3_f32 v54, v54, v38, v39
	v_max3_f32 v54, v54, v40, v41
	v_max3_f32 v54, v54, v42, v43
	v_max3_f32 v54, v54, v44, v45
	v_max3_f32 v54, v54, v46, v47
	v_max3_f32 v54, v54, v48, v49
	v_max3_f32 v54, v54, v18, v19
	v_max3_f32 v54, v54, v20, v21
	v_max3_f32 v54, v54, v22, v23
	v_max3_f32 v54, v54, v24, v25
	v_max3_f32 v54, v54, v26, v27
	v_max3_f32 v54, v54, v28, v29
	v_max3_f32 v54, v54, v30, v31
	v_max3_f32 v70, v54, v32, v33
	v_mov_b32_e32 v71, v70
	s_nop 1
	v_permlane32_swap_b32_e32 v70, v71
	v_max_f32_e32 v71, v71, v71
	v_max_f32_e32 v70, v70, v70
	v_max_f32_e32 v70, v70, v71
	v_max_f32_e32 v75, 0xf149f2ca, v70
	v_add_f32_e32 v71, 0x7149f2ca, v70
	v_sub_f32_e32 v70, 0xf149f2ca, v75
	v_mad_i64_i32 v[54:55], s[2:3], v62, s79, v[50:51]
	v_mad_i64_i32 v[56:57], s[2:3], v64, s79, v[50:51]
	v_mad_i64_i32 v[62:63], s[2:3], v62, s67, v[52:53]
	v_mad_i64_i32 v[64:65], s[2:3], v64, s67, v[52:53]
	v_cmp_ge_f32_e32 vcc, s63, v71
	v_mul_f32_e32 v76, 0x3e0293ee, v70
	v_mad_i64_i32 v[70:71], s[2:3], v77, s79, v[50:51]
	v_mad_i64_i32 v[50:51], s[2:3], v78, s79, v[50:51]
	v_lshl_add_u64 v[54:55], v[54:55], 0, v[0:1]
	v_lshl_add_u64 v[58:59], v[56:57], 0, v[0:1]
	v_lshl_add_u64 v[62:63], v[62:63], 0, v[0:1]
	v_lshl_add_u64 v[66:67], v[64:65], 0, v[0:1]
	v_lshl_add_u64 v[70:71], v[70:71], 0, v[0:1]
	v_lshl_add_u64 v[50:51], v[50:51], 0, v[0:1]
	global_load_dwordx4 v[54:57], v[54:55], off
	s_nop 0
	global_load_dwordx4 v[58:61], v[58:59], off
	s_nop 0
	global_load_dwordx4 v[62:65], v[62:63], off
	s_nop 0
	global_load_dwordx4 v[66:69], v[66:67], off
	s_nop 0
	global_load_dwordx4 v[114:117], v[70:71], off
	global_load_dwordx4 v[118:121], v[50:51], off
	v_mad_i64_i32 v[50:51], s[2:3], v77, s67, v[52:53]
	v_lshl_add_u64 v[50:51], v[50:51], 0, v[0:1]
	v_mad_i64_i32 v[52:53], s[2:3], v78, s67, v[52:53]
	v_lshl_add_u64 v[52:53], v[52:53], 0, v[0:1]
	global_load_dwordx4 v[122:125], v[50:51], off
	global_load_dwordx4 v[126:129], v[52:53], off
	s_cmp_eq_u64 vcc, exec
	v_exp_f32_e32 v0, v76
	s_cselect_b64 vcc, -1, 0
	s_addk_i32 s1, 0x4000
	v_add_u32_e32 v175, s1, v74
	s_add_u32 s1, s84, s86
	s_addc_u32 s3, s85, s87
	v_cndmask_b32_e32 v150, v75, v205, vcc
	s_add_u32 s2, s1, s11
	v_cndmask_b32_e64 v197, v0, 1.0, vcc
	v_mul_f32_e32 v0, 0xbe0293ee, v150
	s_addc_u32 s3, s3, 0
	v_pk_fma_f32 v[142:143], v[18:19], s[62:63], v[0:1] op_sel_hi:[1,0,0]
	v_mov_b64_e32 v[18:19], s[2:3]
	v_mad_i64_i32 v[162:163], s[2:3], v73, s67, v[18:19]
	s_add_u32 s1, s84, s88
	v_mov_b32_e32 v50, v0
	s_addc_u32 s3, s85, s89
	v_fmamk_f32 v34, v34, 0x3e0293ee, v0
	v_fmamk_f32 v35, v35, 0x3e0293ee, v0
	v_fmamk_f32 v36, v36, 0x3e0293ee, v0
	v_fmamk_f32 v37, v37, 0x3e0293ee, v0
	v_fmamk_f32 v38, v38, 0x3e0293ee, v0
	v_fmamk_f32 v39, v39, 0x3e0293ee, v0
	v_fmamk_f32 v40, v40, 0x3e0293ee, v0
	v_fmamk_f32 v41, v41, 0x3e0293ee, v0
	v_fmamk_f32 v42, v42, 0x3e0293ee, v0
	v_fmamk_f32 v43, v43, 0x3e0293ee, v0
	v_fmamk_f32 v44, v44, 0x3e0293ee, v0
	v_fmamk_f32 v45, v45, 0x3e0293ee, v0
	v_fmamk_f32 v46, v46, 0x3e0293ee, v0
	v_fmamk_f32 v47, v47, 0x3e0293ee, v0
	v_fmamk_f32 v48, v48, 0x3e0293ee, v0
	v_fmac_f32_e32 v50, 0x3e0293ee, v49
	s_add_u32 s2, s1, s13
	v_exp_f32_e32 v161, v34
	v_exp_f32_e32 v167, v35
	v_exp_f32_e32 v147, v36
	v_exp_f32_e32 v166, v37
	v_exp_f32_e32 v148, v38
	v_exp_f32_e32 v160, v39
	v_exp_f32_e32 v149, v40
	v_exp_f32_e32 v159, v41
	v_exp_f32_e32 v156, v42
	v_exp_f32_e32 v158, v43
	v_exp_f32_e32 v154, v44
	v_exp_f32_e32 v157, v45
	v_exp_f32_e32 v152, v46
	v_exp_f32_e32 v155, v47
	v_exp_f32_e32 v151, v48
	v_exp_f32_e32 v153, v50
	s_addc_u32 s3, s3, 0
	s_waitcnt vmcnt(4)
	v_mov_b64_e32 v[18:19], s[2:3]
	v_mov_b64_e32 v[14:15], s[28:29]
	v_pk_fma_f32 v[136:137], v[32:33], s[62:63], v[0:1] op_sel_hi:[1,0,0]
	v_pk_fma_f32 v[138:139], v[30:31], s[62:63], v[0:1] op_sel_hi:[1,0,0]
	v_pk_fma_f32 v[144:145], v[28:29], s[62:63], v[0:1] op_sel_hi:[1,0,0]
	v_pk_fma_f32 v[130:131], v[26:27], s[62:63], v[0:1] op_sel_hi:[1,0,0]
	v_pk_fma_f32 v[132:133], v[24:25], s[62:63], v[0:1] op_sel_hi:[1,0,0]
	v_pk_fma_f32 v[134:135], v[22:23], s[62:63], v[0:1] op_sel_hi:[1,0,0]
	v_pk_fma_f32 v[140:141], v[20:21], s[62:63], v[0:1] op_sel_hi:[1,0,0]
	s_waitcnt vmcnt(7)
	ds_write_b128 v192, v[54:57] offset:16384
	s_waitcnt vmcnt(6)
	ds_write_b128 v193, v[58:61] offset:16384
	s_waitcnt vmcnt(5)
	ds_write_b128 v177, v[62:65] offset:49152
	s_waitcnt vmcnt(4)
	ds_write_b128 v191, v[66:69] offset:49152
	v_and_b32_e32 v0, 15, v72
	v_mad_i64_i32 v[164:165], s[2:3], v73, s79, v[18:19]
	v_mov_b64_e32 v[64:65], v[16:17]
	v_mov_b64_e32 v[48:49], v[16:17]
	v_mov_b64_e32 v[32:33], v[16:17]
	s_mov_b32 s24, 0x3fb8aa3b
	v_lshlrev_b32_e32 v0, 4, v0
	v_mov_b64_e32 v[62:63], v[14:15]
	v_mov_b64_e32 v[60:61], v[12:13]
	v_mov_b64_e32 v[58:59], v[10:11]
	v_mov_b64_e32 v[56:57], v[8:9]
	v_mov_b64_e32 v[54:55], v[6:7]
	v_mov_b64_e32 v[52:53], v[4:5]
	v_mov_b64_e32 v[50:51], v[2:3]
	v_mov_b64_e32 v[46:47], v[14:15]
	v_mov_b64_e32 v[44:45], v[12:13]
	v_mov_b64_e32 v[42:43], v[10:11]
	v_mov_b64_e32 v[40:41], v[8:9]
	v_mov_b64_e32 v[38:39], v[6:7]
	v_mov_b64_e32 v[36:37], v[4:5]
	v_mov_b64_e32 v[34:35], v[2:3]
	v_mov_b64_e32 v[30:31], v[14:15]
	v_mov_b64_e32 v[28:29], v[12:13]
	v_mov_b64_e32 v[26:27], v[10:11]
	v_mov_b64_e32 v[24:25], v[8:9]
	v_mov_b64_e32 v[22:23], v[6:7]
	v_mov_b64_e32 v[20:21], v[4:5]
	v_mov_b64_e32 v[18:19], v[2:3]
	s_waitcnt lgkmcnt(0)
	s_barrier
	v_xor_b32_e32 v192, 0x10000, v192
	v_xor_b32_e32 v193, 0x10000, v193
	v_xor_b32_e32 v177, 0x10000, v177
	v_xor_b32_e32 v191, 0x10000, v191
; #define SBAR() __builtin_amdgcn_sched_barrier(0)
; #define SLOAD(i, k0) do { sr_[i].vs0 = ld8(&Vh[(long)((k0) + sr) * LDV + sc]); sr_[i].vs1 = ld8(&Vh[(long)((k0) + 32 + sr) * LDV + sc]); \
;     sr_[i].ks0 = ld8(&Kh[(long)((k0) + sr) * LDK + sc]); sr_[i].ks1 = ld8(&Kh[(long)((k0) + 32 + sr) * LDK + sc]); } while (0)
; __device__ __forceinline__ void finishSM(f32x16& p0, f32x16& p1, float alpha, float& l_reg, bf16x8& pa0, bf16x8& pa1, bf16x8& pa2, bf16x8& pa3) {
; #pragma unroll
;   for (int r = 0; r < 16; ++r) p1[r] = __builtin_amdgcn_exp2f(p1[r]);
;   float ps = 0;
; #pragma unroll
;   for (int r = 0; r < 16; ++r) ps += p0[r];
; #pragma unroll
;   for (int r = 0; r < 16; ++r) ps += p1[r];
;   { auto rr = __builtin_amdgcn_permlane32_swap(__float_as_uint(ps), __float_as_uint(ps), false, false);
;     ps = __uint_as_float(rr[0]) + __uint_as_float(rr[1]); }
;   l_reg = l_reg * alpha + ps;
;   PK4(p0, 0, pa0); PK4(p0, 8, pa1); PK4(p1, 0, pa2); PK4(p1, 8, pa3);
; }
; template <int DLO, int DHI>
; __device__ __forceinline__ void attn_dense_body(const int g_wave, const bf16* __restrict__ Qb, const bf16* __restrict__ Kh, const bf16* __restrict__ Vh,
;                                                 bf16* __restrict__ Ob, int ldo, char* lds) {
;     ...
;   for (int j = 1; j + 1 < NT; j += 2) {
;     SBAR(); qkt<DLO, DHI>(pB0, pB1, (bf16*)((char*)K_lds + SHM_K), qr, r32, hi);
;     finishSM(pA0, pA1, alA, l_reg, pa0, pa1, pa2, pa3); SBAR();
;     SLOAD(SO, (j + 2) * KVBLK); SBAR();
;     pv_d0(o, vb0, pa0, pa1, pa2, pa3); partialSM(pB0, pB1, m_reg, mnB, alB);
.LBB0_1002:
	ds_read_b128 v[66:69], v190 offset:49152
	ds_read_b128 v[70:73], v190 offset:57344
	v_add_f32_e32 v146, 0, v161
	v_add_f32_e32 v146, v167, v146
	v_add_f32_e32 v146, v147, v146
	s_waitcnt lgkmcnt(1)
	v_mfma_f32_32x32x16_bf16 v[82:97], v[66:69], v[102:105], 0
	v_add_f32_e32 v146, v166, v146
	v_add_f32_e32 v146, v148, v146
	ds_read_b128 v[186:189], v194 offset:49152
	ds_read_b128 v[208:211], v194 offset:57344
	v_add_f32_e32 v146, v160, v146
	v_add_f32_e32 v146, v149, v146
	v_add_f32_e32 v146, v159, v146
	v_add_f32_e32 v146, v156, v146
	s_waitcnt lgkmcnt(2)
	v_mfma_f32_32x32x16_bf16 v[66:81], v[70:73], v[102:105], 0
	v_add_f32_e32 v146, v158, v146
	v_add_f32_e32 v146, v154, v146
	v_add_f32_e32 v146, v157, v146
	v_exp_f32_e32 v142, v142
	v_add_f32_e32 v146, v152, v146
	v_exp_f32_e32 v143, v143
	v_add_f32_e32 v146, v155, v146
	s_waitcnt lgkmcnt(1)
	v_mfma_f32_32x32x16_bf16 v[82:97], v[186:189], v[98:101], v[82:97]
	v_exp_f32_e32 v140, v140
	v_add_f32_e32 v146, v151, v146
	v_exp_f32_e32 v141, v141
	v_add_f32_e32 v146, v153, v146
	v_exp_f32_e32 v134, v134
	v_add_f32_e32 v146, v142, v146
	v_exp_f32_e32 v135, v135
	s_waitcnt lgkmcnt(0)
	v_mfma_f32_32x32x16_bf16 v[66:81], v[208:211], v[98:101], v[66:81]
	ds_read_b128 v[186:189], v195 offset:49152
	ds_read_b128 v[208:211], v195 offset:57344
	v_add_f32_e32 v146, v143, v146
	v_exp_f32_e32 v132, v132
	v_add_f32_e32 v146, v140, v146
	v_exp_f32_e32 v133, v133
	v_add_f32_e32 v146, v141, v146
	v_exp_f32_e32 v130, v130
	s_waitcnt lgkmcnt(1)
	v_mfma_f32_32x32x16_bf16 v[82:97], v[186:189], v[106:109], v[82:97]
	v_add_f32_e32 v146, v134, v146
	v_exp_f32_e32 v131, v131
	v_add_f32_e32 v146, v135, v146
	v_exp_f32_e32 v144, v144
	v_add_f32_e32 v146, v132, v146
	v_exp_f32_e32 v145, v145
	v_add_f32_e32 v146, v133, v146
	s_waitcnt lgkmcnt(0)
	v_mfma_f32_32x32x16_bf16 v[66:81], v[208:211], v[106:109], v[66:81]
	ds_read_b128 v[186:189], v196 offset:49152
	ds_read_b128 v[208:211], v196 offset:57344
	v_exp_f32_e32 v138, v138
	v_add_f32_e32 v146, v130, v146
	v_exp_f32_e32 v139, v139
	v_add_f32_e32 v146, v131, v146
	v_exp_f32_e32 v136, v136
	v_add_f32_e32 v146, v144, v146
	s_waitcnt lgkmcnt(1)
	v_mfma_f32_32x32x16_bf16 v[82:97], v[186:189], v[110:113], v[82:97]
	v_exp_f32_e32 v137, v137
	v_add_f32_e32 v146, v145, v146
	v_add_f32_e32 v146, v138, v146
	v_add_f32_e32 v146, v139, v146
	v_add_f32_e32 v146, v136, v146
	v_add_f32_e32 v207, v137, v146
	v_cvt_pk_bf16_f32 v146, v161, v167
	s_waitcnt lgkmcnt(0)
	v_mfma_f32_32x32x16_bf16 v[66:81], v[208:211], v[110:113], v[66:81]
	v_mov_b32_e32 v208, v207
	v_cvt_pk_bf16_f32 v147, v147, v166
	v_cvt_pk_bf16_f32 v148, v148, v160
	s_nop 1
	v_permlane32_swap_b32_e32 v207, v208
	v_cvt_pk_bf16_f32 v149, v149, v159
	v_permlane32_swap_b32_e32 v146, v148
	v_cvt_pk_bf16_f32 v156, v156, v158
	v_cvt_pk_bf16_f32 v157, v154, v157
	v_cvt_pk_bf16_f32 v158, v152, v155
	v_cvt_pk_bf16_f32 v159, v151, v153
	v_cvt_pk_bf16_f32 v152, v142, v143
	v_cvt_pk_bf16_f32 v153, v140, v141
	v_cvt_pk_bf16_f32 v154, v134, v135
	v_cvt_pk_bf16_f32 v155, v132, v133
	v_cvt_pk_bf16_f32 v186, v130, v131
	v_cvt_pk_bf16_f32 v187, v144, v145
	v_cvt_pk_bf16_f32 v188, v138, v139
	v_cvt_pk_bf16_f32 v189, v136, v137
	v_permlane32_swap_b32_e32 v147, v149
	v_permlane32_swap_b32_e32 v156, v158
	v_permlane32_swap_b32_e32 v157, v159
	v_permlane32_swap_b32_e32 v152, v154
	v_permlane32_swap_b32_e32 v153, v155
	v_permlane32_swap_b32_e32 v186, v188
	v_permlane32_swap_b32_e32 v187, v189
	s_waitcnt vmcnt(0)
	ds_write_b128 v192, v[114:117]
	ds_write_b128 v193, v[118:121]
	ds_write_b128 v177, v[122:125] offset:32768
	ds_write_b128 v191, v[126:129] offset:32768
	v_lshl_add_u64 v[168:169], v[164:165], 0, v[0:1]
	s_mov_b32 s1, 0x18fb0000
	v_add_co_u32_e32 v130, vcc, s1, v168
	s_mov_b32 s1, 0x18ff8000
	s_nop 0
	v_addc_co_u32_e32 v131, vcc, 0, v169, vcc
	v_add_co_u32_e32 v134, vcc, s1, v168
	v_lshl_add_u64 v[166:167], v[162:163], 0, v[0:1]
	s_nop 0
	v_addc_co_u32_e32 v135, vcc, 0, v169, vcc
	s_mov_b32 s1, 0x1f648000
	v_add_co_u32_e32 v138, vcc, s1, v166
	s_mov_b32 s1, 0x1f654000
	s_nop 0
	v_addc_co_u32_e32 v139, vcc, 0, v167, vcc
	v_add_co_u32_e32 v142, vcc, s1, v166
	global_load_dwordx4 v[130:133], v[130:131], off
	s_nop 0
	global_load_dwordx4 v[134:137], v[134:135], off
	v_addc_co_u32_e32 v143, vcc, 0, v167, vcc
	global_load_dwordx4 v[138:141], v[138:139], off
	s_nop 0
	global_load_dwordx4 v[142:145], v[142:143], off
	ds_read_b64_tr_b16 v[210:211], v176 offset:0
	ds_read_b64_tr_b16 v[212:213], v176 offset:0x800
	ds_read_b64_tr_b16 v[214:215], v176 offset:0x1000
	ds_read_b64_tr_b16 v[216:217], v176 offset:0x1800
	ds_read_b64_tr_b16 v[218:219], v176 offset:0x2000
	ds_read_b64_tr_b16 v[220:221], v176 offset:0x2800
	ds_read_b64_tr_b16 v[222:223], v176 offset:0x3000
	ds_read_b64_tr_b16 v[224:225], v176 offset:0x3800
	s_waitcnt lgkmcnt(6)
	s_nop 0
	v_mfma_f32_32x32x16_bf16 v[2:17], v[146:149], v[210:213], v[2:17]
	ds_read_b64_tr_b16 v[210:211], v176 offset:0x200
	ds_read_b64_tr_b16 v[212:213], v176 offset:0xa00
	s_waitcnt lgkmcnt(6)
	v_mfma_f32_32x32x16_bf16 v[2:17], v[156:159], v[214:217], v[2:17]
	ds_read_b64_tr_b16 v[214:215], v176 offset:0x1200
	ds_read_b64_tr_b16 v[216:217], v176 offset:0x1a00
	s_waitcnt lgkmcnt(6)
	v_mfma_f32_32x32x16_bf16 v[2:17], v[152:155], v[218:221], v[2:17]
	ds_read_b64_tr_b16 v[218:219], v176 offset:0x2200
	ds_read_b64_tr_b16 v[220:221], v176 offset:0x2a00
	s_waitcnt lgkmcnt(6)
	v_mfma_f32_32x32x16_bf16 v[2:17], v[186:189], v[222:225], v[2:17]
	ds_read_b64_tr_b16 v[222:223], v176 offset:0x3200
	ds_read_b64_tr_b16 v[224:225], v176 offset:0x3a00
	s_waitcnt lgkmcnt(6)
; #define SBAR() __builtin_amdgcn_sched_barrier(0)
; #define SWRITE(b, i) do { *(bf16x8*)((char*)V_lds + (b) * SHM_V + vst0) = sr_[i].vs0;          \
;     *(bf16x8*)((char*)V_lds + (b) * SHM_V + vst1) = sr_[i].vs1; int kc = sc * 2;               \
;     *(bf16x8*)((char*)K_lds + (b) * SHM_K + KSWZ(sr, kc)) = sr_[i].ks0;                       \
;     *(bf16x8*)((char*)K_lds + (b) * SHM_K + KSWZ(32 + sr, kc)) = sr_[i].ks1; } while (0)
; #define SWAIT() asm volatile("s_waitcnt vmcnt(4)" ::: "memory")
; #define RESC(a) do { if (__any((a) < 1.f)) { if (hi == 0) al_l[r32] = (a); asm volatile("s_waitcnt lgkmcnt(0)" ::: "memory"); \
;     _Pragma("unroll") for (int d = 0; d < 4; ++d) _Pragma("unroll") for (int r = 0; r < 16; ++r) o[d][r] *= al_l[crow(r, hi)]; } } while (0)
; template <int D0> __device__ __forceinline__ void pv_one(f32x16& od, int vb, bf16x8 pa0, bf16x8 pa1, bf16x8 pa2, bf16x8 pa3) {
;   const s16x4 l0 = tr_read<v_rd_off(D0, 0, 0)>(vb), h0 = tr_read<v_rd_off(D0, 0, 1)>(vb), l1 = tr_read<v_rd_off(D0, 1, 0)>(vb), h1 = tr_read<v_rd_off(D0, 1, 1)>(vb);
;   const s16x4 l2 = tr_read<v_rd_off(D0, 2, 0)>(vb), h2 = tr_read<v_rd_off(D0, 2, 1)>(vb), l3 = tr_read<v_rd_off(D0, 3, 0)>(vb), h3 = tr_read<v_rd_off(D0, 3, 1)>(vb);
;   asm volatile("s_waitcnt lgkmcnt(0)" ::: "memory"); SBAR();
;     ...
;   od = __builtin_amdgcn_mfma_f32_32x32x16_bf16(pa0, PK(l0, h0), od, 0, 0, 0);
;   od = __builtin_amdgcn_mfma_f32_32x32x16_bf16(pa1, PK(l1, h1), od, 0, 0, 0);
;   od = __builtin_amdgcn_mfma_f32_32x32x16_bf16(pa2, PK(l2, h2), od, 0, 0, 0);
;   od = __builtin_amdgcn_mfma_f32_32x32x16_bf16(pa3, PK(l3, h3), od, 0, 0, 0);
;     ...
; }
; __device__ __forceinline__ void pv_d0(f32x16* o, int vb, bf16x8 pa0, bf16x8 pa1, bf16x8 pa2, bf16x8 pa3) {
;   pv_one<0>(o[0], vb, pa0, pa1, pa2, pa3); pv_one<1>(o[1], vb, pa0, pa1, pa2, pa3); pv_one<2>(o[2], vb, pa0, pa1, pa2, pa3); pv_one<3>(o[3], vb, pa0, pa1, pa2, pa3);
; template <int DLO, int DHI>
; __device__ __forceinline__ void attn_dense_body(const int g_wave, const bf16* __restrict__ Qb, const bf16* __restrict__ Kh, const bf16* __restrict__ Vh,
;                                                 bf16* __restrict__ Ob, int ldo, char* lds) {
;     ...
;     pv_d0(o, vb0, pa0, pa1, pa2, pa3); partialSM(pB0, pB1, m_reg, mnB, alB);
;     __syncthreads(); SWAIT(); SWRITE(0, SE);
;     RESC(alB); __syncthreads();
	v_mfma_f32_32x32x16_bf16 v[50:65], v[146:149], v[210:213], v[50:65]
	ds_read_b64_tr_b16 v[210:211], v176 offset:0x400
	ds_read_b64_tr_b16 v[212:213], v176 offset:0xc00
	s_waitcnt lgkmcnt(6)
	v_mfma_f32_32x32x16_bf16 v[50:65], v[156:159], v[214:217], v[50:65]
	ds_read_b64_tr_b16 v[214:215], v176 offset:0x1400
	ds_read_b64_tr_b16 v[216:217], v176 offset:0x1c00
	s_waitcnt lgkmcnt(6)
	v_mfma_f32_32x32x16_bf16 v[50:65], v[152:155], v[218:221], v[50:65]
	ds_read_b64_tr_b16 v[218:219], v176 offset:0x2400
	ds_read_b64_tr_b16 v[220:221], v176 offset:0x2c00
	s_waitcnt lgkmcnt(6)
	v_mfma_f32_32x32x16_bf16 v[50:65], v[186:189], v[222:225], v[50:65]
	ds_read_b64_tr_b16 v[222:223], v176 offset:0x3400
	ds_read_b64_tr_b16 v[224:225], v176 offset:0x3c00
	s_waitcnt lgkmcnt(6)
	v_mfma_f32_32x32x16_bf16 v[34:49], v[146:149], v[210:213], v[34:49]
	ds_read_b64_tr_b16 v[210:211], v176 offset:0x600
	ds_read_b64_tr_b16 v[212:213], v176 offset:0xe00
	s_waitcnt lgkmcnt(6)
	v_mfma_f32_32x32x16_bf16 v[34:49], v[156:159], v[214:217], v[34:49]
	ds_read_b64_tr_b16 v[214:215], v176 offset:0x1600
	ds_read_b64_tr_b16 v[216:217], v176 offset:0x1e00
	s_waitcnt lgkmcnt(6)
	v_mfma_f32_32x32x16_bf16 v[34:49], v[152:155], v[218:221], v[34:49]
	ds_read_b64_tr_b16 v[218:219], v176 offset:0x2600
	ds_read_b64_tr_b16 v[220:221], v176 offset:0x2e00
	s_waitcnt lgkmcnt(6)
	v_mfma_f32_32x32x16_bf16 v[34:49], v[186:189], v[222:225], v[34:49]
	ds_read_b64_tr_b16 v[222:223], v176 offset:0x3600
	ds_read_b64_tr_b16 v[224:225], v176 offset:0x3e00
	s_waitcnt lgkmcnt(6)
	v_mfma_f32_32x32x16_bf16 v[18:33], v[146:149], v[210:213], v[18:33]
	v_max_f32_e32 v146, v83, v83
	v_max_f32_e32 v147, v82, v82
	v_max_f32_e32 v146, v147, v146
	v_max3_f32 v146, v146, v84, v85
	v_max3_f32 v146, v146, v86, v87
	v_max3_f32 v146, v146, v88, v89
	v_max3_f32 v146, v146, v90, v91
	v_max3_f32 v146, v146, v92, v93
	v_max3_f32 v146, v146, v94, v95
	s_waitcnt lgkmcnt(4)
	v_mfma_f32_32x32x16_bf16 v[18:33], v[156:159], v[214:217], v[18:33]
	v_max3_f32 v146, v146, v96, v97
	v_max3_f32 v146, v146, v66, v67
	v_max3_f32 v146, v146, v68, v69
	v_max3_f32 v146, v146, v70, v71
	v_max3_f32 v146, v146, v72, v73
	v_max3_f32 v146, v146, v74, v75
	v_max3_f32 v146, v146, v76, v77
	v_max3_f32 v146, v146, v78, v79
	s_waitcnt lgkmcnt(2)
	v_mfma_f32_32x32x16_bf16 v[18:33], v[152:155], v[218:221], v[18:33]
	v_max3_f32 v146, v146, v80, v81
	v_mov_b32_e32 v147, v146
	s_nop 1
	v_permlane32_swap_b32_e32 v146, v147
	v_max_f32_e32 v147, v147, v147
	v_max_f32_e32 v146, v146, v146
	v_max_f32_e32 v146, v146, v147
	v_sub_f32_e32 v147, v146, v150
	v_cmp_ge_f32_e32 vcc, s63, v147
	v_max_f32_e32 v147, v150, v150
	v_max_f32_e32 v146, v147, v146
	s_waitcnt lgkmcnt(0)
	v_mfma_f32_32x32x16_bf16 v[18:33], v[186:189], v[222:225], v[18:33]
	v_sub_f32_e32 v147, v150, v146
	v_mul_f32_e32 v147, 0x3e0293ee, v147
	v_exp_f32_e32 v147, v147
	s_cmp_eq_u64 vcc, exec
	s_cselect_b64 s[8:9], -1, 0
	s_waitcnt vmcnt(4)
	v_cndmask_b32_e64 v209, v147, 1.0, s[8:9]
	v_cmp_gt_f32_e32 vcc, 1.0, v209
	s_cbranch_vccz .LBB0_1006
	s_and_saveexec_b64 s[2:3], s[6:7]
	ds_write_b32 v173, v209 offset:128
	s_or_b64 exec, exec, s[2:3]
	s_waitcnt lgkmcnt(0)
	v_add_u32_e32 v147, s15, v172
	ds_read_b128 v[152:155], v147 offset:224
	ds_read_b128 v[156:159], v147 offset:192
	ds_read_b128 v[186:189], v147 offset:160
	ds_read_b128 v[210:213], v147 offset:128
	s_waitcnt lgkmcnt(3)
	v_pk_mul_f32 v[14:15], v[14:15], v[152:153]
	s_waitcnt lgkmcnt(2)
	v_pk_mul_f32 v[10:11], v[10:11], v[156:157]
	s_waitcnt lgkmcnt(1)
	v_pk_mul_f32 v[6:7], v[6:7], v[186:187]
	v_pk_mul_f32 v[16:17], v[16:17], v[154:155]
	v_pk_mul_f32 v[12:13], v[12:13], v[158:159]
	v_pk_mul_f32 v[8:9], v[8:9], v[188:189]
	s_waitcnt lgkmcnt(0)
	v_pk_mul_f32 v[4:5], v[4:5], v[212:213]
	v_pk_mul_f32 v[2:3], v[2:3], v[210:211]
	v_pk_mul_f32 v[62:63], v[62:63], v[152:153]
	v_pk_mul_f32 v[58:59], v[58:59], v[156:157]
	v_pk_mul_f32 v[54:55], v[54:55], v[186:187]
	v_pk_mul_f32 v[64:65], v[64:65], v[154:155]
	v_pk_mul_f32 v[60:61], v[60:61], v[158:159]
	v_pk_mul_f32 v[56:57], v[56:57], v[188:189]
	v_pk_mul_f32 v[52:53], v[52:53], v[212:213]
	v_pk_mul_f32 v[50:51], v[50:51], v[210:211]
	v_pk_mul_f32 v[46:47], v[46:47], v[152:153]
	v_pk_mul_f32 v[42:43], v[42:43], v[156:157]
	v_pk_mul_f32 v[38:39], v[38:39], v[186:187]
	v_pk_mul_f32 v[48:49], v[48:49], v[154:155]
	v_pk_mul_f32 v[44:45], v[44:45], v[158:159]
	v_pk_mul_f32 v[40:41], v[40:41], v[188:189]
	v_pk_mul_f32 v[36:37], v[36:37], v[212:213]
	v_pk_mul_f32 v[34:35], v[34:35], v[210:211]
	v_pk_mul_f32 v[30:31], v[30:31], v[152:153]
	v_pk_mul_f32 v[26:27], v[26:27], v[156:157]
	v_pk_mul_f32 v[22:23], v[22:23], v[186:187]
	v_pk_mul_f32 v[32:33], v[32:33], v[154:155]
	v_pk_mul_f32 v[28:29], v[28:29], v[158:159]
	v_pk_mul_f32 v[24:25], v[24:25], v[188:189]
	v_pk_mul_f32 v[20:21], v[20:21], v[212:213]
	v_pk_mul_f32 v[18:19], v[18:19], v[210:211]
; #define SBAR() __builtin_amdgcn_sched_barrier(0)
; #define SLOAD(i, k0) do { sr_[i].vs0 = ld8(&Vh[(long)((k0) + sr) * LDV + sc]); sr_[i].vs1 = ld8(&Vh[(long)((k0) + 32 + sr) * LDV + sc]); \
;     sr_[i].ks0 = ld8(&Kh[(long)((k0) + sr) * LDK + sc]); sr_[i].ks1 = ld8(&Kh[(long)((k0) + 32 + sr) * LDK + sc]); } while (0)
; __device__ __forceinline__ void finishSM(f32x16& p0, f32x16& p1, float alpha, float& l_reg, bf16x8& pa0, bf16x8& pa1, bf16x8& pa2, bf16x8& pa3) {
; #pragma unroll
;   for (int r = 0; r < 16; ++r) p1[r] = __builtin_amdgcn_exp2f(p1[r]);
;   float ps = 0;
; #pragma unroll
;   for (int r = 0; r < 16; ++r) ps += p0[r];
; #pragma unroll
;   for (int r = 0; r < 16; ++r) ps += p1[r];
;   { auto rr = __builtin_amdgcn_permlane32_swap(__float_as_uint(ps), __float_as_uint(ps), false, false);
;     ps = __uint_as_float(rr[0]) + __uint_as_float(rr[1]); }
;   l_reg = l_reg * alpha + ps;
;   PK4(p0, 0, pa0); PK4(p0, 8, pa1); PK4(p1, 0, pa2); PK4(p1, 8, pa3);
; }
; template <int DLO, int DHI>
; __device__ __forceinline__ void attn_dense_body(const int g_wave, const bf16* __restrict__ Qb, const bf16* __restrict__ Kh, const bf16* __restrict__ Vh,
;                                                 bf16* __restrict__ Ob, int ldo, char* lds) {
;     ...
;     SBAR(); qkt<DLO, DHI>(pA0, pA1, K_lds, qr, r32, hi);
;     finishSM(pB0, pB1, alB, l_reg, pa0, pa1, pa2, pa3); SBAR();
;     if (j + 3 < NT) SLOAD(SE, (j + 3) * KVBLK); SBAR();
;     pv_d0(o, vb0 + (int)SHM_V, pa0, pa1, pa2, pa3); partialSM(pA0, pA1, m_reg, mnA, alA);
.LBB0_1006:
	v_cndmask_b32_e64 v210, v146, v150, s[8:9]
	v_mul_f32_e32 v211, 0xbe0293ee, v210
	v_fmamk_f32 v82, v82, 0x3e0293ee, v211
	v_fmamk_f32 v83, v83, 0x3e0293ee, v211
	v_fmamk_f32 v84, v84, 0x3e0293ee, v211
	v_fmamk_f32 v85, v85, 0x3e0293ee, v211
	v_fmamk_f32 v86, v86, 0x3e0293ee, v211
	v_fmamk_f32 v87, v87, 0x3e0293ee, v211
	v_fmamk_f32 v88, v88, 0x3e0293ee, v211
	v_fmamk_f32 v89, v89, 0x3e0293ee, v211
	v_fmamk_f32 v90, v90, 0x3e0293ee, v211
	v_fmamk_f32 v91, v91, 0x3e0293ee, v211
	v_fmamk_f32 v92, v92, 0x3e0293ee, v211
	v_fmamk_f32 v93, v93, 0x3e0293ee, v211
	v_fmamk_f32 v94, v94, 0x3e0293ee, v211
	v_fmamk_f32 v95, v95, 0x3e0293ee, v211
	v_fmamk_f32 v96, v96, 0x3e0293ee, v211
	v_fmamk_f32 v97, v97, 0x3e0293ee, v211
	v_exp_f32_e32 v146, v82
	v_exp_f32_e32 v161, v83
	v_exp_f32_e32 v147, v84
	v_exp_f32_e32 v160, v85
	v_exp_f32_e32 v148, v86
	v_exp_f32_e32 v159, v87
	v_exp_f32_e32 v149, v88
	v_exp_f32_e32 v158, v89
	v_exp_f32_e32 v150, v90
	v_exp_f32_e32 v157, v91
	v_exp_f32_e32 v151, v92
	v_exp_f32_e32 v156, v93
	v_exp_f32_e32 v152, v94
	v_exp_f32_e32 v155, v95
	v_exp_f32_e32 v153, v96
	v_exp_f32_e32 v154, v97
	v_fmamk_f32 v220, v66, 0x3e0293ee, v211
	v_fmamk_f32 v221, v67, 0x3e0293ee, v211
	v_fmamk_f32 v222, v68, 0x3e0293ee, v211
	v_fmamk_f32 v223, v69, 0x3e0293ee, v211
	v_fmamk_f32 v224, v70, 0x3e0293ee, v211
	v_fmamk_f32 v213, v71, 0x3e0293ee, v211
	v_fmamk_f32 v214, v72, 0x3e0293ee, v211
	v_fmamk_f32 v215, v73, 0x3e0293ee, v211
	v_fmamk_f32 v216, v74, 0x3e0293ee, v211
	v_fmamk_f32 v217, v75, 0x3e0293ee, v211
	v_fmamk_f32 v218, v76, 0x3e0293ee, v211
	v_fmamk_f32 v219, v77, 0x3e0293ee, v211
	v_fmamk_f32 v212, v78, 0x3e0293ee, v211
	v_fmamk_f32 v225, v79, 0x3e0293ee, v211
	v_fmamk_f32 v226, v80, 0x3e0293ee, v211
	v_fmac_f32_e32 v211, 0x3e0293ee, v81
	s_waitcnt lgkmcnt(0)
	s_barrier
	v_xor_b32_e32 v190, 0x10000, v190
	v_xor_b32_e32 v194, 0x10000, v194
	v_xor_b32_e32 v195, 0x10000, v195
	v_xor_b32_e32 v196, 0x10000, v196
	ds_read_b128 v[66:69], v190 offset:32768
	ds_read_b128 v[70:73], v190 offset:40960
	ds_read_b128 v[186:189], v194 offset:32768
	ds_read_b128 v[228:231], v194 offset:40960
	v_exp_f32_e32 v213, v213
	v_exp_f32_e32 v214, v214
	s_waitcnt lgkmcnt(3)
	v_mfma_f32_32x32x16_bf16 v[82:97], v[66:69], v[102:105], 0
	v_exp_f32_e32 v215, v215
	v_exp_f32_e32 v216, v216
	v_exp_f32_e32 v217, v217
	v_exp_f32_e32 v218, v218
	v_exp_f32_e32 v219, v219
	s_waitcnt lgkmcnt(2)
	v_mfma_f32_32x32x16_bf16 v[66:81], v[70:73], v[102:105], 0
	s_waitcnt lgkmcnt(1)
	v_mfma_f32_32x32x16_bf16 v[82:97], v[186:189], v[98:101], v[82:97]
	s_waitcnt lgkmcnt(0)
	v_mfma_f32_32x32x16_bf16 v[66:81], v[228:231], v[98:101], v[66:81]
	ds_read_b128 v[186:189], v195 offset:32768
	ds_read_b128 v[228:231], v195 offset:40960
	s_waitcnt lgkmcnt(1)
	v_mfma_f32_32x32x16_bf16 v[82:97], v[186:189], v[106:109], v[82:97]
	s_waitcnt lgkmcnt(0)
	v_mfma_f32_32x32x16_bf16 v[66:81], v[228:231], v[106:109], v[66:81]
	ds_read_b128 v[186:189], v196 offset:32768
	ds_read_b128 v[228:231], v196 offset:40960
	s_waitcnt lgkmcnt(1)
	v_mfma_f32_32x32x16_bf16 v[82:97], v[186:189], v[110:113], v[82:97]
	v_exp_f32_e32 v186, v220
	v_exp_f32_e32 v220, v224
	v_exp_f32_e32 v224, v211
	v_add_f32_e32 v211, 0, v146
	v_add_f32_e32 v211, v161, v211
	v_add_f32_e32 v211, v147, v211
	v_add_f32_e32 v211, v160, v211
	v_add_f32_e32 v211, v148, v211
	v_add_f32_e32 v211, v159, v211
	v_add_f32_e32 v211, v149, v211
	v_add_f32_e32 v211, v158, v211
	v_add_f32_e32 v211, v150, v211
	v_add_f32_e32 v211, v157, v211
	v_add_f32_e32 v211, v151, v211
	v_add_f32_e32 v211, v156, v211
	v_add_f32_e32 v211, v152, v211
	v_exp_f32_e32 v187, v221
	v_add_f32_e32 v211, v155, v211
	v_exp_f32_e32 v188, v222
	v_add_f32_e32 v211, v153, v211
	v_exp_f32_e32 v189, v223
	v_add_f32_e32 v211, v154, v211
	v_add_f32_e32 v211, v186, v211
	v_add_f32_e32 v211, v187, v211
	v_add_f32_e32 v211, v188, v211
	v_add_f32_e32 v211, v189, v211
	v_add_f32_e32 v211, v220, v211
	v_add_f32_e32 v211, v213, v211
	v_add_f32_e32 v211, v214, v211
	v_add_f32_e32 v211, v215, v211
	v_exp_f32_e32 v221, v212
	v_add_f32_e32 v211, v216, v211
	v_exp_f32_e32 v222, v225
	v_add_f32_e32 v211, v217, v211
	s_waitcnt lgkmcnt(0)
	v_mfma_f32_32x32x16_bf16 v[66:81], v[228:231], v[110:113], v[66:81]
	v_exp_f32_e32 v223, v226
	v_add_f32_e32 v211, v218, v211
	v_add_f32_e32 v211, v219, v211
	v_add_f32_e32 v211, v221, v211
	v_add_f32_e32 v211, v222, v211
	v_add_f32_e32 v211, v223, v211
	v_add_f32_e32 v211, v224, v211
	v_mov_b32_e32 v212, v211
	v_cvt_pk_bf16_f32 v146, v146, v161
	v_cvt_pk_bf16_f32 v147, v147, v160
	v_cvt_pk_bf16_f32 v148, v148, v159
	v_cvt_pk_bf16_f32 v149, v149, v158
	v_cvt_pk_bf16_f32 v150, v150, v157
	v_cvt_pk_bf16_f32 v151, v151, v156
	v_cvt_pk_bf16_f32 v152, v152, v155
	v_cvt_pk_bf16_f32 v153, v153, v154
	v_cvt_pk_bf16_f32 v154, v186, v187
	v_cvt_pk_bf16_f32 v155, v188, v189
	v_cvt_pk_bf16_f32 v156, v220, v213
	v_cvt_pk_bf16_f32 v157, v214, v215
	v_cvt_pk_bf16_f32 v158, v216, v217
	v_cvt_pk_bf16_f32 v159, v218, v219
	v_cvt_pk_bf16_f32 v160, v221, v222
	v_cvt_pk_bf16_f32 v161, v223, v224
	s_nop 1
	v_permlane32_swap_b32_e32 v211, v212
	v_permlane32_swap_b32_e32 v146, v148
	v_permlane32_swap_b32_e32 v147, v149
	v_permlane32_swap_b32_e32 v150, v152
	v_permlane32_swap_b32_e32 v151, v153
	v_permlane32_swap_b32_e32 v154, v156
	v_permlane32_swap_b32_e32 v155, v157
	v_permlane32_swap_b32_e32 v158, v160
	v_permlane32_swap_b32_e32 v159, v161
	s_waitcnt vmcnt(0)
	ds_write_b128 v192, v[130:133] offset:16384
	ds_write_b128 v193, v[134:137] offset:16384
	ds_write_b128 v177, v[138:141] offset:49152
	ds_write_b128 v191, v[142:145] offset:49152
	s_cmp_gt_u32 s34, 60
	s_cselect_b64 s[2:3], -1, 0
	s_and_b64 vcc, exec, s[2:3]
	s_cbranch_vccnz .LBB0_1008
	v_add_co_u32_e32 v114, vcc, 0x19040000, v168
	s_nop 1
	v_addc_co_u32_e32 v115, vcc, 0, v169, vcc
	v_add_co_u32_e32 v118, vcc, 0x19088000, v168
	s_nop 1
	v_addc_co_u32_e32 v119, vcc, 0, v169, vcc
	v_add_co_u32_e32 v122, vcc, 0x1f660000, v166
	global_load_dwordx4 v[114:117], v[114:115], off
	s_nop 0
	global_load_dwordx4 v[118:121], v[118:119], off
	v_addc_co_u32_e32 v123, vcc, 0, v167, vcc
	v_add_co_u32_e32 v126, vcc, 0x1f66c000, v166
	s_nop 1
	v_addc_co_u32_e32 v127, vcc, 0, v167, vcc
	global_load_dwordx4 v[122:125], v[122:123], off
	s_nop 0
	global_load_dwordx4 v[126:129], v[126:127], off
; #define SBAR() __builtin_amdgcn_sched_barrier(0)
; #define SWRITE(b, i) do { *(bf16x8*)((char*)V_lds + (b) * SHM_V + vst0) = sr_[i].vs0;          \
;     *(bf16x8*)((char*)V_lds + (b) * SHM_V + vst1) = sr_[i].vs1; int kc = sc * 2;               \
;     *(bf16x8*)((char*)K_lds + (b) * SHM_K + KSWZ(sr, kc)) = sr_[i].ks0;                       \
;     *(bf16x8*)((char*)K_lds + (b) * SHM_K + KSWZ(32 + sr, kc)) = sr_[i].ks1; } while (0)
; #define SWAIT() asm volatile("s_waitcnt vmcnt(4)" ::: "memory")
; #define RESC(a) do { if (__any((a) < 1.f)) { if (hi == 0) al_l[r32] = (a); asm volatile("s_waitcnt lgkmcnt(0)" ::: "memory"); \
;     _Pragma("unroll") for (int d = 0; d < 4; ++d) _Pragma("unroll") for (int r = 0; r < 16; ++r) o[d][r] *= al_l[crow(r, hi)]; } } while (0)
; template <int D0> __device__ __forceinline__ void pv_one(f32x16& od, int vb, bf16x8 pa0, bf16x8 pa1, bf16x8 pa2, bf16x8 pa3) {
;   const s16x4 l0 = tr_read<v_rd_off(D0, 0, 0)>(vb), h0 = tr_read<v_rd_off(D0, 0, 1)>(vb), l1 = tr_read<v_rd_off(D0, 1, 0)>(vb), h1 = tr_read<v_rd_off(D0, 1, 1)>(vb);
;   const s16x4 l2 = tr_read<v_rd_off(D0, 2, 0)>(vb), h2 = tr_read<v_rd_off(D0, 2, 1)>(vb), l3 = tr_read<v_rd_off(D0, 3, 0)>(vb), h3 = tr_read<v_rd_off(D0, 3, 1)>(vb);
;   asm volatile("s_waitcnt lgkmcnt(0)" ::: "memory"); SBAR();
;     ...
;   od = __builtin_amdgcn_mfma_f32_32x32x16_bf16(pa0, PK(l0, h0), od, 0, 0, 0);
;   od = __builtin_amdgcn_mfma_f32_32x32x16_bf16(pa1, PK(l1, h1), od, 0, 0, 0);
;   od = __builtin_amdgcn_mfma_f32_32x32x16_bf16(pa2, PK(l2, h2), od, 0, 0, 0);
;   od = __builtin_amdgcn_mfma_f32_32x32x16_bf16(pa3, PK(l3, h3), od, 0, 0, 0);
;     ...
; }
; __device__ __forceinline__ void pv_d0(f32x16* o, int vb, bf16x8 pa0, bf16x8 pa1, bf16x8 pa2, bf16x8 pa3) {
;   pv_one<0>(o[0], vb, pa0, pa1, pa2, pa3); pv_one<1>(o[1], vb, pa0, pa1, pa2, pa3); pv_one<2>(o[2], vb, pa0, pa1, pa2, pa3); pv_one<3>(o[3], vb, pa0, pa1, pa2, pa3);
; template <int DLO, int DHI>
; __device__ __forceinline__ void attn_dense_body(const int g_wave, const bf16* __restrict__ Qb, const bf16* __restrict__ Kh, const bf16* __restrict__ Vh,
;                                                 bf16* __restrict__ Ob, int ldo, char* lds) {
;     ...
;     pv_d0(o, vb0 + (int)SHM_V, pa0, pa1, pa2, pa3); partialSM(pA0, pA1, m_reg, mnA, alA);
;     __syncthreads(); SWAIT(); SWRITE(1, SO);
;     RESC(alA); __syncthreads();
.LBB0_1008:
	ds_read_b64_tr_b16 v[166:167], v175 offset:0
	ds_read_b64_tr_b16 v[168:169], v175 offset:0x800
	ds_read_b64_tr_b16 v[186:187], v175 offset:0x1000
	ds_read_b64_tr_b16 v[188:189], v175 offset:0x1800
	ds_read_b64_tr_b16 v[214:215], v175 offset:0x2000
	ds_read_b64_tr_b16 v[216:217], v175 offset:0x2800
	ds_read_b64_tr_b16 v[218:219], v175 offset:0x3000
	ds_read_b64_tr_b16 v[220:221], v175 offset:0x3800
	s_waitcnt lgkmcnt(6)
	s_nop 0
	v_mfma_f32_32x32x16_bf16 v[2:17], v[146:149], v[166:169], v[2:17]
	ds_read_b64_tr_b16 v[166:167], v175 offset:0x200
	ds_read_b64_tr_b16 v[168:169], v175 offset:0xa00
	s_waitcnt lgkmcnt(6)
	v_mfma_f32_32x32x16_bf16 v[2:17], v[150:153], v[186:189], v[2:17]
	ds_read_b64_tr_b16 v[186:187], v175 offset:0x1200
	ds_read_b64_tr_b16 v[188:189], v175 offset:0x1a00
	s_waitcnt lgkmcnt(6)
	v_mfma_f32_32x32x16_bf16 v[2:17], v[154:157], v[214:217], v[2:17]
	ds_read_b64_tr_b16 v[214:215], v175 offset:0x2200
	ds_read_b64_tr_b16 v[216:217], v175 offset:0x2a00
	s_waitcnt lgkmcnt(6)
	v_mfma_f32_32x32x16_bf16 v[2:17], v[158:161], v[218:221], v[2:17]
	ds_read_b64_tr_b16 v[218:219], v175 offset:0x3200
	ds_read_b64_tr_b16 v[220:221], v175 offset:0x3a00
	s_waitcnt lgkmcnt(6)
	v_mfma_f32_32x32x16_bf16 v[50:65], v[146:149], v[166:169], v[50:65]
	ds_read_b64_tr_b16 v[166:167], v175 offset:0x400
	ds_read_b64_tr_b16 v[168:169], v175 offset:0xc00
	s_waitcnt lgkmcnt(6)
	v_mfma_f32_32x32x16_bf16 v[50:65], v[150:153], v[186:189], v[50:65]
	ds_read_b64_tr_b16 v[186:187], v175 offset:0x1400
	ds_read_b64_tr_b16 v[188:189], v175 offset:0x1c00
	s_waitcnt lgkmcnt(6)
	v_mfma_f32_32x32x16_bf16 v[50:65], v[154:157], v[214:217], v[50:65]
	ds_read_b64_tr_b16 v[214:215], v175 offset:0x2400
	ds_read_b64_tr_b16 v[216:217], v175 offset:0x2c00
	s_waitcnt lgkmcnt(6)
	v_mfma_f32_32x32x16_bf16 v[50:65], v[158:161], v[218:221], v[50:65]
	ds_read_b64_tr_b16 v[218:219], v175 offset:0x3400
	ds_read_b64_tr_b16 v[220:221], v175 offset:0x3c00
	s_waitcnt lgkmcnt(6)
	v_mfma_f32_32x32x16_bf16 v[34:49], v[146:149], v[166:169], v[34:49]
	ds_read_b64_tr_b16 v[166:167], v175 offset:0x600
	ds_read_b64_tr_b16 v[168:169], v175 offset:0xe00
	s_waitcnt lgkmcnt(6)
	v_mfma_f32_32x32x16_bf16 v[34:49], v[150:153], v[186:189], v[34:49]
	ds_read_b64_tr_b16 v[186:187], v175 offset:0x1600
	ds_read_b64_tr_b16 v[188:189], v175 offset:0x1e00
	s_waitcnt lgkmcnt(6)
	v_mfma_f32_32x32x16_bf16 v[34:49], v[154:157], v[214:217], v[34:49]
	ds_read_b64_tr_b16 v[214:215], v175 offset:0x2600
	ds_read_b64_tr_b16 v[216:217], v175 offset:0x2e00
	s_waitcnt lgkmcnt(6)
	v_mfma_f32_32x32x16_bf16 v[34:49], v[158:161], v[218:221], v[34:49]
	ds_read_b64_tr_b16 v[218:219], v175 offset:0x3600
	ds_read_b64_tr_b16 v[220:221], v175 offset:0x3e00
	s_waitcnt lgkmcnt(6)
	v_mfma_f32_32x32x16_bf16 v[18:33], v[146:149], v[166:169], v[18:33]
	v_max_f32_e32 v146, v83, v83
	v_max_f32_e32 v147, v82, v82
	v_max_f32_e32 v146, v147, v146
	v_max3_f32 v146, v146, v84, v85
	v_max3_f32 v146, v146, v86, v87
	v_max3_f32 v146, v146, v88, v89
	v_max3_f32 v146, v146, v90, v91
	v_max3_f32 v146, v146, v92, v93
	v_max3_f32 v146, v146, v94, v95
	s_waitcnt lgkmcnt(4)
	v_mfma_f32_32x32x16_bf16 v[18:33], v[150:153], v[186:189], v[18:33]
	v_max3_f32 v146, v146, v96, v97
	v_max3_f32 v146, v146, v66, v67
	v_max3_f32 v146, v146, v68, v69
	v_max3_f32 v146, v146, v70, v71
	v_max3_f32 v146, v146, v72, v73
	v_max3_f32 v146, v146, v74, v75
	v_max3_f32 v146, v146, v76, v77
	v_max3_f32 v146, v146, v78, v79
	s_waitcnt lgkmcnt(2)
	v_mfma_f32_32x32x16_bf16 v[18:33], v[154:157], v[214:217], v[18:33]
	v_max3_f32 v146, v146, v80, v81
	v_mov_b32_e32 v147, v146
	s_nop 1
	v_permlane32_swap_b32_e32 v146, v147
	v_max_f32_e32 v147, v147, v147
	v_max_f32_e32 v146, v146, v146
	v_max_f32_e32 v146, v146, v147
	v_sub_f32_e32 v147, v146, v210
	v_cmp_ge_f32_e32 vcc, s63, v147
	v_max_f32_e32 v147, v210, v210
	v_max_f32_e32 v147, v147, v146
	s_waitcnt lgkmcnt(0)
	v_mfma_f32_32x32x16_bf16 v[18:33], v[158:161], v[218:221], v[18:33]
	v_sub_f32_e32 v146, v210, v147
	v_mul_f32_e32 v146, 0x3e0293ee, v146
	v_exp_f32_e32 v146, v146
	s_cmp_eq_u64 vcc, exec
	s_cselect_b64 s[8:9], -1, 0
	s_waitcnt vmcnt(4)
	v_cndmask_b32_e64 v146, v146, 1.0, s[8:9]
	v_cmp_gt_f32_e32 vcc, 1.0, v146
	s_cbranch_vccz .LBB0_1012
	s_and_saveexec_b64 s[4:5], s[6:7]
	ds_write_b32 v173, v146 offset:128
	s_or_b64 exec, exec, s[4:5]
	s_waitcnt lgkmcnt(0)
	v_add_u32_e32 v142, s15, v172
	ds_read_b128 v[130:133], v142 offset:224
	ds_read_b128 v[134:137], v142 offset:192
	ds_read_b128 v[138:141], v142 offset:160
	ds_read_b128 v[142:145], v142 offset:128
	s_waitcnt lgkmcnt(3)
	v_pk_mul_f32 v[14:15], v[14:15], v[130:131]
	s_waitcnt lgkmcnt(2)
	v_pk_mul_f32 v[10:11], v[10:11], v[134:135]
	s_waitcnt lgkmcnt(1)
	v_pk_mul_f32 v[6:7], v[6:7], v[138:139]
	v_pk_mul_f32 v[16:17], v[16:17], v[132:133]
	v_pk_mul_f32 v[12:13], v[12:13], v[136:137]
	v_pk_mul_f32 v[8:9], v[8:9], v[140:141]
	s_waitcnt lgkmcnt(0)
	v_pk_mul_f32 v[4:5], v[4:5], v[144:145]
	v_pk_mul_f32 v[2:3], v[2:3], v[142:143]
	v_pk_mul_f32 v[62:63], v[62:63], v[130:131]
	v_pk_mul_f32 v[58:59], v[58:59], v[134:135]
	v_pk_mul_f32 v[54:55], v[54:55], v[138:139]
	v_pk_mul_f32 v[64:65], v[64:65], v[132:133]
	v_pk_mul_f32 v[60:61], v[60:61], v[136:137]
	v_pk_mul_f32 v[56:57], v[56:57], v[140:141]
	v_pk_mul_f32 v[52:53], v[52:53], v[144:145]
	v_pk_mul_f32 v[50:51], v[50:51], v[142:143]
	v_pk_mul_f32 v[46:47], v[46:47], v[130:131]
	v_pk_mul_f32 v[42:43], v[42:43], v[134:135]
	v_pk_mul_f32 v[38:39], v[38:39], v[138:139]
	v_pk_mul_f32 v[48:49], v[48:49], v[132:133]
	v_pk_mul_f32 v[44:45], v[44:45], v[136:137]
	v_pk_mul_f32 v[40:41], v[40:41], v[140:141]
	v_pk_mul_f32 v[36:37], v[36:37], v[144:145]
	v_pk_mul_f32 v[34:35], v[34:35], v[142:143]
	v_pk_mul_f32 v[30:31], v[30:31], v[130:131]
	v_pk_mul_f32 v[26:27], v[26:27], v[134:135]
	v_pk_mul_f32 v[22:23], v[22:23], v[138:139]
	v_pk_mul_f32 v[32:33], v[32:33], v[132:133]
	v_pk_mul_f32 v[28:29], v[28:29], v[136:137]
	v_pk_mul_f32 v[24:25], v[24:25], v[140:141]
	v_pk_mul_f32 v[20:21], v[20:21], v[144:145]
	v_pk_mul_f32 v[18:19], v[18:19], v[142:143]
; #define SBAR() __builtin_amdgcn_sched_barrier(0)
; #define SWRITE(b, i) do { *(bf16x8*)((char*)V_lds + (b) * SHM_V + vst0) = sr_[i].vs0;          \
;     *(bf16x8*)((char*)V_lds + (b) * SHM_V + vst1) = sr_[i].vs1; int kc = sc * 2;               \
;     *(bf16x8*)((char*)K_lds + (b) * SHM_K + KSWZ(sr, kc)) = sr_[i].ks0;                       \
;     *(bf16x8*)((char*)K_lds + (b) * SHM_K + KSWZ(32 + sr, kc)) = sr_[i].ks1; } while (0)
; #define SWAIT() asm volatile("s_waitcnt vmcnt(4)" ::: "memory")
; #define RESC(a) do { if (__any((a) < 1.f)) { if (hi == 0) al_l[r32] = (a); asm volatile("s_waitcnt lgkmcnt(0)" ::: "memory"); \
;     _Pragma("unroll") for (int d = 0; d < 4; ++d) _Pragma("unroll") for (int r = 0; r < 16; ++r) o[d][r] *= al_l[crow(r, hi)]; } } while (0)
; template <int DLO, int DHI>
; __device__ __forceinline__ void attn_dense_body(const int g_wave, const bf16* __restrict__ Qb, const bf16* __restrict__ Kh, const bf16* __restrict__ Vh,
;                                                 bf16* __restrict__ Ob, int ldo, char* lds) {
;     ...
;     pv_d0(o, vb0 + (int)SHM_V, pa0, pa1, pa2, pa3); partialSM(pA0, pA1, m_reg, mnA, alA);
;     __syncthreads(); SWAIT(); SWRITE(1, SO);
;     RESC(alA); __syncthreads();
;   }
;   SBAR(); qkt<DLO, DHI>(pB0, pB1, (bf16*)((char*)K_lds + SHM_K), qr, r32, hi);
;   finishSM(pA0, pA1, alA, l_reg, pa0, pa1, pa2, pa3); SBAR();
;   pv_d0(o, vb0, pa0, pa1, pa2, pa3); partialSM(pB0, pB1, m_reg, mnB, alB);
.LBB0_1012:
	v_cndmask_b32_e64 v150, v147, v210, s[8:9]
	v_mul_f32_e32 v136, 0xbe0293ee, v150
	v_mov_b32_e32 v137, v136
	v_fmamk_f32 v82, v82, 0x3e0293ee, v136
	v_fmamk_f32 v83, v83, 0x3e0293ee, v136
	v_fmamk_f32 v84, v84, 0x3e0293ee, v136
	v_fmamk_f32 v85, v85, 0x3e0293ee, v136
	v_fmamk_f32 v86, v86, 0x3e0293ee, v136
	v_fmamk_f32 v87, v87, 0x3e0293ee, v136
	v_fmamk_f32 v88, v88, 0x3e0293ee, v136
	v_fmamk_f32 v89, v89, 0x3e0293ee, v136
	v_fmamk_f32 v90, v90, 0x3e0293ee, v136
	v_fmamk_f32 v91, v91, 0x3e0293ee, v136
	v_fmamk_f32 v92, v92, 0x3e0293ee, v136
	v_fmamk_f32 v93, v93, 0x3e0293ee, v136
	v_fmamk_f32 v94, v94, 0x3e0293ee, v136
	v_fmamk_f32 v95, v95, 0x3e0293ee, v136
	v_fmamk_f32 v96, v96, 0x3e0293ee, v136
	v_fmac_f32_e32 v137, 0x3e0293ee, v97
	v_exp_f32_e32 v161, v82
	v_exp_f32_e32 v167, v83
	v_exp_f32_e32 v147, v84
	v_exp_f32_e32 v166, v85
	v_exp_f32_e32 v148, v86
	v_exp_f32_e32 v160, v87
	v_exp_f32_e32 v149, v88
	v_exp_f32_e32 v159, v89
	v_exp_f32_e32 v156, v90
	v_exp_f32_e32 v158, v91
	v_exp_f32_e32 v154, v92
	v_exp_f32_e32 v157, v93
	v_exp_f32_e32 v152, v94
	v_exp_f32_e32 v155, v95
	v_exp_f32_e32 v151, v96
	v_exp_f32_e32 v153, v137
	v_pk_fma_f32 v[142:143], v[66:67], s[62:63], v[136:137] op_sel_hi:[1,0,0]
	v_add_f32_e32 v66, v207, v208
	s_mov_b64 s[4:5], 0x30000
	v_fmac_f32_e32 v66, v197, v174
	v_add_f32_e32 v174, v211, v212
	v_lshl_add_u64 v[162:163], v[162:163], 0, s[4:5]
	s_mov_b64 s[4:5], 0x120000
	v_pk_fma_f32 v[140:141], v[68:69], s[62:63], v[136:137] op_sel_hi:[1,0,0]
	v_pk_fma_f32 v[134:135], v[70:71], s[62:63], v[136:137] op_sel_hi:[1,0,0]
	v_pk_fma_f32 v[132:133], v[72:73], s[62:63], v[136:137] op_sel_hi:[1,0,0]
	v_pk_fma_f32 v[130:131], v[74:75], s[62:63], v[136:137] op_sel_hi:[1,0,0]
	v_pk_fma_f32 v[144:145], v[76:77], s[62:63], v[136:137] op_sel_hi:[1,0,0]
	v_pk_fma_f32 v[138:139], v[78:79], s[62:63], v[136:137] op_sel_hi:[1,0,0]
	v_pk_fma_f32 v[136:137], v[80:81], s[62:63], v[136:137] op_sel_hi:[1,0,0]
	v_fmac_f32_e32 v174, v66, v209
	s_add_i32 s34, s34, 2
	v_lshl_add_u64 v[164:165], v[164:165], 0, s[4:5]
	s_and_b64 vcc, exec, s[2:3]
	s_waitcnt lgkmcnt(0)
	s_barrier
	v_xor_b32_e32 v176, 0x10000, v176
	v_xor_b32_e32 v175, 0x10000, v175
	v_xor_b32_e32 v192, 0x10000, v192
	v_xor_b32_e32 v193, 0x10000, v193
	v_xor_b32_e32 v177, 0x10000, v177
	v_xor_b32_e32 v191, 0x10000, v191
	s_cbranch_vccnz .LBB0_1014
	v_mov_b32_e32 v197, v146
	s_branch .LBB0_1002
.LBB0_1014:
	ds_read_b128 v[66:69], v190 offset:49152
	ds_read_b128 v[70:73], v190 offset:57344
	v_add_f32_e32 v0, 0, v161
	v_add_f32_e32 v0, v167, v0
	v_add_f32_e32 v0, v147, v0
	s_waitcnt lgkmcnt(1)
	v_mfma_f32_32x32x16_bf16 v[82:97], v[66:69], v[102:105], 0
	v_add_f32_e32 v0, v166, v0
	v_add_f32_e32 v0, v148, v0
	v_add_f32_e32 v0, v160, v0
	v_add_f32_e32 v0, v149, v0
	v_add_f32_e32 v0, v159, v0
	v_add_f32_e32 v0, v156, v0
	v_add_f32_e32 v0, v158, v0
	s_waitcnt lgkmcnt(0)
	v_mfma_f32_32x32x16_bf16 v[66:81], v[70:73], v[102:105], 0
	ds_read_b128 v[102:105], v194 offset:49152
	ds_read_b128 v[114:117], v194 offset:57344
	v_add_f32_e32 v0, v154, v0
	v_add_f32_e32 v0, v157, v0
	v_add_f32_e32 v0, v152, v0
	v_add_f32_e32 v0, v155, v0
	v_add_f32_e32 v0, v151, v0
	v_add_f32_e32 v0, v153, v0
	s_waitcnt lgkmcnt(1)
	v_mfma_f32_32x32x16_bf16 v[82:97], v[102:105], v[98:101], v[82:97]
	v_exp_f32_e32 v118, v145
	v_exp_f32_e32 v119, v138
	v_exp_f32_e32 v120, v139
	v_exp_f32_e32 v121, v136
	v_exp_f32_e32 v122, v137
	s_waitcnt lgkmcnt(0)
	v_mfma_f32_32x32x16_bf16 v[66:81], v[114:117], v[98:101], v[66:81]
	ds_read_b128 v[98:101], v195 offset:49152
	ds_read_b128 v[102:105], v195 offset:57344
	v_exp_f32_e32 v114, v133
	v_exp_f32_e32 v115, v130
	v_exp_f32_e32 v116, v131
	v_exp_f32_e32 v117, v144
	s_waitcnt lgkmcnt(1)
	v_mfma_f32_32x32x16_bf16 v[82:97], v[98:101], v[106:109], v[82:97]
	s_waitcnt lgkmcnt(0)
	v_mfma_f32_32x32x16_bf16 v[66:81], v[102:105], v[106:109], v[66:81]
	ds_read_b128 v[98:101], v196 offset:49152
	ds_read_b128 v[102:105], v196 offset:57344
	v_exp_f32_e32 v108, v143
	v_exp_f32_e32 v109, v140
	s_waitcnt lgkmcnt(1)
	v_mfma_f32_32x32x16_bf16 v[82:97], v[98:101], v[110:113], v[82:97]
	v_exp_f32_e32 v99, v142
	v_cvt_pk_bf16_f32 v100, v161, v167
	v_cvt_pk_bf16_f32 v101, v147, v166
	s_nop 0
	v_add_f32_e32 v0, v99, v0
	v_add_f32_e32 v0, v108, v0
	v_add_f32_e32 v0, v109, v0
	s_waitcnt lgkmcnt(0)
	v_mfma_f32_32x32x16_bf16 v[66:81], v[102:105], v[110:113], v[66:81]
	v_exp_f32_e32 v110, v141
	v_exp_f32_e32 v111, v134
	v_exp_f32_e32 v112, v135
	v_exp_f32_e32 v113, v132
	v_add_f32_e32 v0, v110, v0
	v_add_f32_e32 v0, v111, v0
	v_add_f32_e32 v0, v112, v0
	v_add_f32_e32 v0, v113, v0
	v_add_f32_e32 v0, v114, v0
	v_add_f32_e32 v0, v115, v0
	v_add_f32_e32 v0, v116, v0
	v_add_f32_e32 v0, v117, v0
	v_add_f32_e32 v0, v118, v0
	v_add_f32_e32 v0, v119, v0
	v_add_f32_e32 v0, v120, v0
	v_add_f32_e32 v0, v121, v0
	v_add_f32_e32 v0, v122, v0
	v_mov_b32_e32 v98, v0
	v_cvt_pk_bf16_f32 v102, v148, v160
	s_nop 1
	v_permlane32_swap_b32_e32 v0, v98
	v_cvt_pk_bf16_f32 v103, v149, v159
	v_permlane32_swap_b32_e32 v100, v102
	v_cvt_pk_bf16_f32 v104, v156, v158
	v_cvt_pk_bf16_f32 v105, v154, v157
	v_cvt_pk_bf16_f32 v106, v152, v155
	v_cvt_pk_bf16_f32 v107, v151, v153
	v_cvt_pk_bf16_f32 v108, v99, v108
	v_cvt_pk_bf16_f32 v109, v109, v110
	v_cvt_pk_bf16_f32 v110, v111, v112
	v_cvt_pk_bf16_f32 v111, v113, v114
	v_cvt_pk_bf16_f32 v112, v115, v116
	v_cvt_pk_bf16_f32 v113, v117, v118
	v_cvt_pk_bf16_f32 v114, v119, v120
	v_cvt_pk_bf16_f32 v115, v121, v122
	v_permlane32_swap_b32_e32 v101, v103
	v_permlane32_swap_b32_e32 v104, v106
	v_permlane32_swap_b32_e32 v105, v107
	v_permlane32_swap_b32_e32 v108, v110
	v_permlane32_swap_b32_e32 v109, v111
	v_permlane32_swap_b32_e32 v112, v114
	v_permlane32_swap_b32_e32 v113, v115
	ds_read_b64_tr_b16 v[116:117], v176 offset:0
	ds_read_b64_tr_b16 v[118:119], v176 offset:0x800
	ds_read_b64_tr_b16 v[120:121], v176 offset:0x1000
	ds_read_b64_tr_b16 v[122:123], v176 offset:0x1800
	ds_read_b64_tr_b16 v[124:125], v176 offset:0x2000
	ds_read_b64_tr_b16 v[126:127], v176 offset:0x2800
	ds_read_b64_tr_b16 v[128:129], v176 offset:0x3000
	ds_read_b64_tr_b16 v[130:131], v176 offset:0x3800
	s_waitcnt lgkmcnt(6)
; #define SBAR() __builtin_amdgcn_sched_barrier(0)
; #define RESC(a) do { if (__any((a) < 1.f)) { if (hi == 0) al_l[r32] = (a); asm volatile("s_waitcnt lgkmcnt(0)" ::: "memory"); \
;     _Pragma("unroll") for (int d = 0; d < 4; ++d) _Pragma("unroll") for (int r = 0; r < 16; ++r) o[d][r] *= al_l[crow(r, hi)]; } } while (0)
; template <int D0> __device__ __forceinline__ void pv_one(f32x16& od, int vb, bf16x8 pa0, bf16x8 pa1, bf16x8 pa2, bf16x8 pa3) {
;   const s16x4 l0 = tr_read<v_rd_off(D0, 0, 0)>(vb), h0 = tr_read<v_rd_off(D0, 0, 1)>(vb), l1 = tr_read<v_rd_off(D0, 1, 0)>(vb), h1 = tr_read<v_rd_off(D0, 1, 1)>(vb);
;   const s16x4 l2 = tr_read<v_rd_off(D0, 2, 0)>(vb), h2 = tr_read<v_rd_off(D0, 2, 1)>(vb), l3 = tr_read<v_rd_off(D0, 3, 0)>(vb), h3 = tr_read<v_rd_off(D0, 3, 1)>(vb);
;   asm volatile("s_waitcnt lgkmcnt(0)" ::: "memory"); SBAR();
;     ...
;   od = __builtin_amdgcn_mfma_f32_32x32x16_bf16(pa0, PK(l0, h0), od, 0, 0, 0);
;   od = __builtin_amdgcn_mfma_f32_32x32x16_bf16(pa1, PK(l1, h1), od, 0, 0, 0);
;   od = __builtin_amdgcn_mfma_f32_32x32x16_bf16(pa2, PK(l2, h2), od, 0, 0, 0);
;   od = __builtin_amdgcn_mfma_f32_32x32x16_bf16(pa3, PK(l3, h3), od, 0, 0, 0);
;     ...
; }
; __device__ __forceinline__ void pv_d0(f32x16* o, int vb, bf16x8 pa0, bf16x8 pa1, bf16x8 pa2, bf16x8 pa3) {
;   pv_one<0>(o[0], vb, pa0, pa1, pa2, pa3); pv_one<1>(o[1], vb, pa0, pa1, pa2, pa3); pv_one<2>(o[2], vb, pa0, pa1, pa2, pa3); pv_one<3>(o[3], vb, pa0, pa1, pa2, pa3);
; template <int DLO, int DHI>
; __device__ __forceinline__ void attn_dense_body(const int g_wave, const bf16* __restrict__ Qb, const bf16* __restrict__ Kh, const bf16* __restrict__ Vh,
;                                                 bf16* __restrict__ Ob, int ldo, char* lds) {
;     ...
;   pv_d0(o, vb0, pa0, pa1, pa2, pa3); partialSM(pB0, pB1, m_reg, mnB, alB);
;   __syncthreads(); RESC(alB);
	s_nop 0
	v_mfma_f32_32x32x16_bf16 v[2:17], v[100:103], v[116:119], v[2:17]
	ds_read_b64_tr_b16 v[116:117], v176 offset:0x200
	ds_read_b64_tr_b16 v[118:119], v176 offset:0xa00
	s_waitcnt lgkmcnt(6)
	v_mfma_f32_32x32x16_bf16 v[2:17], v[104:107], v[120:123], v[2:17]
	ds_read_b64_tr_b16 v[120:121], v176 offset:0x1200
	ds_read_b64_tr_b16 v[122:123], v176 offset:0x1a00
	s_waitcnt lgkmcnt(6)
	v_mfma_f32_32x32x16_bf16 v[2:17], v[108:111], v[124:127], v[2:17]
	ds_read_b64_tr_b16 v[124:125], v176 offset:0x2200
	ds_read_b64_tr_b16 v[126:127], v176 offset:0x2a00
	s_waitcnt lgkmcnt(6)
	v_mfma_f32_32x32x16_bf16 v[2:17], v[112:115], v[128:131], v[2:17]
	ds_read_b64_tr_b16 v[128:129], v176 offset:0x3200
	ds_read_b64_tr_b16 v[130:131], v176 offset:0x3a00
	s_waitcnt lgkmcnt(6)
	v_mfma_f32_32x32x16_bf16 v[50:65], v[100:103], v[116:119], v[50:65]
	ds_read_b64_tr_b16 v[116:117], v176 offset:0x400
	ds_read_b64_tr_b16 v[118:119], v176 offset:0xc00
	s_waitcnt lgkmcnt(6)
	v_mfma_f32_32x32x16_bf16 v[50:65], v[104:107], v[120:123], v[50:65]
	ds_read_b64_tr_b16 v[120:121], v176 offset:0x1400
	ds_read_b64_tr_b16 v[122:123], v176 offset:0x1c00
	s_waitcnt lgkmcnt(6)
	v_mfma_f32_32x32x16_bf16 v[50:65], v[108:111], v[124:127], v[50:65]
	ds_read_b64_tr_b16 v[124:125], v176 offset:0x2400
	ds_read_b64_tr_b16 v[126:127], v176 offset:0x2c00
	s_waitcnt lgkmcnt(6)
	v_mfma_f32_32x32x16_bf16 v[50:65], v[112:115], v[128:131], v[50:65]
	ds_read_b64_tr_b16 v[128:129], v176 offset:0x3400
	ds_read_b64_tr_b16 v[130:131], v176 offset:0x3c00
	s_waitcnt lgkmcnt(6)
	v_mfma_f32_32x32x16_bf16 v[34:49], v[100:103], v[116:119], v[34:49]
	ds_read_b64_tr_b16 v[116:117], v176 offset:0x600
	ds_read_b64_tr_b16 v[118:119], v176 offset:0xe00
	s_waitcnt lgkmcnt(6)
	v_mfma_f32_32x32x16_bf16 v[34:49], v[104:107], v[120:123], v[34:49]
	ds_read_b64_tr_b16 v[120:121], v176 offset:0x1600
	ds_read_b64_tr_b16 v[122:123], v176 offset:0x1e00
	s_waitcnt lgkmcnt(6)
	v_mfma_f32_32x32x16_bf16 v[34:49], v[108:111], v[124:127], v[34:49]
	ds_read_b64_tr_b16 v[124:125], v176 offset:0x2600
	ds_read_b64_tr_b16 v[126:127], v176 offset:0x2e00
	s_waitcnt lgkmcnt(6)
	v_mfma_f32_32x32x16_bf16 v[34:49], v[112:115], v[128:131], v[34:49]
	ds_read_b64_tr_b16 v[128:129], v176 offset:0x3600
	ds_read_b64_tr_b16 v[130:131], v176 offset:0x3e00
	s_waitcnt lgkmcnt(6)
	v_mfma_f32_32x32x16_bf16 v[18:33], v[100:103], v[116:119], v[18:33]
	v_max_f32_e32 v99, v83, v83
	v_max_f32_e32 v100, v82, v82
	v_max_f32_e32 v99, v100, v99
	v_max3_f32 v99, v99, v84, v85
	v_max3_f32 v99, v99, v86, v87
	v_max3_f32 v99, v99, v88, v89
	v_max3_f32 v99, v99, v90, v91
	v_max3_f32 v99, v99, v92, v93
	v_max3_f32 v99, v99, v94, v95
	s_waitcnt lgkmcnt(4)
	v_mfma_f32_32x32x16_bf16 v[18:33], v[104:107], v[120:123], v[18:33]
	v_max3_f32 v99, v99, v96, v97
	v_max3_f32 v99, v99, v66, v67
	v_max3_f32 v99, v99, v68, v69
	v_max3_f32 v99, v99, v70, v71
	v_max3_f32 v99, v99, v72, v73
	v_max3_f32 v99, v99, v74, v75
	v_max3_f32 v99, v99, v76, v77
	v_max3_f32 v99, v99, v78, v79
	s_waitcnt lgkmcnt(2)
	v_mfma_f32_32x32x16_bf16 v[18:33], v[108:111], v[124:127], v[18:33]
	v_max3_f32 v99, v99, v80, v81
	v_mov_b32_e32 v100, v99
	s_nop 1
	v_permlane32_swap_b32_e32 v99, v100
	v_max_f32_e32 v100, v100, v100
	v_max_f32_e32 v99, v99, v99
	v_max_f32_e32 v99, v99, v100
	v_sub_f32_e32 v100, v99, v150
	v_cmp_ge_f32_e32 vcc, s63, v100
	v_max_f32_e32 v100, v150, v150
	v_max_f32_e32 v100, v100, v99
	s_waitcnt lgkmcnt(0)
	v_mfma_f32_32x32x16_bf16 v[18:33], v[112:115], v[128:131], v[18:33]
	v_sub_f32_e32 v99, v150, v100
	v_mul_f32_e32 v99, 0x3e0293ee, v99
	v_exp_f32_e32 v99, v99
	s_cmp_eq_u64 vcc, exec
	s_cselect_b64 s[8:9], -1, 0
	v_cndmask_b32_e64 v99, v99, 1.0, s[8:9]
	v_cmp_gt_f32_e32 vcc, 1.0, v99
	s_barrier
	s_cbranch_vccz .LBB0_1018
	s_and_saveexec_b64 s[2:3], s[6:7]
	ds_write_b32 v173, v99 offset:128
	s_or_b64 exec, exec, s[2:3]
	s_waitcnt lgkmcnt(0)
	v_add_u32_e32 v101, s15, v172
	ds_read_b128 v[102:105], v101 offset:224
	ds_read_b128 v[106:109], v101 offset:192
	ds_read_b128 v[110:113], v101 offset:160
	ds_read_b128 v[114:117], v101 offset:128
	s_waitcnt lgkmcnt(3)
	v_pk_mul_f32 v[14:15], v[14:15], v[102:103]
	s_waitcnt lgkmcnt(2)
	v_pk_mul_f32 v[10:11], v[10:11], v[106:107]
	s_waitcnt lgkmcnt(1)
	v_pk_mul_f32 v[6:7], v[6:7], v[110:111]
	v_pk_mul_f32 v[16:17], v[16:17], v[104:105]
	v_pk_mul_f32 v[12:13], v[12:13], v[108:109]
	v_pk_mul_f32 v[8:9], v[8:9], v[112:113]
	s_waitcnt lgkmcnt(0)
	v_pk_mul_f32 v[4:5], v[4:5], v[116:117]
	v_pk_mul_f32 v[2:3], v[2:3], v[114:115]
	v_pk_mul_f32 v[62:63], v[62:63], v[102:103]
	v_pk_mul_f32 v[58:59], v[58:59], v[106:107]
	v_pk_mul_f32 v[54:55], v[54:55], v[110:111]
	v_pk_mul_f32 v[64:65], v[64:65], v[104:105]
	v_pk_mul_f32 v[60:61], v[60:61], v[108:109]
	v_pk_mul_f32 v[56:57], v[56:57], v[112:113]
	v_pk_mul_f32 v[52:53], v[52:53], v[116:117]
	v_pk_mul_f32 v[50:51], v[50:51], v[114:115]
	v_pk_mul_f32 v[46:47], v[46:47], v[102:103]
	v_pk_mul_f32 v[42:43], v[42:43], v[106:107]
	v_pk_mul_f32 v[38:39], v[38:39], v[110:111]
	v_pk_mul_f32 v[48:49], v[48:49], v[104:105]
	v_pk_mul_f32 v[44:45], v[44:45], v[108:109]
	v_pk_mul_f32 v[40:41], v[40:41], v[112:113]
	v_pk_mul_f32 v[36:37], v[36:37], v[116:117]
	v_pk_mul_f32 v[34:35], v[34:35], v[114:115]
	v_pk_mul_f32 v[30:31], v[30:31], v[102:103]
	v_pk_mul_f32 v[26:27], v[26:27], v[106:107]
	v_pk_mul_f32 v[22:23], v[22:23], v[110:111]
	v_pk_mul_f32 v[32:33], v[32:33], v[104:105]
	v_pk_mul_f32 v[28:29], v[28:29], v[108:109]
	v_pk_mul_f32 v[24:25], v[24:25], v[112:113]
	v_pk_mul_f32 v[20:21], v[20:21], v[116:117]
	v_pk_mul_f32 v[18:19], v[18:19], v[114:115]
; #define SBAR() __builtin_amdgcn_sched_barrier(0)
; __device__ __forceinline__ void finishSM(f32x16& p0, f32x16& p1, float alpha, float& l_reg, bf16x8& pa0, bf16x8& pa1, bf16x8& pa2, bf16x8& pa3) {
; #pragma unroll
;   for (int r = 0; r < 16; ++r) p1[r] = __builtin_amdgcn_exp2f(p1[r]);
;   float ps = 0;
; #pragma unroll
;   for (int r = 0; r < 16; ++r) ps += p0[r];
; #pragma unroll
;   for (int r = 0; r < 16; ++r) ps += p1[r];
;   { auto rr = __builtin_amdgcn_permlane32_swap(__float_as_uint(ps), __float_as_uint(ps), false, false);
;     ps = __uint_as_float(rr[0]) + __uint_as_float(rr[1]); }
;   l_reg = l_reg * alpha + ps;
;   PK4(p0, 0, pa0); PK4(p0, 8, pa1); PK4(p1, 0, pa2); PK4(p1, 8, pa3);
; }
; template <int DLO, int DHI>
; __device__ __forceinline__ void attn_dense_body(const int g_wave, const bf16* __restrict__ Qb, const bf16* __restrict__ Kh, const bf16* __restrict__ Vh,
;                                                 bf16* __restrict__ Ob, int ldo, char* lds) {
;     ...
;   finishSM(pB0, pB1, alB, l_reg, pa0, pa1, pa2, pa3); SBAR();
;   pv_d0(o, vb0 + (int)SHM_V, pa0, pa1, pa2, pa3);
.LBB0_1018:
	v_cndmask_b32_e64 v100, v100, v150, s[8:9]
	v_mul_f32_e32 v100, 0xbe0293ee, v100
	v_fmamk_f32 v82, v82, 0x3e0293ee, v100
	v_fmamk_f32 v83, v83, 0x3e0293ee, v100
	v_fmamk_f32 v101, v84, 0x3e0293ee, v100
	v_exp_f32_e32 v84, v82
	v_fmamk_f32 v102, v86, 0x3e0293ee, v100
	v_exp_f32_e32 v86, v83
	v_fmamk_f32 v85, v85, 0x3e0293ee, v100
	v_exp_f32_e32 v82, v101
	v_fmamk_f32 v66, v66, 0x3e0293ee, v100
	v_exp_f32_e32 v85, v85
	v_fmamk_f32 v103, v87, 0x3e0293ee, v100
	v_fmamk_f32 v112, v96, 0x3e0293ee, v100
	v_fmamk_f32 v96, v77, 0x3e0293ee, v100
	v_exp_f32_e32 v77, v102
	v_exp_f32_e32 v101, v66
	v_add_f32_e32 v66, 0, v84
	v_fmamk_f32 v104, v88, 0x3e0293ee, v100
	v_exp_f32_e32 v83, v103
	v_add_f32_e32 v66, v86, v66
	v_fmamk_f32 v105, v89, 0x3e0293ee, v100
	v_fmamk_f32 v111, v95, 0x3e0293ee, v100
	v_fmamk_f32 v95, v76, 0x3e0293ee, v100
	v_exp_f32_e32 v76, v104
	v_add_f32_e32 v66, v82, v66
	v_fmamk_f32 v106, v90, 0x3e0293ee, v100
	v_fmamk_f32 v113, v97, 0x3e0293ee, v100
	v_fmamk_f32 v97, v78, 0x3e0293ee, v100
	v_exp_f32_e32 v78, v105
	v_add_f32_e32 v66, v85, v66
	v_fmamk_f32 v107, v91, 0x3e0293ee, v100
	v_fmamk_f32 v108, v92, 0x3e0293ee, v100
	v_fmamk_f32 v92, v73, 0x3e0293ee, v100
	v_exp_f32_e32 v73, v106
	v_add_f32_e32 v66, v77, v66
	v_fmamk_f32 v110, v94, 0x3e0293ee, v100
	v_fmamk_f32 v94, v75, 0x3e0293ee, v100
	v_exp_f32_e32 v75, v107
	v_add_f32_e32 v66, v83, v66
	v_fmamk_f32 v109, v93, 0x3e0293ee, v100
	v_fmamk_f32 v90, v71, 0x3e0293ee, v100
	v_exp_f32_e32 v71, v108
	v_add_f32_e32 v66, v76, v66
	v_fmamk_f32 v93, v74, 0x3e0293ee, v100
	v_exp_f32_e32 v74, v109
	v_add_f32_e32 v66, v78, v66
	v_fmamk_f32 v88, v69, 0x3e0293ee, v100
	v_exp_f32_e32 v69, v110
	v_add_f32_e32 v66, v73, v66
	v_fmamk_f32 v91, v72, 0x3e0293ee, v100
	v_exp_f32_e32 v72, v111
	v_add_f32_e32 v66, v75, v66
	v_fmamk_f32 v87, v68, 0x3e0293ee, v100
	v_exp_f32_e32 v68, v112
	v_add_f32_e32 v66, v71, v66
	v_fmamk_f32 v89, v70, 0x3e0293ee, v100
	v_exp_f32_e32 v70, v113
	v_add_f32_e32 v66, v74, v66
	v_fmamk_f32 v67, v67, 0x3e0293ee, v100
	v_add_f32_e32 v66, v69, v66
	v_exp_f32_e32 v102, v67
	v_add_f32_e32 v66, v72, v66
	v_exp_f32_e32 v87, v87
	v_add_f32_e32 v66, v68, v66
	v_exp_f32_e32 v88, v88
	v_add_f32_e32 v66, v70, v66
	v_exp_f32_e32 v89, v89
	v_add_f32_e32 v66, v101, v66
	v_exp_f32_e32 v90, v90
	v_add_f32_e32 v66, v102, v66
	v_exp_f32_e32 v91, v91
	v_add_f32_e32 v66, v87, v66
	v_exp_f32_e32 v92, v92
	v_add_f32_e32 v66, v88, v66
	v_exp_f32_e32 v93, v93
	v_add_f32_e32 v66, v89, v66
	v_exp_f32_e32 v94, v94
	v_add_f32_e32 v66, v90, v66
	v_exp_f32_e32 v95, v95
	v_add_f32_e32 v66, v91, v66
	v_exp_f32_e32 v96, v96
	v_add_f32_e32 v66, v92, v66
	v_fmamk_f32 v79, v79, 0x3e0293ee, v100
	v_exp_f32_e32 v97, v97
	v_add_f32_e32 v66, v93, v66
	v_fmamk_f32 v80, v80, 0x3e0293ee, v100
	v_exp_f32_e32 v103, v79
	v_add_f32_e32 v66, v94, v66
	v_fmac_f32_e32 v100, 0x3e0293ee, v81
	v_exp_f32_e32 v104, v80
	v_add_f32_e32 v66, v95, v66
	v_exp_f32_e32 v100, v100
	v_add_f32_e32 v66, v96, v66
	v_add_f32_e32 v66, v97, v66
	v_add_f32_e32 v66, v103, v66
	v_add_f32_e32 v66, v104, v66
	v_add_f32_e32 v66, v100, v66
	v_mov_b32_e32 v67, v66
	s_nop 1
	v_permlane32_swap_b32_e32 v66, v67
	v_cvt_pk_bf16_f32 v80, v84, v86
	v_cvt_pk_bf16_f32 v81, v82, v85
	v_cvt_pk_bf16_f32 v82, v77, v83
	v_cvt_pk_bf16_f32 v83, v76, v78
	v_cvt_pk_bf16_f32 v76, v73, v75
	v_cvt_pk_bf16_f32 v77, v71, v74
	v_cvt_pk_bf16_f32 v78, v69, v72
	v_cvt_pk_bf16_f32 v79, v68, v70
	v_cvt_pk_bf16_f32 v68, v101, v102
	v_cvt_pk_bf16_f32 v69, v87, v88
	v_cvt_pk_bf16_f32 v70, v89, v90
	v_cvt_pk_bf16_f32 v71, v91, v92
	v_cvt_pk_bf16_f32 v72, v93, v94
	v_cvt_pk_bf16_f32 v73, v95, v96
	v_cvt_pk_bf16_f32 v74, v97, v103
	v_cvt_pk_bf16_f32 v75, v104, v100
	s_nop 0
	v_permlane32_swap_b32_e32 v80, v82
	v_permlane32_swap_b32_e32 v81, v83
	v_permlane32_swap_b32_e32 v76, v78
	v_permlane32_swap_b32_e32 v77, v79
	v_permlane32_swap_b32_e32 v68, v70
	v_permlane32_swap_b32_e32 v69, v71
	v_permlane32_swap_b32_e32 v72, v74
	v_permlane32_swap_b32_e32 v73, v75
	ds_read_b64_tr_b16 v[84:85], v175 offset:0
	ds_read_b64_tr_b16 v[86:87], v175 offset:0x800
	ds_read_b64_tr_b16 v[88:89], v175 offset:0x1000
	ds_read_b64_tr_b16 v[90:91], v175 offset:0x1800
	ds_read_b64_tr_b16 v[92:93], v175 offset:0x2000
	ds_read_b64_tr_b16 v[94:95], v175 offset:0x2800
	ds_read_b64_tr_b16 v[100:101], v175 offset:0x3000
	ds_read_b64_tr_b16 v[102:103], v175 offset:0x3800
	s_waitcnt lgkmcnt(6)
	s_nop 0
	v_mfma_f32_32x32x16_bf16 v[2:17], v[80:83], v[84:87], v[2:17]
	ds_read_b64_tr_b16 v[84:85], v175 offset:0x200
	ds_read_b64_tr_b16 v[86:87], v175 offset:0xa00
	s_waitcnt lgkmcnt(6)
	v_mfma_f32_32x32x16_bf16 v[2:17], v[76:79], v[88:91], v[2:17]
	ds_read_b64_tr_b16 v[88:89], v175 offset:0x1200
	ds_read_b64_tr_b16 v[90:91], v175 offset:0x1a00
	s_waitcnt lgkmcnt(6)
	v_mfma_f32_32x32x16_bf16 v[2:17], v[68:71], v[92:95], v[2:17]
	ds_read_b64_tr_b16 v[92:93], v175 offset:0x2200
	ds_read_b64_tr_b16 v[94:95], v175 offset:0x2a00
	s_waitcnt lgkmcnt(6)
	v_mfma_f32_32x32x16_bf16 v[2:17], v[72:75], v[100:103], v[2:17]
	ds_read_b64_tr_b16 v[100:101], v175 offset:0x3200
	ds_read_b64_tr_b16 v[102:103], v175 offset:0x3a00
	s_waitcnt lgkmcnt(6)
	v_mfma_f32_32x32x16_bf16 v[50:65], v[80:83], v[84:87], v[50:65]
	ds_read_b64_tr_b16 v[84:85], v175 offset:0x400
	ds_read_b64_tr_b16 v[86:87], v175 offset:0xc00
	s_waitcnt lgkmcnt(6)
	v_mfma_f32_32x32x16_bf16 v[50:65], v[76:79], v[88:91], v[50:65]
	ds_read_b64_tr_b16 v[88:89], v175 offset:0x1400
	ds_read_b64_tr_b16 v[90:91], v175 offset:0x1c00
	s_waitcnt lgkmcnt(6)
	v_mfma_f32_32x32x16_bf16 v[50:65], v[68:71], v[92:95], v[50:65]
	ds_read_b64_tr_b16 v[92:93], v175 offset:0x2400
	ds_read_b64_tr_b16 v[94:95], v175 offset:0x2c00
	s_waitcnt lgkmcnt(6)
; __device__ __forceinline__ int crow(int r, int hi) { return (r & 3) + 8 * (r >> 2) + 4 * hi; }
; __device__ __forceinline__ unsigned cvtpk(float lo, float hi) { unsigned r; asm volatile("v_cvt_pk_bf16_f32 %0, %1, %2" : "=v"(r) : "v"(lo), "v"(hi)); return r; }
; template <int DLO, int DHI>
; __device__ __forceinline__ void attn_dense_body(const int g_wave, const bf16* __restrict__ Qb, const bf16* __restrict__ Kh, const bf16* __restrict__ Vh,
;                                                 bf16* __restrict__ Ob, int ldo, char* lds) {
;     ...
;   pv_d0(o, vb0 + (int)SHM_V, pa0, pa1, pa2, pa3);
;   if (hi == 0) li_l[r32] = l_reg; asm volatile("s_waitcnt lgkmcnt(0)" ::: "memory");
;   float rli[16];
; #pragma unroll
;   for (int r = 0; r < 16; ++r) rli[r] = __builtin_amdgcn_rcpf(li_l[crow(r, hi)]);
;   unsigned short* Ow = (unsigned short*)Ob + (long)(wid * QBLK) * ldo;
; #pragma unroll
;   for (int r = 0; r < 16; ++r) { int orow = crow(r, hi);
; #pragma unroll
;     for (int d0 = 0; d0 < 4; ++d0) Ow[(long)orow * ldo + d0 * 32 + r32] = (unsigned short)(cvtpk(o[d0][r] * rli[r], 0.f) & 0xffffu); }
	v_mfma_f32_32x32x16_bf16 v[50:65], v[72:75], v[100:103], v[50:65]
	ds_read_b64_tr_b16 v[100:101], v175 offset:0x3400
	ds_read_b64_tr_b16 v[102:103], v175 offset:0x3c00
	s_waitcnt lgkmcnt(6)
	v_mfma_f32_32x32x16_bf16 v[34:49], v[80:83], v[84:87], v[34:49]
	ds_read_b64_tr_b16 v[84:85], v175 offset:0x600
	ds_read_b64_tr_b16 v[86:87], v175 offset:0xe00
	s_waitcnt lgkmcnt(6)
	v_mfma_f32_32x32x16_bf16 v[34:49], v[76:79], v[88:91], v[34:49]
	ds_read_b64_tr_b16 v[88:89], v175 offset:0x1600
	ds_read_b64_tr_b16 v[90:91], v175 offset:0x1e00
	s_waitcnt lgkmcnt(6)
	v_mfma_f32_32x32x16_bf16 v[34:49], v[68:71], v[92:95], v[34:49]
	ds_read_b64_tr_b16 v[92:93], v175 offset:0x2600
	ds_read_b64_tr_b16 v[94:95], v175 offset:0x2e00
	s_waitcnt lgkmcnt(6)
	v_mfma_f32_32x32x16_bf16 v[34:49], v[72:75], v[100:103], v[34:49]
	ds_read_b64_tr_b16 v[100:101], v175 offset:0x3600
	ds_read_b64_tr_b16 v[102:103], v175 offset:0x3e00
	s_waitcnt lgkmcnt(6)
	v_mfma_f32_32x32x16_bf16 v[18:33], v[80:83], v[84:87], v[18:33]
	s_waitcnt lgkmcnt(4)
	v_mfma_f32_32x32x16_bf16 v[18:33], v[76:79], v[88:91], v[18:33]
	s_waitcnt lgkmcnt(2)
	v_mfma_f32_32x32x16_bf16 v[18:33], v[68:71], v[92:95], v[18:33]
	s_waitcnt lgkmcnt(0)
	v_mfma_f32_32x32x16_bf16 v[18:33], v[72:75], v[100:103], v[18:33]
	s_and_saveexec_b64 s[2:3], s[6:7]
	v_add_f32_e32 v0, v0, v98
	v_fmac_f32_e32 v0, v174, v146
	v_add_f32_e32 v66, v66, v67
	v_fmac_f32_e32 v66, v0, v99
	ds_write_b32 v173, v66
	s_or_b64 exec, exec, s[2:3]
	s_waitcnt lgkmcnt(0)
	v_add_u32_e32 v0, s15, v172
	ds_read_b128 v[66:69], v0
	ds_read_b128 v[70:73], v0 offset:32
	s_mul_hi_i32 s3, s10, s14
	s_mul_i32 s2, s10, s14
	s_lshl_b64 s[2:3], s[2:3], 1
	s_waitcnt lgkmcnt(1)
	v_rcp_f32_e32 v74, v66
	v_rcp_f32_e32 v75, v67
	v_rcp_f32_e32 v76, v68
	v_rcp_f32_e32 v77, v69
	ds_read_b128 v[66:69], v0 offset:64
	s_add_u32 s2, s82, s2
	s_waitcnt lgkmcnt(1)
	v_rcp_f32_e32 v78, v70
	v_rcp_f32_e32 v79, v71
	v_rcp_f32_e32 v80, v72
	v_rcp_f32_e32 v81, v73
	ds_read_b128 v[70:73], v0 offset:96
	s_addc_u32 s3, s83, s3
	v_lshlrev_b32_e32 v86, 2, v171
	v_lshlrev_b32_e32 v0, 1, v170
	s_waitcnt lgkmcnt(1)
	v_rcp_f32_e32 v82, v66
	v_rcp_f32_e32 v83, v67
	v_rcp_f32_e32 v84, v68
	v_rcp_f32_e32 v85, v69
	v_lshl_add_u64 v[66:67], s[2:3], 0, v[0:1]
	v_mad_i64_i32 v[68:69], s[2:3], s10, v86, 0
	v_mul_f32_e32 v0, v2, v74
	v_lshl_add_u64 v[68:69], v[68:69], 1, v[66:67]
	v_cvt_pk_bf16_f32 v0, v0, v1
	global_store_short v[68:69], v0, off
	v_mul_f32_e32 v0, v50, v74
	v_cvt_pk_bf16_f32 v0, v0, v1
	global_store_short v[68:69], v0, off offset:64
	v_mul_f32_e32 v0, v34, v74
	v_cvt_pk_bf16_f32 v0, v0, v1
	global_store_short v[68:69], v0, off offset:128
	v_mul_f32_e32 v0, v18, v74
	v_cvt_pk_bf16_f32 v0, v0, v1
	global_store_short v[68:69], v0, off offset:192
	v_or_b32_e32 v0, 1, v86
	v_mad_i64_i32 v[68:69], s[2:3], s10, v0, 0
	v_mul_f32_e32 v0, v3, v75
	v_lshl_add_u64 v[68:69], v[68:69], 1, v[66:67]
	v_cvt_pk_bf16_f32 v0, v0, v1
	global_store_short v[68:69], v0, off
	v_mul_f32_e32 v0, v51, v75
	v_cvt_pk_bf16_f32 v0, v0, v1
	global_store_short v[68:69], v0, off offset:64
	v_mul_f32_e32 v0, v35, v75
	v_cvt_pk_bf16_f32 v0, v0, v1
	global_store_short v[68:69], v0, off offset:128
	v_mul_f32_e32 v0, v19, v75
	v_cvt_pk_bf16_f32 v0, v0, v1
	global_store_short v[68:69], v0, off offset:192
	v_or_b32_e32 v0, 2, v86
	v_mad_i64_i32 v[2:3], s[2:3], s10, v0, 0
	v_mul_f32_e32 v0, v4, v76
	v_lshl_add_u64 v[2:3], v[2:3], 1, v[66:67]
	v_cvt_pk_bf16_f32 v0, v0, v1
	global_store_short v[2:3], v0, off
	v_mul_f32_e32 v0, v52, v76
	v_cvt_pk_bf16_f32 v0, v0, v1
	global_store_short v[2:3], v0, off offset:64
	v_mul_f32_e32 v0, v36, v76
	v_cvt_pk_bf16_f32 v0, v0, v1
	global_store_short v[2:3], v0, off offset:128
	v_mul_f32_e32 v0, v20, v76
	v_cvt_pk_bf16_f32 v0, v0, v1
	global_store_short v[2:3], v0, off offset:192
	v_or_b32_e32 v0, 3, v86
	v_mad_i64_i32 v[2:3], s[2:3], s10, v0, 0
	v_mul_f32_e32 v0, v5, v77
	v_lshl_add_u64 v[2:3], v[2:3], 1, v[66:67]
	v_cvt_pk_bf16_f32 v0, v0, v1
	global_store_short v[2:3], v0, off
	v_mul_f32_e32 v0, v53, v77
	v_cvt_pk_bf16_f32 v0, v0, v1
	global_store_short v[2:3], v0, off offset:64
	v_mul_f32_e32 v0, v37, v77
	v_cvt_pk_bf16_f32 v0, v0, v1
	global_store_short v[2:3], v0, off offset:128
	v_mul_f32_e32 v0, v21, v77
	v_cvt_pk_bf16_f32 v0, v0, v1
	global_store_short v[2:3], v0, off offset:192
	v_add_u32_e32 v0, 8, v86
	v_mad_i64_i32 v[2:3], s[2:3], s10, v0, 0
	v_mul_f32_e32 v0, v6, v78
	v_lshl_add_u64 v[2:3], v[2:3], 1, v[66:67]
	v_cvt_pk_bf16_f32 v0, v0, v1
	global_store_short v[2:3], v0, off
	v_mul_f32_e32 v0, v54, v78
	v_cvt_pk_bf16_f32 v0, v0, v1
	global_store_short v[2:3], v0, off offset:64
	v_mul_f32_e32 v0, v38, v78
	v_cvt_pk_bf16_f32 v0, v0, v1
	global_store_short v[2:3], v0, off offset:128
	v_mul_f32_e32 v0, v22, v78
	v_cvt_pk_bf16_f32 v0, v0, v1
	global_store_short v[2:3], v0, off offset:192
	v_add_u32_e32 v0, 9, v86
	v_mad_i64_i32 v[2:3], s[2:3], s10, v0, 0
	v_mul_f32_e32 v0, v7, v79
	v_lshl_add_u64 v[2:3], v[2:3], 1, v[66:67]
	v_cvt_pk_bf16_f32 v0, v0, v1
	global_store_short v[2:3], v0, off
	v_mul_f32_e32 v0, v55, v79
	v_cvt_pk_bf16_f32 v0, v0, v1
	global_store_short v[2:3], v0, off offset:64
	v_mul_f32_e32 v0, v39, v79
	v_cvt_pk_bf16_f32 v0, v0, v1
	global_store_short v[2:3], v0, off offset:128
	v_mul_f32_e32 v0, v23, v79
	v_cvt_pk_bf16_f32 v0, v0, v1
	global_store_short v[2:3], v0, off offset:192
	v_add_u32_e32 v0, 10, v86
	v_mad_i64_i32 v[2:3], s[2:3], s10, v0, 0
	v_mul_f32_e32 v0, v8, v80
	v_lshl_add_u64 v[2:3], v[2:3], 1, v[66:67]
	v_cvt_pk_bf16_f32 v0, v0, v1
	global_store_short v[2:3], v0, off
	v_mul_f32_e32 v0, v56, v80
	v_cvt_pk_bf16_f32 v0, v0, v1
; __device__ __forceinline__ int crow(int r, int hi) { return (r & 3) + 8 * (r >> 2) + 4 * hi; }
; __device__ __forceinline__ unsigned cvtpk(float lo, float hi) { unsigned r; asm volatile("v_cvt_pk_bf16_f32 %0, %1, %2" : "=v"(r) : "v"(lo), "v"(hi)); return r; }
; template <int DLO, int DHI>
; __device__ __forceinline__ void attn_dense_body(const int g_wave, const bf16* __restrict__ Qb, const bf16* __restrict__ Kh, const bf16* __restrict__ Vh,
;                                                 bf16* __restrict__ Ob, int ldo, char* lds) {
;     ...
;   unsigned short* Ow = (unsigned short*)Ob + (long)(wid * QBLK) * ldo;
; #pragma unroll
;   for (int r = 0; r < 16; ++r) { int orow = crow(r, hi);
; #pragma unroll
;     for (int d0 = 0; d0 < 4; ++d0) Ow[(long)orow * ldo + d0 * 32 + r32] = (unsigned short)(cvtpk(o[d0][r] * rli[r], 0.f) & 0xffffu); }
;   __syncthreads();
	global_store_short v[2:3], v0, off offset:64
	v_mul_f32_e32 v0, v40, v80
	v_cvt_pk_bf16_f32 v0, v0, v1
	global_store_short v[2:3], v0, off offset:128
	v_mul_f32_e32 v0, v24, v80
	v_cvt_pk_bf16_f32 v0, v0, v1
	global_store_short v[2:3], v0, off offset:192
	v_add_u32_e32 v0, 11, v86
	v_mad_i64_i32 v[2:3], s[2:3], s10, v0, 0
	v_mul_f32_e32 v0, v9, v81
	v_lshl_add_u64 v[2:3], v[2:3], 1, v[66:67]
	v_cvt_pk_bf16_f32 v0, v0, v1
	global_store_short v[2:3], v0, off
	v_mul_f32_e32 v0, v57, v81
	v_cvt_pk_bf16_f32 v0, v0, v1
	global_store_short v[2:3], v0, off offset:64
	v_mul_f32_e32 v0, v41, v81
	v_cvt_pk_bf16_f32 v0, v0, v1
	global_store_short v[2:3], v0, off offset:128
	v_mul_f32_e32 v0, v25, v81
	v_cvt_pk_bf16_f32 v0, v0, v1
	global_store_short v[2:3], v0, off offset:192
	v_add_u32_e32 v0, 16, v86
	v_mad_i64_i32 v[2:3], s[2:3], s10, v0, 0
	v_mul_f32_e32 v0, v10, v82
	v_lshl_add_u64 v[2:3], v[2:3], 1, v[66:67]
	v_cvt_pk_bf16_f32 v0, v0, v1
	global_store_short v[2:3], v0, off
	v_mul_f32_e32 v0, v58, v82
	v_cvt_pk_bf16_f32 v0, v0, v1
	global_store_short v[2:3], v0, off offset:64
	v_mul_f32_e32 v0, v42, v82
	v_cvt_pk_bf16_f32 v0, v0, v1
	global_store_short v[2:3], v0, off offset:128
	v_mul_f32_e32 v0, v26, v82
	v_cvt_pk_bf16_f32 v0, v0, v1
	global_store_short v[2:3], v0, off offset:192
	v_add_u32_e32 v0, 17, v86
	v_mad_i64_i32 v[2:3], s[2:3], s10, v0, 0
	v_mul_f32_e32 v0, v11, v83
	v_lshl_add_u64 v[2:3], v[2:3], 1, v[66:67]
	v_cvt_pk_bf16_f32 v0, v0, v1
	global_store_short v[2:3], v0, off
	v_mul_f32_e32 v0, v59, v83
	v_cvt_pk_bf16_f32 v0, v0, v1
	global_store_short v[2:3], v0, off offset:64
	v_mul_f32_e32 v0, v43, v83
	v_cvt_pk_bf16_f32 v0, v0, v1
	global_store_short v[2:3], v0, off offset:128
	v_mul_f32_e32 v0, v27, v83
	v_cvt_pk_bf16_f32 v0, v0, v1
	global_store_short v[2:3], v0, off offset:192
	v_add_u32_e32 v0, 18, v86
	v_mad_i64_i32 v[2:3], s[2:3], s10, v0, 0
	v_mul_f32_e32 v0, v12, v84
	v_lshl_add_u64 v[2:3], v[2:3], 1, v[66:67]
	v_cvt_pk_bf16_f32 v0, v0, v1
	global_store_short v[2:3], v0, off
	v_mul_f32_e32 v0, v60, v84
	v_cvt_pk_bf16_f32 v0, v0, v1
	global_store_short v[2:3], v0, off offset:64
	v_mul_f32_e32 v0, v44, v84
	v_cvt_pk_bf16_f32 v0, v0, v1
	global_store_short v[2:3], v0, off offset:128
	v_mul_f32_e32 v0, v28, v84
	v_cvt_pk_bf16_f32 v0, v0, v1
	global_store_short v[2:3], v0, off offset:192
	v_add_u32_e32 v0, 19, v86
	v_mad_i64_i32 v[2:3], s[2:3], s10, v0, 0
	v_mul_f32_e32 v0, v13, v85
	v_lshl_add_u64 v[2:3], v[2:3], 1, v[66:67]
	v_cvt_pk_bf16_f32 v0, v0, v1
	global_store_short v[2:3], v0, off
	v_mul_f32_e32 v0, v61, v85
	v_cvt_pk_bf16_f32 v0, v0, v1
	global_store_short v[2:3], v0, off offset:64
	v_mul_f32_e32 v0, v45, v85
	s_waitcnt lgkmcnt(0)
	v_rcp_f32_e32 v70, v70
	v_cvt_pk_bf16_f32 v0, v0, v1
	global_store_short v[2:3], v0, off offset:128
	v_mul_f32_e32 v0, v29, v85
	v_cvt_pk_bf16_f32 v0, v0, v1
	global_store_short v[2:3], v0, off offset:192
	v_add_u32_e32 v0, 24, v86
	v_mad_i64_i32 v[2:3], s[2:3], s10, v0, 0
	v_mul_f32_e32 v0, v14, v70
	v_lshl_add_u64 v[2:3], v[2:3], 1, v[66:67]
	v_cvt_pk_bf16_f32 v0, v0, v1
	global_store_short v[2:3], v0, off
	v_mul_f32_e32 v0, v62, v70
	v_cvt_pk_bf16_f32 v0, v0, v1
	global_store_short v[2:3], v0, off offset:64
	v_mul_f32_e32 v0, v46, v70
	v_rcp_f32_e32 v71, v71
	v_cvt_pk_bf16_f32 v0, v0, v1
	global_store_short v[2:3], v0, off offset:128
	v_mul_f32_e32 v0, v30, v70
	v_cvt_pk_bf16_f32 v0, v0, v1
	global_store_short v[2:3], v0, off offset:192
	v_add_u32_e32 v0, 25, v86
	v_mad_i64_i32 v[2:3], s[2:3], s10, v0, 0
	v_mul_f32_e32 v0, v15, v71
	v_lshl_add_u64 v[2:3], v[2:3], 1, v[66:67]
	v_cvt_pk_bf16_f32 v0, v0, v1
	global_store_short v[2:3], v0, off
	v_mul_f32_e32 v0, v63, v71
	v_cvt_pk_bf16_f32 v0, v0, v1
	global_store_short v[2:3], v0, off offset:64
	v_mul_f32_e32 v0, v47, v71
	v_rcp_f32_e32 v72, v72
	v_cvt_pk_bf16_f32 v0, v0, v1
	global_store_short v[2:3], v0, off offset:128
	v_mul_f32_e32 v0, v31, v71
	v_cvt_pk_bf16_f32 v0, v0, v1
	global_store_short v[2:3], v0, off offset:192
	v_add_u32_e32 v0, 26, v86
	v_mad_i64_i32 v[2:3], s[2:3], s10, v0, 0
	v_mul_f32_e32 v0, v16, v72
	v_lshl_add_u64 v[2:3], v[2:3], 1, v[66:67]
	v_cvt_pk_bf16_f32 v0, v0, v1
	global_store_short v[2:3], v0, off
	v_mul_f32_e32 v0, v64, v72
	v_cvt_pk_bf16_f32 v0, v0, v1
	global_store_short v[2:3], v0, off offset:64
	v_mul_f32_e32 v0, v48, v72
	v_rcp_f32_e32 v73, v73
	v_cvt_pk_bf16_f32 v0, v0, v1
	global_store_short v[2:3], v0, off offset:128
	v_mul_f32_e32 v0, v32, v72
	v_cvt_pk_bf16_f32 v0, v0, v1
	global_store_short v[2:3], v0, off offset:192
	v_add_u32_e32 v0, 27, v86
	v_mad_i64_i32 v[2:3], s[2:3], s10, v0, 0
	v_mul_f32_e32 v0, v17, v73
	v_lshl_add_u64 v[2:3], v[2:3], 1, v[66:67]
	v_cvt_pk_bf16_f32 v0, v0, v1
	global_store_short v[2:3], v0, off
	v_mul_f32_e32 v0, v65, v73
	v_cvt_pk_bf16_f32 v0, v0, v1
	global_store_short v[2:3], v0, off offset:64
	v_mul_f32_e32 v0, v49, v73
	v_cvt_pk_bf16_f32 v0, v0, v1
	global_store_short v[2:3], v0, off offset:128
	v_mul_f32_e32 v0, v33, v73
	v_cvt_pk_bf16_f32 v0, v0, v1
	global_store_short v[2:3], v0, off offset:192
	s_waitcnt vmcnt(63) expcnt(7) lgkmcnt(15)
	s_barrier
	s_branch .LBB0_1062
; __device__ __forceinline__ int opaque_lane() { int z; asm volatile("v_mov_b32 %0, 0" : "=v"(z)); return __builtin_amdgcn_mbcnt_hi(-1, __builtin_amdgcn_mbcnt_lo(-1, z)); }
; __device__ __forceinline__ int launder_s(int v) { asm volatile("" : "+s"(v)); return v; }
; __device__ __forceinline__ int v_st(int k, int c) { const int kk = (k & ~0xC) | ((k & 4) << 1) | ((k & 8) >> 1); return ((kk >> 3) * 4 + (c >> 5)) * 512 + ((kk & 7) * 32 + (c & 31)) * 2; }
;   p0 = f32x16{}; p1 = f32x16{};
; #pragma unroll
;   for (int d0 = DLO; d0 < DHI; ++d0) { int cb = (d0 * 16 + hi * 8) * 2;
;     bf16x8 b0 = *reinterpret_cast<const bf16x8*>((const char*)Ks + KSWZ(r32, cb));
;     bf16x8 b1 = *reinterpret_cast<const bf16x8*>((const char*)Ks + KSWZ(32 + r32, cb));
;     p0 = __builtin_amdgcn_mfma_f32_32x32x16_bf16(b0, qr[d0], p0, 0, 0, 0);
;     p1 = __builtin_amdgcn_mfma_f32_32x32x16_bf16(b1, qr[d0], p1, 0, 0, 0); }
; }
; template <int DLO, int DHI>
; __device__ __forceinline__ void attn_dense_body(const int g_wave, const bf16* __restrict__ Qb, const bf16* __restrict__ Kh, const bf16* __restrict__ Vh,
;                                                 bf16* __restrict__ Ob, int ldo, char* lds) {
;   const int wid = launder_s(g_wave), lane = opaque_lane(), tid = (wid << 6) | lane, r32 = lane & 31, hi = lane >> 5;
;   bf16* V_lds = (bf16*)lds; bf16* K_lds = (bf16*)(lds + 2 * SHM_V);
;   float* ws = (float*)(lds + 2 * SHM_V + 2 * SHM_K) + wid * 64; float* li_l = ws; float* al_l = ws + 32;
;   float m_reg = -1e30f, l_reg = 0; f32x16 o[4] = {}; bf16x8 qr[8];
;   const bf16* Qw = Qb + (long)(wid * QBLK + r32) * LDQ + hi * 8;
; #pragma unroll
;   for (int d0 = DLO; d0 < DHI; ++d0) qr[d0] = ld8(Qw + d0 * 16);
;   const int sr = tid >> 4, sc = (tid & 15) * 8, vst0 = v_st(sr, sc), vst1 = v_st(32 + sr, sc);
;   const int vb0 = (int)(uintptr_t)V_lds + v_rd_base(lane);
;   struct { bf16x8 vs0, vs1, ks0, ks1; } sr_[2];
;     ...
;   f32x16 pA0, pA1, pB0, pB1; float mnA, mnB, alA, alB; bf16x8 pa0, pa1, pa2, pa3; constexpr int NT = SEQ / KVBLK;
;   constexpr int SE = 0, SO = 1;
;   SLOAD(SE, 0); asm volatile("s_waitcnt vmcnt(0)" ::: "memory"); SWRITE(0, SE); __syncthreads();
;   qkt<DLO, DHI>(pA0, pA1, K_lds, qr, r32, hi); partialSM(pA0, pA1, m_reg, mnA, alA);
.LBB0_1021:
	s_mov_b32 s1, s64
	v_mov_b32 v0, 0
	s_lshl_b32 s4, s1, 6
	v_mbcnt_lo_u32_b32 v0, -1, v0
	s_waitcnt vmcnt(0)
	v_mbcnt_hi_u32_b32 v72, -1, v0
	v_or_b32_e32 v0, s4, v72
	v_ashrrev_i32_e32 v73, 4, v0
	v_lshlrev_b32_e32 v54, 3, v72
	v_and_b32_e32 v0, 0x78, v54
	v_add_u32_e32 v22, 32, v73
	v_mov_b64_e32 v[50:51], s[94:95]
	v_mov_b64_e32 v[52:53], s[92:93]
	v_lshlrev_b32_e32 v0, 1, v0
	v_mad_i64_i32 v[2:3], s[2:3], v73, s79, v[50:51]
	v_mad_i64_i32 v[4:5], s[2:3], v22, s79, v[50:51]
	v_mad_i64_i32 v[10:11], s[2:3], v73, s67, v[52:53]
	v_mad_i64_i32 v[12:13], s[2:3], v22, s67, v[52:53]
	v_lshl_add_u64 v[2:3], v[2:3], 0, v[0:1]
	v_lshl_add_u64 v[6:7], v[4:5], 0, v[0:1]
	v_lshl_add_u64 v[10:11], v[10:11], 0, v[0:1]
	v_lshl_add_u64 v[14:15], v[12:13], 0, v[0:1]
	v_and_b32_e32 v170, 31, v72
	s_lshl_b32 s14, s1, 5
	global_load_dwordx4 v[2:5], v[2:3], off
	s_nop 0
	global_load_dwordx4 v[6:9], v[6:7], off
	s_nop 0
	global_load_dwordx4 v[10:13], v[10:11], off
	s_nop 0
	global_load_dwordx4 v[14:17], v[14:15], off
	v_or_b32_e32 v18, s14, v170
	v_ashrrev_i32_e32 v171, 5, v72
	v_ashrrev_i32_e32 v19, 31, v18
	v_lshlrev_b64 v[18:19], 12, v[18:19]
	v_lshlrev_b32_e32 v20, 3, v171
	v_lshl_add_u64 v[18:19], s[90:91], 0, v[18:19]
	v_ashrrev_i32_e32 v21, 31, v20
	v_lshl_add_u64 v[18:19], v[20:21], 1, v[18:19]
	global_load_dwordx4 v[102:105], v[18:19], off
	global_load_dwordx4 v[98:101], v[18:19], off offset:32
	global_load_dwordx4 v[106:109], v[18:19], off offset:64
	global_load_dwordx4 v[110:113], v[18:19], off offset:96
	v_and_b32_e32 v23, 0xfffff0, v73
	v_lshlrev_b32_e32 v24, 1, v73
	v_lshrrev_b32_e32 v25, 1, v73
	v_and_b32_e32 v26, 3, v73
	v_mov_b32_e32 v20, s4
	v_and_or_b32 v23, v24, 8, v23
	v_and_or_b32 v24, v25, 4, v26
	v_and_b32_e32 v26, 0xfffff0, v22
	v_lshlrev_b32_e32 v29, 1, v22
	v_bitop3_b32 v20, v72, s80, v20 bitop3:0xc8
	v_bfe_u32 v21, v54, 5, 2
	v_lshlrev_b32_e32 v27, 8, v73
	v_lshlrev_b32_e32 v22, 8, v22
	v_lshrrev_b32_e32 v23, 1, v23
	v_and_or_b32 v26, v29, 8, v26
	v_lshlrev_b32_e32 v55, 4, v72
	v_bitop3_b32 v27, v0, v27, v20 bitop3:0xde
	v_bitop3_b32 v18, v22, v0, v20 bitop3:0xf6
	v_or_b32_e32 v19, v23, v21
	v_lshrrev_b32_e32 v20, 1, v26
	v_lshlrev_b32_e32 v172, 4, v171
	v_lshlrev_b32_e32 v56, 8, v170
	v_and_b32_e32 v57, 0x70, v55
	v_and_b32_e32 v25, 48, v0
	v_lshlrev_b32_e32 v24, 6, v24
	v_add_u32_e32 v191, 0, v18
	v_lshlrev_b32_e32 v18, 9, v19
	v_or_b32_e32 v19, v20, v21
	v_xad_u32 v28, v57, v172, v56
	v_or3_b32 v18, v18, v24, v25
	v_lshlrev_b32_e32 v19, 9, v19
	v_add_u32_e32 v177, 0, v28
	v_or3_b32 v19, v19, v24, v25
	v_add_u32_e32 v192, 0, v18
	v_add_u32_e32 v190, 0, v27
	s_waitcnt vmcnt(0)
	v_add_u32_e32 v193, 0, v19
	v_add_u32_e32 v62, 64, v73
	v_add_u32_e32 v64, 0x60, v73
	v_add_u32_e32 v77, 0x80, v73
	v_add_u32_e32 v78, 0xa0, v73
	s_lshl_b32 s1, s1, 8
	s_add_i32 s15, s1, 0
	s_add_i32 s15, s15, 0x20000
	s_cmp_lg_u32 0, -1
	s_cselect_b32 s1, 0, 0
	s_mov_b32 s16, s17
	s_mov_b32 s18, s17
	s_waitcnt vmcnt(7)
	ds_write_b128 v192, v[2:5]
	s_waitcnt vmcnt(6)
	ds_write_b128 v193, v[6:9]
	s_waitcnt vmcnt(5)
	ds_write_b128 v190, v[10:13] offset:32768
	s_waitcnt vmcnt(4)
	ds_write_b128 v191, v[14:17] offset:32768
	s_waitcnt lgkmcnt(0)
	s_barrier
	ds_read_b128 v[2:5], v177 offset:32768
	ds_read_b128 v[6:9], v177 offset:40960
	s_waitcnt vmcnt(3) lgkmcnt(1)
	v_mfma_f32_32x32x16_bf16 v[34:49], v[2:5], v[102:105], 0
	v_add_u32_e32 v2, 32, v172
	v_xad_u32 v2, v2, v57, v56
	v_add_u32_e32 v194, 0, v2
	ds_read_b128 v[2:5], v194 offset:32768
	v_lshlrev_b32_e32 v10, 1, v72
	s_mov_b32 s19, s17
	s_mov_b32 s20, s17
	s_waitcnt lgkmcnt(1)
	v_mfma_f32_32x32x16_bf16 v[18:33], v[6:9], v[102:105], 0
	ds_read_b128 v[6:9], v194 offset:40960
	s_mov_b32 s21, s17
	s_mov_b32 s22, s17
	s_mov_b32 s23, s17
	s_mov_b32 s24, s17
	s_mov_b32 s25, s17
	s_mov_b32 s26, s17
	s_waitcnt vmcnt(2) lgkmcnt(1)
	v_mfma_f32_32x32x16_bf16 v[34:49], v[2:5], v[98:101], v[34:49]
	v_and_b32_e32 v2, 0xc0, v55
	v_and_or_b32 v11, v54, 24, v2
	v_add_u32_e32 v2, 64, v172
	v_xad_u32 v2, v2, v57, v56
	v_add_u32_e32 v195, 0, v2
	ds_read_b128 v[2:5], v195 offset:32768
	s_mov_b32 s27, s17
	s_waitcnt lgkmcnt(1)
	v_mfma_f32_32x32x16_bf16 v[18:33], v[6:9], v[98:101], v[18:33]
	v_and_b32_e32 v6, 32, v10
	v_and_b32_e32 v7, 0x100, v54
	v_or3_b32 v74, v11, v6, v7
	ds_read_b128 v[6:9], v195 offset:40960
	v_add_u32_e32 v176, s1, v74
	s_mov_b32 s28, s17
	s_mov_b32 s29, s17
	s_waitcnt vmcnt(1) lgkmcnt(1)
	v_mfma_f32_32x32x16_bf16 v[34:49], v[2:5], v[106:109], v[34:49]
	v_add_u32_e32 v2, 0x60, v172
	v_xad_u32 v2, v2, v57, v56
	v_add_u32_e32 v196, 0, v2
	ds_read_b128 v[2:5], v196 offset:32768
	ds_read_b128 v[54:57], v196 offset:40960
	s_mov_b32 s30, s17
	s_mov_b32 s31, s17
	s_waitcnt lgkmcnt(2)
	v_mfma_f32_32x32x16_bf16 v[18:33], v[6:9], v[106:109], v[18:33]
	s_mov_b32 s34, 1
	v_cmp_gt_u32_e64 s[6:7], 32, v72
	v_lshl_add_u32 v173, v170, 2, s15
	v_mov_b32_e32 v174, 0
	s_waitcnt vmcnt(0) lgkmcnt(1)
	v_mfma_f32_32x32x16_bf16 v[34:49], v[2:5], v[110:113], v[34:49]
	v_mov_b64_e32 v[2:3], s[16:17]
	v_mov_b64_e32 v[16:17], s[30:31]
	v_mov_b64_e32 v[4:5], s[18:19]
	v_mov_b64_e32 v[6:7], s[20:21]
	v_mov_b64_e32 v[8:9], s[22:23]
	v_mov_b64_e32 v[10:11], s[24:25]
	v_mov_b64_e32 v[12:13], s[26:27]
	s_waitcnt lgkmcnt(0)
; #define SLOAD(i, k0) do { sr_[i].vs0 = ld8(&Vh[(long)((k0) + sr) * LDV + sc]); sr_[i].vs1 = ld8(&Vh[(long)((k0) + 32 + sr) * LDV + sc]); \
;     sr_[i].ks0 = ld8(&Kh[(long)((k0) + sr) * LDK + sc]); sr_[i].ks1 = ld8(&Kh[(long)((k0) + 32 + sr) * LDK + sc]); } while (0)
; #define SWRITE(b, i) do { *(bf16x8*)((char*)V_lds + (b) * SHM_V + vst0) = sr_[i].vs0;          \
;     *(bf16x8*)((char*)V_lds + (b) * SHM_V + vst1) = sr_[i].vs1; int kc = sc * 2;               \
;     *(bf16x8*)((char*)K_lds + (b) * SHM_K + KSWZ(sr, kc)) = sr_[i].ks0;                       \
;     *(bf16x8*)((char*)K_lds + (b) * SHM_K + KSWZ(32 + sr, kc)) = sr_[i].ks1; } while (0)
; #define SWAIT() asm volatile("s_waitcnt vmcnt(4)" ::: "memory")
; __device__ __forceinline__ void partialSM(f32x16& p0, f32x16& p1, float& m_reg, float& mn, float& alpha) {
;   constexpr float C = SCALE * 1.4426950408889634f;
;   float pmax = p0[0];
; #pragma unroll
;   for (int r = 1; r < 16; ++r) pmax = fmaxf(pmax, p0[r]);
; #pragma unroll
;   for (int r = 0; r < 16; ++r) pmax = fmaxf(pmax, p1[r]);
;   { auto rr = __builtin_amdgcn_permlane32_swap(__float_as_uint(pmax), __float_as_uint(pmax), false, false);
;     pmax = fmaxf(__uint_as_float(rr[0]), __uint_as_float(rr[1])); }
;   if (__builtin_expect(__all(pmax - m_reg <= THR / SCALE), 1)) { mn = m_reg; alpha = 1.f; }
;   else { mn = fmaxf(m_reg, pmax); alpha = __builtin_amdgcn_exp2f((m_reg - mn) * C); m_reg = mn; }
;   float mnC = -mn * C;
; #pragma unroll
;   for (int r = 0; r < 16; ++r) p0[r] = fmaf(p0[r], C, mnC);
; #pragma unroll
;   for (int r = 0; r < 16; ++r) p1[r] = fmaf(p1[r], C, mnC);
; #pragma unroll
;   for (int r = 0; r < 16; ++r) p0[r] = __builtin_amdgcn_exp2f(p0[r]);
; }
; template <int DLO, int DHI>
; __device__ __forceinline__ void attn_dense_body(const int g_wave, const bf16* __restrict__ Qb, const bf16* __restrict__ Kh, const bf16* __restrict__ Vh,
;                                                 bf16* __restrict__ Ob, int ldo, char* lds) {
;     ...
;   SLOAD(SE, 0); asm volatile("s_waitcnt vmcnt(0)" ::: "memory"); SWRITE(0, SE); __syncthreads();
;   qkt<DLO, DHI>(pA0, pA1, K_lds, qr, r32, hi); partialSM(pA0, pA1, m_reg, mnA, alA);
;   SLOAD(SO, KVBLK); SLOAD(SE, 2 * KVBLK);
;   SWAIT(); SWRITE(1, SO); __syncthreads();
	v_mfma_f32_32x32x16_bf16 v[18:33], v[54:57], v[110:113], v[18:33]
	s_nop 2
	v_max_f32_e32 v54, v35, v35
	v_max_f32_e32 v55, v34, v34
	v_max_f32_e32 v54, v55, v54
	v_max3_f32 v54, v54, v36, v37
	v_max3_f32 v54, v54, v38, v39
	v_max3_f32 v54, v54, v40, v41
	v_max3_f32 v54, v54, v42, v43
	v_max3_f32 v54, v54, v44, v45
	v_max3_f32 v54, v54, v46, v47
	v_max3_f32 v54, v54, v48, v49
	v_max3_f32 v54, v54, v18, v19
	v_max3_f32 v54, v54, v20, v21
	v_max3_f32 v54, v54, v22, v23
	v_max3_f32 v54, v54, v24, v25
	v_max3_f32 v54, v54, v26, v27
	v_max3_f32 v54, v54, v28, v29
	v_max3_f32 v54, v54, v30, v31
	v_max3_f32 v70, v54, v32, v33
	v_mov_b32_e32 v71, v70
	s_nop 1
	v_permlane32_swap_b32_e32 v70, v71
	v_max_f32_e32 v71, v71, v71
	v_max_f32_e32 v70, v70, v70
	v_max_f32_e32 v70, v70, v71
	v_max_f32_e32 v75, 0xf149f2ca, v70
	v_add_f32_e32 v71, 0x7149f2ca, v70
	v_sub_f32_e32 v70, 0xf149f2ca, v75
	v_mad_i64_i32 v[54:55], s[2:3], v62, s79, v[50:51]
	v_mad_i64_i32 v[56:57], s[2:3], v64, s79, v[50:51]
	v_mad_i64_i32 v[62:63], s[2:3], v62, s67, v[52:53]
	v_mad_i64_i32 v[64:65], s[2:3], v64, s67, v[52:53]
	v_cmp_ge_f32_e32 vcc, s63, v71
	v_mul_f32_e32 v76, 0x3e0293ee, v70
	v_mad_i64_i32 v[70:71], s[2:3], v77, s79, v[50:51]
	v_mad_i64_i32 v[50:51], s[2:3], v78, s79, v[50:51]
	v_lshl_add_u64 v[54:55], v[54:55], 0, v[0:1]
	v_lshl_add_u64 v[58:59], v[56:57], 0, v[0:1]
	v_lshl_add_u64 v[62:63], v[62:63], 0, v[0:1]
	v_lshl_add_u64 v[66:67], v[64:65], 0, v[0:1]
	v_lshl_add_u64 v[70:71], v[70:71], 0, v[0:1]
	v_lshl_add_u64 v[50:51], v[50:51], 0, v[0:1]
	global_load_dwordx4 v[54:57], v[54:55], off
	s_nop 0
	global_load_dwordx4 v[58:61], v[58:59], off
	s_nop 0
	global_load_dwordx4 v[62:65], v[62:63], off
	s_nop 0
	global_load_dwordx4 v[66:69], v[66:67], off
	s_nop 0
	global_load_dwordx4 v[114:117], v[70:71], off
	global_load_dwordx4 v[118:121], v[50:51], off
	v_mad_i64_i32 v[50:51], s[2:3], v77, s67, v[52:53]
	v_lshl_add_u64 v[50:51], v[50:51], 0, v[0:1]
	v_mad_i64_i32 v[52:53], s[2:3], v78, s67, v[52:53]
	v_lshl_add_u64 v[52:53], v[52:53], 0, v[0:1]
	global_load_dwordx4 v[122:125], v[50:51], off
	global_load_dwordx4 v[126:129], v[52:53], off
	s_cmp_eq_u64 vcc, exec
	v_exp_f32_e32 v0, v76
	s_cselect_b64 vcc, -1, 0
	s_addk_i32 s1, 0x4000
	v_add_u32_e32 v175, s1, v74
	s_add_u32 s1, s84, s86
	s_addc_u32 s3, s85, s87
	v_cndmask_b32_e32 v150, v75, v205, vcc
	s_add_u32 s2, s1, s11
	v_cndmask_b32_e64 v197, v0, 1.0, vcc
	v_mul_f32_e32 v0, 0xbe0293ee, v150
	s_addc_u32 s3, s3, 0
	v_pk_fma_f32 v[142:143], v[18:19], s[62:63], v[0:1] op_sel_hi:[1,0,0]
	v_mov_b64_e32 v[18:19], s[2:3]
	v_mad_i64_i32 v[162:163], s[2:3], v73, s67, v[18:19]
	s_add_u32 s1, s84, s88
	v_mov_b32_e32 v50, v0
	s_addc_u32 s3, s85, s89
	v_fmamk_f32 v34, v34, 0x3e0293ee, v0
	v_fmamk_f32 v35, v35, 0x3e0293ee, v0
	v_fmamk_f32 v36, v36, 0x3e0293ee, v0
	v_fmamk_f32 v37, v37, 0x3e0293ee, v0
	v_fmamk_f32 v38, v38, 0x3e0293ee, v0
	v_fmamk_f32 v39, v39, 0x3e0293ee, v0
	v_fmamk_f32 v40, v40, 0x3e0293ee, v0
	v_fmamk_f32 v41, v41, 0x3e0293ee, v0
	v_fmamk_f32 v42, v42, 0x3e0293ee, v0
	v_fmamk_f32 v43, v43, 0x3e0293ee, v0
	v_fmamk_f32 v44, v44, 0x3e0293ee, v0
	v_fmamk_f32 v45, v45, 0x3e0293ee, v0
	v_fmamk_f32 v46, v46, 0x3e0293ee, v0
	v_fmamk_f32 v47, v47, 0x3e0293ee, v0
	v_fmamk_f32 v48, v48, 0x3e0293ee, v0
	v_fmac_f32_e32 v50, 0x3e0293ee, v49
	s_add_u32 s2, s1, s13
	v_exp_f32_e32 v161, v34
	v_exp_f32_e32 v167, v35
	v_exp_f32_e32 v147, v36
	v_exp_f32_e32 v166, v37
	v_exp_f32_e32 v148, v38
	v_exp_f32_e32 v160, v39
	v_exp_f32_e32 v149, v40
	v_exp_f32_e32 v159, v41
	v_exp_f32_e32 v156, v42
	v_exp_f32_e32 v158, v43
	v_exp_f32_e32 v154, v44
	v_exp_f32_e32 v157, v45
	v_exp_f32_e32 v152, v46
	v_exp_f32_e32 v155, v47
	v_exp_f32_e32 v151, v48
	v_exp_f32_e32 v153, v50
	s_addc_u32 s3, s3, 0
	s_waitcnt vmcnt(4)
	v_mov_b64_e32 v[18:19], s[2:3]
	v_mov_b64_e32 v[14:15], s[28:29]
	v_pk_fma_f32 v[136:137], v[32:33], s[62:63], v[0:1] op_sel_hi:[1,0,0]
	v_pk_fma_f32 v[138:139], v[30:31], s[62:63], v[0:1] op_sel_hi:[1,0,0]
	v_pk_fma_f32 v[144:145], v[28:29], s[62:63], v[0:1] op_sel_hi:[1,0,0]
	v_pk_fma_f32 v[130:131], v[26:27], s[62:63], v[0:1] op_sel_hi:[1,0,0]
	v_pk_fma_f32 v[132:133], v[24:25], s[62:63], v[0:1] op_sel_hi:[1,0,0]
	v_pk_fma_f32 v[134:135], v[22:23], s[62:63], v[0:1] op_sel_hi:[1,0,0]
	v_pk_fma_f32 v[140:141], v[20:21], s[62:63], v[0:1] op_sel_hi:[1,0,0]
	s_waitcnt vmcnt(7)
	ds_write_b128 v192, v[54:57] offset:16384
	s_waitcnt vmcnt(6)
	ds_write_b128 v193, v[58:61] offset:16384
	s_waitcnt vmcnt(5)
	ds_write_b128 v190, v[62:65] offset:49152
	s_waitcnt vmcnt(4)
	ds_write_b128 v191, v[66:69] offset:49152
	v_and_b32_e32 v0, 15, v72
	v_mad_i64_i32 v[164:165], s[2:3], v73, s79, v[18:19]
	v_mov_b64_e32 v[64:65], v[16:17]
	v_mov_b64_e32 v[48:49], v[16:17]
	v_mov_b64_e32 v[32:33], v[16:17]
	s_mov_b32 s24, 0x3fb8aa3b
	v_lshlrev_b32_e32 v0, 4, v0
	v_mov_b64_e32 v[62:63], v[14:15]
	v_mov_b64_e32 v[60:61], v[12:13]
	v_mov_b64_e32 v[58:59], v[10:11]
	v_mov_b64_e32 v[56:57], v[8:9]
	v_mov_b64_e32 v[54:55], v[6:7]
	v_mov_b64_e32 v[52:53], v[4:5]
	v_mov_b64_e32 v[50:51], v[2:3]
	v_mov_b64_e32 v[46:47], v[14:15]
	v_mov_b64_e32 v[44:45], v[12:13]
	v_mov_b64_e32 v[42:43], v[10:11]
	v_mov_b64_e32 v[40:41], v[8:9]
	v_mov_b64_e32 v[38:39], v[6:7]
	v_mov_b64_e32 v[36:37], v[4:5]
	v_mov_b64_e32 v[34:35], v[2:3]
	v_mov_b64_e32 v[30:31], v[14:15]
	v_mov_b64_e32 v[28:29], v[12:13]
	v_mov_b64_e32 v[26:27], v[10:11]
	v_mov_b64_e32 v[24:25], v[8:9]
	v_mov_b64_e32 v[22:23], v[6:7]
	v_mov_b64_e32 v[20:21], v[4:5]
	v_mov_b64_e32 v[18:19], v[2:3]
	s_waitcnt lgkmcnt(0)
	s_barrier
	v_xor_b32_e32 v192, 0x10000, v192
	v_xor_b32_e32 v193, 0x10000, v193
	v_xor_b32_e32 v190, 0x10000, v190
	v_xor_b32_e32 v191, 0x10000, v191
; #define SBAR() __builtin_amdgcn_sched_barrier(0)
; #define SLOAD(i, k0) do { sr_[i].vs0 = ld8(&Vh[(long)((k0) + sr) * LDV + sc]); sr_[i].vs1 = ld8(&Vh[(long)((k0) + 32 + sr) * LDV + sc]); \
;     sr_[i].ks0 = ld8(&Kh[(long)((k0) + sr) * LDK + sc]); sr_[i].ks1 = ld8(&Kh[(long)((k0) + 32 + sr) * LDK + sc]); } while (0)
; __device__ __forceinline__ void finishSM(f32x16& p0, f32x16& p1, float alpha, float& l_reg, bf16x8& pa0, bf16x8& pa1, bf16x8& pa2, bf16x8& pa3) {
; #pragma unroll
;   for (int r = 0; r < 16; ++r) p1[r] = __builtin_amdgcn_exp2f(p1[r]);
;   float ps = 0;
; #pragma unroll
;   for (int r = 0; r < 16; ++r) ps += p0[r];
; #pragma unroll
;   for (int r = 0; r < 16; ++r) ps += p1[r];
;   { auto rr = __builtin_amdgcn_permlane32_swap(__float_as_uint(ps), __float_as_uint(ps), false, false);
;     ps = __uint_as_float(rr[0]) + __uint_as_float(rr[1]); }
;   l_reg = l_reg * alpha + ps;
;   PK4(p0, 0, pa0); PK4(p0, 8, pa1); PK4(p1, 0, pa2); PK4(p1, 8, pa3);
; }
; template <int DLO, int DHI>
; __device__ __forceinline__ void attn_dense_body(const int g_wave, const bf16* __restrict__ Qb, const bf16* __restrict__ Kh, const bf16* __restrict__ Vh,
;                                                 bf16* __restrict__ Ob, int ldo, char* lds) {
;     ...
;   for (int j = 1; j + 1 < NT; j += 2) {
;     SBAR(); qkt<DLO, DHI>(pB0, pB1, (bf16*)((char*)K_lds + SHM_K), qr, r32, hi);
;     finishSM(pA0, pA1, alA, l_reg, pa0, pa1, pa2, pa3); SBAR();
;     SLOAD(SO, (j + 2) * KVBLK); SBAR();
;     pv_d0(o, vb0, pa0, pa1, pa2, pa3); partialSM(pB0, pB1, m_reg, mnB, alB);
.LBB0_1022:
	ds_read_b128 v[66:69], v177 offset:49152
	ds_read_b128 v[70:73], v177 offset:57344
	v_add_f32_e32 v146, 0, v161
	v_add_f32_e32 v146, v167, v146
	v_add_f32_e32 v146, v147, v146
	s_waitcnt lgkmcnt(1)
	v_mfma_f32_32x32x16_bf16 v[82:97], v[66:69], v[102:105], 0
	v_add_f32_e32 v146, v166, v146
	v_add_f32_e32 v146, v148, v146
	ds_read_b128 v[186:189], v194 offset:49152
	ds_read_b128 v[208:211], v194 offset:57344
	v_add_f32_e32 v146, v160, v146
	v_add_f32_e32 v146, v149, v146
	v_add_f32_e32 v146, v159, v146
	v_add_f32_e32 v146, v156, v146
	s_waitcnt lgkmcnt(2)
	v_mfma_f32_32x32x16_bf16 v[66:81], v[70:73], v[102:105], 0
	v_add_f32_e32 v146, v158, v146
	v_add_f32_e32 v146, v154, v146
	v_add_f32_e32 v146, v157, v146
	v_exp_f32_e32 v142, v142
	v_add_f32_e32 v146, v152, v146
	v_exp_f32_e32 v143, v143
	v_add_f32_e32 v146, v155, v146
	s_waitcnt lgkmcnt(1)
	v_mfma_f32_32x32x16_bf16 v[82:97], v[186:189], v[98:101], v[82:97]
	v_exp_f32_e32 v140, v140
	v_add_f32_e32 v146, v151, v146
	v_exp_f32_e32 v141, v141
	v_add_f32_e32 v146, v153, v146
	v_exp_f32_e32 v134, v134
	v_add_f32_e32 v146, v142, v146
	v_exp_f32_e32 v135, v135
	s_waitcnt lgkmcnt(0)
	v_mfma_f32_32x32x16_bf16 v[66:81], v[208:211], v[98:101], v[66:81]
	ds_read_b128 v[186:189], v195 offset:49152
	ds_read_b128 v[208:211], v195 offset:57344
	v_add_f32_e32 v146, v143, v146
	v_exp_f32_e32 v132, v132
	v_add_f32_e32 v146, v140, v146
	v_exp_f32_e32 v133, v133
	v_add_f32_e32 v146, v141, v146
	v_exp_f32_e32 v130, v130
	s_waitcnt lgkmcnt(1)
	v_mfma_f32_32x32x16_bf16 v[82:97], v[186:189], v[106:109], v[82:97]
	v_add_f32_e32 v146, v134, v146
	v_exp_f32_e32 v131, v131
	v_add_f32_e32 v146, v135, v146
	v_exp_f32_e32 v144, v144
	v_add_f32_e32 v146, v132, v146
	v_exp_f32_e32 v145, v145
	v_add_f32_e32 v146, v133, v146
	s_waitcnt lgkmcnt(0)
	v_mfma_f32_32x32x16_bf16 v[66:81], v[208:211], v[106:109], v[66:81]
	ds_read_b128 v[186:189], v196 offset:49152
	ds_read_b128 v[208:211], v196 offset:57344
	v_exp_f32_e32 v138, v138
	v_add_f32_e32 v146, v130, v146
	v_exp_f32_e32 v139, v139
	v_add_f32_e32 v146, v131, v146
	v_exp_f32_e32 v136, v136
	v_add_f32_e32 v146, v144, v146
	s_waitcnt lgkmcnt(1)
	v_mfma_f32_32x32x16_bf16 v[82:97], v[186:189], v[110:113], v[82:97]
	v_exp_f32_e32 v137, v137
	v_add_f32_e32 v146, v145, v146
	v_add_f32_e32 v146, v138, v146
	v_add_f32_e32 v146, v139, v146
	v_add_f32_e32 v146, v136, v146
	v_add_f32_e32 v207, v137, v146
	v_cvt_pk_bf16_f32 v146, v161, v167
	s_waitcnt lgkmcnt(0)
	v_mfma_f32_32x32x16_bf16 v[66:81], v[208:211], v[110:113], v[66:81]
	v_mov_b32_e32 v208, v207
	v_cvt_pk_bf16_f32 v147, v147, v166
	v_cvt_pk_bf16_f32 v148, v148, v160
	s_nop 1
	v_permlane32_swap_b32_e32 v207, v208
	v_cvt_pk_bf16_f32 v149, v149, v159
	v_permlane32_swap_b32_e32 v146, v148
	v_cvt_pk_bf16_f32 v156, v156, v158
	v_cvt_pk_bf16_f32 v157, v154, v157
	v_cvt_pk_bf16_f32 v158, v152, v155
	v_cvt_pk_bf16_f32 v159, v151, v153
	v_cvt_pk_bf16_f32 v152, v142, v143
	v_cvt_pk_bf16_f32 v153, v140, v141
	v_cvt_pk_bf16_f32 v154, v134, v135
	v_cvt_pk_bf16_f32 v155, v132, v133
	v_cvt_pk_bf16_f32 v186, v130, v131
	v_cvt_pk_bf16_f32 v187, v144, v145
	v_cvt_pk_bf16_f32 v188, v138, v139
	v_cvt_pk_bf16_f32 v189, v136, v137
	v_permlane32_swap_b32_e32 v147, v149
	v_permlane32_swap_b32_e32 v156, v158
	v_permlane32_swap_b32_e32 v157, v159
	v_permlane32_swap_b32_e32 v152, v154
	v_permlane32_swap_b32_e32 v153, v155
	v_permlane32_swap_b32_e32 v186, v188
	v_permlane32_swap_b32_e32 v187, v189
	s_waitcnt vmcnt(0)
	ds_write_b128 v192, v[114:117]
	ds_write_b128 v193, v[118:121]
	ds_write_b128 v190, v[122:125] offset:32768
	ds_write_b128 v191, v[126:129] offset:32768
	v_lshl_add_u64 v[168:169], v[164:165], 0, v[0:1]
	s_mov_b32 s1, 0x18fb0000
	v_add_co_u32_e32 v130, vcc, s1, v168
	s_mov_b32 s1, 0x18ff8000
	s_nop 0
	v_addc_co_u32_e32 v131, vcc, 0, v169, vcc
	v_add_co_u32_e32 v134, vcc, s1, v168
	v_lshl_add_u64 v[166:167], v[162:163], 0, v[0:1]
	s_nop 0
	v_addc_co_u32_e32 v135, vcc, 0, v169, vcc
	s_mov_b32 s1, 0x1f648000
	v_add_co_u32_e32 v138, vcc, s1, v166
	s_mov_b32 s1, 0x1f654000
	s_nop 0
	v_addc_co_u32_e32 v139, vcc, 0, v167, vcc
	v_add_co_u32_e32 v142, vcc, s1, v166
	global_load_dwordx4 v[130:133], v[130:131], off
	s_nop 0
	global_load_dwordx4 v[134:137], v[134:135], off
	v_addc_co_u32_e32 v143, vcc, 0, v167, vcc
	global_load_dwordx4 v[138:141], v[138:139], off
	s_nop 0
	global_load_dwordx4 v[142:145], v[142:143], off
	ds_read_b64_tr_b16 v[210:211], v176 offset:0
	ds_read_b64_tr_b16 v[212:213], v176 offset:0x800
	ds_read_b64_tr_b16 v[214:215], v176 offset:0x1000
	ds_read_b64_tr_b16 v[216:217], v176 offset:0x1800
	ds_read_b64_tr_b16 v[218:219], v176 offset:0x2000
	ds_read_b64_tr_b16 v[220:221], v176 offset:0x2800
	ds_read_b64_tr_b16 v[222:223], v176 offset:0x3000
	ds_read_b64_tr_b16 v[224:225], v176 offset:0x3800
	s_waitcnt lgkmcnt(6)
	s_nop 0
	v_mfma_f32_32x32x16_bf16 v[2:17], v[146:149], v[210:213], v[2:17]
	ds_read_b64_tr_b16 v[210:211], v176 offset:0x200
	ds_read_b64_tr_b16 v[212:213], v176 offset:0xa00
	s_waitcnt lgkmcnt(6)
	v_mfma_f32_32x32x16_bf16 v[2:17], v[156:159], v[214:217], v[2:17]
	ds_read_b64_tr_b16 v[214:215], v176 offset:0x1200
	ds_read_b64_tr_b16 v[216:217], v176 offset:0x1a00
	s_waitcnt lgkmcnt(6)
	v_mfma_f32_32x32x16_bf16 v[2:17], v[152:155], v[218:221], v[2:17]
	ds_read_b64_tr_b16 v[218:219], v176 offset:0x2200
	ds_read_b64_tr_b16 v[220:221], v176 offset:0x2a00
	s_waitcnt lgkmcnt(6)
	v_mfma_f32_32x32x16_bf16 v[2:17], v[186:189], v[222:225], v[2:17]
	ds_read_b64_tr_b16 v[222:223], v176 offset:0x3200
	ds_read_b64_tr_b16 v[224:225], v176 offset:0x3a00
	s_waitcnt lgkmcnt(6)
; #define SBAR() __builtin_amdgcn_sched_barrier(0)
; #define SWRITE(b, i) do { *(bf16x8*)((char*)V_lds + (b) * SHM_V + vst0) = sr_[i].vs0;          \
;     *(bf16x8*)((char*)V_lds + (b) * SHM_V + vst1) = sr_[i].vs1; int kc = sc * 2;               \
;     *(bf16x8*)((char*)K_lds + (b) * SHM_K + KSWZ(sr, kc)) = sr_[i].ks0;                       \
;     *(bf16x8*)((char*)K_lds + (b) * SHM_K + KSWZ(32 + sr, kc)) = sr_[i].ks1; } while (0)
; #define SWAIT() asm volatile("s_waitcnt vmcnt(4)" ::: "memory")
; #define RESC(a) do { if (__any((a) < 1.f)) { if (hi == 0) al_l[r32] = (a); asm volatile("s_waitcnt lgkmcnt(0)" ::: "memory"); \
;     _Pragma("unroll") for (int d = 0; d < 4; ++d) _Pragma("unroll") for (int r = 0; r < 16; ++r) o[d][r] *= al_l[crow(r, hi)]; } } while (0)
; template <int D0> __device__ __forceinline__ void pv_one(f32x16& od, int vb, bf16x8 pa0, bf16x8 pa1, bf16x8 pa2, bf16x8 pa3) {
;   const s16x4 l0 = tr_read<v_rd_off(D0, 0, 0)>(vb), h0 = tr_read<v_rd_off(D0, 0, 1)>(vb), l1 = tr_read<v_rd_off(D0, 1, 0)>(vb), h1 = tr_read<v_rd_off(D0, 1, 1)>(vb);
;   const s16x4 l2 = tr_read<v_rd_off(D0, 2, 0)>(vb), h2 = tr_read<v_rd_off(D0, 2, 1)>(vb), l3 = tr_read<v_rd_off(D0, 3, 0)>(vb), h3 = tr_read<v_rd_off(D0, 3, 1)>(vb);
;   asm volatile("s_waitcnt lgkmcnt(0)" ::: "memory"); SBAR();
;     ...
;   od = __builtin_amdgcn_mfma_f32_32x32x16_bf16(pa0, PK(l0, h0), od, 0, 0, 0);
;   od = __builtin_amdgcn_mfma_f32_32x32x16_bf16(pa1, PK(l1, h1), od, 0, 0, 0);
;   od = __builtin_amdgcn_mfma_f32_32x32x16_bf16(pa2, PK(l2, h2), od, 0, 0, 0);
;   od = __builtin_amdgcn_mfma_f32_32x32x16_bf16(pa3, PK(l3, h3), od, 0, 0, 0);
;     ...
; }
; __device__ __forceinline__ void pv_d0(f32x16* o, int vb, bf16x8 pa0, bf16x8 pa1, bf16x8 pa2, bf16x8 pa3) {
;   pv_one<0>(o[0], vb, pa0, pa1, pa2, pa3); pv_one<1>(o[1], vb, pa0, pa1, pa2, pa3); pv_one<2>(o[2], vb, pa0, pa1, pa2, pa3); pv_one<3>(o[3], vb, pa0, pa1, pa2, pa3);
; template <int DLO, int DHI>
; __device__ __forceinline__ void attn_dense_body(const int g_wave, const bf16* __restrict__ Qb, const bf16* __restrict__ Kh, const bf16* __restrict__ Vh,
;                                                 bf16* __restrict__ Ob, int ldo, char* lds) {
;     ...
;     pv_d0(o, vb0, pa0, pa1, pa2, pa3); partialSM(pB0, pB1, m_reg, mnB, alB);
;     __syncthreads(); SWAIT(); SWRITE(0, SE);
;     RESC(alB); __syncthreads();
	v_mfma_f32_32x32x16_bf16 v[50:65], v[146:149], v[210:213], v[50:65]
	ds_read_b64_tr_b16 v[210:211], v176 offset:0x400
	ds_read_b64_tr_b16 v[212:213], v176 offset:0xc00
	s_waitcnt lgkmcnt(6)
	v_mfma_f32_32x32x16_bf16 v[50:65], v[156:159], v[214:217], v[50:65]
	ds_read_b64_tr_b16 v[214:215], v176 offset:0x1400
	ds_read_b64_tr_b16 v[216:217], v176 offset:0x1c00
	s_waitcnt lgkmcnt(6)
	v_mfma_f32_32x32x16_bf16 v[50:65], v[152:155], v[218:221], v[50:65]
	ds_read_b64_tr_b16 v[218:219], v176 offset:0x2400
	ds_read_b64_tr_b16 v[220:221], v176 offset:0x2c00
	s_waitcnt lgkmcnt(6)
	v_mfma_f32_32x32x16_bf16 v[50:65], v[186:189], v[222:225], v[50:65]
	ds_read_b64_tr_b16 v[222:223], v176 offset:0x3400
	ds_read_b64_tr_b16 v[224:225], v176 offset:0x3c00
	s_waitcnt lgkmcnt(6)
	v_mfma_f32_32x32x16_bf16 v[34:49], v[146:149], v[210:213], v[34:49]
	ds_read_b64_tr_b16 v[210:211], v176 offset:0x600
	ds_read_b64_tr_b16 v[212:213], v176 offset:0xe00
	s_waitcnt lgkmcnt(6)
	v_mfma_f32_32x32x16_bf16 v[34:49], v[156:159], v[214:217], v[34:49]
	ds_read_b64_tr_b16 v[214:215], v176 offset:0x1600
	ds_read_b64_tr_b16 v[216:217], v176 offset:0x1e00
	s_waitcnt lgkmcnt(6)
	v_mfma_f32_32x32x16_bf16 v[34:49], v[152:155], v[218:221], v[34:49]
	ds_read_b64_tr_b16 v[218:219], v176 offset:0x2600
	ds_read_b64_tr_b16 v[220:221], v176 offset:0x2e00
	s_waitcnt lgkmcnt(6)
	v_mfma_f32_32x32x16_bf16 v[34:49], v[186:189], v[222:225], v[34:49]
	ds_read_b64_tr_b16 v[222:223], v176 offset:0x3600
	ds_read_b64_tr_b16 v[224:225], v176 offset:0x3e00
	s_waitcnt lgkmcnt(6)
	v_mfma_f32_32x32x16_bf16 v[18:33], v[146:149], v[210:213], v[18:33]
	v_max_f32_e32 v146, v83, v83
	v_max_f32_e32 v147, v82, v82
	v_max_f32_e32 v146, v147, v146
	v_max3_f32 v146, v146, v84, v85
	v_max3_f32 v146, v146, v86, v87
	v_max3_f32 v146, v146, v88, v89
	v_max3_f32 v146, v146, v90, v91
	v_max3_f32 v146, v146, v92, v93
	v_max3_f32 v146, v146, v94, v95
	s_waitcnt lgkmcnt(4)
	v_mfma_f32_32x32x16_bf16 v[18:33], v[156:159], v[214:217], v[18:33]
	v_max3_f32 v146, v146, v96, v97
	v_max3_f32 v146, v146, v66, v67
	v_max3_f32 v146, v146, v68, v69
	v_max3_f32 v146, v146, v70, v71
	v_max3_f32 v146, v146, v72, v73
	v_max3_f32 v146, v146, v74, v75
	v_max3_f32 v146, v146, v76, v77
	v_max3_f32 v146, v146, v78, v79
	s_waitcnt lgkmcnt(2)
	v_mfma_f32_32x32x16_bf16 v[18:33], v[152:155], v[218:221], v[18:33]
	v_max3_f32 v146, v146, v80, v81
	v_mov_b32_e32 v147, v146
	s_nop 1
	v_permlane32_swap_b32_e32 v146, v147
	v_max_f32_e32 v147, v147, v147
	v_max_f32_e32 v146, v146, v146
	v_max_f32_e32 v146, v146, v147
	v_sub_f32_e32 v147, v146, v150
	v_cmp_ge_f32_e32 vcc, s63, v147
	v_max_f32_e32 v147, v150, v150
	v_max_f32_e32 v146, v147, v146
	s_waitcnt lgkmcnt(0)
	v_mfma_f32_32x32x16_bf16 v[18:33], v[186:189], v[222:225], v[18:33]
	v_sub_f32_e32 v147, v150, v146
	v_mul_f32_e32 v147, 0x3e0293ee, v147
	v_exp_f32_e32 v147, v147
	s_cmp_eq_u64 vcc, exec
	s_cselect_b64 s[8:9], -1, 0
	s_waitcnt vmcnt(4)
	v_cndmask_b32_e64 v209, v147, 1.0, s[8:9]
	v_cmp_gt_f32_e32 vcc, 1.0, v209
	s_cbranch_vccz .LBB0_1026
	s_and_saveexec_b64 s[2:3], s[6:7]
	ds_write_b32 v173, v209 offset:128
	s_or_b64 exec, exec, s[2:3]
	s_waitcnt lgkmcnt(0)
	v_add_u32_e32 v147, s15, v172
	ds_read_b128 v[152:155], v147 offset:224
	ds_read_b128 v[156:159], v147 offset:192
	ds_read_b128 v[186:189], v147 offset:160
	ds_read_b128 v[210:213], v147 offset:128
	s_waitcnt lgkmcnt(3)
	v_pk_mul_f32 v[14:15], v[14:15], v[152:153]
	s_waitcnt lgkmcnt(2)
	v_pk_mul_f32 v[10:11], v[10:11], v[156:157]
	s_waitcnt lgkmcnt(1)
	v_pk_mul_f32 v[6:7], v[6:7], v[186:187]
	v_pk_mul_f32 v[16:17], v[16:17], v[154:155]
	v_pk_mul_f32 v[12:13], v[12:13], v[158:159]
	v_pk_mul_f32 v[8:9], v[8:9], v[188:189]
	s_waitcnt lgkmcnt(0)
	v_pk_mul_f32 v[4:5], v[4:5], v[212:213]
	v_pk_mul_f32 v[2:3], v[2:3], v[210:211]
	v_pk_mul_f32 v[62:63], v[62:63], v[152:153]
	v_pk_mul_f32 v[58:59], v[58:59], v[156:157]
	v_pk_mul_f32 v[54:55], v[54:55], v[186:187]
	v_pk_mul_f32 v[64:65], v[64:65], v[154:155]
	v_pk_mul_f32 v[60:61], v[60:61], v[158:159]
	v_pk_mul_f32 v[56:57], v[56:57], v[188:189]
	v_pk_mul_f32 v[52:53], v[52:53], v[212:213]
	v_pk_mul_f32 v[50:51], v[50:51], v[210:211]
	v_pk_mul_f32 v[46:47], v[46:47], v[152:153]
	v_pk_mul_f32 v[42:43], v[42:43], v[156:157]
	v_pk_mul_f32 v[38:39], v[38:39], v[186:187]
	v_pk_mul_f32 v[48:49], v[48:49], v[154:155]
	v_pk_mul_f32 v[44:45], v[44:45], v[158:159]
	v_pk_mul_f32 v[40:41], v[40:41], v[188:189]
	v_pk_mul_f32 v[36:37], v[36:37], v[212:213]
	v_pk_mul_f32 v[34:35], v[34:35], v[210:211]
	v_pk_mul_f32 v[30:31], v[30:31], v[152:153]
	v_pk_mul_f32 v[26:27], v[26:27], v[156:157]
	v_pk_mul_f32 v[22:23], v[22:23], v[186:187]
	v_pk_mul_f32 v[32:33], v[32:33], v[154:155]
	v_pk_mul_f32 v[28:29], v[28:29], v[158:159]
	v_pk_mul_f32 v[24:25], v[24:25], v[188:189]
	v_pk_mul_f32 v[20:21], v[20:21], v[212:213]
	v_pk_mul_f32 v[18:19], v[18:19], v[210:211]
; #define SBAR() __builtin_amdgcn_sched_barrier(0)
; #define SLOAD(i, k0) do { sr_[i].vs0 = ld8(&Vh[(long)((k0) + sr) * LDV + sc]); sr_[i].vs1 = ld8(&Vh[(long)((k0) + 32 + sr) * LDV + sc]); \
;     sr_[i].ks0 = ld8(&Kh[(long)((k0) + sr) * LDK + sc]); sr_[i].ks1 = ld8(&Kh[(long)((k0) + 32 + sr) * LDK + sc]); } while (0)
; __device__ __forceinline__ void finishSM(f32x16& p0, f32x16& p1, float alpha, float& l_reg, bf16x8& pa0, bf16x8& pa1, bf16x8& pa2, bf16x8& pa3) {
; #pragma unroll
;   for (int r = 0; r < 16; ++r) p1[r] = __builtin_amdgcn_exp2f(p1[r]);
;   float ps = 0;
; #pragma unroll
;   for (int r = 0; r < 16; ++r) ps += p0[r];
; #pragma unroll
;   for (int r = 0; r < 16; ++r) ps += p1[r];
;   { auto rr = __builtin_amdgcn_permlane32_swap(__float_as_uint(ps), __float_as_uint(ps), false, false);
;     ps = __uint_as_float(rr[0]) + __uint_as_float(rr[1]); }
;   l_reg = l_reg * alpha + ps;
;   PK4(p0, 0, pa0); PK4(p0, 8, pa1); PK4(p1, 0, pa2); PK4(p1, 8, pa3);
; }
; template <int DLO, int DHI>
; __device__ __forceinline__ void attn_dense_body(const int g_wave, const bf16* __restrict__ Qb, const bf16* __restrict__ Kh, const bf16* __restrict__ Vh,
;                                                 bf16* __restrict__ Ob, int ldo, char* lds) {
;     ...
;     SBAR(); qkt<DLO, DHI>(pA0, pA1, K_lds, qr, r32, hi);
;     finishSM(pB0, pB1, alB, l_reg, pa0, pa1, pa2, pa3); SBAR();
;     if (j + 3 < NT) SLOAD(SE, (j + 3) * KVBLK); SBAR();
;     pv_d0(o, vb0 + (int)SHM_V, pa0, pa1, pa2, pa3); partialSM(pA0, pA1, m_reg, mnA, alA);
.LBB0_1026:
	v_cndmask_b32_e64 v210, v146, v150, s[8:9]
	v_mul_f32_e32 v211, 0xbe0293ee, v210
	v_fmamk_f32 v82, v82, 0x3e0293ee, v211
	v_fmamk_f32 v83, v83, 0x3e0293ee, v211
	v_fmamk_f32 v84, v84, 0x3e0293ee, v211
	v_fmamk_f32 v85, v85, 0x3e0293ee, v211
	v_fmamk_f32 v86, v86, 0x3e0293ee, v211
	v_fmamk_f32 v87, v87, 0x3e0293ee, v211
	v_fmamk_f32 v88, v88, 0x3e0293ee, v211
	v_fmamk_f32 v89, v89, 0x3e0293ee, v211
	v_fmamk_f32 v90, v90, 0x3e0293ee, v211
	v_fmamk_f32 v91, v91, 0x3e0293ee, v211
	v_fmamk_f32 v92, v92, 0x3e0293ee, v211
	v_fmamk_f32 v93, v93, 0x3e0293ee, v211
	v_fmamk_f32 v94, v94, 0x3e0293ee, v211
	v_fmamk_f32 v95, v95, 0x3e0293ee, v211
	v_fmamk_f32 v96, v96, 0x3e0293ee, v211
	v_fmamk_f32 v97, v97, 0x3e0293ee, v211
	v_exp_f32_e32 v146, v82
	v_exp_f32_e32 v161, v83
	v_exp_f32_e32 v147, v84
	v_exp_f32_e32 v160, v85
	v_exp_f32_e32 v148, v86
	v_exp_f32_e32 v159, v87
	v_exp_f32_e32 v149, v88
	v_exp_f32_e32 v158, v89
	v_exp_f32_e32 v150, v90
	v_exp_f32_e32 v157, v91
	v_exp_f32_e32 v151, v92
	v_exp_f32_e32 v156, v93
	v_exp_f32_e32 v152, v94
	v_exp_f32_e32 v155, v95
	v_exp_f32_e32 v153, v96
	v_exp_f32_e32 v154, v97
	v_fmamk_f32 v220, v66, 0x3e0293ee, v211
	v_fmamk_f32 v221, v67, 0x3e0293ee, v211
	v_fmamk_f32 v222, v68, 0x3e0293ee, v211
	v_fmamk_f32 v223, v69, 0x3e0293ee, v211
	v_fmamk_f32 v224, v70, 0x3e0293ee, v211
	v_fmamk_f32 v213, v71, 0x3e0293ee, v211
	v_fmamk_f32 v214, v72, 0x3e0293ee, v211
	v_fmamk_f32 v215, v73, 0x3e0293ee, v211
	v_fmamk_f32 v216, v74, 0x3e0293ee, v211
	v_fmamk_f32 v217, v75, 0x3e0293ee, v211
	v_fmamk_f32 v218, v76, 0x3e0293ee, v211
	v_fmamk_f32 v219, v77, 0x3e0293ee, v211
	v_fmamk_f32 v212, v78, 0x3e0293ee, v211
	v_fmamk_f32 v225, v79, 0x3e0293ee, v211
	v_fmamk_f32 v226, v80, 0x3e0293ee, v211
	v_fmac_f32_e32 v211, 0x3e0293ee, v81
	s_waitcnt lgkmcnt(0)
	s_barrier
	v_xor_b32_e32 v177, 0x10000, v177
	v_xor_b32_e32 v194, 0x10000, v194
	v_xor_b32_e32 v195, 0x10000, v195
	v_xor_b32_e32 v196, 0x10000, v196
	ds_read_b128 v[66:69], v177 offset:32768
	ds_read_b128 v[70:73], v177 offset:40960
	ds_read_b128 v[186:189], v194 offset:32768
	ds_read_b128 v[228:231], v194 offset:40960
	v_exp_f32_e32 v213, v213
	v_exp_f32_e32 v214, v214
	s_waitcnt lgkmcnt(3)
	v_mfma_f32_32x32x16_bf16 v[82:97], v[66:69], v[102:105], 0
	v_exp_f32_e32 v215, v215
	v_exp_f32_e32 v216, v216
	v_exp_f32_e32 v217, v217
	v_exp_f32_e32 v218, v218
	v_exp_f32_e32 v219, v219
	s_waitcnt lgkmcnt(2)
	v_mfma_f32_32x32x16_bf16 v[66:81], v[70:73], v[102:105], 0
	s_waitcnt lgkmcnt(1)
	v_mfma_f32_32x32x16_bf16 v[82:97], v[186:189], v[98:101], v[82:97]
	s_waitcnt lgkmcnt(0)
	v_mfma_f32_32x32x16_bf16 v[66:81], v[228:231], v[98:101], v[66:81]
	ds_read_b128 v[186:189], v195 offset:32768
	ds_read_b128 v[228:231], v195 offset:40960
	s_waitcnt lgkmcnt(1)
	v_mfma_f32_32x32x16_bf16 v[82:97], v[186:189], v[106:109], v[82:97]
	s_waitcnt lgkmcnt(0)
	v_mfma_f32_32x32x16_bf16 v[66:81], v[228:231], v[106:109], v[66:81]
	ds_read_b128 v[186:189], v196 offset:32768
	ds_read_b128 v[228:231], v196 offset:40960
	s_waitcnt lgkmcnt(1)
	v_mfma_f32_32x32x16_bf16 v[82:97], v[186:189], v[110:113], v[82:97]
	v_exp_f32_e32 v186, v220
	v_exp_f32_e32 v220, v224
	v_exp_f32_e32 v224, v211
	v_add_f32_e32 v211, 0, v146
	v_add_f32_e32 v211, v161, v211
	v_add_f32_e32 v211, v147, v211
	v_add_f32_e32 v211, v160, v211
	v_add_f32_e32 v211, v148, v211
	v_add_f32_e32 v211, v159, v211
	v_add_f32_e32 v211, v149, v211
	v_add_f32_e32 v211, v158, v211
	v_add_f32_e32 v211, v150, v211
	v_add_f32_e32 v211, v157, v211
	v_add_f32_e32 v211, v151, v211
	v_add_f32_e32 v211, v156, v211
	v_add_f32_e32 v211, v152, v211
	v_exp_f32_e32 v187, v221
	v_add_f32_e32 v211, v155, v211
	v_exp_f32_e32 v188, v222
	v_add_f32_e32 v211, v153, v211
	v_exp_f32_e32 v189, v223
	v_add_f32_e32 v211, v154, v211
	v_add_f32_e32 v211, v186, v211
	v_add_f32_e32 v211, v187, v211
	v_add_f32_e32 v211, v188, v211
	v_add_f32_e32 v211, v189, v211
	v_add_f32_e32 v211, v220, v211
	v_add_f32_e32 v211, v213, v211
	v_add_f32_e32 v211, v214, v211
	v_add_f32_e32 v211, v215, v211
	v_exp_f32_e32 v221, v212
	v_add_f32_e32 v211, v216, v211
	v_exp_f32_e32 v222, v225
	v_add_f32_e32 v211, v217, v211
	s_waitcnt lgkmcnt(0)
	v_mfma_f32_32x32x16_bf16 v[66:81], v[228:231], v[110:113], v[66:81]
	v_exp_f32_e32 v223, v226
	v_add_f32_e32 v211, v218, v211
	v_add_f32_e32 v211, v219, v211
	v_add_f32_e32 v211, v221, v211
	v_add_f32_e32 v211, v222, v211
	v_add_f32_e32 v211, v223, v211
	v_add_f32_e32 v211, v224, v211
	v_mov_b32_e32 v212, v211
	v_cvt_pk_bf16_f32 v146, v146, v161
	v_cvt_pk_bf16_f32 v147, v147, v160
	v_cvt_pk_bf16_f32 v148, v148, v159
	v_cvt_pk_bf16_f32 v149, v149, v158
	v_cvt_pk_bf16_f32 v150, v150, v157
	v_cvt_pk_bf16_f32 v151, v151, v156
	v_cvt_pk_bf16_f32 v152, v152, v155
	v_cvt_pk_bf16_f32 v153, v153, v154
	v_cvt_pk_bf16_f32 v154, v186, v187
	v_cvt_pk_bf16_f32 v155, v188, v189
	v_cvt_pk_bf16_f32 v156, v220, v213
	v_cvt_pk_bf16_f32 v157, v214, v215
	v_cvt_pk_bf16_f32 v158, v216, v217
	v_cvt_pk_bf16_f32 v159, v218, v219
	v_cvt_pk_bf16_f32 v160, v221, v222
	v_cvt_pk_bf16_f32 v161, v223, v224
	s_nop 1
	v_permlane32_swap_b32_e32 v211, v212
	v_permlane32_swap_b32_e32 v146, v148
	v_permlane32_swap_b32_e32 v147, v149
	v_permlane32_swap_b32_e32 v150, v152
	v_permlane32_swap_b32_e32 v151, v153
	v_permlane32_swap_b32_e32 v154, v156
	v_permlane32_swap_b32_e32 v155, v157
	v_permlane32_swap_b32_e32 v158, v160
	v_permlane32_swap_b32_e32 v159, v161
	s_waitcnt vmcnt(0)
	ds_write_b128 v192, v[130:133] offset:16384
	ds_write_b128 v193, v[134:137] offset:16384
	ds_write_b128 v190, v[138:141] offset:49152
	ds_write_b128 v191, v[142:145] offset:49152
	s_cmp_gt_u32 s34, 60
	s_cselect_b64 s[2:3], -1, 0
	s_and_b64 vcc, exec, s[2:3]
	s_cbranch_vccnz .LBB0_1028
	v_add_co_u32_e32 v114, vcc, 0x19040000, v168
	s_nop 1
	v_addc_co_u32_e32 v115, vcc, 0, v169, vcc
	v_add_co_u32_e32 v118, vcc, 0x19088000, v168
	s_nop 1
	v_addc_co_u32_e32 v119, vcc, 0, v169, vcc
	v_add_co_u32_e32 v122, vcc, 0x1f660000, v166
	global_load_dwordx4 v[114:117], v[114:115], off
	s_nop 0
	global_load_dwordx4 v[118:121], v[118:119], off
	v_addc_co_u32_e32 v123, vcc, 0, v167, vcc
	v_add_co_u32_e32 v126, vcc, 0x1f66c000, v166
	s_nop 1
	v_addc_co_u32_e32 v127, vcc, 0, v167, vcc
	global_load_dwordx4 v[122:125], v[122:123], off
	s_nop 0
	global_load_dwordx4 v[126:129], v[126:127], off

; #define SBAR() __builtin_amdgcn_sched_barrier(0)
; #define SWRITE(b, i) do { *(bf16x8*)((char*)V_lds + (b) * SHM_V + vst0) = sr_[i].vs0;          \
;     *(bf16x8*)((char*)V_lds + (b) * SHM_V + vst1) = sr_[i].vs1; int kc = sc * 2;               \
;     *(bf16x8*)((char*)K_lds + (b) * SHM_K + KSWZ(sr, kc)) = sr_[i].ks0;                       \
;     *(bf16x8*)((char*)K_lds + (b) * SHM_K + KSWZ(32 + sr, kc)) = sr_[i].ks1; } while (0)
; #define SWAIT() asm volatile("s_waitcnt vmcnt(4)" ::: "memory")
; #define RESC(a) do { if (__any((a) < 1.f)) { if (hi == 0) al_l[r32] = (a); asm volatile("s_waitcnt lgkmcnt(0)" ::: "memory"); \
;     _Pragma("unroll") for (int d = 0; d < 4; ++d) _Pragma("unroll") for (int r = 0; r < 16; ++r) o[d][r] *= al_l[crow(r, hi)]; } } while (0)
; template <int DLO, int DHI>
; __device__ __forceinline__ void attn_dense_body(const int g_wave, const bf16* __restrict__ Qb, const bf16* __restrict__ Kh, const bf16* __restrict__ Vh,
;                                                 bf16* __restrict__ Ob, int ldo, char* lds) {
;     ...
;     pv_d0(o, vb0 + (int)SHM_V, pa0, pa1, pa2, pa3); partialSM(pA0, pA1, m_reg, mnA, alA);
;     __syncthreads(); SWAIT(); SWRITE(1, SO);
;     RESC(alA); __syncthreads();
;   }
;   SBAR(); qkt<DLO, DHI>(pB0, pB1, (bf16*)((char*)K_lds + SHM_K), qr, r32, hi);
;   finishSM(pA0, pA1, alA, l_reg, pa0, pa1, pa2, pa3); SBAR();
;   pv_d0(o, vb0, pa0, pa1, pa2, pa3); partialSM(pB0, pB1, m_reg, mnB, alB);
.LBB0_1032:
	v_cndmask_b32_e64 v150, v147, v210, s[8:9]
	v_mul_f32_e32 v136, 0xbe0293ee, v150
	v_mov_b32_e32 v137, v136
	v_fmamk_f32 v82, v82, 0x3e0293ee, v136
	v_fmamk_f32 v83, v83, 0x3e0293ee, v136
	v_fmamk_f32 v84, v84, 0x3e0293ee, v136
	v_fmamk_f32 v85, v85, 0x3e0293ee, v136
	v_fmamk_f32 v86, v86, 0x3e0293ee, v136
	v_fmamk_f32 v87, v87, 0x3e0293ee, v136
	v_fmamk_f32 v88, v88, 0x3e0293ee, v136
	v_fmamk_f32 v89, v89, 0x3e0293ee, v136
	v_fmamk_f32 v90, v90, 0x3e0293ee, v136
	v_fmamk_f32 v91, v91, 0x3e0293ee, v136
	v_fmamk_f32 v92, v92, 0x3e0293ee, v136
	v_fmamk_f32 v93, v93, 0x3e0293ee, v136
	v_fmamk_f32 v94, v94, 0x3e0293ee, v136
	v_fmamk_f32 v95, v95, 0x3e0293ee, v136
	v_fmamk_f32 v96, v96, 0x3e0293ee, v136
	v_fmac_f32_e32 v137, 0x3e0293ee, v97
	v_exp_f32_e32 v161, v82
	v_exp_f32_e32 v167, v83
	v_exp_f32_e32 v147, v84
	v_exp_f32_e32 v166, v85
	v_exp_f32_e32 v148, v86
	v_exp_f32_e32 v160, v87
	v_exp_f32_e32 v149, v88
	v_exp_f32_e32 v159, v89
	v_exp_f32_e32 v156, v90
	v_exp_f32_e32 v158, v91
	v_exp_f32_e32 v154, v92
	v_exp_f32_e32 v157, v93
	v_exp_f32_e32 v152, v94
	v_exp_f32_e32 v155, v95
	v_exp_f32_e32 v151, v96
	v_exp_f32_e32 v153, v137
	v_pk_fma_f32 v[142:143], v[66:67], s[62:63], v[136:137] op_sel_hi:[1,0,0]
	v_add_f32_e32 v66, v207, v208
	s_mov_b64 s[4:5], 0x30000
	v_fmac_f32_e32 v66, v197, v174
	v_add_f32_e32 v174, v211, v212
	v_lshl_add_u64 v[162:163], v[162:163], 0, s[4:5]
	s_mov_b64 s[4:5], 0x120000
	v_pk_fma_f32 v[140:141], v[68:69], s[62:63], v[136:137] op_sel_hi:[1,0,0]
	v_pk_fma_f32 v[134:135], v[70:71], s[62:63], v[136:137] op_sel_hi:[1,0,0]
	v_pk_fma_f32 v[132:133], v[72:73], s[62:63], v[136:137] op_sel_hi:[1,0,0]
	v_pk_fma_f32 v[130:131], v[74:75], s[62:63], v[136:137] op_sel_hi:[1,0,0]
	v_pk_fma_f32 v[144:145], v[76:77], s[62:63], v[136:137] op_sel_hi:[1,0,0]
	v_pk_fma_f32 v[138:139], v[78:79], s[62:63], v[136:137] op_sel_hi:[1,0,0]
	v_pk_fma_f32 v[136:137], v[80:81], s[62:63], v[136:137] op_sel_hi:[1,0,0]
	v_fmac_f32_e32 v174, v66, v209
	s_add_i32 s34, s34, 2
	v_lshl_add_u64 v[164:165], v[164:165], 0, s[4:5]
	s_and_b64 vcc, exec, s[2:3]
	s_waitcnt lgkmcnt(0)
	s_barrier
	v_xor_b32_e32 v176, 0x10000, v176
	v_xor_b32_e32 v175, 0x10000, v175
	v_xor_b32_e32 v192, 0x10000, v192
	v_xor_b32_e32 v193, 0x10000, v193
	v_xor_b32_e32 v190, 0x10000, v190
	v_xor_b32_e32 v191, 0x10000, v191
	s_cbranch_vccnz .LBB0_1034
	v_mov_b32_e32 v197, v146
	s_branch .LBB0_1022
.LBB0_1034:
	ds_read_b128 v[66:69], v177 offset:49152
	ds_read_b128 v[70:73], v177 offset:57344
	v_add_f32_e32 v0, 0, v161
	v_add_f32_e32 v0, v167, v0
	v_add_f32_e32 v0, v147, v0
	s_waitcnt lgkmcnt(1)
	v_mfma_f32_32x32x16_bf16 v[82:97], v[66:69], v[102:105], 0
	v_add_f32_e32 v0, v166, v0
	v_add_f32_e32 v0, v148, v0
	v_add_f32_e32 v0, v160, v0
	v_add_f32_e32 v0, v149, v0
	v_add_f32_e32 v0, v159, v0
	v_add_f32_e32 v0, v156, v0
	v_add_f32_e32 v0, v158, v0
	s_waitcnt lgkmcnt(0)
	v_mfma_f32_32x32x16_bf16 v[66:81], v[70:73], v[102:105], 0
	ds_read_b128 v[102:105], v194 offset:49152
	ds_read_b128 v[114:117], v194 offset:57344
	v_add_f32_e32 v0, v154, v0
	v_add_f32_e32 v0, v157, v0
	v_add_f32_e32 v0, v152, v0
	v_add_f32_e32 v0, v155, v0
	v_add_f32_e32 v0, v151, v0
	v_add_f32_e32 v0, v153, v0
	s_waitcnt lgkmcnt(1)
	v_mfma_f32_32x32x16_bf16 v[82:97], v[102:105], v[98:101], v[82:97]
	v_exp_f32_e32 v118, v145
	v_exp_f32_e32 v119, v138
	v_exp_f32_e32 v120, v139
	v_exp_f32_e32 v121, v136
	v_exp_f32_e32 v122, v137
	s_waitcnt lgkmcnt(0)
	v_mfma_f32_32x32x16_bf16 v[66:81], v[114:117], v[98:101], v[66:81]
	ds_read_b128 v[98:101], v195 offset:49152
	ds_read_b128 v[102:105], v195 offset:57344
	v_exp_f32_e32 v114, v133
	v_exp_f32_e32 v115, v130
	v_exp_f32_e32 v116, v131
	v_exp_f32_e32 v117, v144
	s_waitcnt lgkmcnt(1)
	v_mfma_f32_32x32x16_bf16 v[82:97], v[98:101], v[106:109], v[82:97]
	s_waitcnt lgkmcnt(0)
	v_mfma_f32_32x32x16_bf16 v[66:81], v[102:105], v[106:109], v[66:81]
	ds_read_b128 v[98:101], v196 offset:49152
	ds_read_b128 v[102:105], v196 offset:57344
	v_exp_f32_e32 v108, v143
	v_exp_f32_e32 v109, v140
	s_waitcnt lgkmcnt(1)
	v_mfma_f32_32x32x16_bf16 v[82:97], v[98:101], v[110:113], v[82:97]
	v_exp_f32_e32 v99, v142
	v_cvt_pk_bf16_f32 v100, v161, v167
	v_cvt_pk_bf16_f32 v101, v147, v166
	s_nop 0
	v_add_f32_e32 v0, v99, v0
	v_add_f32_e32 v0, v108, v0
	v_add_f32_e32 v0, v109, v0
	s_waitcnt lgkmcnt(0)
	v_mfma_f32_32x32x16_bf16 v[66:81], v[102:105], v[110:113], v[66:81]
	v_exp_f32_e32 v110, v141
	v_exp_f32_e32 v111, v134
	v_exp_f32_e32 v112, v135
	v_exp_f32_e32 v113, v132
	v_add_f32_e32 v0, v110, v0
	v_add_f32_e32 v0, v111, v0
	v_add_f32_e32 v0, v112, v0
	v_add_f32_e32 v0, v113, v0
	v_add_f32_e32 v0, v114, v0
	v_add_f32_e32 v0, v115, v0
	v_add_f32_e32 v0, v116, v0
	v_add_f32_e32 v0, v117, v0
	v_add_f32_e32 v0, v118, v0
	v_add_f32_e32 v0, v119, v0
	v_add_f32_e32 v0, v120, v0
	v_add_f32_e32 v0, v121, v0
	v_add_f32_e32 v0, v122, v0
	v_mov_b32_e32 v98, v0
	v_cvt_pk_bf16_f32 v102, v148, v160
	s_nop 1
	v_permlane32_swap_b32_e32 v0, v98
	v_cvt_pk_bf16_f32 v103, v149, v159
	v_permlane32_swap_b32_e32 v100, v102
	v_cvt_pk_bf16_f32 v104, v156, v158
	v_cvt_pk_bf16_f32 v105, v154, v157
	v_cvt_pk_bf16_f32 v106, v152, v155
	v_cvt_pk_bf16_f32 v107, v151, v153
	v_cvt_pk_bf16_f32 v108, v99, v108
	v_cvt_pk_bf16_f32 v109, v109, v110
	v_cvt_pk_bf16_f32 v110, v111, v112
	v_cvt_pk_bf16_f32 v111, v113, v114
	v_cvt_pk_bf16_f32 v112, v115, v116
	v_cvt_pk_bf16_f32 v113, v117, v118
	v_cvt_pk_bf16_f32 v114, v119, v120
	v_cvt_pk_bf16_f32 v115, v121, v122
	v_permlane32_swap_b32_e32 v101, v103
	v_permlane32_swap_b32_e32 v104, v106
	v_permlane32_swap_b32_e32 v105, v107
	v_permlane32_swap_b32_e32 v108, v110
	v_permlane32_swap_b32_e32 v109, v111
	v_permlane32_swap_b32_e32 v112, v114
	v_permlane32_swap_b32_e32 v113, v115
	ds_read_b64_tr_b16 v[116:117], v176 offset:0
	ds_read_b64_tr_b16 v[118:119], v176 offset:0x800
	ds_read_b64_tr_b16 v[120:121], v176 offset:0x1000
	ds_read_b64_tr_b16 v[122:123], v176 offset:0x1800
	ds_read_b64_tr_b16 v[124:125], v176 offset:0x2000
	ds_read_b64_tr_b16 v[126:127], v176 offset:0x2800
	ds_read_b64_tr_b16 v[128:129], v176 offset:0x3000
	ds_read_b64_tr_b16 v[130:131], v176 offset:0x3800
	s_waitcnt lgkmcnt(6)
; #define SBAR() __builtin_amdgcn_sched_barrier(0)
; #define RESC(a) do { if (__any((a) < 1.f)) { if (hi == 0) al_l[r32] = (a); asm volatile("s_waitcnt lgkmcnt(0)" ::: "memory"); \
;     _Pragma("unroll") for (int d = 0; d < 4; ++d) _Pragma("unroll") for (int r = 0; r < 16; ++r) o[d][r] *= al_l[crow(r, hi)]; } } while (0)
; template <int D0> __device__ __forceinline__ void pv_one(f32x16& od, int vb, bf16x8 pa0, bf16x8 pa1, bf16x8 pa2, bf16x8 pa3) {
;   const s16x4 l0 = tr_read<v_rd_off(D0, 0, 0)>(vb), h0 = tr_read<v_rd_off(D0, 0, 1)>(vb), l1 = tr_read<v_rd_off(D0, 1, 0)>(vb), h1 = tr_read<v_rd_off(D0, 1, 1)>(vb);
;   const s16x4 l2 = tr_read<v_rd_off(D0, 2, 0)>(vb), h2 = tr_read<v_rd_off(D0, 2, 1)>(vb), l3 = tr_read<v_rd_off(D0, 3, 0)>(vb), h3 = tr_read<v_rd_off(D0, 3, 1)>(vb);
;   asm volatile("s_waitcnt lgkmcnt(0)" ::: "memory"); SBAR();
;     ...
;   od = __builtin_amdgcn_mfma_f32_32x32x16_bf16(pa0, PK(l0, h0), od, 0, 0, 0);
;   od = __builtin_amdgcn_mfma_f32_32x32x16_bf16(pa1, PK(l1, h1), od, 0, 0, 0);
;   od = __builtin_amdgcn_mfma_f32_32x32x16_bf16(pa2, PK(l2, h2), od, 0, 0, 0);
;   od = __builtin_amdgcn_mfma_f32_32x32x16_bf16(pa3, PK(l3, h3), od, 0, 0, 0);
;     ...
; }
; __device__ __forceinline__ void pv_d0(f32x16* o, int vb, bf16x8 pa0, bf16x8 pa1, bf16x8 pa2, bf16x8 pa3) {
;   pv_one<0>(o[0], vb, pa0, pa1, pa2, pa3); pv_one<1>(o[1], vb, pa0, pa1, pa2, pa3); pv_one<2>(o[2], vb, pa0, pa1, pa2, pa3); pv_one<3>(o[3], vb, pa0, pa1, pa2, pa3);
; template <int DLO, int DHI>
; __device__ __forceinline__ void attn_dense_body(const int g_wave, const bf16* __restrict__ Qb, const bf16* __restrict__ Kh, const bf16* __restrict__ Vh,
;                                                 bf16* __restrict__ Ob, int ldo, char* lds) {
;     ...
;   pv_d0(o, vb0, pa0, pa1, pa2, pa3); partialSM(pB0, pB1, m_reg, mnB, alB);
;   __syncthreads(); RESC(alB);
	s_nop 0
	v_mfma_f32_32x32x16_bf16 v[2:17], v[100:103], v[116:119], v[2:17]
	ds_read_b64_tr_b16 v[116:117], v176 offset:0x200
	ds_read_b64_tr_b16 v[118:119], v176 offset:0xa00
	s_waitcnt lgkmcnt(6)
	v_mfma_f32_32x32x16_bf16 v[2:17], v[104:107], v[120:123], v[2:17]
	ds_read_b64_tr_b16 v[120:121], v176 offset:0x1200
	ds_read_b64_tr_b16 v[122:123], v176 offset:0x1a00
	s_waitcnt lgkmcnt(6)
	v_mfma_f32_32x32x16_bf16 v[2:17], v[108:111], v[124:127], v[2:17]
	ds_read_b64_tr_b16 v[124:125], v176 offset:0x2200
	ds_read_b64_tr_b16 v[126:127], v176 offset:0x2a00
	s_waitcnt lgkmcnt(6)
	v_mfma_f32_32x32x16_bf16 v[2:17], v[112:115], v[128:131], v[2:17]
	ds_read_b64_tr_b16 v[128:129], v176 offset:0x3200
	ds_read_b64_tr_b16 v[130:131], v176 offset:0x3a00
	s_waitcnt lgkmcnt(6)
	v_mfma_f32_32x32x16_bf16 v[50:65], v[100:103], v[116:119], v[50:65]
	ds_read_b64_tr_b16 v[116:117], v176 offset:0x400
	ds_read_b64_tr_b16 v[118:119], v176 offset:0xc00
	s_waitcnt lgkmcnt(6)
	v_mfma_f32_32x32x16_bf16 v[50:65], v[104:107], v[120:123], v[50:65]
	ds_read_b64_tr_b16 v[120:121], v176 offset:0x1400
	ds_read_b64_tr_b16 v[122:123], v176 offset:0x1c00
	s_waitcnt lgkmcnt(6)
	v_mfma_f32_32x32x16_bf16 v[50:65], v[108:111], v[124:127], v[50:65]
	ds_read_b64_tr_b16 v[124:125], v176 offset:0x2400
	ds_read_b64_tr_b16 v[126:127], v176 offset:0x2c00
	s_waitcnt lgkmcnt(6)
	v_mfma_f32_32x32x16_bf16 v[50:65], v[112:115], v[128:131], v[50:65]
	ds_read_b64_tr_b16 v[128:129], v176 offset:0x3400
	ds_read_b64_tr_b16 v[130:131], v176 offset:0x3c00
	s_waitcnt lgkmcnt(6)
	v_mfma_f32_32x32x16_bf16 v[34:49], v[100:103], v[116:119], v[34:49]
	ds_read_b64_tr_b16 v[116:117], v176 offset:0x600
	ds_read_b64_tr_b16 v[118:119], v176 offset:0xe00
	s_waitcnt lgkmcnt(6)
	v_mfma_f32_32x32x16_bf16 v[34:49], v[104:107], v[120:123], v[34:49]
	ds_read_b64_tr_b16 v[120:121], v176 offset:0x1600
	ds_read_b64_tr_b16 v[122:123], v176 offset:0x1e00
	s_waitcnt lgkmcnt(6)
	v_mfma_f32_32x32x16_bf16 v[34:49], v[108:111], v[124:127], v[34:49]
	ds_read_b64_tr_b16 v[124:125], v176 offset:0x2600
	ds_read_b64_tr_b16 v[126:127], v176 offset:0x2e00
	s_waitcnt lgkmcnt(6)
	v_mfma_f32_32x32x16_bf16 v[34:49], v[112:115], v[128:131], v[34:49]
	ds_read_b64_tr_b16 v[128:129], v176 offset:0x3600
	ds_read_b64_tr_b16 v[130:131], v176 offset:0x3e00
	s_waitcnt lgkmcnt(6)
	v_mfma_f32_32x32x16_bf16 v[18:33], v[100:103], v[116:119], v[18:33]
	v_max_f32_e32 v99, v83, v83
	v_max_f32_e32 v100, v82, v82
	v_max_f32_e32 v99, v100, v99
	v_max3_f32 v99, v99, v84, v85
	v_max3_f32 v99, v99, v86, v87
	v_max3_f32 v99, v99, v88, v89
	v_max3_f32 v99, v99, v90, v91
	v_max3_f32 v99, v99, v92, v93
	v_max3_f32 v99, v99, v94, v95
	s_waitcnt lgkmcnt(4)
	v_mfma_f32_32x32x16_bf16 v[18:33], v[104:107], v[120:123], v[18:33]
	v_max3_f32 v99, v99, v96, v97
	v_max3_f32 v99, v99, v66, v67
	v_max3_f32 v99, v99, v68, v69
	v_max3_f32 v99, v99, v70, v71
	v_max3_f32 v99, v99, v72, v73
	v_max3_f32 v99, v99, v74, v75
	v_max3_f32 v99, v99, v76, v77
	v_max3_f32 v99, v99, v78, v79
	s_waitcnt lgkmcnt(2)
	v_mfma_f32_32x32x16_bf16 v[18:33], v[108:111], v[124:127], v[18:33]
	v_max3_f32 v99, v99, v80, v81
	v_mov_b32_e32 v100, v99
	s_nop 1
	v_permlane32_swap_b32_e32 v99, v100
	v_max_f32_e32 v100, v100, v100
	v_max_f32_e32 v99, v99, v99
	v_max_f32_e32 v99, v99, v100
	v_sub_f32_e32 v100, v99, v150
	v_cmp_ge_f32_e32 vcc, s63, v100
	v_max_f32_e32 v100, v150, v150
	v_max_f32_e32 v100, v100, v99
	s_waitcnt lgkmcnt(0)
	v_mfma_f32_32x32x16_bf16 v[18:33], v[112:115], v[128:131], v[18:33]
	v_sub_f32_e32 v99, v150, v100
	v_mul_f32_e32 v99, 0x3e0293ee, v99
	v_exp_f32_e32 v99, v99
	s_cmp_eq_u64 vcc, exec
	s_cselect_b64 s[8:9], -1, 0
	v_cndmask_b32_e64 v99, v99, 1.0, s[8:9]
	v_cmp_gt_f32_e32 vcc, 1.0, v99
	s_barrier
	s_cbranch_vccz .LBB0_1038
	s_and_saveexec_b64 s[2:3], s[6:7]
	ds_write_b32 v173, v99 offset:128
	s_or_b64 exec, exec, s[2:3]
	s_waitcnt lgkmcnt(0)
	v_add_u32_e32 v101, s15, v172
	ds_read_b128 v[102:105], v101 offset:224
	ds_read_b128 v[106:109], v101 offset:192
	ds_read_b128 v[110:113], v101 offset:160
	ds_read_b128 v[114:117], v101 offset:128
	s_waitcnt lgkmcnt(3)
	v_pk_mul_f32 v[14:15], v[14:15], v[102:103]
	s_waitcnt lgkmcnt(2)
	v_pk_mul_f32 v[10:11], v[10:11], v[106:107]
	s_waitcnt lgkmcnt(1)
	v_pk_mul_f32 v[6:7], v[6:7], v[110:111]
	v_pk_mul_f32 v[16:17], v[16:17], v[104:105]
	v_pk_mul_f32 v[12:13], v[12:13], v[108:109]
	v_pk_mul_f32 v[8:9], v[8:9], v[112:113]
	s_waitcnt lgkmcnt(0)
	v_pk_mul_f32 v[4:5], v[4:5], v[116:117]
	v_pk_mul_f32 v[2:3], v[2:3], v[114:115]
	v_pk_mul_f32 v[62:63], v[62:63], v[102:103]
	v_pk_mul_f32 v[58:59], v[58:59], v[106:107]
	v_pk_mul_f32 v[54:55], v[54:55], v[110:111]
	v_pk_mul_f32 v[64:65], v[64:65], v[104:105]
	v_pk_mul_f32 v[60:61], v[60:61], v[108:109]
	v_pk_mul_f32 v[56:57], v[56:57], v[112:113]
	v_pk_mul_f32 v[52:53], v[52:53], v[116:117]
	v_pk_mul_f32 v[50:51], v[50:51], v[114:115]
	v_pk_mul_f32 v[46:47], v[46:47], v[102:103]
	v_pk_mul_f32 v[42:43], v[42:43], v[106:107]
	v_pk_mul_f32 v[38:39], v[38:39], v[110:111]
	v_pk_mul_f32 v[48:49], v[48:49], v[104:105]
	v_pk_mul_f32 v[44:45], v[44:45], v[108:109]
	v_pk_mul_f32 v[40:41], v[40:41], v[112:113]
	v_pk_mul_f32 v[36:37], v[36:37], v[116:117]
	v_pk_mul_f32 v[34:35], v[34:35], v[114:115]
	v_pk_mul_f32 v[30:31], v[30:31], v[102:103]
	v_pk_mul_f32 v[26:27], v[26:27], v[106:107]
	v_pk_mul_f32 v[22:23], v[22:23], v[110:111]
	v_pk_mul_f32 v[32:33], v[32:33], v[104:105]
	v_pk_mul_f32 v[28:29], v[28:29], v[108:109]
	v_pk_mul_f32 v[24:25], v[24:25], v[112:113]
	v_pk_mul_f32 v[20:21], v[20:21], v[116:117]
	v_pk_mul_f32 v[18:19], v[18:19], v[114:115]
; #define SBAR() __builtin_amdgcn_sched_barrier(0)
; __device__ __forceinline__ void finishSM(f32x16& p0, f32x16& p1, float alpha, float& l_reg, bf16x8& pa0, bf16x8& pa1, bf16x8& pa2, bf16x8& pa3) {
; #pragma unroll
;   for (int r = 0; r < 16; ++r) p1[r] = __builtin_amdgcn_exp2f(p1[r]);
;   float ps = 0;
; #pragma unroll
;   for (int r = 0; r < 16; ++r) ps += p0[r];
; #pragma unroll
;   for (int r = 0; r < 16; ++r) ps += p1[r];
;   { auto rr = __builtin_amdgcn_permlane32_swap(__float_as_uint(ps), __float_as_uint(ps), false, false);
;     ps = __uint_as_float(rr[0]) + __uint_as_float(rr[1]); }
;   l_reg = l_reg * alpha + ps;
;   PK4(p0, 0, pa0); PK4(p0, 8, pa1); PK4(p1, 0, pa2); PK4(p1, 8, pa3);
; }
; template <int DLO, int DHI>
; __device__ __forceinline__ void attn_dense_body(const int g_wave, const bf16* __restrict__ Qb, const bf16* __restrict__ Kh, const bf16* __restrict__ Vh,
;                                                 bf16* __restrict__ Ob, int ldo, char* lds) {
;     ...
;   finishSM(pB0, pB1, alB, l_reg, pa0, pa1, pa2, pa3); SBAR();
;   pv_d0(o, vb0 + (int)SHM_V, pa0, pa1, pa2, pa3);
.LBB0_1038:
	v_cndmask_b32_e64 v100, v100, v150, s[8:9]
	v_mul_f32_e32 v100, 0xbe0293ee, v100
	v_fmamk_f32 v82, v82, 0x3e0293ee, v100
	v_fmamk_f32 v83, v83, 0x3e0293ee, v100
	v_fmamk_f32 v101, v84, 0x3e0293ee, v100
	v_exp_f32_e32 v84, v82
	v_fmamk_f32 v102, v86, 0x3e0293ee, v100
	v_exp_f32_e32 v86, v83
	v_fmamk_f32 v85, v85, 0x3e0293ee, v100
	v_exp_f32_e32 v82, v101
	v_fmamk_f32 v66, v66, 0x3e0293ee, v100
	v_exp_f32_e32 v85, v85
	v_fmamk_f32 v103, v87, 0x3e0293ee, v100
	v_fmamk_f32 v112, v96, 0x3e0293ee, v100
	v_fmamk_f32 v96, v77, 0x3e0293ee, v100
	v_exp_f32_e32 v77, v102
	v_exp_f32_e32 v101, v66
	v_add_f32_e32 v66, 0, v84
	v_fmamk_f32 v104, v88, 0x3e0293ee, v100
	v_exp_f32_e32 v83, v103
	v_add_f32_e32 v66, v86, v66
	v_fmamk_f32 v105, v89, 0x3e0293ee, v100
	v_fmamk_f32 v111, v95, 0x3e0293ee, v100
	v_fmamk_f32 v95, v76, 0x3e0293ee, v100
	v_exp_f32_e32 v76, v104
	v_add_f32_e32 v66, v82, v66
	v_fmamk_f32 v106, v90, 0x3e0293ee, v100
	v_fmamk_f32 v113, v97, 0x3e0293ee, v100
	v_fmamk_f32 v97, v78, 0x3e0293ee, v100
	v_exp_f32_e32 v78, v105
	v_add_f32_e32 v66, v85, v66
	v_fmamk_f32 v107, v91, 0x3e0293ee, v100
	v_fmamk_f32 v108, v92, 0x3e0293ee, v100
	v_fmamk_f32 v92, v73, 0x3e0293ee, v100
	v_exp_f32_e32 v73, v106
	v_add_f32_e32 v66, v77, v66
	v_fmamk_f32 v110, v94, 0x3e0293ee, v100
	v_fmamk_f32 v94, v75, 0x3e0293ee, v100
	v_exp_f32_e32 v75, v107
	v_add_f32_e32 v66, v83, v66
	v_fmamk_f32 v109, v93, 0x3e0293ee, v100
	v_fmamk_f32 v90, v71, 0x3e0293ee, v100
	v_exp_f32_e32 v71, v108
	v_add_f32_e32 v66, v76, v66
	v_fmamk_f32 v93, v74, 0x3e0293ee, v100
	v_exp_f32_e32 v74, v109
	v_add_f32_e32 v66, v78, v66
	v_fmamk_f32 v88, v69, 0x3e0293ee, v100
	v_exp_f32_e32 v69, v110
	v_add_f32_e32 v66, v73, v66
	v_fmamk_f32 v91, v72, 0x3e0293ee, v100
	v_exp_f32_e32 v72, v111
	v_add_f32_e32 v66, v75, v66
	v_fmamk_f32 v87, v68, 0x3e0293ee, v100
	v_exp_f32_e32 v68, v112
	v_add_f32_e32 v66, v71, v66
	v_fmamk_f32 v89, v70, 0x3e0293ee, v100
	v_exp_f32_e32 v70, v113
	v_add_f32_e32 v66, v74, v66
	v_fmamk_f32 v67, v67, 0x3e0293ee, v100
	v_add_f32_e32 v66, v69, v66
	v_exp_f32_e32 v102, v67
	v_add_f32_e32 v66, v72, v66
	v_exp_f32_e32 v87, v87
	v_add_f32_e32 v66, v68, v66
	v_exp_f32_e32 v88, v88
	v_add_f32_e32 v66, v70, v66
	v_exp_f32_e32 v89, v89
	v_add_f32_e32 v66, v101, v66
	v_exp_f32_e32 v90, v90
	v_add_f32_e32 v66, v102, v66
	v_exp_f32_e32 v91, v91
	v_add_f32_e32 v66, v87, v66
	v_exp_f32_e32 v92, v92
	v_add_f32_e32 v66, v88, v66
	v_exp_f32_e32 v93, v93
	v_add_f32_e32 v66, v89, v66
	v_exp_f32_e32 v94, v94
	v_add_f32_e32 v66, v90, v66
	v_exp_f32_e32 v95, v95
	v_add_f32_e32 v66, v91, v66
	v_exp_f32_e32 v96, v96
	v_add_f32_e32 v66, v92, v66
	v_fmamk_f32 v79, v79, 0x3e0293ee, v100
	v_exp_f32_e32 v97, v97
	v_add_f32_e32 v66, v93, v66
	v_fmamk_f32 v80, v80, 0x3e0293ee, v100
	v_exp_f32_e32 v103, v79
	v_add_f32_e32 v66, v94, v66
	v_fmac_f32_e32 v100, 0x3e0293ee, v81
	v_exp_f32_e32 v104, v80
	v_add_f32_e32 v66, v95, v66
	v_exp_f32_e32 v100, v100
	v_add_f32_e32 v66, v96, v66
	v_add_f32_e32 v66, v97, v66
	v_add_f32_e32 v66, v103, v66
	v_add_f32_e32 v66, v104, v66
	v_add_f32_e32 v66, v100, v66
	v_mov_b32_e32 v67, v66
	s_nop 1
	v_permlane32_swap_b32_e32 v66, v67
	v_cvt_pk_bf16_f32 v80, v84, v86
	v_cvt_pk_bf16_f32 v81, v82, v85
	v_cvt_pk_bf16_f32 v82, v77, v83
	v_cvt_pk_bf16_f32 v83, v76, v78
	v_cvt_pk_bf16_f32 v76, v73, v75
	v_cvt_pk_bf16_f32 v77, v71, v74
	v_cvt_pk_bf16_f32 v78, v69, v72
	v_cvt_pk_bf16_f32 v79, v68, v70
	v_cvt_pk_bf16_f32 v68, v101, v102
	v_cvt_pk_bf16_f32 v69, v87, v88
	v_cvt_pk_bf16_f32 v70, v89, v90
	v_cvt_pk_bf16_f32 v71, v91, v92
	v_cvt_pk_bf16_f32 v72, v93, v94
	v_cvt_pk_bf16_f32 v73, v95, v96
	v_cvt_pk_bf16_f32 v74, v97, v103
	v_cvt_pk_bf16_f32 v75, v104, v100
	s_nop 0
	v_permlane32_swap_b32_e32 v80, v82
	v_permlane32_swap_b32_e32 v81, v83
	v_permlane32_swap_b32_e32 v76, v78
	v_permlane32_swap_b32_e32 v77, v79
	v_permlane32_swap_b32_e32 v68, v70
	v_permlane32_swap_b32_e32 v69, v71
	v_permlane32_swap_b32_e32 v72, v74
	v_permlane32_swap_b32_e32 v73, v75
	ds_read_b64_tr_b16 v[84:85], v175 offset:0
	ds_read_b64_tr_b16 v[86:87], v175 offset:0x800
	ds_read_b64_tr_b16 v[88:89], v175 offset:0x1000
	ds_read_b64_tr_b16 v[90:91], v175 offset:0x1800
	ds_read_b64_tr_b16 v[92:93], v175 offset:0x2000
	ds_read_b64_tr_b16 v[94:95], v175 offset:0x2800
	ds_read_b64_tr_b16 v[100:101], v175 offset:0x3000
	ds_read_b64_tr_b16 v[102:103], v175 offset:0x3800
	s_waitcnt lgkmcnt(6)
	s_nop 0
	v_mfma_f32_32x32x16_bf16 v[2:17], v[80:83], v[84:87], v[2:17]
	ds_read_b64_tr_b16 v[84:85], v175 offset:0x200
	ds_read_b64_tr_b16 v[86:87], v175 offset:0xa00
	s_waitcnt lgkmcnt(6)
	v_mfma_f32_32x32x16_bf16 v[2:17], v[76:79], v[88:91], v[2:17]
	ds_read_b64_tr_b16 v[88:89], v175 offset:0x1200
	ds_read_b64_tr_b16 v[90:91], v175 offset:0x1a00
	s_waitcnt lgkmcnt(6)
	v_mfma_f32_32x32x16_bf16 v[2:17], v[68:71], v[92:95], v[2:17]
	ds_read_b64_tr_b16 v[92:93], v175 offset:0x2200
	ds_read_b64_tr_b16 v[94:95], v175 offset:0x2a00
	s_waitcnt lgkmcnt(6)
	v_mfma_f32_32x32x16_bf16 v[2:17], v[72:75], v[100:103], v[2:17]
	ds_read_b64_tr_b16 v[100:101], v175 offset:0x3200
	ds_read_b64_tr_b16 v[102:103], v175 offset:0x3a00
	s_waitcnt lgkmcnt(6)
	v_mfma_f32_32x32x16_bf16 v[50:65], v[80:83], v[84:87], v[50:65]
	ds_read_b64_tr_b16 v[84:85], v175 offset:0x400
	ds_read_b64_tr_b16 v[86:87], v175 offset:0xc00
	s_waitcnt lgkmcnt(6)
	v_mfma_f32_32x32x16_bf16 v[50:65], v[76:79], v[88:91], v[50:65]
	ds_read_b64_tr_b16 v[88:89], v175 offset:0x1400
	ds_read_b64_tr_b16 v[90:91], v175 offset:0x1c00
	s_waitcnt lgkmcnt(6)
	v_mfma_f32_32x32x16_bf16 v[50:65], v[68:71], v[92:95], v[50:65]
	ds_read_b64_tr_b16 v[92:93], v175 offset:0x2400
	ds_read_b64_tr_b16 v[94:95], v175 offset:0x2c00
	s_waitcnt lgkmcnt(6)
; __device__ __forceinline__ int crow(int r, int hi) { return (r & 3) + 8 * (r >> 2) + 4 * hi; }
; __device__ __forceinline__ unsigned cvtpk(float lo, float hi) { unsigned r; asm volatile("v_cvt_pk_bf16_f32 %0, %1, %2" : "=v"(r) : "v"(lo), "v"(hi)); return r; }
; template <int DLO, int DHI>
; __device__ __forceinline__ void attn_dense_body(const int g_wave, const bf16* __restrict__ Qb, const bf16* __restrict__ Kh, const bf16* __restrict__ Vh,
;                                                 bf16* __restrict__ Ob, int ldo, char* lds) {
;     ...
;   pv_d0(o, vb0 + (int)SHM_V, pa0, pa1, pa2, pa3);
;   if (hi == 0) li_l[r32] = l_reg; asm volatile("s_waitcnt lgkmcnt(0)" ::: "memory");
;   float rli[16];
; #pragma unroll
;   for (int r = 0; r < 16; ++r) rli[r] = __builtin_amdgcn_rcpf(li_l[crow(r, hi)]);
;   unsigned short* Ow = (unsigned short*)Ob + (long)(wid * QBLK) * ldo;
; #pragma unroll
;   for (int r = 0; r < 16; ++r) { int orow = crow(r, hi);
; #pragma unroll
;     for (int d0 = 0; d0 < 4; ++d0) Ow[(long)orow * ldo + d0 * 32 + r32] = (unsigned short)(cvtpk(o[d0][r] * rli[r], 0.f) & 0xffffu); }
	v_mfma_f32_32x32x16_bf16 v[50:65], v[72:75], v[100:103], v[50:65]
	ds_read_b64_tr_b16 v[100:101], v175 offset:0x3400
	ds_read_b64_tr_b16 v[102:103], v175 offset:0x3c00
	s_waitcnt lgkmcnt(6)
	v_mfma_f32_32x32x16_bf16 v[34:49], v[80:83], v[84:87], v[34:49]
	ds_read_b64_tr_b16 v[84:85], v175 offset:0x600
	ds_read_b64_tr_b16 v[86:87], v175 offset:0xe00
	s_waitcnt lgkmcnt(6)
	v_mfma_f32_32x32x16_bf16 v[34:49], v[76:79], v[88:91], v[34:49]
	ds_read_b64_tr_b16 v[88:89], v175 offset:0x1600
	ds_read_b64_tr_b16 v[90:91], v175 offset:0x1e00
	s_waitcnt lgkmcnt(6)
	v_mfma_f32_32x32x16_bf16 v[34:49], v[68:71], v[92:95], v[34:49]
	ds_read_b64_tr_b16 v[92:93], v175 offset:0x2600
	ds_read_b64_tr_b16 v[94:95], v175 offset:0x2e00
	s_waitcnt lgkmcnt(6)
	v_mfma_f32_32x32x16_bf16 v[34:49], v[72:75], v[100:103], v[34:49]
	ds_read_b64_tr_b16 v[100:101], v175 offset:0x3600
	ds_read_b64_tr_b16 v[102:103], v175 offset:0x3e00
	s_waitcnt lgkmcnt(6)
	v_mfma_f32_32x32x16_bf16 v[18:33], v[80:83], v[84:87], v[18:33]
	s_waitcnt lgkmcnt(4)
	v_mfma_f32_32x32x16_bf16 v[18:33], v[76:79], v[88:91], v[18:33]
	s_waitcnt lgkmcnt(2)
	v_mfma_f32_32x32x16_bf16 v[18:33], v[68:71], v[92:95], v[18:33]
	s_waitcnt lgkmcnt(0)
	v_mfma_f32_32x32x16_bf16 v[18:33], v[72:75], v[100:103], v[18:33]
	s_and_saveexec_b64 s[2:3], s[6:7]
	v_add_f32_e32 v0, v0, v98
	v_fmac_f32_e32 v0, v174, v146
	v_add_f32_e32 v66, v66, v67
	v_fmac_f32_e32 v66, v0, v99
	ds_write_b32 v173, v66
	s_or_b64 exec, exec, s[2:3]
	s_waitcnt lgkmcnt(0)
	v_add_u32_e32 v0, s15, v172
	ds_read_b128 v[66:69], v0
	ds_read_b128 v[70:73], v0 offset:32
	s_mul_hi_i32 s3, s10, s14
	s_mul_i32 s2, s10, s14
	s_lshl_b64 s[2:3], s[2:3], 1
	s_waitcnt lgkmcnt(1)
	v_rcp_f32_e32 v74, v66
	v_rcp_f32_e32 v75, v67
	v_rcp_f32_e32 v76, v68
	v_rcp_f32_e32 v77, v69
	ds_read_b128 v[66:69], v0 offset:64
	s_add_u32 s2, s82, s2
	s_waitcnt lgkmcnt(1)
	v_rcp_f32_e32 v78, v70
	v_rcp_f32_e32 v79, v71
	v_rcp_f32_e32 v80, v72
	v_rcp_f32_e32 v81, v73
	ds_read_b128 v[70:73], v0 offset:96
	s_addc_u32 s3, s83, s3
	v_lshlrev_b32_e32 v86, 2, v171
	v_lshlrev_b32_e32 v0, 1, v170
	s_waitcnt lgkmcnt(1)
	v_rcp_f32_e32 v82, v66
	v_rcp_f32_e32 v83, v67
	v_rcp_f32_e32 v84, v68
	v_rcp_f32_e32 v85, v69
	v_lshl_add_u64 v[66:67], s[2:3], 0, v[0:1]
	v_mad_i64_i32 v[68:69], s[2:3], s10, v86, 0
	v_mul_f32_e32 v0, v2, v74
	v_lshl_add_u64 v[68:69], v[68:69], 1, v[66:67]
	v_cvt_pk_bf16_f32 v0, v0, v1
	global_store_short v[68:69], v0, off
	v_mul_f32_e32 v0, v50, v74
	v_cvt_pk_bf16_f32 v0, v0, v1
	global_store_short v[68:69], v0, off offset:64
	v_mul_f32_e32 v0, v34, v74
	v_cvt_pk_bf16_f32 v0, v0, v1
	global_store_short v[68:69], v0, off offset:128
	v_mul_f32_e32 v0, v18, v74
	v_cvt_pk_bf16_f32 v0, v0, v1
	global_store_short v[68:69], v0, off offset:192
	v_or_b32_e32 v0, 1, v86
	v_mad_i64_i32 v[68:69], s[2:3], s10, v0, 0
	v_mul_f32_e32 v0, v3, v75
	v_lshl_add_u64 v[68:69], v[68:69], 1, v[66:67]
	v_cvt_pk_bf16_f32 v0, v0, v1
	global_store_short v[68:69], v0, off
	v_mul_f32_e32 v0, v51, v75
	v_cvt_pk_bf16_f32 v0, v0, v1
	global_store_short v[68:69], v0, off offset:64
	v_mul_f32_e32 v0, v35, v75
	v_cvt_pk_bf16_f32 v0, v0, v1
	global_store_short v[68:69], v0, off offset:128
	v_mul_f32_e32 v0, v19, v75
	v_cvt_pk_bf16_f32 v0, v0, v1
	global_store_short v[68:69], v0, off offset:192
	v_or_b32_e32 v0, 2, v86
	v_mad_i64_i32 v[2:3], s[2:3], s10, v0, 0
	v_mul_f32_e32 v0, v4, v76
	v_lshl_add_u64 v[2:3], v[2:3], 1, v[66:67]
	v_cvt_pk_bf16_f32 v0, v0, v1
	global_store_short v[2:3], v0, off
	v_mul_f32_e32 v0, v52, v76
	v_cvt_pk_bf16_f32 v0, v0, v1
	global_store_short v[2:3], v0, off offset:64
	v_mul_f32_e32 v0, v36, v76
	v_cvt_pk_bf16_f32 v0, v0, v1
	global_store_short v[2:3], v0, off offset:128
	v_mul_f32_e32 v0, v20, v76
	v_cvt_pk_bf16_f32 v0, v0, v1
	global_store_short v[2:3], v0, off offset:192
	v_or_b32_e32 v0, 3, v86
	v_mad_i64_i32 v[2:3], s[2:3], s10, v0, 0
	v_mul_f32_e32 v0, v5, v77
	v_lshl_add_u64 v[2:3], v[2:3], 1, v[66:67]
	v_cvt_pk_bf16_f32 v0, v0, v1
	global_store_short v[2:3], v0, off
	v_mul_f32_e32 v0, v53, v77
	v_cvt_pk_bf16_f32 v0, v0, v1
	global_store_short v[2:3], v0, off offset:64
	v_mul_f32_e32 v0, v37, v77
	v_cvt_pk_bf16_f32 v0, v0, v1
	global_store_short v[2:3], v0, off offset:128
	v_mul_f32_e32 v0, v21, v77
	v_cvt_pk_bf16_f32 v0, v0, v1
	global_store_short v[2:3], v0, off offset:192
	v_add_u32_e32 v0, 8, v86
	v_mad_i64_i32 v[2:3], s[2:3], s10, v0, 0
	v_mul_f32_e32 v0, v6, v78
	v_lshl_add_u64 v[2:3], v[2:3], 1, v[66:67]
	v_cvt_pk_bf16_f32 v0, v0, v1
	global_store_short v[2:3], v0, off
	v_mul_f32_e32 v0, v54, v78
	v_cvt_pk_bf16_f32 v0, v0, v1
	global_store_short v[2:3], v0, off offset:64
	v_mul_f32_e32 v0, v38, v78
	v_cvt_pk_bf16_f32 v0, v0, v1
	global_store_short v[2:3], v0, off offset:128
	v_mul_f32_e32 v0, v22, v78
	v_cvt_pk_bf16_f32 v0, v0, v1
	global_store_short v[2:3], v0, off offset:192
	v_add_u32_e32 v0, 9, v86
	v_mad_i64_i32 v[2:3], s[2:3], s10, v0, 0
	v_mul_f32_e32 v0, v7, v79
	v_lshl_add_u64 v[2:3], v[2:3], 1, v[66:67]
	v_cvt_pk_bf16_f32 v0, v0, v1
	global_store_short v[2:3], v0, off
	v_mul_f32_e32 v0, v55, v79
	v_cvt_pk_bf16_f32 v0, v0, v1
	global_store_short v[2:3], v0, off offset:64
	v_mul_f32_e32 v0, v39, v79
	v_cvt_pk_bf16_f32 v0, v0, v1
	global_store_short v[2:3], v0, off offset:128
	v_mul_f32_e32 v0, v23, v79
	v_cvt_pk_bf16_f32 v0, v0, v1
	global_store_short v[2:3], v0, off offset:192
	v_add_u32_e32 v0, 10, v86
; __device__ __forceinline__ int crow(int r, int hi) { return (r & 3) + 8 * (r >> 2) + 4 * hi; }
; __device__ __forceinline__ unsigned cvtpk(float lo, float hi) { unsigned r; asm volatile("v_cvt_pk_bf16_f32 %0, %1, %2" : "=v"(r) : "v"(lo), "v"(hi)); return r; }
; template <int DLO, int DHI>
; __device__ __forceinline__ void attn_dense_body(const int g_wave, const bf16* __restrict__ Qb, const bf16* __restrict__ Kh, const bf16* __restrict__ Vh,
;                                                 bf16* __restrict__ Ob, int ldo, char* lds) {
;     ...
;   unsigned short* Ow = (unsigned short*)Ob + (long)(wid * QBLK) * ldo;
; #pragma unroll
;   for (int r = 0; r < 16; ++r) { int orow = crow(r, hi);
; #pragma unroll
;     for (int d0 = 0; d0 < 4; ++d0) Ow[(long)orow * ldo + d0 * 32 + r32] = (unsigned short)(cvtpk(o[d0][r] * rli[r], 0.f) & 0xffffu); }
;   __syncthreads();
	v_mad_i64_i32 v[2:3], s[2:3], s10, v0, 0
	v_mul_f32_e32 v0, v8, v80
	v_lshl_add_u64 v[2:3], v[2:3], 1, v[66:67]
	v_cvt_pk_bf16_f32 v0, v0, v1
	global_store_short v[2:3], v0, off
	v_mul_f32_e32 v0, v56, v80
	v_cvt_pk_bf16_f32 v0, v0, v1
	global_store_short v[2:3], v0, off offset:64
	v_mul_f32_e32 v0, v40, v80
	v_cvt_pk_bf16_f32 v0, v0, v1
	global_store_short v[2:3], v0, off offset:128
	v_mul_f32_e32 v0, v24, v80
	v_cvt_pk_bf16_f32 v0, v0, v1
	global_store_short v[2:3], v0, off offset:192
	v_add_u32_e32 v0, 11, v86
	v_mad_i64_i32 v[2:3], s[2:3], s10, v0, 0
	v_mul_f32_e32 v0, v9, v81
	v_lshl_add_u64 v[2:3], v[2:3], 1, v[66:67]
	v_cvt_pk_bf16_f32 v0, v0, v1
	global_store_short v[2:3], v0, off
	v_mul_f32_e32 v0, v57, v81
	v_cvt_pk_bf16_f32 v0, v0, v1
	global_store_short v[2:3], v0, off offset:64
	v_mul_f32_e32 v0, v41, v81
	v_cvt_pk_bf16_f32 v0, v0, v1
	global_store_short v[2:3], v0, off offset:128
	v_mul_f32_e32 v0, v25, v81
	v_cvt_pk_bf16_f32 v0, v0, v1
	global_store_short v[2:3], v0, off offset:192
	v_add_u32_e32 v0, 16, v86
	v_mad_i64_i32 v[2:3], s[2:3], s10, v0, 0
	v_mul_f32_e32 v0, v10, v82
	v_lshl_add_u64 v[2:3], v[2:3], 1, v[66:67]
	v_cvt_pk_bf16_f32 v0, v0, v1
	global_store_short v[2:3], v0, off
	v_mul_f32_e32 v0, v58, v82
	v_cvt_pk_bf16_f32 v0, v0, v1
	global_store_short v[2:3], v0, off offset:64
	v_mul_f32_e32 v0, v42, v82
	v_cvt_pk_bf16_f32 v0, v0, v1
	global_store_short v[2:3], v0, off offset:128
	v_mul_f32_e32 v0, v26, v82
	v_cvt_pk_bf16_f32 v0, v0, v1
	global_store_short v[2:3], v0, off offset:192
	v_add_u32_e32 v0, 17, v86
	v_mad_i64_i32 v[2:3], s[2:3], s10, v0, 0
	v_mul_f32_e32 v0, v11, v83
	v_lshl_add_u64 v[2:3], v[2:3], 1, v[66:67]
	v_cvt_pk_bf16_f32 v0, v0, v1
	global_store_short v[2:3], v0, off
	v_mul_f32_e32 v0, v59, v83
	v_cvt_pk_bf16_f32 v0, v0, v1
	global_store_short v[2:3], v0, off offset:64
	v_mul_f32_e32 v0, v43, v83
	v_cvt_pk_bf16_f32 v0, v0, v1
	global_store_short v[2:3], v0, off offset:128
	v_mul_f32_e32 v0, v27, v83
	v_cvt_pk_bf16_f32 v0, v0, v1
	global_store_short v[2:3], v0, off offset:192
	v_add_u32_e32 v0, 18, v86
	v_mad_i64_i32 v[2:3], s[2:3], s10, v0, 0
	v_mul_f32_e32 v0, v12, v84
	v_lshl_add_u64 v[2:3], v[2:3], 1, v[66:67]
	v_cvt_pk_bf16_f32 v0, v0, v1
	global_store_short v[2:3], v0, off
	v_mul_f32_e32 v0, v60, v84
	v_cvt_pk_bf16_f32 v0, v0, v1
	global_store_short v[2:3], v0, off offset:64
	v_mul_f32_e32 v0, v44, v84
	v_cvt_pk_bf16_f32 v0, v0, v1
	global_store_short v[2:3], v0, off offset:128
	v_mul_f32_e32 v0, v28, v84
	v_cvt_pk_bf16_f32 v0, v0, v1
	global_store_short v[2:3], v0, off offset:192
	v_add_u32_e32 v0, 19, v86
	v_mad_i64_i32 v[2:3], s[2:3], s10, v0, 0
	v_mul_f32_e32 v0, v13, v85
	v_lshl_add_u64 v[2:3], v[2:3], 1, v[66:67]
	v_cvt_pk_bf16_f32 v0, v0, v1
	global_store_short v[2:3], v0, off
	v_mul_f32_e32 v0, v61, v85
	v_cvt_pk_bf16_f32 v0, v0, v1
	global_store_short v[2:3], v0, off offset:64
	v_mul_f32_e32 v0, v45, v85
	s_waitcnt lgkmcnt(0)
	v_rcp_f32_e32 v70, v70
	v_cvt_pk_bf16_f32 v0, v0, v1
	global_store_short v[2:3], v0, off offset:128
	v_mul_f32_e32 v0, v29, v85
	v_cvt_pk_bf16_f32 v0, v0, v1
	global_store_short v[2:3], v0, off offset:192
	v_add_u32_e32 v0, 24, v86
	v_mad_i64_i32 v[2:3], s[2:3], s10, v0, 0
	v_mul_f32_e32 v0, v14, v70
	v_lshl_add_u64 v[2:3], v[2:3], 1, v[66:67]
	v_cvt_pk_bf16_f32 v0, v0, v1
	global_store_short v[2:3], v0, off
	v_mul_f32_e32 v0, v62, v70
	v_cvt_pk_bf16_f32 v0, v0, v1
	global_store_short v[2:3], v0, off offset:64
	v_mul_f32_e32 v0, v46, v70
	v_rcp_f32_e32 v71, v71
	v_cvt_pk_bf16_f32 v0, v0, v1
	global_store_short v[2:3], v0, off offset:128
	v_mul_f32_e32 v0, v30, v70
	v_cvt_pk_bf16_f32 v0, v0, v1
	global_store_short v[2:3], v0, off offset:192
	v_add_u32_e32 v0, 25, v86
	v_mad_i64_i32 v[2:3], s[2:3], s10, v0, 0
	v_mul_f32_e32 v0, v15, v71
	v_lshl_add_u64 v[2:3], v[2:3], 1, v[66:67]
	v_cvt_pk_bf16_f32 v0, v0, v1
	global_store_short v[2:3], v0, off
	v_mul_f32_e32 v0, v63, v71
	v_cvt_pk_bf16_f32 v0, v0, v1
	global_store_short v[2:3], v0, off offset:64
	v_mul_f32_e32 v0, v47, v71
	v_rcp_f32_e32 v72, v72
	v_cvt_pk_bf16_f32 v0, v0, v1
	global_store_short v[2:3], v0, off offset:128
	v_mul_f32_e32 v0, v31, v71
	v_cvt_pk_bf16_f32 v0, v0, v1
	global_store_short v[2:3], v0, off offset:192
	v_add_u32_e32 v0, 26, v86
	v_mad_i64_i32 v[2:3], s[2:3], s10, v0, 0
	v_mul_f32_e32 v0, v16, v72
	v_lshl_add_u64 v[2:3], v[2:3], 1, v[66:67]
	v_cvt_pk_bf16_f32 v0, v0, v1
	global_store_short v[2:3], v0, off
	v_mul_f32_e32 v0, v64, v72
	v_cvt_pk_bf16_f32 v0, v0, v1
	global_store_short v[2:3], v0, off offset:64
	v_mul_f32_e32 v0, v48, v72
	v_rcp_f32_e32 v73, v73
	v_cvt_pk_bf16_f32 v0, v0, v1
	global_store_short v[2:3], v0, off offset:128
	v_mul_f32_e32 v0, v32, v72
	v_cvt_pk_bf16_f32 v0, v0, v1
	global_store_short v[2:3], v0, off offset:192
	v_add_u32_e32 v0, 27, v86
	v_mad_i64_i32 v[2:3], s[2:3], s10, v0, 0
	v_mul_f32_e32 v0, v17, v73
	v_lshl_add_u64 v[2:3], v[2:3], 1, v[66:67]
	v_cvt_pk_bf16_f32 v0, v0, v1
	global_store_short v[2:3], v0, off
	v_mul_f32_e32 v0, v65, v73
	v_cvt_pk_bf16_f32 v0, v0, v1
	global_store_short v[2:3], v0, off offset:64
	v_mul_f32_e32 v0, v49, v73
	v_cvt_pk_bf16_f32 v0, v0, v1
	global_store_short v[2:3], v0, off offset:128
	v_mul_f32_e32 v0, v33, v73
	v_cvt_pk_bf16_f32 v0, v0, v1
	global_store_short v[2:3], v0, off offset:192
	s_waitcnt vmcnt(63) expcnt(7) lgkmcnt(15)
	s_barrier
	s_mov_b64 s[4:5], 0

; __device__ __forceinline__ int opaque_lane() { int z; asm volatile("v_mov_b32 %0, 0" : "=v"(z)); return __builtin_amdgcn_mbcnt_hi(-1, __builtin_amdgcn_mbcnt_lo(-1, z)); }
; __device__ __forceinline__ int launder_s(int v) { asm volatile("" : "+s"(v)); return v; }
; __device__ __forceinline__ int v_st(int k, int c) { const int kk = (k & ~0xC) | ((k & 4) << 1) | ((k & 8) >> 1); return ((kk >> 3) * 4 + (c >> 5)) * 512 + ((kk & 7) * 32 + (c & 31)) * 2; }
; __device__ __forceinline__ int v_rd_base(int lane) { return ((lane & 3) << 3) | (((lane >> 2) & 3) << 6) | (((lane >> 4) & 1) << 5) | (((lane >> 5) & 1) << 8); }
; #define SLOAD(i, k0) do { sr_[i].vs0 = ld8(&Vh[(long)((k0) + sr) * LDV + sc]); sr_[i].vs1 = ld8(&Vh[(long)((k0) + 32 + sr) * LDV + sc]); \
;     sr_[i].ks0 = ld8(&Kh[(long)((k0) + sr) * LDK + sc]); sr_[i].ks1 = ld8(&Kh[(long)((k0) + 32 + sr) * LDK + sc]); } while (0)
; template <int DLO, int DHI>
; __device__ __forceinline__ void attn_dense_body(const int g_wave, const bf16* __restrict__ Qb, const bf16* __restrict__ Kh, const bf16* __restrict__ Vh,
;                                                 bf16* __restrict__ Ob, int ldo, char* lds) {
;   const int wid = launder_s(g_wave), lane = opaque_lane(), tid = (wid << 6) | lane, r32 = lane & 31, hi = lane >> 5;
;   bf16* V_lds = (bf16*)lds; bf16* K_lds = (bf16*)(lds + 2 * SHM_V);
;   float* ws = (float*)(lds + 2 * SHM_V + 2 * SHM_K) + wid * 64; float* li_l = ws; float* al_l = ws + 32;
;   float m_reg = -1e30f, l_reg = 0; f32x16 o[4] = {}; bf16x8 qr[8];
;   const bf16* Qw = Qb + (long)(wid * QBLK + r32) * LDQ + hi * 8;
; #pragma unroll
;   for (int d0 = DLO; d0 < DHI; ++d0) qr[d0] = ld8(Qw + d0 * 16);
;   const int sr = tid >> 4, sc = (tid & 15) * 8, vst0 = v_st(sr, sc), vst1 = v_st(32 + sr, sc);
;   const int vb0 = (int)(uintptr_t)V_lds + v_rd_base(lane);
;   struct { bf16x8 vs0, vs1, ks0, ks1; } sr_[2];
;     ...
;   f32x16 pA0, pA1, pB0, pB1; float mnA, mnB, alA, alB; bf16x8 pa0, pa1, pa2, pa3; constexpr int NT = SEQ / KVBLK;
;   constexpr int SE = 0, SO = 1;
;   SLOAD(SE, 0); asm volatile("s_waitcnt vmcnt(0)" ::: "memory"); SWRITE(0, SE); __syncthreads();
;   qkt<DLO, DHI>(pA0, pA1, K_lds, qr, r32, hi); partialSM(pA0, pA1, m_reg, mnA, alA);
.LBB0_1042:
	s_mov_b32 s1, s64
	v_mov_b32 v0, 0
	s_lshl_b32 s4, s1, 6
	v_mbcnt_lo_u32_b32 v0, -1, v0
	s_waitcnt vmcnt(0)
	v_mbcnt_hi_u32_b32 v72, -1, v0
	v_or_b32_e32 v0, s4, v72
	v_ashrrev_i32_e32 v73, 4, v0
	v_lshlrev_b32_e32 v54, 3, v72
	v_and_b32_e32 v0, 0x78, v54
	v_add_u32_e32 v22, 32, v73
	v_mov_b64_e32 v[50:51], s[94:95]
	v_mov_b64_e32 v[52:53], s[92:93]
	v_lshlrev_b32_e32 v0, 1, v0
	v_mad_i64_i32 v[2:3], s[2:3], v73, s79, v[50:51]
	v_mad_i64_i32 v[4:5], s[2:3], v22, s79, v[50:51]
	v_mad_i64_i32 v[10:11], s[2:3], v73, s67, v[52:53]
	v_mad_i64_i32 v[12:13], s[2:3], v22, s67, v[52:53]
	v_lshl_add_u64 v[2:3], v[2:3], 0, v[0:1]
	v_lshl_add_u64 v[6:7], v[4:5], 0, v[0:1]
	v_lshl_add_u64 v[10:11], v[10:11], 0, v[0:1]
	v_lshl_add_u64 v[14:15], v[12:13], 0, v[0:1]
	global_load_dwordx4 v[2:5], v[2:3], off
	s_nop 0
	global_load_dwordx4 v[6:9], v[6:7], off
	s_nop 0
	global_load_dwordx4 v[10:13], v[10:11], off
	s_nop 0
	global_load_dwordx4 v[14:17], v[14:15], off
	v_and_b32_e32 v207, 31, v72
	s_lshl_b32 s14, s1, 5
	v_or_b32_e32 v18, s14, v207
	v_ashrrev_i32_e32 v208, 5, v72
	v_ashrrev_i32_e32 v19, 31, v18
	v_lshlrev_b64 v[18:19], 12, v[18:19]
	v_lshlrev_b32_e32 v20, 3, v208
	v_lshl_add_u64 v[18:19], s[90:91], 0, v[18:19]
	v_ashrrev_i32_e32 v21, 31, v20
	v_lshl_add_u64 v[18:19], v[20:21], 1, v[18:19]
	global_load_dwordx4 v[118:121], v[18:19], off
	global_load_dwordx4 v[110:113], v[18:19], off offset:32
	global_load_dwordx4 v[126:129], v[18:19], off offset:64
	global_load_dwordx4 v[122:125], v[18:19], off offset:96
	global_load_dwordx4 v[114:117], v[18:19], off offset:128
	global_load_dwordx4 v[106:109], v[18:19], off offset:160
	global_load_dwordx4 v[102:105], v[18:19], off offset:192
	global_load_dwordx4 v[98:101], v[18:19], off offset:224
	v_and_b32_e32 v23, 0xfffff0, v73
	v_lshlrev_b32_e32 v24, 1, v73
	v_lshrrev_b32_e32 v25, 1, v73
	v_and_b32_e32 v26, 3, v73
	v_mov_b32_e32 v20, s4
	v_and_or_b32 v23, v24, 8, v23
	v_and_or_b32 v24, v25, 4, v26
	v_and_b32_e32 v26, 0xfffff0, v22
	v_lshlrev_b32_e32 v28, 1, v22
	v_bitop3_b32 v20, v72, s80, v20 bitop3:0xc8
	v_bfe_u32 v21, v54, 5, 2
	v_lshlrev_b32_e32 v27, 8, v73
	v_lshlrev_b32_e32 v22, 8, v22
	v_lshrrev_b32_e32 v23, 1, v23
	v_and_or_b32 v26, v28, 8, v26
	v_bitop3_b32 v27, v0, v27, v20 bitop3:0xde
	v_bitop3_b32 v20, v22, v0, v20 bitop3:0xf6
	v_or_b32_e32 v22, v23, v21
	v_lshrrev_b32_e32 v23, 1, v26
	v_and_b32_e32 v25, 48, v0
	v_lshlrev_b32_e32 v24, 6, v24
	v_lshlrev_b32_e32 v18, 9, v22
	v_or_b32_e32 v19, v23, v21
	v_lshlrev_b32_e32 v55, 4, v72
	v_or3_b32 v18, v18, v24, v25
	v_lshlrev_b32_e32 v19, 9, v19
	v_lshlrev_b32_e32 v209, 4, v208
	v_lshlrev_b32_e32 v56, 8, v207
	v_and_b32_e32 v57, 0x70, v55
	v_or3_b32 v19, v19, v24, v25
	v_add_u32_e32 v216, 0, v18
	v_add_u32_e32 v214, 0, v27
	v_add_u32_e32 v215, 0, v20
	s_waitcnt vmcnt(0)
	v_add_u32_e32 v217, 0, v19
	v_add_u32_e32 v62, 64, v73
	v_add_u32_e32 v64, 0x60, v73
	v_add_u32_e32 v77, 0x80, v73
	v_add_u32_e32 v78, 0xa0, v73
	s_lshl_b32 s1, s1, 8
	s_add_i32 s15, s1, 0
	s_add_i32 s15, s15, 0x20000
	s_cmp_lg_u32 0, -1
	s_cselect_b32 s1, 0, 0
	s_mov_b32 s16, s17
	s_mov_b32 s18, s17
	s_mov_b32 s19, s17
	s_mov_b32 s20, s17
	s_waitcnt vmcnt(11)
	ds_write_b128 v216, v[2:5]
	s_waitcnt vmcnt(10)
	ds_write_b128 v217, v[6:9]
	s_waitcnt vmcnt(9)
	ds_write_b128 v214, v[10:13] offset:32768
	s_waitcnt vmcnt(8)
	ds_write_b128 v215, v[14:17] offset:32768
	v_xad_u32 v2, v57, v209, v56
	v_add_u32_e32 v218, 0, v2
	s_waitcnt lgkmcnt(0)
	s_barrier
	ds_read_b128 v[2:5], v218 offset:32768
	ds_read_b128 v[6:9], v218 offset:40960
	s_waitcnt vmcnt(7) lgkmcnt(1)
	v_mfma_f32_32x32x16_bf16 v[34:49], v[2:5], v[118:121], 0
	v_add_u32_e32 v2, 32, v209
	v_xad_u32 v2, v2, v57, v56
	v_add_u32_e32 v225, 0, v2
	v_lshlrev_b32_e32 v10, 1, v72
	s_mov_b32 s21, s17
	s_mov_b32 s22, s17
	s_mov_b32 s23, s17
	s_waitcnt lgkmcnt(0)
	v_mfma_f32_32x32x16_bf16 v[18:33], v[6:9], v[118:121], 0
	ds_read_b128 v[2:5], v225 offset:32768
	ds_read_b128 v[6:9], v225 offset:40960
	s_mov_b32 s24, s17
	s_mov_b32 s25, s17
	s_mov_b32 s26, s17
	s_mov_b32 s27, s17
	s_mov_b32 s28, s17
	s_mov_b32 s29, s17
	s_waitcnt vmcnt(6) lgkmcnt(1)
	v_mfma_f32_32x32x16_bf16 v[34:49], v[2:5], v[110:113], v[34:49]
	v_add_u32_e32 v2, 64, v209
	v_xad_u32 v2, v2, v57, v56
	v_add_u32_e32 v224, 0, v2
	s_mov_b32 s30, s17
	s_mov_b32 s31, s17
	s_mov_b32 s34, 1
	v_cmp_gt_u32_e64 s[6:7], 32, v72
	s_waitcnt lgkmcnt(0)
	v_mfma_f32_32x32x16_bf16 v[18:33], v[6:9], v[110:113], v[18:33]
	ds_read_b128 v[2:5], v224 offset:32768
	ds_read_b128 v[6:9], v224 offset:40960
	v_lshl_add_u32 v210, v207, 2, s15
	v_mov_b32_e32 v211, 0
	s_waitcnt vmcnt(5) lgkmcnt(1)
	v_mfma_f32_32x32x16_bf16 v[34:49], v[2:5], v[126:129], v[34:49]
	v_add_u32_e32 v2, 0x60, v209
	v_xad_u32 v2, v2, v57, v56
	v_add_u32_e32 v222, 0, v2
	s_waitcnt lgkmcnt(0)
	v_mfma_f32_32x32x16_bf16 v[18:33], v[6:9], v[126:129], v[18:33]
	ds_read_b128 v[2:5], v222 offset:32768
	ds_read_b128 v[6:9], v222 offset:40960
	s_waitcnt vmcnt(4) lgkmcnt(1)
	v_mfma_f32_32x32x16_bf16 v[34:49], v[2:5], v[122:125], v[34:49]
	v_add_u32_e32 v2, 0x80, v209
	v_xad_u32 v2, v2, v57, v56
	v_add_u32_e32 v220, 0, v2
	s_waitcnt lgkmcnt(0)
	v_mfma_f32_32x32x16_bf16 v[18:33], v[6:9], v[122:125], v[18:33]
	ds_read_b128 v[2:5], v220 offset:32768
	ds_read_b128 v[6:9], v220 offset:40960
	s_waitcnt vmcnt(3) lgkmcnt(1)
	v_mfma_f32_32x32x16_bf16 v[34:49], v[2:5], v[114:117], v[34:49]
	v_add_u32_e32 v2, 0xa0, v209
	v_xad_u32 v2, v2, v57, v56
	v_add_u32_e32 v219, 0, v2
	ds_read_b128 v[2:5], v219 offset:32768
	s_waitcnt lgkmcnt(1)
	v_mfma_f32_32x32x16_bf16 v[18:33], v[6:9], v[114:117], v[18:33]
	ds_read_b128 v[6:9], v219 offset:40960
	s_waitcnt vmcnt(2) lgkmcnt(1)
; #define SLOAD(i, k0) do { sr_[i].vs0 = ld8(&Vh[(long)((k0) + sr) * LDV + sc]); sr_[i].vs1 = ld8(&Vh[(long)((k0) + 32 + sr) * LDV + sc]); \
;     sr_[i].ks0 = ld8(&Kh[(long)((k0) + sr) * LDK + sc]); sr_[i].ks1 = ld8(&Kh[(long)((k0) + 32 + sr) * LDK + sc]); } while (0)
; #define SWRITE(b, i) do { *(bf16x8*)((char*)V_lds + (b) * SHM_V + vst0) = sr_[i].vs0;          \
;     *(bf16x8*)((char*)V_lds + (b) * SHM_V + vst1) = sr_[i].vs1; int kc = sc * 2;               \
;     *(bf16x8*)((char*)K_lds + (b) * SHM_K + KSWZ(sr, kc)) = sr_[i].ks0;                       \
;     *(bf16x8*)((char*)K_lds + (b) * SHM_K + KSWZ(32 + sr, kc)) = sr_[i].ks1; } while (0)
; #define SWAIT() asm volatile("s_waitcnt vmcnt(4)" ::: "memory")
; __device__ __forceinline__ void partialSM(f32x16& p0, f32x16& p1, float& m_reg, float& mn, float& alpha) {
;   constexpr float C = SCALE * 1.4426950408889634f;
;   float pmax = p0[0];
; #pragma unroll
;   for (int r = 1; r < 16; ++r) pmax = fmaxf(pmax, p0[r]);
; #pragma unroll
;   for (int r = 0; r < 16; ++r) pmax = fmaxf(pmax, p1[r]);
;   { auto rr = __builtin_amdgcn_permlane32_swap(__float_as_uint(pmax), __float_as_uint(pmax), false, false);
;     pmax = fmaxf(__uint_as_float(rr[0]), __uint_as_float(rr[1])); }
;   if (__builtin_expect(__all(pmax - m_reg <= THR / SCALE), 1)) { mn = m_reg; alpha = 1.f; }
;   else { mn = fmaxf(m_reg, pmax); alpha = __builtin_amdgcn_exp2f((m_reg - mn) * C); m_reg = mn; }
;   float mnC = -mn * C;
; #pragma unroll
;   for (int r = 0; r < 16; ++r) p0[r] = fmaf(p0[r], C, mnC);
; #pragma unroll
;   for (int r = 0; r < 16; ++r) p1[r] = fmaf(p1[r], C, mnC);
; #pragma unroll
;   for (int r = 0; r < 16; ++r) p0[r] = __builtin_amdgcn_exp2f(p0[r]);
; }
; template <int DLO, int DHI>
; __device__ __forceinline__ void attn_dense_body(const int g_wave, const bf16* __restrict__ Qb, const bf16* __restrict__ Kh, const bf16* __restrict__ Vh,
;                                                 bf16* __restrict__ Ob, int ldo, char* lds) {
;     ...
;   qkt<DLO, DHI>(pA0, pA1, K_lds, qr, r32, hi); partialSM(pA0, pA1, m_reg, mnA, alA);
;   SLOAD(SO, KVBLK); SLOAD(SE, 2 * KVBLK);
;   SWAIT(); SWRITE(1, SO); __syncthreads();
	v_mfma_f32_32x32x16_bf16 v[34:49], v[2:5], v[106:109], v[34:49]
	v_and_b32_e32 v2, 0xc0, v55
	v_and_or_b32 v11, v54, 24, v2
	v_add_u32_e32 v2, 0xc0, v209
	v_xad_u32 v2, v2, v57, v56
	v_add_u32_e32 v221, 0, v2
	ds_read_b128 v[2:5], v221 offset:32768
	s_waitcnt lgkmcnt(1)
	v_mfma_f32_32x32x16_bf16 v[18:33], v[6:9], v[106:109], v[18:33]
	v_and_b32_e32 v6, 32, v10
	v_and_b32_e32 v7, 0x100, v54
	v_or3_b32 v74, v11, v6, v7
	ds_read_b128 v[6:9], v221 offset:40960
	v_add_u32_e32 v213, s1, v74
	s_waitcnt vmcnt(1) lgkmcnt(1)
	v_mfma_f32_32x32x16_bf16 v[34:49], v[2:5], v[102:105], v[34:49]
	v_add_u32_e32 v2, 0xe0, v209
	v_xad_u32 v2, v2, v57, v56
	v_add_u32_e32 v223, 0, v2
	ds_read_b128 v[2:5], v223 offset:32768
	ds_read_b128 v[54:57], v223 offset:40960
	s_waitcnt lgkmcnt(2)
	v_mfma_f32_32x32x16_bf16 v[18:33], v[6:9], v[102:105], v[18:33]
	s_waitcnt vmcnt(0) lgkmcnt(1)
	v_mfma_f32_32x32x16_bf16 v[34:49], v[2:5], v[98:101], v[34:49]
	v_mov_b64_e32 v[2:3], s[16:17]
	v_mov_b64_e32 v[16:17], s[30:31]
	v_mov_b64_e32 v[4:5], s[18:19]
	v_mov_b64_e32 v[6:7], s[20:21]
	v_mov_b64_e32 v[8:9], s[22:23]
	v_mov_b64_e32 v[10:11], s[24:25]
	v_mov_b64_e32 v[12:13], s[26:27]
	s_waitcnt lgkmcnt(0)
	v_mfma_f32_32x32x16_bf16 v[18:33], v[54:57], v[98:101], v[18:33]
	s_nop 2
	v_max_f32_e32 v54, v35, v35
	v_max_f32_e32 v55, v34, v34
	v_max_f32_e32 v54, v55, v54
	v_max3_f32 v54, v54, v36, v37
	v_max3_f32 v54, v54, v38, v39
	v_max3_f32 v54, v54, v40, v41
	v_max3_f32 v54, v54, v42, v43
	v_max3_f32 v54, v54, v44, v45
	v_max3_f32 v54, v54, v46, v47
	v_max3_f32 v54, v54, v48, v49
	v_max3_f32 v54, v54, v18, v19
	v_max3_f32 v54, v54, v20, v21
	v_max3_f32 v54, v54, v22, v23
	v_max3_f32 v54, v54, v24, v25
	v_max3_f32 v54, v54, v26, v27
	v_max3_f32 v54, v54, v28, v29
	v_max3_f32 v54, v54, v30, v31
	v_max3_f32 v70, v54, v32, v33
	v_mov_b32_e32 v71, v70
	s_nop 1
	v_permlane32_swap_b32_e32 v70, v71
	v_max_f32_e32 v71, v71, v71
	v_max_f32_e32 v70, v70, v70
	v_max_f32_e32 v70, v70, v71
	v_max_f32_e32 v75, 0xf149f2ca, v70
	v_add_f32_e32 v71, 0x7149f2ca, v70
	v_sub_f32_e32 v70, 0xf149f2ca, v75
	v_mad_i64_i32 v[54:55], s[2:3], v62, s79, v[50:51]
	v_mad_i64_i32 v[56:57], s[2:3], v64, s79, v[50:51]
	v_mad_i64_i32 v[62:63], s[2:3], v62, s67, v[52:53]
	v_mad_i64_i32 v[64:65], s[2:3], v64, s67, v[52:53]
	v_cmp_ge_f32_e32 vcc, s63, v71
	v_mul_f32_e32 v76, 0x3e0293ee, v70
	v_mad_i64_i32 v[70:71], s[2:3], v77, s79, v[50:51]
	v_mad_i64_i32 v[50:51], s[2:3], v78, s79, v[50:51]
	v_lshl_add_u64 v[54:55], v[54:55], 0, v[0:1]
	v_lshl_add_u64 v[58:59], v[56:57], 0, v[0:1]
	v_lshl_add_u64 v[62:63], v[62:63], 0, v[0:1]
	v_lshl_add_u64 v[66:67], v[64:65], 0, v[0:1]
	v_lshl_add_u64 v[70:71], v[70:71], 0, v[0:1]
	v_lshl_add_u64 v[50:51], v[50:51], 0, v[0:1]
	global_load_dwordx4 v[54:57], v[54:55], off
	s_nop 0
	global_load_dwordx4 v[58:61], v[58:59], off
	s_nop 0
	global_load_dwordx4 v[62:65], v[62:63], off
	s_nop 0
	global_load_dwordx4 v[66:69], v[66:67], off
	s_nop 0
	global_load_dwordx4 v[130:133], v[70:71], off
	global_load_dwordx4 v[134:137], v[50:51], off
	v_mad_i64_i32 v[50:51], s[2:3], v77, s67, v[52:53]
	v_lshl_add_u64 v[50:51], v[50:51], 0, v[0:1]
	v_mad_i64_i32 v[52:53], s[2:3], v78, s67, v[52:53]
	v_lshl_add_u64 v[52:53], v[52:53], 0, v[0:1]
	global_load_dwordx4 v[138:141], v[50:51], off
	global_load_dwordx4 v[142:145], v[52:53], off
	s_cmp_eq_u64 vcc, exec
	v_exp_f32_e32 v0, v76
	s_cselect_b64 vcc, -1, 0
	s_addk_i32 s1, 0x4000
	v_add_u32_e32 v212, s1, v74
	s_add_u32 s1, s84, s86
	s_addc_u32 s3, s85, s87
	v_cndmask_b32_e32 v170, v75, v205, vcc
	s_add_u32 s2, s1, s11
	v_cndmask_b32_e64 v226, v0, 1.0, vcc
	v_mul_f32_e32 v0, 0xbe0293ee, v170
	s_addc_u32 s3, s3, 0
	v_pk_fma_f32 v[158:159], v[18:19], s[62:63], v[0:1] op_sel_hi:[1,0,0]
	v_mov_b64_e32 v[18:19], s[2:3]
	v_mad_i64_i32 v[190:191], s[2:3], v73, s67, v[18:19]
	s_add_u32 s1, s84, s88
	v_mov_b32_e32 v50, v0
	s_addc_u32 s3, s85, s89
	v_fmamk_f32 v34, v34, 0x3e0293ee, v0
	v_fmamk_f32 v35, v35, 0x3e0293ee, v0
	v_fmamk_f32 v36, v36, 0x3e0293ee, v0
	v_fmamk_f32 v37, v37, 0x3e0293ee, v0
	v_fmamk_f32 v38, v38, 0x3e0293ee, v0
	v_fmamk_f32 v39, v39, 0x3e0293ee, v0
	v_fmamk_f32 v40, v40, 0x3e0293ee, v0
	v_fmamk_f32 v41, v41, 0x3e0293ee, v0
	v_fmamk_f32 v42, v42, 0x3e0293ee, v0
	v_fmamk_f32 v43, v43, 0x3e0293ee, v0
	v_fmamk_f32 v44, v44, 0x3e0293ee, v0
	v_fmamk_f32 v45, v45, 0x3e0293ee, v0
	v_fmamk_f32 v46, v46, 0x3e0293ee, v0
	v_fmamk_f32 v47, v47, 0x3e0293ee, v0
	v_fmamk_f32 v48, v48, 0x3e0293ee, v0
	v_fmac_f32_e32 v50, 0x3e0293ee, v49
	s_add_u32 s2, s1, s13
	v_exp_f32_e32 v177, v34
	v_exp_f32_e32 v195, v35
	v_exp_f32_e32 v163, v36
	v_exp_f32_e32 v194, v37
	v_exp_f32_e32 v164, v38
	v_exp_f32_e32 v176, v39
	v_exp_f32_e32 v165, v40
	v_exp_f32_e32 v175, v41
	v_exp_f32_e32 v166, v42
	v_exp_f32_e32 v174, v43
	v_exp_f32_e32 v167, v44
	v_exp_f32_e32 v173, v45
	v_exp_f32_e32 v168, v46
	v_exp_f32_e32 v172, v47
	v_exp_f32_e32 v169, v48
	v_exp_f32_e32 v171, v50
	s_addc_u32 s3, s3, 0
	s_waitcnt vmcnt(4)
	v_mov_b64_e32 v[18:19], s[2:3]
	v_mov_b64_e32 v[14:15], s[28:29]
	v_pk_fma_f32 v[152:153], v[32:33], s[62:63], v[0:1] op_sel_hi:[1,0,0]
	v_pk_fma_f32 v[154:155], v[30:31], s[62:63], v[0:1] op_sel_hi:[1,0,0]
	v_pk_fma_f32 v[160:161], v[28:29], s[62:63], v[0:1] op_sel_hi:[1,0,0]
	v_pk_fma_f32 v[146:147], v[26:27], s[62:63], v[0:1] op_sel_hi:[1,0,0]
	v_pk_fma_f32 v[148:149], v[24:25], s[62:63], v[0:1] op_sel_hi:[1,0,0]
	v_pk_fma_f32 v[150:151], v[22:23], s[62:63], v[0:1] op_sel_hi:[1,0,0]
	v_pk_fma_f32 v[156:157], v[20:21], s[62:63], v[0:1] op_sel_hi:[1,0,0]
	s_waitcnt vmcnt(7)
	ds_write_b128 v216, v[54:57] offset:16384
	s_waitcnt vmcnt(6)
	ds_write_b128 v217, v[58:61] offset:16384
	s_waitcnt vmcnt(5)
	ds_write_b128 v214, v[62:65] offset:49152
	s_waitcnt vmcnt(4)
	ds_write_b128 v215, v[66:69] offset:49152
	v_and_b32_e32 v0, 15, v72
	v_mad_i64_i32 v[192:193], s[2:3], v73, s79, v[18:19]
	v_mov_b64_e32 v[64:65], v[16:17]
	v_mov_b64_e32 v[48:49], v[16:17]
	v_mov_b64_e32 v[32:33], v[16:17]
	s_mov_b32 s24, 0x3fb8aa3b
	v_lshlrev_b32_e32 v0, 4, v0
	v_mov_b64_e32 v[62:63], v[14:15]
	v_mov_b64_e32 v[60:61], v[12:13]
	v_mov_b64_e32 v[58:59], v[10:11]
	v_mov_b64_e32 v[56:57], v[8:9]
	v_mov_b64_e32 v[54:55], v[6:7]
	v_mov_b64_e32 v[52:53], v[4:5]
	v_mov_b64_e32 v[50:51], v[2:3]
	v_mov_b64_e32 v[46:47], v[14:15]
	v_mov_b64_e32 v[44:45], v[12:13]
	v_mov_b64_e32 v[42:43], v[10:11]
	v_mov_b64_e32 v[40:41], v[8:9]
	v_mov_b64_e32 v[38:39], v[6:7]
	v_mov_b64_e32 v[36:37], v[4:5]
	v_mov_b64_e32 v[34:35], v[2:3]
	v_mov_b64_e32 v[30:31], v[14:15]
	v_mov_b64_e32 v[28:29], v[12:13]
	v_mov_b64_e32 v[26:27], v[10:11]
	v_mov_b64_e32 v[24:25], v[8:9]
	v_mov_b64_e32 v[22:23], v[6:7]
	v_mov_b64_e32 v[20:21], v[4:5]
	v_mov_b64_e32 v[18:19], v[2:3]
	s_waitcnt lgkmcnt(0)
	s_barrier
	v_xor_b32_e32 v216, 0x10000, v216
	v_xor_b32_e32 v217, 0x10000, v217
	v_xor_b32_e32 v214, 0x10000, v214
	v_xor_b32_e32 v215, 0x10000, v215
; #define SBAR() __builtin_amdgcn_sched_barrier(0)
; #define SLOAD(i, k0) do { sr_[i].vs0 = ld8(&Vh[(long)((k0) + sr) * LDV + sc]); sr_[i].vs1 = ld8(&Vh[(long)((k0) + 32 + sr) * LDV + sc]); \
;     sr_[i].ks0 = ld8(&Kh[(long)((k0) + sr) * LDK + sc]); sr_[i].ks1 = ld8(&Kh[(long)((k0) + 32 + sr) * LDK + sc]); } while (0)
; __device__ __forceinline__ void finishSM(f32x16& p0, f32x16& p1, float alpha, float& l_reg, bf16x8& pa0, bf16x8& pa1, bf16x8& pa2, bf16x8& pa3) {
; #pragma unroll
;   for (int r = 0; r < 16; ++r) p1[r] = __builtin_amdgcn_exp2f(p1[r]);
;   float ps = 0;
; #pragma unroll
;   for (int r = 0; r < 16; ++r) ps += p0[r];
; #pragma unroll
;   for (int r = 0; r < 16; ++r) ps += p1[r];
;   { auto rr = __builtin_amdgcn_permlane32_swap(__float_as_uint(ps), __float_as_uint(ps), false, false);
;     ps = __uint_as_float(rr[0]) + __uint_as_float(rr[1]); }
;   l_reg = l_reg * alpha + ps;
;   PK4(p0, 0, pa0); PK4(p0, 8, pa1); PK4(p1, 0, pa2); PK4(p1, 8, pa3);
; }
;   p0 = f32x16{}; p1 = f32x16{};
; #pragma unroll
;   for (int d0 = DLO; d0 < DHI; ++d0) { int cb = (d0 * 16 + hi * 8) * 2;
;     bf16x8 b0 = *reinterpret_cast<const bf16x8*>((const char*)Ks + KSWZ(r32, cb));
;     bf16x8 b1 = *reinterpret_cast<const bf16x8*>((const char*)Ks + KSWZ(32 + r32, cb));
;     p0 = __builtin_amdgcn_mfma_f32_32x32x16_bf16(b0, qr[d0], p0, 0, 0, 0);
;     p1 = __builtin_amdgcn_mfma_f32_32x32x16_bf16(b1, qr[d0], p1, 0, 0, 0); }
; }
; template <int DLO, int DHI>
; __device__ __forceinline__ void attn_dense_body(const int g_wave, const bf16* __restrict__ Qb, const bf16* __restrict__ Kh, const bf16* __restrict__ Vh,
;                                                 bf16* __restrict__ Ob, int ldo, char* lds) {
;     ...
;     SBAR(); qkt<DLO, DHI>(pB0, pB1, (bf16*)((char*)K_lds + SHM_K), qr, r32, hi);
;     finishSM(pA0, pA1, alA, l_reg, pa0, pa1, pa2, pa3); SBAR();
;     SLOAD(SO, (j + 2) * KVBLK); SBAR();
;     pv_d0(o, vb0, pa0, pa1, pa2, pa3); partialSM(pB0, pB1, m_reg, mnB, alB);
.LBB0_1043:
	ds_read_b128 v[66:69], v218 offset:49152
	ds_read_b128 v[70:73], v218 offset:57344
	ds_read_b128 v[228:231], v225 offset:49152
	ds_read_b128 v[232:235], v225 offset:57344
	v_add_f32_e32 v162, 0, v177
	v_add_f32_e32 v162, v195, v162
	s_waitcnt lgkmcnt(3)
	v_mfma_f32_32x32x16_bf16 v[82:97], v[66:69], v[118:121], 0
	v_add_f32_e32 v162, v163, v162
	v_add_f32_e32 v162, v194, v162
	v_add_f32_e32 v162, v164, v162
	v_add_f32_e32 v162, v176, v162
	v_add_f32_e32 v162, v165, v162
	v_add_f32_e32 v162, v175, v162
	v_add_f32_e32 v162, v166, v162
	s_waitcnt lgkmcnt(2)
	v_mfma_f32_32x32x16_bf16 v[66:81], v[70:73], v[118:121], 0
	v_add_f32_e32 v162, v174, v162
	v_add_f32_e32 v162, v167, v162
	v_add_f32_e32 v162, v173, v162
	v_exp_f32_e32 v158, v158
	v_add_f32_e32 v162, v168, v162
	v_exp_f32_e32 v159, v159
	v_add_f32_e32 v162, v172, v162
	s_waitcnt lgkmcnt(1)
	v_mfma_f32_32x32x16_bf16 v[82:97], v[228:231], v[110:113], v[82:97]
	v_exp_f32_e32 v156, v156
	v_add_f32_e32 v162, v169, v162
	v_exp_f32_e32 v157, v157
	v_add_f32_e32 v162, v171, v162
	v_exp_f32_e32 v150, v150
	v_add_f32_e32 v162, v158, v162
	v_exp_f32_e32 v151, v151
	s_waitcnt lgkmcnt(0)
	v_mfma_f32_32x32x16_bf16 v[66:81], v[232:235], v[110:113], v[66:81]
	ds_read_b128 v[228:231], v224 offset:49152
	ds_read_b128 v[232:235], v224 offset:57344
	v_add_f32_e32 v162, v159, v162
	v_exp_f32_e32 v148, v148
	v_add_f32_e32 v162, v156, v162
	v_exp_f32_e32 v149, v149
	v_add_f32_e32 v162, v157, v162
	v_exp_f32_e32 v146, v146
	s_waitcnt lgkmcnt(1)
	v_mfma_f32_32x32x16_bf16 v[82:97], v[228:231], v[126:129], v[82:97]
	v_add_f32_e32 v162, v150, v162
	v_exp_f32_e32 v147, v147
	v_add_f32_e32 v162, v151, v162
	v_exp_f32_e32 v160, v160
	v_add_f32_e32 v162, v148, v162
	v_exp_f32_e32 v161, v161
	v_add_f32_e32 v162, v149, v162
	s_waitcnt lgkmcnt(0)
	v_mfma_f32_32x32x16_bf16 v[66:81], v[232:235], v[126:129], v[66:81]
	ds_read_b128 v[228:231], v222 offset:49152
	ds_read_b128 v[232:235], v222 offset:57344
	v_exp_f32_e32 v154, v154
	v_add_f32_e32 v162, v146, v162
	v_exp_f32_e32 v155, v155
	v_add_f32_e32 v162, v147, v162
	v_exp_f32_e32 v152, v152
	v_add_f32_e32 v162, v160, v162
	s_waitcnt lgkmcnt(1)
	v_mfma_f32_32x32x16_bf16 v[82:97], v[228:231], v[122:125], v[82:97]
	v_exp_f32_e32 v153, v153
	v_add_f32_e32 v162, v161, v162
	v_add_f32_e32 v162, v154, v162
	v_add_f32_e32 v162, v155, v162
	v_add_f32_e32 v162, v152, v162
	v_add_f32_e32 v227, v153, v162
	s_waitcnt lgkmcnt(0)
	v_mfma_f32_32x32x16_bf16 v[66:81], v[232:235], v[122:125], v[66:81]
	ds_read_b128 v[228:231], v220 offset:49152
	ds_read_b128 v[232:235], v220 offset:57344
	s_waitcnt lgkmcnt(1)
	v_mfma_f32_32x32x16_bf16 v[82:97], v[228:231], v[114:117], v[82:97]
	s_waitcnt lgkmcnt(0)
	v_mfma_f32_32x32x16_bf16 v[66:81], v[232:235], v[114:117], v[66:81]
	ds_read_b128 v[228:231], v219 offset:49152
	ds_read_b128 v[232:235], v219 offset:57344
	s_waitcnt lgkmcnt(1)
	v_mfma_f32_32x32x16_bf16 v[82:97], v[228:231], v[106:109], v[82:97]
	s_waitcnt lgkmcnt(0)
	v_mfma_f32_32x32x16_bf16 v[66:81], v[232:235], v[106:109], v[66:81]
	ds_read_b128 v[228:231], v221 offset:49152
	ds_read_b128 v[232:235], v221 offset:57344
	s_waitcnt lgkmcnt(1)
	v_mfma_f32_32x32x16_bf16 v[82:97], v[228:231], v[102:105], v[82:97]
	s_waitcnt lgkmcnt(0)
	v_mfma_f32_32x32x16_bf16 v[66:81], v[232:235], v[102:105], v[66:81]
	ds_read_b128 v[228:231], v223 offset:49152
	ds_read_b128 v[232:235], v223 offset:57344
	v_cvt_pk_bf16_f32 v162, v177, v195
	v_cvt_pk_bf16_f32 v163, v163, v194
	v_cvt_pk_bf16_f32 v164, v164, v176
	v_cvt_pk_bf16_f32 v165, v165, v175
	v_cvt_pk_bf16_f32 v166, v166, v174
	v_cvt_pk_bf16_f32 v167, v167, v173
	s_waitcnt lgkmcnt(1)
	v_mfma_f32_32x32x16_bf16 v[82:97], v[228:231], v[98:101], v[82:97]
	v_mov_b32_e32 v228, v227
	s_nop 1
	v_permlane32_swap_b32_e32 v227, v228
	v_permlane32_swap_b32_e32 v162, v164
	v_cvt_pk_bf16_f32 v168, v168, v172
	v_cvt_pk_bf16_f32 v169, v169, v171
	s_waitcnt lgkmcnt(0)
	v_mfma_f32_32x32x16_bf16 v[66:81], v[232:235], v[98:101], v[66:81]
	v_cvt_pk_bf16_f32 v172, v158, v159
	v_cvt_pk_bf16_f32 v173, v156, v157
	v_cvt_pk_bf16_f32 v174, v150, v151
	v_cvt_pk_bf16_f32 v175, v148, v149
	v_cvt_pk_bf16_f32 v230, v146, v147
	v_cvt_pk_bf16_f32 v231, v160, v161
	v_cvt_pk_bf16_f32 v232, v154, v155
	v_cvt_pk_bf16_f32 v233, v152, v153
	v_permlane32_swap_b32_e32 v163, v165
	v_permlane32_swap_b32_e32 v166, v168
	v_permlane32_swap_b32_e32 v167, v169
	v_permlane32_swap_b32_e32 v172, v174
	v_permlane32_swap_b32_e32 v173, v175
	v_permlane32_swap_b32_e32 v230, v232
	v_permlane32_swap_b32_e32 v231, v233
	s_waitcnt vmcnt(0)
	ds_write_b128 v216, v[130:133]
	ds_write_b128 v217, v[134:137]
	ds_write_b128 v214, v[138:141] offset:32768
	ds_write_b128 v215, v[142:145] offset:32768
	v_lshl_add_u64 v[196:197], v[192:193], 0, v[0:1]
	s_mov_b32 s1, 0x18fb0000
	v_add_co_u32_e32 v146, vcc, s1, v196
	s_mov_b32 s1, 0x18ff8000
	s_nop 0
	v_addc_co_u32_e32 v147, vcc, 0, v197, vcc
	v_add_co_u32_e32 v150, vcc, s1, v196
	v_lshl_add_u64 v[194:195], v[190:191], 0, v[0:1]
	s_nop 0
	v_addc_co_u32_e32 v151, vcc, 0, v197, vcc
	s_mov_b32 s1, 0x1f648000
	v_add_co_u32_e32 v154, vcc, s1, v194
	s_mov_b32 s1, 0x1f654000
	s_nop 0
	v_addc_co_u32_e32 v155, vcc, 0, v195, vcc
	v_add_co_u32_e32 v158, vcc, s1, v194
	global_load_dwordx4 v[146:149], v[146:147], off
	s_nop 0
	global_load_dwordx4 v[150:153], v[150:151], off
	v_addc_co_u32_e32 v159, vcc, 0, v195, vcc
	global_load_dwordx4 v[154:157], v[154:155], off
	s_nop 0
	global_load_dwordx4 v[158:161], v[158:159], off
	ds_read_b64_tr_b16 v[234:235], v213 offset:0
	ds_read_b64_tr_b16 v[236:237], v213 offset:0x800
	ds_read_b64_tr_b16 v[238:239], v213 offset:0x1000
	ds_read_b64_tr_b16 v[240:241], v213 offset:0x1800
	ds_read_b64_tr_b16 v[242:243], v213 offset:0x2000
	ds_read_b64_tr_b16 v[244:245], v213 offset:0x2800
	ds_read_b64_tr_b16 v[246:247], v213 offset:0x3000
	ds_read_b64_tr_b16 v[248:249], v213 offset:0x3800
	s_waitcnt lgkmcnt(6)
; #define SBAR() __builtin_amdgcn_sched_barrier(0)
; template <int D0> __device__ __forceinline__ void pv_one(f32x16& od, int vb, bf16x8 pa0, bf16x8 pa1, bf16x8 pa2, bf16x8 pa3) {
;   const s16x4 l0 = tr_read<v_rd_off(D0, 0, 0)>(vb), h0 = tr_read<v_rd_off(D0, 0, 1)>(vb), l1 = tr_read<v_rd_off(D0, 1, 0)>(vb), h1 = tr_read<v_rd_off(D0, 1, 1)>(vb);
;   const s16x4 l2 = tr_read<v_rd_off(D0, 2, 0)>(vb), h2 = tr_read<v_rd_off(D0, 2, 1)>(vb), l3 = tr_read<v_rd_off(D0, 3, 0)>(vb), h3 = tr_read<v_rd_off(D0, 3, 1)>(vb);
;   asm volatile("s_waitcnt lgkmcnt(0)" ::: "memory"); SBAR();
;     ...
;   od = __builtin_amdgcn_mfma_f32_32x32x16_bf16(pa0, PK(l0, h0), od, 0, 0, 0);
;   od = __builtin_amdgcn_mfma_f32_32x32x16_bf16(pa1, PK(l1, h1), od, 0, 0, 0);
;   od = __builtin_amdgcn_mfma_f32_32x32x16_bf16(pa2, PK(l2, h2), od, 0, 0, 0);
;   od = __builtin_amdgcn_mfma_f32_32x32x16_bf16(pa3, PK(l3, h3), od, 0, 0, 0);
;     ...
; }
; __device__ __forceinline__ void pv_d0(f32x16* o, int vb, bf16x8 pa0, bf16x8 pa1, bf16x8 pa2, bf16x8 pa3) {
;   pv_one<0>(o[0], vb, pa0, pa1, pa2, pa3); pv_one<1>(o[1], vb, pa0, pa1, pa2, pa3); pv_one<2>(o[2], vb, pa0, pa1, pa2, pa3); pv_one<3>(o[3], vb, pa0, pa1, pa2, pa3);
; }
	s_nop 0
	v_mfma_f32_32x32x16_bf16 v[2:17], v[162:165], v[234:237], v[2:17]
	ds_read_b64_tr_b16 v[234:235], v213 offset:0x200
	ds_read_b64_tr_b16 v[236:237], v213 offset:0xa00
	s_waitcnt lgkmcnt(6)
	v_mfma_f32_32x32x16_bf16 v[2:17], v[166:169], v[238:241], v[2:17]
	ds_read_b64_tr_b16 v[238:239], v213 offset:0x1200
	ds_read_b64_tr_b16 v[240:241], v213 offset:0x1a00
	s_waitcnt lgkmcnt(6)
	v_mfma_f32_32x32x16_bf16 v[2:17], v[172:175], v[242:245], v[2:17]
	ds_read_b64_tr_b16 v[242:243], v213 offset:0x2200
	ds_read_b64_tr_b16 v[244:245], v213 offset:0x2a00
	s_waitcnt lgkmcnt(6)
	v_mfma_f32_32x32x16_bf16 v[2:17], v[230:233], v[246:249], v[2:17]
	ds_read_b64_tr_b16 v[246:247], v213 offset:0x3200
	ds_read_b64_tr_b16 v[248:249], v213 offset:0x3a00
	s_waitcnt lgkmcnt(6)
	v_mfma_f32_32x32x16_bf16 v[50:65], v[162:165], v[234:237], v[50:65]
	ds_read_b64_tr_b16 v[234:235], v213 offset:0x400
	ds_read_b64_tr_b16 v[236:237], v213 offset:0xc00
	s_waitcnt lgkmcnt(6)
	v_mfma_f32_32x32x16_bf16 v[50:65], v[166:169], v[238:241], v[50:65]
	ds_read_b64_tr_b16 v[238:239], v213 offset:0x1400
	ds_read_b64_tr_b16 v[240:241], v213 offset:0x1c00
	s_waitcnt lgkmcnt(6)
	v_mfma_f32_32x32x16_bf16 v[50:65], v[172:175], v[242:245], v[50:65]
	ds_read_b64_tr_b16 v[242:243], v213 offset:0x2400
	ds_read_b64_tr_b16 v[244:245], v213 offset:0x2c00
	s_waitcnt lgkmcnt(6)
	v_mfma_f32_32x32x16_bf16 v[50:65], v[230:233], v[246:249], v[50:65]
	ds_read_b64_tr_b16 v[246:247], v213 offset:0x3400
	ds_read_b64_tr_b16 v[248:249], v213 offset:0x3c00
	s_waitcnt lgkmcnt(6)
	v_mfma_f32_32x32x16_bf16 v[34:49], v[162:165], v[234:237], v[34:49]
	ds_read_b64_tr_b16 v[234:235], v213 offset:0x600
	ds_read_b64_tr_b16 v[236:237], v213 offset:0xe00
	s_waitcnt lgkmcnt(6)
	v_mfma_f32_32x32x16_bf16 v[34:49], v[166:169], v[238:241], v[34:49]
	ds_read_b64_tr_b16 v[238:239], v213 offset:0x1600
	ds_read_b64_tr_b16 v[240:241], v213 offset:0x1e00
	s_waitcnt lgkmcnt(6)
	v_mfma_f32_32x32x16_bf16 v[34:49], v[172:175], v[242:245], v[34:49]
	ds_read_b64_tr_b16 v[242:243], v213 offset:0x2600
	ds_read_b64_tr_b16 v[244:245], v213 offset:0x2e00
	s_waitcnt lgkmcnt(6)
	v_mfma_f32_32x32x16_bf16 v[34:49], v[230:233], v[246:249], v[34:49]
	ds_read_b64_tr_b16 v[246:247], v213 offset:0x3600
	ds_read_b64_tr_b16 v[248:249], v213 offset:0x3e00
	s_waitcnt lgkmcnt(6)
	v_mfma_f32_32x32x16_bf16 v[18:33], v[162:165], v[234:237], v[18:33]
	v_max_f32_e32 v162, v83, v83
	v_max_f32_e32 v163, v82, v82
	v_max_f32_e32 v162, v163, v162
	v_max3_f32 v162, v162, v84, v85
	v_max3_f32 v162, v162, v86, v87
	v_max3_f32 v162, v162, v88, v89
	v_max3_f32 v162, v162, v90, v91
	v_max3_f32 v162, v162, v92, v93
	v_max3_f32 v162, v162, v94, v95
	s_waitcnt lgkmcnt(4)
	v_mfma_f32_32x32x16_bf16 v[18:33], v[166:169], v[238:241], v[18:33]
	v_max3_f32 v162, v162, v96, v97
	v_max3_f32 v162, v162, v66, v67
	v_max3_f32 v162, v162, v68, v69
	v_max3_f32 v162, v162, v70, v71
	v_max3_f32 v162, v162, v72, v73
	v_max3_f32 v162, v162, v74, v75
	v_max3_f32 v162, v162, v76, v77
	v_max3_f32 v162, v162, v78, v79
	s_waitcnt lgkmcnt(2)
	v_mfma_f32_32x32x16_bf16 v[18:33], v[172:175], v[242:245], v[18:33]
	v_max3_f32 v162, v162, v80, v81
	v_mov_b32_e32 v163, v162
	s_nop 1
	v_permlane32_swap_b32_e32 v162, v163
	v_max_f32_e32 v163, v163, v163
	v_max_f32_e32 v162, v162, v162
	v_max_f32_e32 v162, v162, v163
	v_sub_f32_e32 v163, v162, v170
	v_cmp_ge_f32_e32 vcc, s63, v163
	v_max_f32_e32 v163, v170, v170
	v_max_f32_e32 v162, v163, v162
	s_waitcnt lgkmcnt(0)
	v_mfma_f32_32x32x16_bf16 v[18:33], v[230:233], v[246:249], v[18:33]
	v_sub_f32_e32 v163, v170, v162
	v_mul_f32_e32 v163, 0x3e0293ee, v163
	v_exp_f32_e32 v163, v163
	s_cmp_eq_u64 vcc, exec
	s_cselect_b64 s[8:9], -1, 0
	s_waitcnt vmcnt(4)
	v_cndmask_b32_e64 v229, v163, 1.0, s[8:9]
	v_cmp_gt_f32_e32 vcc, 1.0, v229
	s_cbranch_vccz .LBB0_1047
	s_and_saveexec_b64 s[2:3], s[6:7]
	ds_write_b32 v210, v229 offset:128
	s_or_b64 exec, exec, s[2:3]
	s_waitcnt lgkmcnt(0)
	v_add_u32_e32 v163, s15, v209
	ds_read_b128 v[164:167], v163 offset:224
	ds_read_b128 v[172:175], v163 offset:192
	ds_read_b128 v[230:233], v163 offset:160
	ds_read_b128 v[234:237], v163 offset:128
	s_waitcnt lgkmcnt(3)
	v_pk_mul_f32 v[14:15], v[14:15], v[164:165]
	s_waitcnt lgkmcnt(2)
	v_pk_mul_f32 v[10:11], v[10:11], v[172:173]
	s_waitcnt lgkmcnt(1)
	v_pk_mul_f32 v[6:7], v[6:7], v[230:231]
	v_pk_mul_f32 v[16:17], v[16:17], v[166:167]
	v_pk_mul_f32 v[12:13], v[12:13], v[174:175]
	v_pk_mul_f32 v[8:9], v[8:9], v[232:233]
	s_waitcnt lgkmcnt(0)
	v_pk_mul_f32 v[4:5], v[4:5], v[236:237]
	v_pk_mul_f32 v[2:3], v[2:3], v[234:235]
	v_pk_mul_f32 v[62:63], v[62:63], v[164:165]
	v_pk_mul_f32 v[58:59], v[58:59], v[172:173]
	v_pk_mul_f32 v[54:55], v[54:55], v[230:231]
	v_pk_mul_f32 v[64:65], v[64:65], v[166:167]
	v_pk_mul_f32 v[60:61], v[60:61], v[174:175]
	v_pk_mul_f32 v[56:57], v[56:57], v[232:233]
	v_pk_mul_f32 v[52:53], v[52:53], v[236:237]
	v_pk_mul_f32 v[50:51], v[50:51], v[234:235]
	v_pk_mul_f32 v[46:47], v[46:47], v[164:165]
	v_pk_mul_f32 v[42:43], v[42:43], v[172:173]
	v_pk_mul_f32 v[38:39], v[38:39], v[230:231]
	v_pk_mul_f32 v[48:49], v[48:49], v[166:167]
	v_pk_mul_f32 v[44:45], v[44:45], v[174:175]
	v_pk_mul_f32 v[40:41], v[40:41], v[232:233]
	v_pk_mul_f32 v[36:37], v[36:37], v[236:237]
	v_pk_mul_f32 v[34:35], v[34:35], v[234:235]
	v_pk_mul_f32 v[30:31], v[30:31], v[164:165]
	v_pk_mul_f32 v[26:27], v[26:27], v[172:173]
	v_pk_mul_f32 v[22:23], v[22:23], v[230:231]
	v_pk_mul_f32 v[32:33], v[32:33], v[166:167]
	v_pk_mul_f32 v[28:29], v[28:29], v[174:175]
	v_pk_mul_f32 v[24:25], v[24:25], v[232:233]
	v_pk_mul_f32 v[20:21], v[20:21], v[236:237]
	v_pk_mul_f32 v[18:19], v[18:19], v[234:235]
; #define SBAR() __builtin_amdgcn_sched_barrier(0)
; #define SLOAD(i, k0) do { sr_[i].vs0 = ld8(&Vh[(long)((k0) + sr) * LDV + sc]); sr_[i].vs1 = ld8(&Vh[(long)((k0) + 32 + sr) * LDV + sc]); \
;     sr_[i].ks0 = ld8(&Kh[(long)((k0) + sr) * LDK + sc]); sr_[i].ks1 = ld8(&Kh[(long)((k0) + 32 + sr) * LDK + sc]); } while (0)
; __device__ __forceinline__ void partialSM(f32x16& p0, f32x16& p1, float& m_reg, float& mn, float& alpha) {
;     ...
;   float mnC = -mn * C;
; #pragma unroll
;   for (int r = 0; r < 16; ++r) p0[r] = fmaf(p0[r], C, mnC);
; #pragma unroll
;   for (int r = 0; r < 16; ++r) p1[r] = fmaf(p1[r], C, mnC);
; #pragma unroll
;   for (int r = 0; r < 16; ++r) p0[r] = __builtin_amdgcn_exp2f(p0[r]);
; }
; __device__ __forceinline__ void finishSM(f32x16& p0, f32x16& p1, float alpha, float& l_reg, bf16x8& pa0, bf16x8& pa1, bf16x8& pa2, bf16x8& pa3) {
; #pragma unroll
;   for (int r = 0; r < 16; ++r) p1[r] = __builtin_amdgcn_exp2f(p1[r]);
;   float ps = 0;
; #pragma unroll
;   for (int r = 0; r < 16; ++r) ps += p0[r];
; #pragma unroll
;   for (int r = 0; r < 16; ++r) ps += p1[r];
;   { auto rr = __builtin_amdgcn_permlane32_swap(__float_as_uint(ps), __float_as_uint(ps), false, false);
;     ps = __uint_as_float(rr[0]) + __uint_as_float(rr[1]); }
;   l_reg = l_reg * alpha + ps;
;   PK4(p0, 0, pa0); PK4(p0, 8, pa1); PK4(p1, 0, pa2); PK4(p1, 8, pa3);
; }
;   p0 = f32x16{}; p1 = f32x16{};
; #pragma unroll
;   for (int d0 = DLO; d0 < DHI; ++d0) { int cb = (d0 * 16 + hi * 8) * 2;
;     bf16x8 b0 = *reinterpret_cast<const bf16x8*>((const char*)Ks + KSWZ(r32, cb));
;     bf16x8 b1 = *reinterpret_cast<const bf16x8*>((const char*)Ks + KSWZ(32 + r32, cb));
;     p0 = __builtin_amdgcn_mfma_f32_32x32x16_bf16(b0, qr[d0], p0, 0, 0, 0);
;     p1 = __builtin_amdgcn_mfma_f32_32x32x16_bf16(b1, qr[d0], p1, 0, 0, 0); }
; }
; template <int DLO, int DHI>
; __device__ __forceinline__ void attn_dense_body(const int g_wave, const bf16* __restrict__ Qb, const bf16* __restrict__ Kh, const bf16* __restrict__ Vh,
;                                                 bf16* __restrict__ Ob, int ldo, char* lds) {
;     ...
;     __syncthreads(); SWAIT(); SWRITE(0, SE);
;     RESC(alB); __syncthreads();
;     SBAR(); qkt<DLO, DHI>(pA0, pA1, K_lds, qr, r32, hi);
;     finishSM(pB0, pB1, alB, l_reg, pa0, pa1, pa2, pa3); SBAR();
;     if (j + 3 < NT) SLOAD(SE, (j + 3) * KVBLK); SBAR();
.LBB0_1047:
	v_cndmask_b32_e64 v230, v162, v170, s[8:9]
	v_mul_f32_e32 v231, 0xbe0293ee, v230
	v_fmamk_f32 v82, v82, 0x3e0293ee, v231
	v_fmamk_f32 v83, v83, 0x3e0293ee, v231
	v_fmamk_f32 v84, v84, 0x3e0293ee, v231
	v_fmamk_f32 v85, v85, 0x3e0293ee, v231
	v_fmamk_f32 v86, v86, 0x3e0293ee, v231
	v_fmamk_f32 v87, v87, 0x3e0293ee, v231
	v_fmamk_f32 v88, v88, 0x3e0293ee, v231
	v_fmamk_f32 v89, v89, 0x3e0293ee, v231
	v_fmamk_f32 v90, v90, 0x3e0293ee, v231
	v_fmamk_f32 v91, v91, 0x3e0293ee, v231
	v_fmamk_f32 v92, v92, 0x3e0293ee, v231
	v_fmamk_f32 v93, v93, 0x3e0293ee, v231
	v_fmamk_f32 v94, v94, 0x3e0293ee, v231
	v_fmamk_f32 v95, v95, 0x3e0293ee, v231
	v_fmamk_f32 v96, v96, 0x3e0293ee, v231
	v_fmamk_f32 v97, v97, 0x3e0293ee, v231
	v_exp_f32_e32 v162, v82
	v_exp_f32_e32 v177, v83
	v_exp_f32_e32 v163, v84
	v_exp_f32_e32 v176, v85
	v_exp_f32_e32 v164, v86
	v_exp_f32_e32 v175, v87
	v_exp_f32_e32 v165, v88
	v_exp_f32_e32 v174, v89
	v_exp_f32_e32 v166, v90
	v_exp_f32_e32 v173, v91
	v_exp_f32_e32 v167, v92
	v_exp_f32_e32 v172, v93
	v_exp_f32_e32 v168, v94
	v_exp_f32_e32 v171, v95
	v_exp_f32_e32 v169, v96
	v_exp_f32_e32 v170, v97
	v_fmamk_f32 v240, v66, 0x3e0293ee, v231
	v_fmamk_f32 v241, v67, 0x3e0293ee, v231
	v_fmamk_f32 v242, v68, 0x3e0293ee, v231
	v_fmamk_f32 v243, v69, 0x3e0293ee, v231
	v_fmamk_f32 v244, v70, 0x3e0293ee, v231
	v_fmamk_f32 v233, v71, 0x3e0293ee, v231
	v_fmamk_f32 v234, v72, 0x3e0293ee, v231
	v_fmamk_f32 v235, v73, 0x3e0293ee, v231
	v_fmamk_f32 v236, v74, 0x3e0293ee, v231
	v_fmamk_f32 v237, v75, 0x3e0293ee, v231
	v_fmamk_f32 v238, v76, 0x3e0293ee, v231
	v_fmamk_f32 v239, v77, 0x3e0293ee, v231
	v_fmamk_f32 v232, v78, 0x3e0293ee, v231
	v_fmamk_f32 v245, v79, 0x3e0293ee, v231
	v_fmamk_f32 v246, v80, 0x3e0293ee, v231
	v_fmac_f32_e32 v231, 0x3e0293ee, v81
	s_waitcnt lgkmcnt(0)
	s_barrier
	v_xor_b32_e32 v218, 0x10000, v218
	v_xor_b32_e32 v225, 0x10000, v225
	v_xor_b32_e32 v224, 0x10000, v224
	v_xor_b32_e32 v222, 0x10000, v222
	v_xor_b32_e32 v220, 0x10000, v220
	v_xor_b32_e32 v219, 0x10000, v219
	v_xor_b32_e32 v221, 0x10000, v221
	v_xor_b32_e32 v223, 0x10000, v223
	ds_read_b128 v[66:69], v218 offset:32768
	ds_read_b128 v[70:73], v218 offset:40960
	ds_read_b128 v[248:251], v225 offset:32768
	ds_read_b128 v[186:189], v225 offset:40960
	v_exp_f32_e32 v233, v233
	v_exp_f32_e32 v234, v234
	s_waitcnt lgkmcnt(3)
	v_mfma_f32_32x32x16_bf16 v[82:97], v[66:69], v[118:121], 0
	v_exp_f32_e32 v235, v235
	v_exp_f32_e32 v236, v236
	v_exp_f32_e32 v237, v237
	v_exp_f32_e32 v238, v238
	v_exp_f32_e32 v239, v239
	s_waitcnt lgkmcnt(2)
	v_mfma_f32_32x32x16_bf16 v[66:81], v[70:73], v[118:121], 0
	s_waitcnt lgkmcnt(1)
	v_mfma_f32_32x32x16_bf16 v[82:97], v[248:251], v[110:113], v[82:97]
	s_waitcnt lgkmcnt(0)
	v_mfma_f32_32x32x16_bf16 v[66:81], v[186:189], v[110:113], v[66:81]
	ds_read_b128 v[186:189], v224 offset:32768
	ds_read_b128 v[248:251], v224 offset:40960
	s_waitcnt lgkmcnt(1)
	v_mfma_f32_32x32x16_bf16 v[82:97], v[186:189], v[126:129], v[82:97]
	s_waitcnt lgkmcnt(0)
	v_mfma_f32_32x32x16_bf16 v[66:81], v[248:251], v[126:129], v[66:81]
	ds_read_b128 v[186:189], v222 offset:32768
	ds_read_b128 v[248:251], v222 offset:40960
	s_waitcnt lgkmcnt(1)
	v_mfma_f32_32x32x16_bf16 v[82:97], v[186:189], v[122:125], v[82:97]
	s_waitcnt lgkmcnt(0)
	v_mfma_f32_32x32x16_bf16 v[66:81], v[248:251], v[122:125], v[66:81]
	ds_read_b128 v[186:189], v220 offset:32768
	ds_read_b128 v[248:251], v220 offset:40960
	s_waitcnt lgkmcnt(1)
	v_mfma_f32_32x32x16_bf16 v[82:97], v[186:189], v[114:117], v[82:97]
	s_waitcnt lgkmcnt(0)
	v_mfma_f32_32x32x16_bf16 v[66:81], v[248:251], v[114:117], v[66:81]
	ds_read_b128 v[186:189], v219 offset:32768
	ds_read_b128 v[248:251], v219 offset:40960
	s_waitcnt lgkmcnt(1)
	v_mfma_f32_32x32x16_bf16 v[82:97], v[186:189], v[106:109], v[82:97]
	s_waitcnt lgkmcnt(0)
	v_mfma_f32_32x32x16_bf16 v[66:81], v[248:251], v[106:109], v[66:81]
	ds_read_b128 v[186:189], v221 offset:32768
	ds_read_b128 v[248:251], v221 offset:40960
	s_waitcnt lgkmcnt(1)
	v_mfma_f32_32x32x16_bf16 v[82:97], v[186:189], v[102:105], v[82:97]
	s_waitcnt lgkmcnt(0)
	v_mfma_f32_32x32x16_bf16 v[66:81], v[248:251], v[102:105], v[66:81]
	ds_read_b128 v[186:189], v223 offset:32768
	ds_read_b128 v[248:251], v223 offset:40960
	s_waitcnt lgkmcnt(1)
	v_mfma_f32_32x32x16_bf16 v[82:97], v[186:189], v[98:101], v[82:97]
	v_exp_f32_e32 v186, v240
	v_exp_f32_e32 v240, v244
	v_exp_f32_e32 v244, v231
	v_add_f32_e32 v231, 0, v162
	v_add_f32_e32 v231, v177, v231
	v_add_f32_e32 v231, v163, v231
	v_add_f32_e32 v231, v176, v231
	v_add_f32_e32 v231, v164, v231
	v_add_f32_e32 v231, v175, v231
	v_add_f32_e32 v231, v165, v231
	v_add_f32_e32 v231, v174, v231
	v_add_f32_e32 v231, v166, v231
	v_add_f32_e32 v231, v173, v231
	v_add_f32_e32 v231, v167, v231
	v_add_f32_e32 v231, v172, v231
	v_add_f32_e32 v231, v168, v231
	v_exp_f32_e32 v187, v241
	v_add_f32_e32 v231, v171, v231
	v_exp_f32_e32 v188, v242
	v_add_f32_e32 v231, v169, v231
	v_exp_f32_e32 v189, v243
	v_add_f32_e32 v231, v170, v231
	v_add_f32_e32 v231, v186, v231
	v_add_f32_e32 v231, v187, v231
	v_add_f32_e32 v231, v188, v231
	v_add_f32_e32 v231, v189, v231
	v_add_f32_e32 v231, v240, v231
	v_add_f32_e32 v231, v233, v231
	v_add_f32_e32 v231, v234, v231
	v_add_f32_e32 v231, v235, v231
	v_exp_f32_e32 v241, v232
	v_add_f32_e32 v231, v236, v231
	v_exp_f32_e32 v242, v245
	v_add_f32_e32 v231, v237, v231
	s_waitcnt lgkmcnt(0)
	v_mfma_f32_32x32x16_bf16 v[66:81], v[248:251], v[98:101], v[66:81]
	v_exp_f32_e32 v243, v246
	v_add_f32_e32 v231, v238, v231
	v_add_f32_e32 v231, v239, v231
	v_add_f32_e32 v231, v241, v231
	v_add_f32_e32 v231, v242, v231
	v_add_f32_e32 v231, v243, v231
	v_add_f32_e32 v231, v244, v231
	v_mov_b32_e32 v232, v231
	v_cvt_pk_bf16_f32 v162, v162, v177
	v_cvt_pk_bf16_f32 v163, v163, v176
	v_cvt_pk_bf16_f32 v164, v164, v175
	v_cvt_pk_bf16_f32 v165, v165, v174
	v_cvt_pk_bf16_f32 v166, v166, v173
	v_cvt_pk_bf16_f32 v167, v167, v172
	v_cvt_pk_bf16_f32 v168, v168, v171
	v_cvt_pk_bf16_f32 v169, v169, v170
	v_cvt_pk_bf16_f32 v170, v186, v187
	v_cvt_pk_bf16_f32 v171, v188, v189
	v_cvt_pk_bf16_f32 v172, v240, v233
	v_cvt_pk_bf16_f32 v173, v234, v235
	v_cvt_pk_bf16_f32 v174, v236, v237
	v_cvt_pk_bf16_f32 v175, v238, v239
	v_cvt_pk_bf16_f32 v176, v241, v242
	v_cvt_pk_bf16_f32 v177, v243, v244
	s_nop 1
	v_permlane32_swap_b32_e32 v231, v232
	v_permlane32_swap_b32_e32 v162, v164
	v_permlane32_swap_b32_e32 v163, v165
	v_permlane32_swap_b32_e32 v166, v168
	v_permlane32_swap_b32_e32 v167, v169
	v_permlane32_swap_b32_e32 v170, v172
	v_permlane32_swap_b32_e32 v171, v173
	v_permlane32_swap_b32_e32 v174, v176
	v_permlane32_swap_b32_e32 v175, v177
	s_waitcnt vmcnt(0)
	ds_write_b128 v216, v[146:149] offset:16384
	ds_write_b128 v217, v[150:153] offset:16384
	ds_write_b128 v214, v[154:157] offset:49152
	ds_write_b128 v215, v[158:161] offset:49152
	s_cmp_gt_u32 s34, 60
	s_cselect_b64 s[2:3], -1, 0
	s_and_b64 vcc, exec, s[2:3]
	s_cbranch_vccnz .LBB0_1049
; #define SBAR() __builtin_amdgcn_sched_barrier(0)
; #define SLOAD(i, k0) do { sr_[i].vs0 = ld8(&Vh[(long)((k0) + sr) * LDV + sc]); sr_[i].vs1 = ld8(&Vh[(long)((k0) + 32 + sr) * LDV + sc]); \
;     sr_[i].ks0 = ld8(&Kh[(long)((k0) + sr) * LDK + sc]); sr_[i].ks1 = ld8(&Kh[(long)((k0) + 32 + sr) * LDK + sc]); } while (0)
; #define SWRITE(b, i) do { *(bf16x8*)((char*)V_lds + (b) * SHM_V + vst0) = sr_[i].vs0;          \
;     *(bf16x8*)((char*)V_lds + (b) * SHM_V + vst1) = sr_[i].vs1; int kc = sc * 2;               \
;     *(bf16x8*)((char*)K_lds + (b) * SHM_K + KSWZ(sr, kc)) = sr_[i].ks0;                       \
;     *(bf16x8*)((char*)K_lds + (b) * SHM_K + KSWZ(32 + sr, kc)) = sr_[i].ks1; } while (0)
; template <int D0> __device__ __forceinline__ void pv_one(f32x16& od, int vb, bf16x8 pa0, bf16x8 pa1, bf16x8 pa2, bf16x8 pa3) {
;   const s16x4 l0 = tr_read<v_rd_off(D0, 0, 0)>(vb), h0 = tr_read<v_rd_off(D0, 0, 1)>(vb), l1 = tr_read<v_rd_off(D0, 1, 0)>(vb), h1 = tr_read<v_rd_off(D0, 1, 1)>(vb);
;   const s16x4 l2 = tr_read<v_rd_off(D0, 2, 0)>(vb), h2 = tr_read<v_rd_off(D0, 2, 1)>(vb), l3 = tr_read<v_rd_off(D0, 3, 0)>(vb), h3 = tr_read<v_rd_off(D0, 3, 1)>(vb);
;   asm volatile("s_waitcnt lgkmcnt(0)" ::: "memory"); SBAR();
;     ...
;   od = __builtin_amdgcn_mfma_f32_32x32x16_bf16(pa0, PK(l0, h0), od, 0, 0, 0);
;   od = __builtin_amdgcn_mfma_f32_32x32x16_bf16(pa1, PK(l1, h1), od, 0, 0, 0);
;   od = __builtin_amdgcn_mfma_f32_32x32x16_bf16(pa2, PK(l2, h2), od, 0, 0, 0);
;   od = __builtin_amdgcn_mfma_f32_32x32x16_bf16(pa3, PK(l3, h3), od, 0, 0, 0);
;     ...
; }
; __device__ __forceinline__ void pv_d0(f32x16* o, int vb, bf16x8 pa0, bf16x8 pa1, bf16x8 pa2, bf16x8 pa3) {
;   pv_one<0>(o[0], vb, pa0, pa1, pa2, pa3); pv_one<1>(o[1], vb, pa0, pa1, pa2, pa3); pv_one<2>(o[2], vb, pa0, pa1, pa2, pa3); pv_one<3>(o[3], vb, pa0, pa1, pa2, pa3);
; }
; template <int DLO, int DHI>
; __device__ __forceinline__ void attn_dense_body(const int g_wave, const bf16* __restrict__ Qb, const bf16* __restrict__ Kh, const bf16* __restrict__ Vh,
;                                                 bf16* __restrict__ Ob, int ldo, char* lds) {
;     ...
;     if (j + 3 < NT) SLOAD(SE, (j + 3) * KVBLK); SBAR();
;     pv_d0(o, vb0 + (int)SHM_V, pa0, pa1, pa2, pa3); partialSM(pA0, pA1, m_reg, mnA, alA);
;     __syncthreads(); SWAIT(); SWRITE(1, SO);
;     RESC(alA); __syncthreads();
	v_add_co_u32_e32 v130, vcc, 0x19040000, v196
	s_nop 1
	v_addc_co_u32_e32 v131, vcc, 0, v197, vcc
	v_add_co_u32_e32 v134, vcc, 0x19088000, v196
	s_nop 1
	v_addc_co_u32_e32 v135, vcc, 0, v197, vcc
	v_add_co_u32_e32 v138, vcc, 0x1f660000, v194
	global_load_dwordx4 v[130:133], v[130:131], off
	s_nop 0
	global_load_dwordx4 v[134:137], v[134:135], off
	v_addc_co_u32_e32 v139, vcc, 0, v195, vcc
	v_add_co_u32_e32 v142, vcc, 0x1f66c000, v194
	s_nop 1
	v_addc_co_u32_e32 v143, vcc, 0, v195, vcc
	global_load_dwordx4 v[138:141], v[138:139], off
	s_nop 0
	global_load_dwordx4 v[142:145], v[142:143], off
.LBB0_1049:
	ds_read_b64_tr_b16 v[186:187], v212 offset:0
	ds_read_b64_tr_b16 v[188:189], v212 offset:0x800
	ds_read_b64_tr_b16 v[194:195], v212 offset:0x1000
	ds_read_b64_tr_b16 v[196:197], v212 offset:0x1800
	ds_read_b64_tr_b16 v[234:235], v212 offset:0x2000
	ds_read_b64_tr_b16 v[236:237], v212 offset:0x2800
	ds_read_b64_tr_b16 v[238:239], v212 offset:0x3000
	ds_read_b64_tr_b16 v[240:241], v212 offset:0x3800
	s_waitcnt lgkmcnt(6)
	s_nop 0
	v_mfma_f32_32x32x16_bf16 v[2:17], v[162:165], v[186:189], v[2:17]
	ds_read_b64_tr_b16 v[186:187], v212 offset:0x200
	ds_read_b64_tr_b16 v[188:189], v212 offset:0xa00
	s_waitcnt lgkmcnt(6)
	v_mfma_f32_32x32x16_bf16 v[2:17], v[166:169], v[194:197], v[2:17]
	ds_read_b64_tr_b16 v[194:195], v212 offset:0x1200
	ds_read_b64_tr_b16 v[196:197], v212 offset:0x1a00
	s_waitcnt lgkmcnt(6)
	v_mfma_f32_32x32x16_bf16 v[2:17], v[170:173], v[234:237], v[2:17]
	ds_read_b64_tr_b16 v[234:235], v212 offset:0x2200
	ds_read_b64_tr_b16 v[236:237], v212 offset:0x2a00
	s_waitcnt lgkmcnt(6)
	v_mfma_f32_32x32x16_bf16 v[2:17], v[174:177], v[238:241], v[2:17]
	ds_read_b64_tr_b16 v[238:239], v212 offset:0x3200
	ds_read_b64_tr_b16 v[240:241], v212 offset:0x3a00
	s_waitcnt lgkmcnt(6)
	v_mfma_f32_32x32x16_bf16 v[50:65], v[162:165], v[186:189], v[50:65]
	ds_read_b64_tr_b16 v[186:187], v212 offset:0x400
	ds_read_b64_tr_b16 v[188:189], v212 offset:0xc00
	s_waitcnt lgkmcnt(6)
	v_mfma_f32_32x32x16_bf16 v[50:65], v[166:169], v[194:197], v[50:65]
	ds_read_b64_tr_b16 v[194:195], v212 offset:0x1400
	ds_read_b64_tr_b16 v[196:197], v212 offset:0x1c00
	s_waitcnt lgkmcnt(6)
	v_mfma_f32_32x32x16_bf16 v[50:65], v[170:173], v[234:237], v[50:65]
	ds_read_b64_tr_b16 v[234:235], v212 offset:0x2400
	ds_read_b64_tr_b16 v[236:237], v212 offset:0x2c00
	s_waitcnt lgkmcnt(6)
	v_mfma_f32_32x32x16_bf16 v[50:65], v[174:177], v[238:241], v[50:65]
	ds_read_b64_tr_b16 v[238:239], v212 offset:0x3400
	ds_read_b64_tr_b16 v[240:241], v212 offset:0x3c00
	s_waitcnt lgkmcnt(6)
	v_mfma_f32_32x32x16_bf16 v[34:49], v[162:165], v[186:189], v[34:49]
	ds_read_b64_tr_b16 v[186:187], v212 offset:0x600
	ds_read_b64_tr_b16 v[188:189], v212 offset:0xe00
	s_waitcnt lgkmcnt(6)
	v_mfma_f32_32x32x16_bf16 v[34:49], v[166:169], v[194:197], v[34:49]
	ds_read_b64_tr_b16 v[194:195], v212 offset:0x1600
	ds_read_b64_tr_b16 v[196:197], v212 offset:0x1e00
	s_waitcnt lgkmcnt(6)
	v_mfma_f32_32x32x16_bf16 v[34:49], v[170:173], v[234:237], v[34:49]
	ds_read_b64_tr_b16 v[234:235], v212 offset:0x2600
	ds_read_b64_tr_b16 v[236:237], v212 offset:0x2e00
	s_waitcnt lgkmcnt(6)
	v_mfma_f32_32x32x16_bf16 v[34:49], v[174:177], v[238:241], v[34:49]
	ds_read_b64_tr_b16 v[238:239], v212 offset:0x3600
	ds_read_b64_tr_b16 v[240:241], v212 offset:0x3e00
	s_waitcnt lgkmcnt(6)
	v_mfma_f32_32x32x16_bf16 v[18:33], v[162:165], v[186:189], v[18:33]
	v_max_f32_e32 v162, v83, v83
	v_max_f32_e32 v163, v82, v82
	v_max_f32_e32 v162, v163, v162
	v_max3_f32 v162, v162, v84, v85
	v_max3_f32 v162, v162, v86, v87
	v_max3_f32 v162, v162, v88, v89
	v_max3_f32 v162, v162, v90, v91
	v_max3_f32 v162, v162, v92, v93
	v_max3_f32 v162, v162, v94, v95
	s_waitcnt lgkmcnt(4)
	v_mfma_f32_32x32x16_bf16 v[18:33], v[166:169], v[194:197], v[18:33]
	v_max3_f32 v162, v162, v96, v97
	v_max3_f32 v162, v162, v66, v67
	v_max3_f32 v162, v162, v68, v69
	v_max3_f32 v162, v162, v70, v71
	v_max3_f32 v162, v162, v72, v73
	v_max3_f32 v162, v162, v74, v75
	v_max3_f32 v162, v162, v76, v77
	v_max3_f32 v162, v162, v78, v79
	s_waitcnt lgkmcnt(2)
	v_mfma_f32_32x32x16_bf16 v[18:33], v[170:173], v[234:237], v[18:33]
	v_max3_f32 v162, v162, v80, v81
	v_mov_b32_e32 v163, v162
	s_nop 1
	v_permlane32_swap_b32_e32 v162, v163
	v_max_f32_e32 v163, v163, v163
	v_max_f32_e32 v162, v162, v162
	v_max_f32_e32 v162, v162, v163
	v_sub_f32_e32 v163, v162, v230
	v_cmp_ge_f32_e32 vcc, s63, v163
	v_max_f32_e32 v163, v230, v230
	v_max_f32_e32 v163, v163, v162
	s_waitcnt lgkmcnt(0)
	v_mfma_f32_32x32x16_bf16 v[18:33], v[174:177], v[238:241], v[18:33]
	v_sub_f32_e32 v162, v230, v163
	v_mul_f32_e32 v162, 0x3e0293ee, v162
	v_exp_f32_e32 v162, v162
	s_cmp_eq_u64 vcc, exec
	s_cselect_b64 s[8:9], -1, 0
	s_waitcnt vmcnt(4)
	v_cndmask_b32_e64 v162, v162, 1.0, s[8:9]
	v_cmp_gt_f32_e32 vcc, 1.0, v162
	s_cbranch_vccz .LBB0_1053
	s_and_saveexec_b64 s[4:5], s[6:7]
	ds_write_b32 v210, v162 offset:128
	s_or_b64 exec, exec, s[4:5]
	s_waitcnt lgkmcnt(0)
	v_add_u32_e32 v158, s15, v209
	ds_read_b128 v[146:149], v158 offset:224
	ds_read_b128 v[150:153], v158 offset:192
	ds_read_b128 v[154:157], v158 offset:160
	ds_read_b128 v[158:161], v158 offset:128
	s_waitcnt lgkmcnt(3)
	v_pk_mul_f32 v[14:15], v[14:15], v[146:147]
	s_waitcnt lgkmcnt(2)
	v_pk_mul_f32 v[10:11], v[10:11], v[150:151]
	s_waitcnt lgkmcnt(1)
	v_pk_mul_f32 v[6:7], v[6:7], v[154:155]
	v_pk_mul_f32 v[16:17], v[16:17], v[148:149]
	v_pk_mul_f32 v[12:13], v[12:13], v[152:153]
	v_pk_mul_f32 v[8:9], v[8:9], v[156:157]
	s_waitcnt lgkmcnt(0)
	v_pk_mul_f32 v[4:5], v[4:5], v[160:161]
	v_pk_mul_f32 v[2:3], v[2:3], v[158:159]
	v_pk_mul_f32 v[62:63], v[62:63], v[146:147]
	v_pk_mul_f32 v[58:59], v[58:59], v[150:151]
	v_pk_mul_f32 v[54:55], v[54:55], v[154:155]
	v_pk_mul_f32 v[64:65], v[64:65], v[148:149]
	v_pk_mul_f32 v[60:61], v[60:61], v[152:153]
	v_pk_mul_f32 v[56:57], v[56:57], v[156:157]
	v_pk_mul_f32 v[52:53], v[52:53], v[160:161]
	v_pk_mul_f32 v[50:51], v[50:51], v[158:159]
	v_pk_mul_f32 v[46:47], v[46:47], v[146:147]
	v_pk_mul_f32 v[42:43], v[42:43], v[150:151]
	v_pk_mul_f32 v[38:39], v[38:39], v[154:155]
	v_pk_mul_f32 v[48:49], v[48:49], v[148:149]
	v_pk_mul_f32 v[44:45], v[44:45], v[152:153]
	v_pk_mul_f32 v[40:41], v[40:41], v[156:157]
	v_pk_mul_f32 v[36:37], v[36:37], v[160:161]
	v_pk_mul_f32 v[34:35], v[34:35], v[158:159]
	v_pk_mul_f32 v[30:31], v[30:31], v[146:147]
	v_pk_mul_f32 v[26:27], v[26:27], v[150:151]
	v_pk_mul_f32 v[22:23], v[22:23], v[154:155]
	v_pk_mul_f32 v[32:33], v[32:33], v[148:149]
	v_pk_mul_f32 v[28:29], v[28:29], v[152:153]
	v_pk_mul_f32 v[24:25], v[24:25], v[156:157]
	v_pk_mul_f32 v[20:21], v[20:21], v[160:161]
	v_pk_mul_f32 v[18:19], v[18:19], v[158:159]
; #define SBAR() __builtin_amdgcn_sched_barrier(0)
; #define RESC(a) do { if (__any((a) < 1.f)) { if (hi == 0) al_l[r32] = (a); asm volatile("s_waitcnt lgkmcnt(0)" ::: "memory"); \
;     _Pragma("unroll") for (int d = 0; d < 4; ++d) _Pragma("unroll") for (int r = 0; r < 16; ++r) o[d][r] *= al_l[crow(r, hi)]; } } while (0)
; __device__ __forceinline__ void partialSM(f32x16& p0, f32x16& p1, float& m_reg, float& mn, float& alpha) {
;     ...
;   float mnC = -mn * C;
; #pragma unroll
;   for (int r = 0; r < 16; ++r) p0[r] = fmaf(p0[r], C, mnC);
; #pragma unroll
;   for (int r = 0; r < 16; ++r) p1[r] = fmaf(p1[r], C, mnC);
; #pragma unroll
;   for (int r = 0; r < 16; ++r) p0[r] = __builtin_amdgcn_exp2f(p0[r]);
; }
; __device__ __forceinline__ void finishSM(f32x16& p0, f32x16& p1, float alpha, float& l_reg, bf16x8& pa0, bf16x8& pa1, bf16x8& pa2, bf16x8& pa3) {
; #pragma unroll
;   for (int r = 0; r < 16; ++r) p1[r] = __builtin_amdgcn_exp2f(p1[r]);
;   float ps = 0;
; #pragma unroll
;   for (int r = 0; r < 16; ++r) ps += p0[r];
; #pragma unroll
;   for (int r = 0; r < 16; ++r) ps += p1[r];
;   { auto rr = __builtin_amdgcn_permlane32_swap(__float_as_uint(ps), __float_as_uint(ps), false, false);
;     ps = __uint_as_float(rr[0]) + __uint_as_float(rr[1]); }
;   l_reg = l_reg * alpha + ps;
;   PK4(p0, 0, pa0); PK4(p0, 8, pa1); PK4(p1, 0, pa2); PK4(p1, 8, pa3);
; }
;   p0 = f32x16{}; p1 = f32x16{};
; #pragma unroll
;   for (int d0 = DLO; d0 < DHI; ++d0) { int cb = (d0 * 16 + hi * 8) * 2;
;     bf16x8 b0 = *reinterpret_cast<const bf16x8*>((const char*)Ks + KSWZ(r32, cb));
;     bf16x8 b1 = *reinterpret_cast<const bf16x8*>((const char*)Ks + KSWZ(32 + r32, cb));
;     p0 = __builtin_amdgcn_mfma_f32_32x32x16_bf16(b0, qr[d0], p0, 0, 0, 0);
;     p1 = __builtin_amdgcn_mfma_f32_32x32x16_bf16(b1, qr[d0], p1, 0, 0, 0); }
; }
; template <int DLO, int DHI>
; __device__ __forceinline__ void attn_dense_body(const int g_wave, const bf16* __restrict__ Qb, const bf16* __restrict__ Kh, const bf16* __restrict__ Vh,
;                                                 bf16* __restrict__ Ob, int ldo, char* lds) {
;     ...
;     RESC(alA); __syncthreads();
;   }
;   SBAR(); qkt<DLO, DHI>(pB0, pB1, (bf16*)((char*)K_lds + SHM_K), qr, r32, hi);
;   finishSM(pA0, pA1, alA, l_reg, pa0, pa1, pa2, pa3); SBAR();
.LBB0_1053:
	v_cndmask_b32_e64 v170, v163, v230, s[8:9]
	v_mul_f32_e32 v152, 0xbe0293ee, v170
	v_mov_b32_e32 v153, v152
	v_fmamk_f32 v82, v82, 0x3e0293ee, v152
	v_fmamk_f32 v83, v83, 0x3e0293ee, v152
	v_fmamk_f32 v84, v84, 0x3e0293ee, v152
	v_fmamk_f32 v85, v85, 0x3e0293ee, v152
	v_fmamk_f32 v86, v86, 0x3e0293ee, v152
	v_fmamk_f32 v87, v87, 0x3e0293ee, v152
	v_fmamk_f32 v88, v88, 0x3e0293ee, v152
	v_fmamk_f32 v89, v89, 0x3e0293ee, v152
	v_fmamk_f32 v90, v90, 0x3e0293ee, v152
	v_fmamk_f32 v91, v91, 0x3e0293ee, v152
	v_fmamk_f32 v92, v92, 0x3e0293ee, v152
	v_fmamk_f32 v93, v93, 0x3e0293ee, v152
	v_fmamk_f32 v94, v94, 0x3e0293ee, v152
	v_fmamk_f32 v95, v95, 0x3e0293ee, v152
	v_fmamk_f32 v96, v96, 0x3e0293ee, v152
	v_fmac_f32_e32 v153, 0x3e0293ee, v97
	v_exp_f32_e32 v177, v82
	v_exp_f32_e32 v195, v83
	v_exp_f32_e32 v163, v84
	v_exp_f32_e32 v194, v85
	v_exp_f32_e32 v164, v86
	v_exp_f32_e32 v176, v87
	v_exp_f32_e32 v165, v88
	v_exp_f32_e32 v175, v89
	v_exp_f32_e32 v166, v90
	v_exp_f32_e32 v174, v91
	v_exp_f32_e32 v167, v92
	v_exp_f32_e32 v173, v93
	v_exp_f32_e32 v168, v94
	v_exp_f32_e32 v172, v95
	v_exp_f32_e32 v169, v96
	v_exp_f32_e32 v171, v153
	v_pk_fma_f32 v[158:159], v[66:67], s[62:63], v[152:153] op_sel_hi:[1,0,0]
	v_add_f32_e32 v66, v227, v228
	s_mov_b64 s[4:5], 0x30000
	v_fmac_f32_e32 v66, v226, v211
	v_add_f32_e32 v211, v231, v232
	v_lshl_add_u64 v[190:191], v[190:191], 0, s[4:5]
	s_mov_b64 s[4:5], 0x120000
	v_pk_fma_f32 v[156:157], v[68:69], s[62:63], v[152:153] op_sel_hi:[1,0,0]
	v_pk_fma_f32 v[150:151], v[70:71], s[62:63], v[152:153] op_sel_hi:[1,0,0]
	v_pk_fma_f32 v[148:149], v[72:73], s[62:63], v[152:153] op_sel_hi:[1,0,0]
	v_pk_fma_f32 v[146:147], v[74:75], s[62:63], v[152:153] op_sel_hi:[1,0,0]
	v_pk_fma_f32 v[160:161], v[76:77], s[62:63], v[152:153] op_sel_hi:[1,0,0]
	v_pk_fma_f32 v[154:155], v[78:79], s[62:63], v[152:153] op_sel_hi:[1,0,0]
	v_pk_fma_f32 v[152:153], v[80:81], s[62:63], v[152:153] op_sel_hi:[1,0,0]
	v_fmac_f32_e32 v211, v66, v229
	s_add_i32 s34, s34, 2
	v_lshl_add_u64 v[192:193], v[192:193], 0, s[4:5]
	s_and_b64 vcc, exec, s[2:3]
	s_waitcnt lgkmcnt(0)
	s_barrier
	v_xor_b32_e32 v213, 0x10000, v213
	v_xor_b32_e32 v212, 0x10000, v212
	v_xor_b32_e32 v216, 0x10000, v216
	v_xor_b32_e32 v217, 0x10000, v217
	v_xor_b32_e32 v214, 0x10000, v214
	v_xor_b32_e32 v215, 0x10000, v215
	s_cbranch_vccnz .LBB0_1055
	v_mov_b32_e32 v226, v162
	s_branch .LBB0_1043
.LBB0_1055:
	ds_read_b128 v[66:69], v218 offset:49152
	ds_read_b128 v[70:73], v218 offset:57344
	v_add_f32_e32 v0, 0, v177
	v_add_f32_e32 v0, v195, v0
	v_add_f32_e32 v0, v163, v0
	s_waitcnt lgkmcnt(1)
	v_mfma_f32_32x32x16_bf16 v[82:97], v[66:69], v[118:121], 0
	v_add_f32_e32 v0, v194, v0
	v_add_f32_e32 v0, v164, v0
	v_add_f32_e32 v0, v176, v0
	v_add_f32_e32 v0, v165, v0
	v_add_f32_e32 v0, v175, v0
	v_add_f32_e32 v0, v166, v0
	v_add_f32_e32 v0, v174, v0
	s_waitcnt lgkmcnt(0)
	v_mfma_f32_32x32x16_bf16 v[66:81], v[70:73], v[118:121], 0
	ds_read_b128 v[118:121], v225 offset:49152
	ds_read_b128 v[130:133], v225 offset:57344
	v_add_f32_e32 v0, v167, v0
	v_add_f32_e32 v0, v173, v0
	v_add_f32_e32 v0, v168, v0
	v_add_f32_e32 v0, v172, v0
	v_add_f32_e32 v0, v169, v0
	v_add_f32_e32 v0, v171, v0
	s_waitcnt lgkmcnt(1)
	v_mfma_f32_32x32x16_bf16 v[82:97], v[118:121], v[110:113], v[82:97]
	s_waitcnt lgkmcnt(0)
	v_mfma_f32_32x32x16_bf16 v[66:81], v[130:133], v[110:113], v[66:81]
	ds_read_b128 v[110:113], v224 offset:49152
	ds_read_b128 v[118:121], v224 offset:57344
	s_waitcnt lgkmcnt(1)
	v_mfma_f32_32x32x16_bf16 v[82:97], v[110:113], v[126:129], v[82:97]
	s_waitcnt lgkmcnt(0)
	v_mfma_f32_32x32x16_bf16 v[66:81], v[118:121], v[126:129], v[66:81]
	ds_read_b128 v[110:113], v222 offset:49152
	ds_read_b128 v[118:121], v222 offset:57344
	s_waitcnt lgkmcnt(1)
	v_mfma_f32_32x32x16_bf16 v[82:97], v[110:113], v[122:125], v[82:97]
	s_waitcnt lgkmcnt(0)
	v_mfma_f32_32x32x16_bf16 v[66:81], v[118:121], v[122:125], v[66:81]
	ds_read_b128 v[110:113], v220 offset:49152
	ds_read_b128 v[118:121], v220 offset:57344
	v_exp_f32_e32 v122, v153
	s_waitcnt lgkmcnt(1)
	v_mfma_f32_32x32x16_bf16 v[82:97], v[110:113], v[114:117], v[82:97]
	s_waitcnt lgkmcnt(0)
	v_mfma_f32_32x32x16_bf16 v[66:81], v[118:121], v[114:117], v[66:81]
	ds_read_b128 v[110:113], v219 offset:49152
	ds_read_b128 v[114:117], v219 offset:57344
	v_exp_f32_e32 v118, v161
	v_exp_f32_e32 v119, v154
	v_exp_f32_e32 v120, v155
	v_exp_f32_e32 v121, v152
	s_waitcnt lgkmcnt(1)
	v_mfma_f32_32x32x16_bf16 v[82:97], v[110:113], v[106:109], v[82:97]
	s_waitcnt lgkmcnt(0)
	v_mfma_f32_32x32x16_bf16 v[66:81], v[114:117], v[106:109], v[66:81]
	ds_read_b128 v[106:109], v221 offset:49152
	ds_read_b128 v[110:113], v221 offset:57344
	v_exp_f32_e32 v114, v149
	v_exp_f32_e32 v115, v146
	v_exp_f32_e32 v116, v147
	v_exp_f32_e32 v117, v160
	s_waitcnt lgkmcnt(1)
	v_mfma_f32_32x32x16_bf16 v[82:97], v[106:109], v[102:105], v[82:97]
	s_waitcnt lgkmcnt(0)
	v_mfma_f32_32x32x16_bf16 v[66:81], v[110:113], v[102:105], v[66:81]
	ds_read_b128 v[102:105], v223 offset:49152
	ds_read_b128 v[106:109], v223 offset:57344
	v_exp_f32_e32 v110, v157
	v_exp_f32_e32 v111, v150
	v_exp_f32_e32 v112, v151
	v_exp_f32_e32 v113, v148
	s_waitcnt lgkmcnt(1)
	v_mfma_f32_32x32x16_bf16 v[82:97], v[102:105], v[98:101], v[82:97]
	s_waitcnt lgkmcnt(0)
; __device__ __forceinline__ void finishSM(f32x16& p0, f32x16& p1, float alpha, float& l_reg, bf16x8& pa0, bf16x8& pa1, bf16x8& pa2, bf16x8& pa3) {
; #pragma unroll
;   for (int r = 0; r < 16; ++r) p1[r] = __builtin_amdgcn_exp2f(p1[r]);
;   float ps = 0;
; #pragma unroll
;   for (int r = 0; r < 16; ++r) ps += p0[r];
; #pragma unroll
;   for (int r = 0; r < 16; ++r) ps += p1[r];
;   { auto rr = __builtin_amdgcn_permlane32_swap(__float_as_uint(ps), __float_as_uint(ps), false, false);
;     ps = __uint_as_float(rr[0]) + __uint_as_float(rr[1]); }
;   l_reg = l_reg * alpha + ps;
;   PK4(p0, 0, pa0); PK4(p0, 8, pa1); PK4(p1, 0, pa2); PK4(p1, 8, pa3);
; }
;   p0 = f32x16{}; p1 = f32x16{};
; #pragma unroll
;   for (int d0 = DLO; d0 < DHI; ++d0) { int cb = (d0 * 16 + hi * 8) * 2;
;     bf16x8 b0 = *reinterpret_cast<const bf16x8*>((const char*)Ks + KSWZ(r32, cb));
;     bf16x8 b1 = *reinterpret_cast<const bf16x8*>((const char*)Ks + KSWZ(32 + r32, cb));
;     p0 = __builtin_amdgcn_mfma_f32_32x32x16_bf16(b0, qr[d0], p0, 0, 0, 0);
;     p1 = __builtin_amdgcn_mfma_f32_32x32x16_bf16(b1, qr[d0], p1, 0, 0, 0); }
; }
; __device__ __forceinline__ int v_st(int k, int c) { const int kk = (k & ~0xC) | ((k & 4) << 1) | ((k & 8) >> 1); return ((kk >> 3) * 4 + (c >> 5)) * 512 + ((kk & 7) * 32 + (c & 31)) * 2; }
; __device__ __forceinline__ int v_rd_base(int lane) { return ((lane & 3) << 3) | (((lane >> 2) & 3) << 6) | (((lane >> 4) & 1) << 5) | (((lane >> 5) & 1) << 8); }
; template <int OFF> __device__ __forceinline__ s16x4 tr_read(int vb) {
;   s16x4 r; asm volatile("ds_read_b64_tr_b16 %0, %1 offset:%2" : "=&v"(r) : "v"(vb), "i"(OFF) : "memory"); return r;
; }
; template <int D0> __device__ __forceinline__ void pv_one(f32x16& od, int vb, bf16x8 pa0, bf16x8 pa1, bf16x8 pa2, bf16x8 pa3) {
;   const s16x4 l0 = tr_read<v_rd_off(D0, 0, 0)>(vb), h0 = tr_read<v_rd_off(D0, 0, 1)>(vb), l1 = tr_read<v_rd_off(D0, 1, 0)>(vb), h1 = tr_read<v_rd_off(D0, 1, 1)>(vb);
;   const s16x4 l2 = tr_read<v_rd_off(D0, 2, 0)>(vb), h2 = tr_read<v_rd_off(D0, 2, 1)>(vb), l3 = tr_read<v_rd_off(D0, 3, 0)>(vb), h3 = tr_read<v_rd_off(D0, 3, 1)>(vb);
;   asm volatile("s_waitcnt lgkmcnt(0)" ::: "memory"); SBAR();
;     ...
;   od = __builtin_amdgcn_mfma_f32_32x32x16_bf16(pa0, PK(l0, h0), od, 0, 0, 0);
;   od = __builtin_amdgcn_mfma_f32_32x32x16_bf16(pa1, PK(l1, h1), od, 0, 0, 0);
	v_mfma_f32_32x32x16_bf16 v[66:81], v[106:109], v[98:101], v[66:81]
	v_exp_f32_e32 v99, v158
	v_exp_f32_e32 v108, v159
	v_exp_f32_e32 v109, v156
	v_cvt_pk_bf16_f32 v100, v177, v195
	v_add_f32_e32 v0, v99, v0
	v_add_f32_e32 v0, v108, v0
	v_add_f32_e32 v0, v109, v0
	v_add_f32_e32 v0, v110, v0
	v_add_f32_e32 v0, v111, v0
	v_add_f32_e32 v0, v112, v0
	v_add_f32_e32 v0, v113, v0
	v_add_f32_e32 v0, v114, v0
	v_add_f32_e32 v0, v115, v0
	v_add_f32_e32 v0, v116, v0
	v_add_f32_e32 v0, v117, v0
	v_add_f32_e32 v0, v118, v0
	v_add_f32_e32 v0, v119, v0
	v_add_f32_e32 v0, v120, v0
	v_add_f32_e32 v0, v121, v0
	v_add_f32_e32 v0, v122, v0
	v_mov_b32_e32 v98, v0
	v_cvt_pk_bf16_f32 v101, v163, v194
	v_cvt_pk_bf16_f32 v102, v164, v176
	s_nop 1
	v_permlane32_swap_b32_e32 v0, v98
	v_cvt_pk_bf16_f32 v103, v165, v175
	v_permlane32_swap_b32_e32 v100, v102
	v_cvt_pk_bf16_f32 v104, v166, v174
	v_cvt_pk_bf16_f32 v105, v167, v173
	v_cvt_pk_bf16_f32 v106, v168, v172
	v_cvt_pk_bf16_f32 v107, v169, v171
	v_cvt_pk_bf16_f32 v108, v99, v108
	v_cvt_pk_bf16_f32 v109, v109, v110
	v_cvt_pk_bf16_f32 v110, v111, v112
	v_cvt_pk_bf16_f32 v111, v113, v114
	v_cvt_pk_bf16_f32 v112, v115, v116
	v_cvt_pk_bf16_f32 v113, v117, v118
	v_cvt_pk_bf16_f32 v114, v119, v120
	v_cvt_pk_bf16_f32 v115, v121, v122
	v_permlane32_swap_b32_e32 v101, v103
	v_permlane32_swap_b32_e32 v104, v106
	v_permlane32_swap_b32_e32 v105, v107
	v_permlane32_swap_b32_e32 v108, v110
	v_permlane32_swap_b32_e32 v109, v111
	v_permlane32_swap_b32_e32 v112, v114
	v_permlane32_swap_b32_e32 v113, v115
	ds_read_b64_tr_b16 v[116:117], v213 offset:0
	ds_read_b64_tr_b16 v[118:119], v213 offset:0x800
	ds_read_b64_tr_b16 v[120:121], v213 offset:0x1000
	ds_read_b64_tr_b16 v[122:123], v213 offset:0x1800
	ds_read_b64_tr_b16 v[124:125], v213 offset:0x2000
	ds_read_b64_tr_b16 v[126:127], v213 offset:0x2800
	ds_read_b64_tr_b16 v[128:129], v213 offset:0x3000
	ds_read_b64_tr_b16 v[130:131], v213 offset:0x3800
	s_waitcnt lgkmcnt(6)
	s_nop 0
	v_mfma_f32_32x32x16_bf16 v[2:17], v[100:103], v[116:119], v[2:17]
	ds_read_b64_tr_b16 v[116:117], v213 offset:0x200
	ds_read_b64_tr_b16 v[118:119], v213 offset:0xa00
	s_waitcnt lgkmcnt(6)
	v_mfma_f32_32x32x16_bf16 v[2:17], v[104:107], v[120:123], v[2:17]
	ds_read_b64_tr_b16 v[120:121], v213 offset:0x1200
	ds_read_b64_tr_b16 v[122:123], v213 offset:0x1a00
	s_waitcnt lgkmcnt(6)
	v_mfma_f32_32x32x16_bf16 v[2:17], v[108:111], v[124:127], v[2:17]
	ds_read_b64_tr_b16 v[124:125], v213 offset:0x2200
	ds_read_b64_tr_b16 v[126:127], v213 offset:0x2a00
	s_waitcnt lgkmcnt(6)
	v_mfma_f32_32x32x16_bf16 v[2:17], v[112:115], v[128:131], v[2:17]
	ds_read_b64_tr_b16 v[128:129], v213 offset:0x3200
	ds_read_b64_tr_b16 v[130:131], v213 offset:0x3a00
	s_waitcnt lgkmcnt(6)
	v_mfma_f32_32x32x16_bf16 v[50:65], v[100:103], v[116:119], v[50:65]
	ds_read_b64_tr_b16 v[116:117], v213 offset:0x400
	ds_read_b64_tr_b16 v[118:119], v213 offset:0xc00
	s_waitcnt lgkmcnt(6)
	v_mfma_f32_32x32x16_bf16 v[50:65], v[104:107], v[120:123], v[50:65]
	ds_read_b64_tr_b16 v[120:121], v213 offset:0x1400
	ds_read_b64_tr_b16 v[122:123], v213 offset:0x1c00
	s_waitcnt lgkmcnt(6)
	v_mfma_f32_32x32x16_bf16 v[50:65], v[108:111], v[124:127], v[50:65]
	ds_read_b64_tr_b16 v[124:125], v213 offset:0x2400
	ds_read_b64_tr_b16 v[126:127], v213 offset:0x2c00
	s_waitcnt lgkmcnt(6)
	v_mfma_f32_32x32x16_bf16 v[50:65], v[112:115], v[128:131], v[50:65]
	ds_read_b64_tr_b16 v[128:129], v213 offset:0x3400
	ds_read_b64_tr_b16 v[130:131], v213 offset:0x3c00
	s_waitcnt lgkmcnt(6)
	v_mfma_f32_32x32x16_bf16 v[34:49], v[100:103], v[116:119], v[34:49]
	ds_read_b64_tr_b16 v[116:117], v213 offset:0x600
	ds_read_b64_tr_b16 v[118:119], v213 offset:0xe00
	s_waitcnt lgkmcnt(6)
	v_mfma_f32_32x32x16_bf16 v[34:49], v[104:107], v[120:123], v[34:49]
	ds_read_b64_tr_b16 v[120:121], v213 offset:0x1600
	ds_read_b64_tr_b16 v[122:123], v213 offset:0x1e00
	s_waitcnt lgkmcnt(6)
	v_mfma_f32_32x32x16_bf16 v[34:49], v[108:111], v[124:127], v[34:49]
	ds_read_b64_tr_b16 v[124:125], v213 offset:0x2600
	ds_read_b64_tr_b16 v[126:127], v213 offset:0x2e00
	s_waitcnt lgkmcnt(6)
	v_mfma_f32_32x32x16_bf16 v[34:49], v[112:115], v[128:131], v[34:49]
	ds_read_b64_tr_b16 v[128:129], v213 offset:0x3600
	ds_read_b64_tr_b16 v[130:131], v213 offset:0x3e00
	s_waitcnt lgkmcnt(6)
	v_mfma_f32_32x32x16_bf16 v[18:33], v[100:103], v[116:119], v[18:33]
	v_max_f32_e32 v99, v83, v83
	v_max_f32_e32 v100, v82, v82
	v_max_f32_e32 v99, v100, v99
	v_max3_f32 v99, v99, v84, v85
	v_max3_f32 v99, v99, v86, v87
	v_max3_f32 v99, v99, v88, v89
	v_max3_f32 v99, v99, v90, v91
	v_max3_f32 v99, v99, v92, v93
	v_max3_f32 v99, v99, v94, v95
	s_waitcnt lgkmcnt(4)
	v_mfma_f32_32x32x16_bf16 v[18:33], v[104:107], v[120:123], v[18:33]
	v_max3_f32 v99, v99, v96, v97
	v_max3_f32 v99, v99, v66, v67
	v_max3_f32 v99, v99, v68, v69
	v_max3_f32 v99, v99, v70, v71
	v_max3_f32 v99, v99, v72, v73
	v_max3_f32 v99, v99, v74, v75
	v_max3_f32 v99, v99, v76, v77
	v_max3_f32 v99, v99, v78, v79
	s_waitcnt lgkmcnt(2)
	v_mfma_f32_32x32x16_bf16 v[18:33], v[108:111], v[124:127], v[18:33]
	v_max3_f32 v99, v99, v80, v81
	v_mov_b32_e32 v100, v99
	s_nop 1
	v_permlane32_swap_b32_e32 v99, v100
	v_max_f32_e32 v100, v100, v100
	v_max_f32_e32 v99, v99, v99
	v_max_f32_e32 v99, v99, v100
	v_sub_f32_e32 v100, v99, v170
	v_cmp_ge_f32_e32 vcc, s63, v100
	v_max_f32_e32 v100, v170, v170
	v_max_f32_e32 v100, v100, v99
	s_waitcnt lgkmcnt(0)
	v_mfma_f32_32x32x16_bf16 v[18:33], v[112:115], v[128:131], v[18:33]
	v_sub_f32_e32 v99, v170, v100
	v_mul_f32_e32 v99, 0x3e0293ee, v99
	v_exp_f32_e32 v99, v99
	s_cmp_eq_u64 vcc, exec
	s_cselect_b64 s[8:9], -1, 0
	v_cndmask_b32_e64 v99, v99, 1.0, s[8:9]
	v_cmp_gt_f32_e32 vcc, 1.0, v99
	s_barrier
; #define SBAR() __builtin_amdgcn_sched_barrier(0)
; #define RESC(a) do { if (__any((a) < 1.f)) { if (hi == 0) al_l[r32] = (a); asm volatile("s_waitcnt lgkmcnt(0)" ::: "memory"); \
;     _Pragma("unroll") for (int d = 0; d < 4; ++d) _Pragma("unroll") for (int r = 0; r < 16; ++r) o[d][r] *= al_l[crow(r, hi)]; } } while (0)
; __device__ __forceinline__ void finishSM(f32x16& p0, f32x16& p1, float alpha, float& l_reg, bf16x8& pa0, bf16x8& pa1, bf16x8& pa2, bf16x8& pa3) {
; #pragma unroll
;   for (int r = 0; r < 16; ++r) p1[r] = __builtin_amdgcn_exp2f(p1[r]);
;   float ps = 0;
; #pragma unroll
;   for (int r = 0; r < 16; ++r) ps += p0[r];
; #pragma unroll
;   for (int r = 0; r < 16; ++r) ps += p1[r];
;   { auto rr = __builtin_amdgcn_permlane32_swap(__float_as_uint(ps), __float_as_uint(ps), false, false);
;     ps = __uint_as_float(rr[0]) + __uint_as_float(rr[1]); }
;   l_reg = l_reg * alpha + ps;
;   PK4(p0, 0, pa0); PK4(p0, 8, pa1); PK4(p1, 0, pa2); PK4(p1, 8, pa3);
; }
; template <int DLO, int DHI>
; __device__ __forceinline__ void attn_dense_body(const int g_wave, const bf16* __restrict__ Qb, const bf16* __restrict__ Kh, const bf16* __restrict__ Vh,
;                                                 bf16* __restrict__ Ob, int ldo, char* lds) {
;     ...
;   __syncthreads(); RESC(alB);
;   finishSM(pB0, pB1, alB, l_reg, pa0, pa1, pa2, pa3); SBAR();
;   pv_d0(o, vb0 + (int)SHM_V, pa0, pa1, pa2, pa3);
	s_cbranch_vccz .LBB0_1059
	s_and_saveexec_b64 s[2:3], s[6:7]
	ds_write_b32 v210, v99 offset:128
	s_or_b64 exec, exec, s[2:3]
	s_waitcnt lgkmcnt(0)
	v_add_u32_e32 v101, s15, v209
	ds_read_b128 v[102:105], v101 offset:224
	ds_read_b128 v[106:109], v101 offset:192
	ds_read_b128 v[110:113], v101 offset:160
	ds_read_b128 v[114:117], v101 offset:128
	s_waitcnt lgkmcnt(3)
	v_pk_mul_f32 v[14:15], v[14:15], v[102:103]
	s_waitcnt lgkmcnt(2)
	v_pk_mul_f32 v[10:11], v[10:11], v[106:107]
	s_waitcnt lgkmcnt(1)
	v_pk_mul_f32 v[6:7], v[6:7], v[110:111]
	v_pk_mul_f32 v[16:17], v[16:17], v[104:105]
	v_pk_mul_f32 v[12:13], v[12:13], v[108:109]
	v_pk_mul_f32 v[8:9], v[8:9], v[112:113]
	s_waitcnt lgkmcnt(0)
	v_pk_mul_f32 v[4:5], v[4:5], v[116:117]
	v_pk_mul_f32 v[2:3], v[2:3], v[114:115]
	v_pk_mul_f32 v[62:63], v[62:63], v[102:103]
	v_pk_mul_f32 v[58:59], v[58:59], v[106:107]
	v_pk_mul_f32 v[54:55], v[54:55], v[110:111]
	v_pk_mul_f32 v[64:65], v[64:65], v[104:105]
	v_pk_mul_f32 v[60:61], v[60:61], v[108:109]
	v_pk_mul_f32 v[56:57], v[56:57], v[112:113]
	v_pk_mul_f32 v[52:53], v[52:53], v[116:117]
	v_pk_mul_f32 v[50:51], v[50:51], v[114:115]
	v_pk_mul_f32 v[46:47], v[46:47], v[102:103]
	v_pk_mul_f32 v[42:43], v[42:43], v[106:107]
	v_pk_mul_f32 v[38:39], v[38:39], v[110:111]
	v_pk_mul_f32 v[48:49], v[48:49], v[104:105]
	v_pk_mul_f32 v[44:45], v[44:45], v[108:109]
	v_pk_mul_f32 v[40:41], v[40:41], v[112:113]
	v_pk_mul_f32 v[36:37], v[36:37], v[116:117]
	v_pk_mul_f32 v[34:35], v[34:35], v[114:115]
	v_pk_mul_f32 v[30:31], v[30:31], v[102:103]
	v_pk_mul_f32 v[26:27], v[26:27], v[106:107]
	v_pk_mul_f32 v[22:23], v[22:23], v[110:111]
	v_pk_mul_f32 v[32:33], v[32:33], v[104:105]
	v_pk_mul_f32 v[28:29], v[28:29], v[108:109]
	v_pk_mul_f32 v[24:25], v[24:25], v[112:113]
	v_pk_mul_f32 v[20:21], v[20:21], v[116:117]
	v_pk_mul_f32 v[18:19], v[18:19], v[114:115]
.LBB0_1059:
	v_cndmask_b32_e64 v100, v100, v170, s[8:9]
	v_mul_f32_e32 v100, 0xbe0293ee, v100
	v_fmamk_f32 v82, v82, 0x3e0293ee, v100
	v_fmamk_f32 v83, v83, 0x3e0293ee, v100
	v_fmamk_f32 v101, v84, 0x3e0293ee, v100
	v_exp_f32_e32 v84, v82
	v_fmamk_f32 v102, v86, 0x3e0293ee, v100
	v_exp_f32_e32 v86, v83
	v_fmamk_f32 v85, v85, 0x3e0293ee, v100
	v_exp_f32_e32 v82, v101
	v_fmamk_f32 v66, v66, 0x3e0293ee, v100
	v_exp_f32_e32 v85, v85
	v_fmamk_f32 v103, v87, 0x3e0293ee, v100
	v_fmamk_f32 v112, v96, 0x3e0293ee, v100
	v_fmamk_f32 v96, v77, 0x3e0293ee, v100
	v_exp_f32_e32 v77, v102
	v_exp_f32_e32 v101, v66
	v_add_f32_e32 v66, 0, v84
	v_fmamk_f32 v104, v88, 0x3e0293ee, v100
	v_exp_f32_e32 v83, v103
	v_add_f32_e32 v66, v86, v66
	v_fmamk_f32 v105, v89, 0x3e0293ee, v100
	v_fmamk_f32 v111, v95, 0x3e0293ee, v100
	v_fmamk_f32 v95, v76, 0x3e0293ee, v100
	v_exp_f32_e32 v76, v104
	v_add_f32_e32 v66, v82, v66
	v_fmamk_f32 v106, v90, 0x3e0293ee, v100
	v_fmamk_f32 v113, v97, 0x3e0293ee, v100
	v_fmamk_f32 v97, v78, 0x3e0293ee, v100
	v_exp_f32_e32 v78, v105
	v_add_f32_e32 v66, v85, v66
	v_fmamk_f32 v107, v91, 0x3e0293ee, v100
	v_fmamk_f32 v108, v92, 0x3e0293ee, v100
	v_fmamk_f32 v92, v73, 0x3e0293ee, v100
	v_exp_f32_e32 v73, v106
	v_add_f32_e32 v66, v77, v66
	v_fmamk_f32 v110, v94, 0x3e0293ee, v100
	v_fmamk_f32 v94, v75, 0x3e0293ee, v100
	v_exp_f32_e32 v75, v107
	v_add_f32_e32 v66, v83, v66
	v_fmamk_f32 v109, v93, 0x3e0293ee, v100
	v_fmamk_f32 v90, v71, 0x3e0293ee, v100
	v_exp_f32_e32 v71, v108
	v_add_f32_e32 v66, v76, v66
	v_fmamk_f32 v93, v74, 0x3e0293ee, v100
	v_exp_f32_e32 v74, v109
	v_add_f32_e32 v66, v78, v66
	v_fmamk_f32 v88, v69, 0x3e0293ee, v100
	v_exp_f32_e32 v69, v110
	v_add_f32_e32 v66, v73, v66
	v_fmamk_f32 v91, v72, 0x3e0293ee, v100
	v_exp_f32_e32 v72, v111
	v_add_f32_e32 v66, v75, v66
	v_fmamk_f32 v87, v68, 0x3e0293ee, v100
	v_exp_f32_e32 v68, v112
	v_add_f32_e32 v66, v71, v66
	v_fmamk_f32 v89, v70, 0x3e0293ee, v100
	v_exp_f32_e32 v70, v113
	v_add_f32_e32 v66, v74, v66
	v_fmamk_f32 v67, v67, 0x3e0293ee, v100
	v_add_f32_e32 v66, v69, v66
	v_exp_f32_e32 v102, v67
	v_add_f32_e32 v66, v72, v66
	v_exp_f32_e32 v87, v87
	v_add_f32_e32 v66, v68, v66
	v_exp_f32_e32 v88, v88
	v_add_f32_e32 v66, v70, v66
	v_exp_f32_e32 v89, v89
	v_add_f32_e32 v66, v101, v66
	v_exp_f32_e32 v90, v90
	v_add_f32_e32 v66, v102, v66
	v_exp_f32_e32 v91, v91
	v_add_f32_e32 v66, v87, v66
	v_exp_f32_e32 v92, v92
	v_add_f32_e32 v66, v88, v66
	v_exp_f32_e32 v93, v93
	v_add_f32_e32 v66, v89, v66
	v_exp_f32_e32 v94, v94
	v_add_f32_e32 v66, v90, v66
	v_exp_f32_e32 v95, v95
	v_add_f32_e32 v66, v91, v66
	v_exp_f32_e32 v96, v96
	v_add_f32_e32 v66, v92, v66
	v_fmamk_f32 v79, v79, 0x3e0293ee, v100
	v_exp_f32_e32 v97, v97
	v_add_f32_e32 v66, v93, v66
	v_fmamk_f32 v80, v80, 0x3e0293ee, v100
	v_exp_f32_e32 v103, v79
	v_add_f32_e32 v66, v94, v66
	v_fmac_f32_e32 v100, 0x3e0293ee, v81
	v_exp_f32_e32 v104, v80
	v_add_f32_e32 v66, v95, v66
	v_exp_f32_e32 v100, v100
	v_add_f32_e32 v66, v96, v66
	v_add_f32_e32 v66, v97, v66
	v_add_f32_e32 v66, v103, v66
	v_add_f32_e32 v66, v104, v66
	v_add_f32_e32 v66, v100, v66
	v_mov_b32_e32 v67, v66
	s_nop 1
	v_permlane32_swap_b32_e32 v66, v67
	v_cvt_pk_bf16_f32 v80, v84, v86
	v_cvt_pk_bf16_f32 v81, v82, v85
	v_cvt_pk_bf16_f32 v82, v77, v83
	v_cvt_pk_bf16_f32 v83, v76, v78
	v_cvt_pk_bf16_f32 v76, v73, v75
	v_cvt_pk_bf16_f32 v77, v71, v74
	v_cvt_pk_bf16_f32 v78, v69, v72
	v_cvt_pk_bf16_f32 v79, v68, v70
	v_cvt_pk_bf16_f32 v68, v101, v102
	v_cvt_pk_bf16_f32 v69, v87, v88
	v_cvt_pk_bf16_f32 v70, v89, v90
	v_cvt_pk_bf16_f32 v71, v91, v92
	v_cvt_pk_bf16_f32 v72, v93, v94
	v_cvt_pk_bf16_f32 v73, v95, v96
	v_cvt_pk_bf16_f32 v74, v97, v103
	v_cvt_pk_bf16_f32 v75, v104, v100
	s_nop 0
	v_permlane32_swap_b32_e32 v80, v82
	v_permlane32_swap_b32_e32 v81, v83
	v_permlane32_swap_b32_e32 v76, v78
	v_permlane32_swap_b32_e32 v77, v79
	v_permlane32_swap_b32_e32 v68, v70
	v_permlane32_swap_b32_e32 v69, v71
	v_permlane32_swap_b32_e32 v72, v74
	v_permlane32_swap_b32_e32 v73, v75
	ds_read_b64_tr_b16 v[84:85], v212 offset:0
	ds_read_b64_tr_b16 v[86:87], v212 offset:0x800
	ds_read_b64_tr_b16 v[88:89], v212 offset:0x1000
	ds_read_b64_tr_b16 v[90:91], v212 offset:0x1800
	ds_read_b64_tr_b16 v[92:93], v212 offset:0x2000
	ds_read_b64_tr_b16 v[94:95], v212 offset:0x2800
	ds_read_b64_tr_b16 v[100:101], v212 offset:0x3000
	ds_read_b64_tr_b16 v[102:103], v212 offset:0x3800
	s_waitcnt lgkmcnt(6)
; #define SBAR() __builtin_amdgcn_sched_barrier(0)
; template <int D0> __device__ __forceinline__ void pv_one(f32x16& od, int vb, bf16x8 pa0, bf16x8 pa1, bf16x8 pa2, bf16x8 pa3) {
;   const s16x4 l0 = tr_read<v_rd_off(D0, 0, 0)>(vb), h0 = tr_read<v_rd_off(D0, 0, 1)>(vb), l1 = tr_read<v_rd_off(D0, 1, 0)>(vb), h1 = tr_read<v_rd_off(D0, 1, 1)>(vb);
;   const s16x4 l2 = tr_read<v_rd_off(D0, 2, 0)>(vb), h2 = tr_read<v_rd_off(D0, 2, 1)>(vb), l3 = tr_read<v_rd_off(D0, 3, 0)>(vb), h3 = tr_read<v_rd_off(D0, 3, 1)>(vb);
;   asm volatile("s_waitcnt lgkmcnt(0)" ::: "memory"); SBAR();
;     ...
;   od = __builtin_amdgcn_mfma_f32_32x32x16_bf16(pa0, PK(l0, h0), od, 0, 0, 0);
;   od = __builtin_amdgcn_mfma_f32_32x32x16_bf16(pa1, PK(l1, h1), od, 0, 0, 0);
;   od = __builtin_amdgcn_mfma_f32_32x32x16_bf16(pa2, PK(l2, h2), od, 0, 0, 0);
;   od = __builtin_amdgcn_mfma_f32_32x32x16_bf16(pa3, PK(l3, h3), od, 0, 0, 0);
;     ...
; }
; __device__ __forceinline__ void pv_d0(f32x16* o, int vb, bf16x8 pa0, bf16x8 pa1, bf16x8 pa2, bf16x8 pa3) {
;   pv_one<0>(o[0], vb, pa0, pa1, pa2, pa3); pv_one<1>(o[1], vb, pa0, pa1, pa2, pa3); pv_one<2>(o[2], vb, pa0, pa1, pa2, pa3); pv_one<3>(o[3], vb, pa0, pa1, pa2, pa3);
; template <int DLO, int DHI>
; __device__ __forceinline__ void attn_dense_body(const int g_wave, const bf16* __restrict__ Qb, const bf16* __restrict__ Kh, const bf16* __restrict__ Vh,
;                                                 bf16* __restrict__ Ob, int ldo, char* lds) {
;     ...
;   pv_d0(o, vb0 + (int)SHM_V, pa0, pa1, pa2, pa3);
;   if (hi == 0) li_l[r32] = l_reg; asm volatile("s_waitcnt lgkmcnt(0)" ::: "memory");
	s_nop 0
	v_mfma_f32_32x32x16_bf16 v[2:17], v[80:83], v[84:87], v[2:17]
	ds_read_b64_tr_b16 v[84:85], v212 offset:0x200
	ds_read_b64_tr_b16 v[86:87], v212 offset:0xa00
	s_waitcnt lgkmcnt(6)
	v_mfma_f32_32x32x16_bf16 v[2:17], v[76:79], v[88:91], v[2:17]
	ds_read_b64_tr_b16 v[88:89], v212 offset:0x1200
	ds_read_b64_tr_b16 v[90:91], v212 offset:0x1a00
	s_waitcnt lgkmcnt(6)
	v_mfma_f32_32x32x16_bf16 v[2:17], v[68:71], v[92:95], v[2:17]
	ds_read_b64_tr_b16 v[92:93], v212 offset:0x2200
	ds_read_b64_tr_b16 v[94:95], v212 offset:0x2a00
	s_waitcnt lgkmcnt(6)
	v_mfma_f32_32x32x16_bf16 v[2:17], v[72:75], v[100:103], v[2:17]
	ds_read_b64_tr_b16 v[100:101], v212 offset:0x3200
	ds_read_b64_tr_b16 v[102:103], v212 offset:0x3a00
	s_waitcnt lgkmcnt(6)
	v_mfma_f32_32x32x16_bf16 v[50:65], v[80:83], v[84:87], v[50:65]
	ds_read_b64_tr_b16 v[84:85], v212 offset:0x400
	ds_read_b64_tr_b16 v[86:87], v212 offset:0xc00
	s_waitcnt lgkmcnt(6)
	v_mfma_f32_32x32x16_bf16 v[50:65], v[76:79], v[88:91], v[50:65]
	ds_read_b64_tr_b16 v[88:89], v212 offset:0x1400
	ds_read_b64_tr_b16 v[90:91], v212 offset:0x1c00
	s_waitcnt lgkmcnt(6)
	v_mfma_f32_32x32x16_bf16 v[50:65], v[68:71], v[92:95], v[50:65]
	ds_read_b64_tr_b16 v[92:93], v212 offset:0x2400
	ds_read_b64_tr_b16 v[94:95], v212 offset:0x2c00
	s_waitcnt lgkmcnt(6)
	v_mfma_f32_32x32x16_bf16 v[50:65], v[72:75], v[100:103], v[50:65]
	ds_read_b64_tr_b16 v[100:101], v212 offset:0x3400
	ds_read_b64_tr_b16 v[102:103], v212 offset:0x3c00
	s_waitcnt lgkmcnt(6)
	v_mfma_f32_32x32x16_bf16 v[34:49], v[80:83], v[84:87], v[34:49]
	ds_read_b64_tr_b16 v[84:85], v212 offset:0x600
	ds_read_b64_tr_b16 v[86:87], v212 offset:0xe00
	s_waitcnt lgkmcnt(6)
	v_mfma_f32_32x32x16_bf16 v[34:49], v[76:79], v[88:91], v[34:49]
	ds_read_b64_tr_b16 v[88:89], v212 offset:0x1600
	ds_read_b64_tr_b16 v[90:91], v212 offset:0x1e00
	s_waitcnt lgkmcnt(6)
	v_mfma_f32_32x32x16_bf16 v[34:49], v[68:71], v[92:95], v[34:49]
	ds_read_b64_tr_b16 v[92:93], v212 offset:0x2600
	ds_read_b64_tr_b16 v[94:95], v212 offset:0x2e00
	s_waitcnt lgkmcnt(6)
	v_mfma_f32_32x32x16_bf16 v[34:49], v[72:75], v[100:103], v[34:49]
	ds_read_b64_tr_b16 v[100:101], v212 offset:0x3600
	ds_read_b64_tr_b16 v[102:103], v212 offset:0x3e00
	s_waitcnt lgkmcnt(6)
	v_mfma_f32_32x32x16_bf16 v[18:33], v[80:83], v[84:87], v[18:33]
	s_waitcnt lgkmcnt(4)
	v_mfma_f32_32x32x16_bf16 v[18:33], v[76:79], v[88:91], v[18:33]
	s_waitcnt lgkmcnt(2)
	v_mfma_f32_32x32x16_bf16 v[18:33], v[68:71], v[92:95], v[18:33]
	s_waitcnt lgkmcnt(0)
	v_mfma_f32_32x32x16_bf16 v[18:33], v[72:75], v[100:103], v[18:33]
	s_and_saveexec_b64 s[2:3], s[6:7]
	s_cbranch_execz .LBB0_993
	v_add_f32_e32 v0, v0, v98
	v_fmac_f32_e32 v0, v211, v162
	v_add_f32_e32 v66, v66, v67
	v_fmac_f32_e32 v66, v0, v99
	ds_write_b32 v210, v66
	s_branch .LBB0_993

; __device__ __forceinline__ int opaque_lane() { int z; asm volatile("v_mov_b32 %0, 0" : "=v"(z)); return __builtin_amdgcn_mbcnt_hi(-1, __builtin_amdgcn_mbcnt_lo(-1, z)); }
; __device__ __forceinline__ int launder_s(int v) { asm volatile("" : "+s"(v)); return v; }
; __device__ __forceinline__ int crow(int r, int hi) { return (r & 3) + 8 * (r >> 2) + 4 * hi; }
; __device__ __forceinline__ int v_st(int k, int c) { const int kk = (k & ~0xC) | ((k & 4) << 1) | ((k & 8) >> 1); return ((kk >> 3) * 4 + (c >> 5)) * 512 + ((kk & 7) * 32 + (c & 31)) * 2; }
; __device__ __forceinline__ void na_item(const int g_wave, int b, int r, int hp, const bf16* __restrict__ proj, const float* __restrict__ rpb, bf16* __restrict__ cat, char* lds) {
;   const int wid = launder_s(g_wave), lane = opaque_lane(), tid = (wid << 6) | lane, r32 = lane & 31, hi = lane >> 5;
;   const bool active = wid < 4;
;   const int hl = (wid >> 1) & 1, hh = 2 * hp + hl, half = wid & 1;
;   const int c = half * 32 + r32;
;   const long tq = (long)b * 4096 + r * 64 + c;
;   int rs = r - 4; rs = rs < 0 ? 0 : (rs > 56 ? 56 : rs);
;   int cs = c - 8; cs = cs < 0 ? 0 : (cs > 48 ? 48 : cs);
;   char* Kl = lds + hl * 32768; char* Vl = Kl + 16384;
;   float* ws = (float*)(lds + 131072) + wid * 64; float* li_l = ws; float* al_l = ws + 32;
;   bf16x8 qr[8];
; #pragma unroll
;   for (int d0 = 0; d0 < 8; ++d0) qr[d0] = ld8(proj + tq * 4608 + hh * 128 + d0 * 16 + hi * 8);
;   const int sr = tid >> 4, sc = (tid & 15) * 8, vst0 = v_st(sr, sc), vst1 = v_st(32 + sr, sc);
;   const int vb = (int)(uintptr_t)Vl + v_rd_base(lane);
;   float m_reg = -1e30f, l_reg = 0.f; f32x16 o[4] = {};
;   constexpr float C = SCALE * 1.4426950408889634f, L2E = 1.4426950408889634f, NEG = -1e30f;
;   float* btab = (float*)(lds + 65536);
;     ...
;     for (int q = 0; q < 16; ++q) {
;       const int j0 = crow(q, hi), j1 = 32 + j0;
;       { const bool ok = (j0 >= cs) && (j0 < cs + 16); int dc = j0 - c + 15; dc = dc < 0 ? 0 : (dc > 30 ? 30 : dc);
;         const float bv = bp[dc]; p0[q] = ok ? fmaf(p0[q], C, bv) : NEG; tmax = fmaxf(tmax, p0[q]); }
;       { const bool ok = (j1 >= cs) && (j1 < cs + 16); int dc = j1 - c + 15; dc = dc < 0 ? 0 : (dc > 30 ? 30 : dc);
;         const float bv = bp[dc]; p1[q] = ok ? fmaf(p1[q], C, bv) : NEG; tmax = fmaxf(tmax, p1[q]); }
.LBB0_1075:
	s_or_b64 exec, exec, s[2:3]
	s_lshr_b32 s2, s41, 1
	v_lshlrev_b32_e32 v4, 9, v9
	v_ashrrev_i32_e32 v9, 4, v2
	s_and_b32 s2, s2, 63
	s_waitcnt vmcnt(0)
	v_and_b32_e32 v12, 0xfffff0, v9
	v_lshlrev_b32_e32 v13, 1, v9
	v_med3_u32 v0, s2, 4, 60
	s_movk_i32 s3, 0x7c
	s_cmp_gt_u32 s2, 4
	v_and_or_b32 v12, v13, 8, v12
	v_lshrrev_b32_e32 v13, 1, v9
	v_and_b32_e32 v15, 3, v9
	v_mul_lo_u32 v0, v0, s3
	s_mul_i32 s69, s2, 0x7c
	s_cselect_b32 s3, 0, 0
	s_cselect_b32 s2, s2, 4
	v_and_or_b32 v13, v13, 4, v15
	v_add_u32_e32 v15, 32, v9
	v_cmp_lt_u64_e64 s[4:5], s[2:3], 60
	v_and_b32_e32 v17, 0xfffff0, v15
	v_lshlrev_b32_e32 v18, 1, v15
	s_and_b64 s[4:5], s[4:5], exec
	v_lshlrev_b32_e32 v10, 3, v6
	v_and_or_b32 v17, v18, 8, v17
	s_cselect_b32 s65, s2, 60
	s_lshl_b32 s3, s13, 2
	v_lshrrev_b32_e32 v12, 1, v12
	v_bfe_u32 v14, v10, 5, 2
	v_lshrrev_b32_e32 v17, 1, v17
	s_lshl_b32 s2, s33, 15
	s_add_i32 s42, s3, 0
	v_or_b32_e32 v12, v12, v14
	v_or_b32_e32 v14, v17, v14
	v_lshlrev_b32_e32 v17, 4, v6
	s_add_i32 s2, s2, 0
	s_add_i32 s42, s42, 0x20000
	v_and_b32_e32 v17, 0xc0, v17
	v_lshlrev_b32_e32 v18, 1, v6
	s_cmp_lt_i32 s12, 4
	v_and_b32_e32 v11, 0x78, v10
	v_and_or_b32 v17, v10, 24, v17
	v_and_b32_e32 v18, 32, v18
	v_and_b32_e32 v10, 0x100, v10
	s_cselect_b64 s[24:25], -1, 0
	s_add_i32 s3, s2, 0x4000
	v_lshlrev_b32_e32 v11, 1, v11
	v_or3_b32 v10, v17, v18, v10
	v_lshlrev_b32_e32 v135, 4, v8
	v_add_u32_e32 v133, s3, v10
	v_bitop3_b32 v17, v11, v2, s80 bitop3:0x78
	v_lshlrev_b32_e32 v2, 4, v131
	v_add_u32_e32 v10, 32, v135
	v_bitop3_b32 v141, v10, v2, s80 bitop3:0x78
	v_add_u32_e32 v10, 64, v135
	v_bitop3_b32 v143, v10, v2, s80 bitop3:0x78
	v_add_u32_e32 v10, 0x60, v135
	v_bitop3_b32 v145, v10, v2, s80 bitop3:0x78
	v_add_u32_e32 v10, 0x80, v135
	v_bitop3_b32 v149, v10, v2, s80 bitop3:0x78
	v_add_u32_e32 v10, 0xa0, v135
	v_bitop3_b32 v151, v10, v2, s80 bitop3:0x78
	v_add_u32_e32 v10, 0xc0, v135
	v_med3_u32 v3, v7, 8, 56
	v_bitop3_b32 v153, v10, v2, s80 bitop3:0x78
	v_add_u32_e32 v10, 0xe0, v135
	v_add_u32_e32 v5, -8, v3
	v_bitop3_b32 v137, v2, v135, s80 bitop3:0x6c
	v_bitop3_b32 v155, v10, v2, s80 bitop3:0x78
	v_lshlrev_b32_e32 v160, 2, v8
	v_add_u32_e32 v2, 8, v3
	v_lshl_add_u32 v8, v13, 6, 0
	v_lshl_add_u32 v29, v12, 9, v8
	v_lshl_add_u32 v30, v14, 9, v8
	v_add_u32_e32 v8, 32, v160
	v_cmp_ge_i32_e32 vcc, v160, v5
	v_cmp_lt_i32_e64 s[8:9], v160, v2
	s_and_b64 s[26:27], vcc, s[8:9]
	v_cmp_ge_i32_e32 vcc, v8, v5
	v_cmp_lt_i32_e64 s[8:9], v8, v2
	v_or_b32_e32 v158, 1, v160
	v_and_b32_e32 v16, 48, v11
	s_and_b64 s[28:29], vcc, s[8:9]
	v_add_u32_e32 v11, 33, v160
	v_cmp_ge_i32_e32 vcc, v158, v5
	v_cmp_lt_i32_e64 s[8:9], v158, v2
	s_and_b64 s[30:31], vcc, s[8:9]
	v_cmp_ge_i32_e32 vcc, v11, v5
	v_cmp_lt_i32_e64 s[8:9], v11, v2
	v_or_b32_e32 v156, 2, v160
	s_and_b64 s[82:83], vcc, s[8:9]
	v_add_u32_e32 v12, 34, v160
	v_cmp_ge_i32_e32 vcc, v156, v5
	v_cmp_lt_i32_e64 s[8:9], v156, v2
	s_and_b64 s[84:85], vcc, s[8:9]
	v_cmp_ge_i32_e32 vcc, v12, v5
	v_cmp_lt_i32_e64 s[8:9], v12, v2
	v_or_b32_e32 v154, 3, v160
	s_and_b64 s[86:87], vcc, s[8:9]
	v_add_u32_e32 v13, 35, v160
	v_cmp_ge_i32_e32 vcc, v154, v5
	v_cmp_lt_i32_e64 s[8:9], v154, v2
	s_and_b64 s[88:89], vcc, s[8:9]
	v_cmp_ge_i32_e32 vcc, v13, v5
	v_cmp_lt_i32_e64 s[8:9], v13, v2
	v_add_u32_e32 v152, 8, v160
	s_and_b64 s[90:91], vcc, s[8:9]
	v_cmp_lt_i32_e64 s[8:9], v160, v3
	v_sub_u32_e32 v3, v152, v7
	s_mulk_i32 s33, 0x744
	v_add_u32_e32 v14, 40, v160
	v_cmp_ge_i32_e32 vcc, v152, v5
	v_med3_i32 v3, v3, -15, 15
	v_add_u32_e32 v0, s33, v0
	s_and_b64 s[92:93], s[8:9], vcc
	v_cmp_ge_i32_e32 vcc, v14, v5
	v_cmp_lt_i32_e64 s[8:9], v14, v2
	v_sub_u32_e32 v14, v14, v7
	v_lshl_add_u32 v3, v3, 2, v0
	v_med3_i32 v14, v14, -15, 15
	v_add_u32_e32 v150, 9, v160
	v_subrev_u32_e32 v3, s69, v3
	v_sub_u32_e32 v31, v150, v7
	v_add_u32_e32 v169, s40, v3
	v_lshl_add_u32 v3, v14, 2, v0
	v_lshl_add_u32 v28, v15, 8, 0
	s_and_b64 s[94:95], vcc, s[8:9]
	v_add_u32_e32 v15, 41, v160
	v_cmp_ge_i32_e32 vcc, v150, v5
	v_cmp_lt_i32_e64 s[8:9], v150, v2
	v_med3_i32 v31, v31, -15, 15
	v_subrev_u32_e32 v3, s69, v3
	s_and_b64 s[96:97], vcc, s[8:9]
	v_cmp_ge_i32_e32 vcc, v15, v5
	v_cmp_lt_i32_e64 s[8:9], v15, v2
	v_sub_u32_e32 v15, v15, v7
	v_add_u32_e32 v170, s40, v3
	v_lshl_add_u32 v3, v31, 2, v0
	v_med3_i32 v15, v15, -15, 15
	v_add_u32_e32 v148, 10, v160
	v_subrev_u32_e32 v3, s69, v3
	v_sub_u32_e32 v33, v148, v7
	v_add_u32_e32 v171, s40, v3
	v_lshl_add_u32 v3, v15, 2, v0
	s_and_b64 s[60:61], vcc, s[8:9]
	v_add_u32_e32 v32, 42, v160
	v_cmp_ge_i32_e32 vcc, v148, v5
	v_cmp_lt_i32_e64 s[8:9], v148, v2
	v_med3_i32 v33, v33, -15, 15
	v_subrev_u32_e32 v3, s69, v3
	s_and_b64 s[38:39], vcc, s[8:9]
	v_cmp_ge_i32_e32 vcc, v32, v5
	v_cmp_lt_i32_e64 s[8:9], v32, v2
	v_sub_u32_e32 v32, v32, v7
	v_add_u32_e32 v172, s40, v3
	v_lshl_add_u32 v3, v33, 2, v0
	v_med3_i32 v32, v32, -15, 15
	v_add_u32_e32 v146, 11, v160
	v_subrev_u32_e32 v3, s69, v3
	v_sub_u32_e32 v35, v146, v7
	v_add_u32_e32 v173, s40, v3
	v_lshl_add_u32 v3, v32, 2, v0
	s_and_b64 s[74:75], vcc, s[8:9]
	v_add_u32_e32 v34, 43, v160
	v_cmp_ge_i32_e32 vcc, v146, v5
	v_cmp_lt_i32_e64 s[8:9], v146, v2
	v_med3_i32 v35, v35, -15, 15
	v_subrev_u32_e32 v3, s69, v3
	s_and_b64 s[36:37], vcc, s[8:9]
	v_cmp_ge_i32_e32 vcc, v34, v5
	v_cmp_lt_i32_e64 s[8:9], v34, v2
	v_sub_u32_e32 v34, v34, v7
	v_add_u32_e32 v144, 16, v160
	v_add_u32_e32 v174, s40, v3
	v_lshl_add_u32 v3, v35, 2, v0
	s_and_b64 s[78:79], vcc, s[8:9]
	v_med3_i32 v34, v34, -15, 15
	v_add_u32_e32 v36, 48, v160
	v_cmp_ge_i32_e32 vcc, v144, v5
	v_cmp_lt_i32_e64 s[8:9], v144, v2
	v_subrev_u32_e32 v3, s69, v3
	s_and_b64 s[4:5], vcc, s[8:9]
; __device__ __forceinline__ int crow(int r, int hi) { return (r & 3) + 8 * (r >> 2) + 4 * hi; }
; __device__ __forceinline__ void na_item(const int g_wave, int b, int r, int hp, const bf16* __restrict__ proj, const float* __restrict__ rpb, bf16* __restrict__ cat, char* lds) {
;     ...
;     for (int q = 0; q < 16; ++q) {
;       const int j0 = crow(q, hi), j1 = 32 + j0;
;       { const bool ok = (j0 >= cs) && (j0 < cs + 16); int dc = j0 - c + 15; dc = dc < 0 ? 0 : (dc > 30 ? 30 : dc);
;         const float bv = bp[dc]; p0[q] = ok ? fmaf(p0[q], C, bv) : NEG; tmax = fmaxf(tmax, p0[q]); }
;       { const bool ok = (j1 >= cs) && (j1 < cs + 16); int dc = j1 - c + 15; dc = dc < 0 ? 0 : (dc > 30 ? 30 : dc);
;         const float bv = bp[dc]; p1[q] = ok ? fmaf(p1[q], C, bv) : NEG; tmax = fmaxf(tmax, p1[q]); }
	v_sub_u32_e32 v37, v144, v7
	v_cmp_ge_i32_e32 vcc, v36, v5
	v_cmp_lt_i32_e64 s[8:9], v36, v2
	v_add_u32_e32 v142, 17, v160
	v_add_u32_e32 v175, s40, v3
	v_lshl_add_u32 v3, v34, 2, v0
	v_med3_i32 v37, v37, -15, 15
	s_and_b64 s[14:15], vcc, s[8:9]
	v_add_u32_e32 v38, 49, v160
	v_cmp_ge_i32_e32 vcc, v142, v5
	v_cmp_lt_i32_e64 s[8:9], v142, v2
	v_subrev_u32_e32 v3, s69, v3
	v_sub_u32_e32 v36, v36, v7
	s_and_b64 s[70:71], vcc, s[8:9]
	v_cmp_ge_i32_e32 vcc, v38, v5
	v_cmp_lt_i32_e64 s[8:9], v38, v2
	v_add_u32_e32 v140, 18, v160
	v_add_u32_e32 v176, s40, v3
	v_lshl_add_u32 v3, v37, 2, v0
	v_med3_i32 v36, v36, -15, 15
	s_and_b64 s[76:77], vcc, s[8:9]
	v_add_u32_e32 v40, 50, v160
	v_cmp_ge_i32_e32 vcc, v140, v5
	v_cmp_lt_i32_e64 s[8:9], v140, v2
	v_subrev_u32_e32 v3, s69, v3
	v_sub_u32_e32 v39, v142, v7
	s_and_b64 s[12:13], vcc, s[8:9]
	v_cmp_ge_i32_e32 vcc, v40, v5
	v_cmp_lt_i32_e64 s[8:9], v40, v2
	v_add_u32_e32 v138, 19, v160
	v_add_u32_e32 v177, s40, v3
	v_lshl_add_u32 v3, v36, 2, v0
	v_med3_i32 v39, v39, -15, 15
	s_and_b64 s[48:49], vcc, s[8:9]
	v_add_u32_e32 v42, 51, v160
	v_cmp_ge_i32_e32 vcc, v138, v5
	v_cmp_lt_i32_e64 s[8:9], v138, v2
	v_subrev_u32_e32 v3, s69, v3
	v_lshlrev_b32_e32 v18, 8, v131
	v_sub_u32_e32 v38, v38, v7
	s_and_b64 s[46:47], vcc, s[8:9]
	v_cmp_ge_i32_e32 vcc, v42, v5
	v_cmp_lt_i32_e64 s[8:9], v42, v2
	v_add_u32_e32 v136, 24, v160
	v_add_u32_e32 v190, s40, v3
	v_lshl_add_u32 v3, v39, 2, v0
	v_add_u32_e32 v19, s2, v137
	v_add_u32_e32 v139, s2, v18
	v_add_u32_e32 v20, s2, v141
	v_add_u32_e32 v21, s2, v143
	v_add_u32_e32 v22, s2, v145
	v_add_u32_e32 v23, s2, v149
	v_add_u32_e32 v24, s2, v151
	v_add_u32_e32 v25, s2, v153
	v_add_u32_e32 v26, s2, v155
	v_med3_i32 v38, v38, -15, 15
	s_and_b64 s[2:3], vcc, s[8:9]
	v_add_u32_e32 v44, 56, v160
	v_cmp_ge_i32_e32 vcc, v136, v5
	v_cmp_lt_i32_e64 s[8:9], v136, v2
	v_subrev_u32_e32 v3, s69, v3
	v_sub_u32_e32 v41, v140, v7
	s_and_b64 s[50:51], vcc, s[8:9]
	v_cmp_ge_i32_e32 vcc, v44, v5
	v_cmp_lt_i32_e64 s[8:9], v44, v2
	v_add_u32_e32 v134, 25, v160
	v_add_u32_e32 v191, s40, v3
	v_lshl_add_u32 v3, v38, 2, v0
	v_med3_i32 v41, v41, -15, 15
	s_and_b64 s[56:57], vcc, s[8:9]
	v_add_u32_e32 v46, 57, v160
	v_cmp_ge_i32_e32 vcc, v134, v5
	v_cmp_lt_i32_e64 s[8:9], v134, v2
	v_subrev_u32_e32 v3, s69, v3
	v_sub_u32_e32 v40, v40, v7
	s_and_b64 s[58:59], vcc, s[8:9]
	v_cmp_ge_i32_e32 vcc, v46, v5
	v_cmp_lt_i32_e64 s[8:9], v46, v2
	v_add_u32_e32 v132, 26, v160
	v_add_u32_e32 v192, s40, v3
	v_lshl_add_u32 v3, v41, 2, v0
	v_med3_i32 v40, v40, -15, 15
	s_and_b64 s[44:45], vcc, s[8:9]
	v_add_u32_e32 v48, 58, v160
	v_cmp_ge_i32_e32 vcc, v132, v5
	v_cmp_lt_i32_e64 s[8:9], v132, v2
	v_subrev_u32_e32 v3, s69, v3
	v_sub_u32_e32 v10, v160, v7
	v_sub_u32_e32 v43, v138, v7
	s_and_b64 s[80:81], vcc, s[8:9]
	v_cmp_ge_i32_e32 vcc, v48, v5
	v_cmp_lt_i32_e64 s[8:9], v48, v2
	v_add_u32_e32 v130, 27, v160
	v_add_u32_e32 v193, s40, v3
	v_lshl_add_u32 v3, v40, 2, v0
	v_med3_i32 v10, v10, -15, 15
	v_med3_i32 v43, v43, -15, 15
	s_and_b64 s[34:35], vcc, s[8:9]
	v_add_u32_e32 v50, 59, v160
	v_cmp_ge_i32_e32 vcc, v130, v5
	v_cmp_lt_i32_e64 s[8:9], v130, v2
	v_subrev_u32_e32 v3, s69, v3
	v_sub_u32_e32 v8, v8, v7
	v_sub_u32_e32 v42, v42, v7
	s_and_b64 s[72:73], vcc, s[8:9]
	v_cmp_ge_i32_e32 vcc, v50, v5
	v_lshl_add_u32 v5, v10, 2, v0
	v_add_u32_e32 v194, s40, v3
	v_lshl_add_u32 v3, v43, 2, v0
	v_med3_i32 v8, v8, -15, 15
	v_med3_i32 v42, v42, -15, 15
	v_subrev_u32_e32 v5, s69, v5
	v_subrev_u32_e32 v3, s69, v3
	v_sub_u32_e32 v45, v136, v7
	v_add_u32_e32 v157, s40, v5
	v_lshl_add_u32 v5, v8, 2, v0
	v_add_u32_e32 v195, s40, v3
	v_lshl_add_u32 v3, v42, 2, v0
	v_med3_i32 v45, v45, -15, 15
	v_subrev_u32_e32 v5, s69, v5
	v_subrev_u32_e32 v3, s69, v3
	v_sub_u32_e32 v44, v44, v7
	v_add_u32_e32 v159, s40, v5
	v_sub_u32_e32 v5, v160, v131
	v_add_u32_e32 v196, s40, v3
	v_lshl_add_u32 v3, v45, 2, v0
	v_med3_i32 v44, v44, -15, 15
	v_subrev_u32_e32 v5, s1, v5
	v_subrev_u32_e32 v3, s69, v3
	v_sub_u32_e32 v11, v11, v7
	v_sub_u32_e32 v12, v12, v7
	v_sub_u32_e32 v13, v13, v7
	v_sub_u32_e32 v47, v134, v7
	v_sub_u32_e32 v46, v46, v7
	v_sub_u32_e32 v49, v132, v7
	v_sub_u32_e32 v48, v48, v7
	v_sub_u32_e32 v51, v130, v7
	v_cmp_lt_i32_e64 s[8:9], v50, v2
	v_sub_u32_e32 v2, v50, v7
	v_add_u32_e32 v7, 1, v5
	v_add_u32_e32 v197, s40, v3
	v_lshl_add_u32 v3, v44, 2, v0
	v_med3_i32 v47, v47, -15, 15
	v_med3_i32 v7, v7, -15, 15
	v_subrev_u32_e32 v3, s69, v3
	v_lshl_add_u32 v7, v7, 2, v0
	v_add_u32_e32 v207, s40, v3
	v_lshl_add_u32 v3, v47, 2, v0
	v_med3_i32 v11, v11, -15, 15
	v_med3_i32 v46, v46, -15, 15
	v_subrev_u32_e32 v7, s69, v7
	v_subrev_u32_e32 v3, s69, v3
	v_add_u32_e32 v161, s40, v7
	v_lshl_add_u32 v7, v11, 2, v0
	v_add_u32_e32 v208, s40, v3
	v_lshl_add_u32 v3, v46, 2, v0
	v_med3_i32 v49, v49, -15, 15
	v_subrev_u32_e32 v7, s69, v7
	v_subrev_u32_e32 v3, s69, v3
	v_add_u32_e32 v164, s40, v7
	v_add_u32_e32 v7, 2, v5
	v_add_u32_e32 v5, 3, v5
	v_add_u32_e32 v209, s40, v3
	v_lshl_add_u32 v3, v49, 2, v0
	v_med3_i32 v48, v48, -15, 15
	v_med3_i32 v7, v7, -15, 15
	v_med3_i32 v5, v5, -15, 15
	v_subrev_u32_e32 v3, s69, v3
	v_lshl_add_u32 v7, v7, 2, v0
	v_lshl_add_u32 v5, v5, 2, v0
	v_add_u32_e32 v210, s40, v3
	v_lshl_add_u32 v3, v48, 2, v0
	s_mul_hi_u32 s64, s65, 0x90000
	s_mul_i32 s65, s65, 0x90000
	v_med3_i32 v12, v12, -15, 15
	v_med3_i32 v13, v13, -15, 15
	v_med3_i32 v51, v51, -15, 15
	s_and_b64 s[8:9], vcc, s[8:9]
	v_med3_i32 v2, v2, -15, 15
	v_subrev_u32_e32 v7, s69, v7
	v_subrev_u32_e32 v5, s69, v5
	v_subrev_u32_e32 v3, s69, v3
	s_mul_hi_i32 s33, s68, 0x2400000
	s_mul_i32 s68, s68, 0x2400000
	v_add_u32_e32 v165, s40, v7
	v_lshl_add_u32 v7, v12, 2, v0
; __device__ __forceinline__ void na_item(const int g_wave, int b, int r, int hp, const bf16* __restrict__ proj, const float* __restrict__ rpb, bf16* __restrict__ cat, char* lds) {
;     ...
;   float m_reg = -1e30f, l_reg = 0.f; f32x16 o[4] = {};
;   constexpr float C = SCALE * 1.4426950408889634f, L2E = 1.4426950408889634f, NEG = -1e30f;
;   float* btab = (float*)(lds + 65536);
;   for (int i2 = tid; i2 < 2 * 465; i2 += 512) btab[i2] = rpb[hp * 2 * 465 + i2] * L2E;
;   for (int i = 0; i < 8; ++i) {
;     const int kr = rs + i;
;     const bf16* krow0 = proj + ((long)b * 4096 + kr * 64 + sr) * 4608 + sc + hp * 256;
;     const bf16* krow1 = krow0 + 32 * 4608;
;     bf16x8 stg[2][4];
; #pragma unroll
;     for (int j = 0; j < 2; ++j) { stg[j][0] = ld8(krow0 + 512 + j * 128); stg[j][1] = ld8(krow1 + 512 + j * 128); stg[j][2] = ld8(krow0 + 1024 + j * 128); stg[j][3] = ld8(krow1 + 1024 + j * 128); }
;     __syncthreads();
; #pragma unroll
;     for (int j = 0; j < 2; ++j) { char* kl = lds + j * 32768; char* vl = kl + 16384;
;       *(bf16x8*)(kl + KSWZ(sr, sc * 2)) = stg[j][0]; *(bf16x8*)(kl + KSWZ(32 + sr, sc * 2)) = stg[j][1];
;       *(bf16x8*)(vl + vst0) = stg[j][2]; *(bf16x8*)(vl + vst1) = stg[j][3]; }
;     __syncthreads();
	v_add_u32_e32 v167, s40, v5
	v_lshl_add_u32 v5, v13, 2, v0
	v_add_u32_e32 v211, s40, v3
	v_lshl_add_u32 v3, v51, 2, v0
	v_lshl_add_u32 v0, v2, 2, v0
	s_add_u32 s68, s68, s65
	v_subrev_u32_e32 v7, s69, v7
	v_subrev_u32_e32 v5, s69, v5
	v_subrev_u32_e32 v3, s69, v3
	v_subrev_u32_e32 v0, s69, v0
	s_addc_u32 s69, s33, s64
	v_add_u32_e32 v212, s40, v3
	v_add_u32_e32 v213, s40, v0
	v_mov_b64_e32 v[2:3], s[68:69]
	v_and_b32_e32 v0, 15, v6
	v_mad_i64_i32 v[2:3], s[64:65], v9, s66, v[2:3]
	v_lshlrev_b32_e32 v0, 4, v0
	v_or3_b32 v2, v2, v4, v0
	v_lshl_add_u32 v27, v9, 8, 0
	v_lshl_add_u64 v[2:3], s[20:21], 0, v[2:3]
	s_mov_b64 s[64:65], 0x18bc0400
	v_mov_b32_e32 v14, v1
	v_mov_b32_e32 v15, v1
	v_cmp_gt_u32_e64 s[6:7], 32, v6
	v_add_u32_e32 v166, s40, v7
	v_add_u32_e32 v168, s40, v5
	v_lshl_add_u64 v[162:163], v[2:3], 0, s[64:65]
	v_mov_b32_e32 v0, v1
	v_mov_b32_e32 v2, v1
	v_mov_b32_e32 v3, v1
	v_mov_b32_e32 v4, v1
	v_mov_b32_e32 v5, v1
	v_mov_b32_e32 v6, v1
	v_mov_b32_e32 v7, v1
	v_mov_b32_e32 v8, v1
	v_mov_b32_e32 v9, v1
	v_mov_b32_e32 v10, v1
	v_mov_b32_e32 v11, v1
	v_mov_b32_e32 v12, v1
	v_mov_b32_e32 v13, v1
	v_add_u32_e32 v214, v27, v17
	v_add_u32_e32 v215, v28, v17
	v_add_u32_e32 v216, v29, v16
	v_add_u32_e32 v217, v30, v16
	v_add_u32_e32 v218, v19, v18
	v_add_u32_e32 v219, v20, v18
	v_add_u32_e32 v220, v21, v18
	v_add_u32_e32 v221, v22, v18
	v_add_u32_e32 v222, v23, v18
	v_add_u32_e32 v223, v24, v18
	v_add_u32_e32 v224, v25, v18
	v_add_u32_e32 v225, v26, v18
	v_mov_b64_e32 v[64:65], v[14:15]
	v_mov_b64_e32 v[48:49], v[14:15]
	v_mov_b64_e32 v[32:33], v[14:15]
	v_mov_b64_e32 v[62:63], v[12:13]
	v_mov_b64_e32 v[60:61], v[10:11]
	v_mov_b64_e32 v[58:59], v[8:9]
	v_mov_b64_e32 v[56:57], v[6:7]
	v_mov_b64_e32 v[54:55], v[4:5]
	v_mov_b64_e32 v[52:53], v[2:3]
	v_mov_b64_e32 v[50:51], v[0:1]
	v_mov_b64_e32 v[46:47], v[12:13]
	v_mov_b64_e32 v[44:45], v[10:11]
	v_mov_b64_e32 v[42:43], v[8:9]
	v_mov_b64_e32 v[40:41], v[6:7]
	v_mov_b64_e32 v[38:39], v[4:5]
	v_mov_b64_e32 v[36:37], v[2:3]
	v_mov_b64_e32 v[34:35], v[0:1]
	v_mov_b64_e32 v[30:31], v[12:13]
	v_mov_b64_e32 v[28:29], v[10:11]
	v_mov_b64_e32 v[26:27], v[8:9]
	v_mov_b64_e32 v[24:25], v[6:7]
	v_mov_b64_e32 v[22:23], v[4:5]
	v_mov_b64_e32 v[20:21], v[2:3]
	v_mov_b64_e32 v[18:19], v[0:1]
	v_mov_b64_e32 v[16:17], v[14:15]
	s_mov_b32 s43, 0
	v_lshl_add_u32 v147, v131, 2, s42
	v_mov_b32_e32 v226, 0
	v_mov_b32_e32 v227, 0xf149f2ca
	v_mov_b64_e32 v[14:15], v[12:13]
	v_mov_b64_e32 v[12:13], v[10:11]
	v_mov_b64_e32 v[10:11], v[8:9]
	v_mov_b64_e32 v[8:9], v[6:7]
	v_mov_b64_e32 v[6:7], v[4:5]
	v_mov_b64_e32 v[4:5], v[2:3]
	v_mov_b64_e32 v[2:3], v[0:1]
	s_andn2_b64 vcc, exec, s[24:25]
	s_cbranch_vccz .Lna_pre_done
	v_add_u32_e32 v66, 0xfffff000, v214
	v_add_u32_e32 v67, 0xfffff000, v216
	v_add_co_u32_e32 v68, vcc, 0xfffdc000, v162
	s_nop 1
	v_addc_co_u32_e32 v69, vcc, -1, v163, vcc
	v_add_co_u32_e32 v70, vcc, 0x24000, v162
	s_nop 1
	v_addc_co_u32_e32 v71, vcc, 0, v163, vcc
	v_add_co_u32_e32 v72, vcc, 0x48000, v162
	s_nop 1
	v_addc_co_u32_e32 v73, vcc, 0, v163, vcc
	global_load_dwordx4 v[2:5], v[68:69], off
	global_load_dwordx4 v[6:9], v[68:69], off offset:1024
	global_load_dwordx4 v[10:13], v[68:69], off offset:256
	global_load_dwordx4 v[14:17], v[68:69], off offset:1280
	global_load_dwordx4 v[18:21], v[162:163], off
	global_load_dwordx4 v[22:25], v[162:163], off offset:1024
	global_load_dwordx4 v[26:29], v[162:163], off offset:256
	global_load_dwordx4 v[30:33], v[162:163], off offset:1280
	global_load_dwordx4 v[34:37], v[70:71], off
	global_load_dwordx4 v[38:41], v[70:71], off offset:1024
	global_load_dwordx4 v[42:45], v[70:71], off offset:256
	global_load_dwordx4 v[46:49], v[70:71], off offset:1280
	global_load_dwordx4 v[50:53], v[72:73], off
	global_load_dwordx4 v[54:57], v[72:73], off offset:1024
	global_load_dwordx4 v[58:61], v[72:73], off offset:256
	global_load_dwordx4 v[62:65], v[72:73], off offset:1280
.Lna_pre_done:
.LBB0_1076:
	s_andn2_b64 vcc, exec, s[24:25]
	s_waitcnt lgkmcnt(0)
	s_barrier
	s_cbranch_vccz .Lna_active
	s_waitcnt vmcnt(0)
	ds_write_b128 v66, v[2:5]
	ds_write_b128 v67, v[6:9] offset:16384
	ds_write_b128 v66, v[10:13] offset:32768
	ds_write_b128 v67, v[14:17] offset:49152
	ds_write_b128 v66, v[18:21] offset:4096
	ds_write_b128 v67, v[22:25] offset:20480
	ds_write_b128 v66, v[26:29] offset:36864
	ds_write_b128 v67, v[30:33] offset:53248
	ds_write_b128 v66, v[34:37] offset:8192
	ds_write_b128 v67, v[38:41] offset:24576
	ds_write_b128 v66, v[42:45] offset:40960
	ds_write_b128 v67, v[46:49] offset:57344
	ds_write_b128 v66, v[50:53] offset:12288
	ds_write_b128 v67, v[54:57] offset:28672
	ds_write_b128 v66, v[58:61] offset:45056
	ds_write_b128 v67, v[62:65] offset:61440
	s_waitcnt lgkmcnt(0)
	s_barrier
	s_branch .LBB0_1144
; __device__ __forceinline__ int crow(int r, int hi) { return (r & 3) + 8 * (r >> 2) + 4 * hi; }
;   p0 = f32x16{}; p1 = f32x16{};
; #pragma unroll
;   for (int d0 = DLO; d0 < DHI; ++d0) { int cb = (d0 * 16 + hi * 8) * 2;
;     bf16x8 b0 = *reinterpret_cast<const bf16x8*>((const char*)Ks + KSWZ(r32, cb));
;     bf16x8 b1 = *reinterpret_cast<const bf16x8*>((const char*)Ks + KSWZ(32 + r32, cb));
;     p0 = __builtin_amdgcn_mfma_f32_32x32x16_bf16(b0, qr[d0], p0, 0, 0, 0);
;     p1 = __builtin_amdgcn_mfma_f32_32x32x16_bf16(b1, qr[d0], p1, 0, 0, 0); }
; }
; __device__ __forceinline__ void na_item(const int g_wave, int b, int r, int hp, const bf16* __restrict__ proj, const float* __restrict__ rpb, bf16* __restrict__ cat, char* lds) {
;     ...
;     qkt(p0, p1, (const bf16*)Kl, qr, r32, hi);
;     const float* bp = btab + (hl * 15 + (kr - r + 7)) * 31;
;     float tmax = NEG;
; #pragma unroll
;     for (int q = 0; q < 16; ++q) {
;       const int j0 = crow(q, hi), j1 = 32 + j0;
;       { const bool ok = (j0 >= cs) && (j0 < cs + 16); int dc = j0 - c + 15; dc = dc < 0 ? 0 : (dc > 30 ? 30 : dc);
;         const float bv = bp[dc]; p0[q] = ok ? fmaf(p0[q], C, bv) : NEG; tmax = fmaxf(tmax, p0[q]); }
;       { const bool ok = (j1 >= cs) && (j1 < cs + 16); int dc = j1 - c + 15; dc = dc < 0 ? 0 : (dc > 30 ? 30 : dc);
;         const float bv = bp[dc]; p1[q] = ok ? fmaf(p1[q], C, bv) : NEG; tmax = fmaxf(tmax, p1[q]); }
.Lna_active:
	s_barrier
	ds_read_b128 v[230:233], v218
	v_add_u32_e32 v0, v139, v137
	ds_read_b128 v[234:237], v0 offset:8192
	ds_read_b128 v[238:241], v219
	v_add_u32_e32 v0, v139, v141
	ds_read_b128 v[242:245], v0 offset:8192
	ds_read_b128 v[246:249], v220
	v_add_u32_e32 v0, v139, v143
	ds_read_b128 v[186:189], v0 offset:8192
	s_waitcnt lgkmcnt(5)
	v_mfma_f32_32x32x16_bf16 v[82:97], v[230:233], v[122:125], 0
	ds_read_b128 v[230:233], v221
	s_waitcnt lgkmcnt(5)
	v_mfma_f32_32x32x16_bf16 v[66:81], v[234:237], v[122:125], 0
	v_add_u32_e32 v0, v139, v145
	ds_read_b128 v[234:237], v0 offset:8192
	s_waitcnt lgkmcnt(5)
	v_mfma_f32_32x32x16_bf16 v[82:97], v[238:241], v[98:101], v[82:97]
	ds_read_b128 v[238:241], v222
	s_waitcnt lgkmcnt(5)
	v_mfma_f32_32x32x16_bf16 v[66:81], v[242:245], v[98:101], v[66:81]
	v_add_u32_e32 v0, v139, v149
	ds_read_b128 v[242:245], v0 offset:8192
	s_waitcnt lgkmcnt(5)
	v_mfma_f32_32x32x16_bf16 v[82:97], v[246:249], v[102:105], v[82:97]
	ds_read_b128 v[246:249], v223
	s_waitcnt lgkmcnt(5)
	v_mfma_f32_32x32x16_bf16 v[66:81], v[186:189], v[102:105], v[66:81]
	v_add_u32_e32 v0, v139, v151
	ds_read_b128 v[186:189], v0 offset:8192
	s_waitcnt lgkmcnt(5)
	v_mfma_f32_32x32x16_bf16 v[82:97], v[230:233], v[106:109], v[82:97]
	ds_read_b128 v[230:233], v224
	s_waitcnt lgkmcnt(5)
	v_mfma_f32_32x32x16_bf16 v[66:81], v[234:237], v[106:109], v[66:81]
	v_add_u32_e32 v0, v139, v153
	ds_read_b128 v[234:237], v0 offset:8192
	s_waitcnt lgkmcnt(5)
	v_mfma_f32_32x32x16_bf16 v[82:97], v[238:241], v[110:113], v[82:97]
	ds_read_b128 v[238:241], v225
	s_waitcnt lgkmcnt(5)
	v_mfma_f32_32x32x16_bf16 v[66:81], v[242:245], v[110:113], v[66:81]
	v_add_u32_e32 v0, v139, v155
	ds_read_b128 v[242:245], v0 offset:8192
	s_waitcnt lgkmcnt(5)
	v_mfma_f32_32x32x16_bf16 v[82:97], v[246:249], v[114:117], v[82:97]
	s_waitcnt lgkmcnt(4)
	v_mfma_f32_32x32x16_bf16 v[66:81], v[186:189], v[114:117], v[66:81]
	s_waitcnt lgkmcnt(3)
	v_mfma_f32_32x32x16_bf16 v[82:97], v[230:233], v[118:121], v[82:97]
	s_waitcnt lgkmcnt(2)
	v_mfma_f32_32x32x16_bf16 v[66:81], v[234:237], v[118:121], v[66:81]
	s_waitcnt lgkmcnt(1)
	v_mfma_f32_32x32x16_bf16 v[82:97], v[238:241], v[126:129], v[82:97]
	s_waitcnt lgkmcnt(0)
	v_mfma_f32_32x32x16_bf16 v[66:81], v[242:245], v[126:129], v[66:81]
	v_mov_b32_e32 v244, 0xf149f2ca
	v_add_u32_e32 v230, s43, v157
	ds_read_b32 v230, v230
	v_add_u32_e32 v231, s43, v159
	ds_read_b32 v231, v231
	v_add_u32_e32 v232, s43, v161
	ds_read_b32 v232, v232
	v_add_u32_e32 v233, s43, v164
	ds_read_b32 v233, v233
	v_add_u32_e32 v234, s43, v165
	ds_read_b32 v234, v234
	v_add_u32_e32 v235, s43, v166
	ds_read_b32 v235, v235
	v_add_u32_e32 v236, s43, v167
	ds_read_b32 v236, v236
	v_add_u32_e32 v237, s43, v168
	ds_read_b32 v237, v237
	v_add_u32_e32 v238, s43, v169
	ds_read_b32 v238, v238
	v_add_u32_e32 v239, s43, v170
	ds_read_b32 v239, v239
	v_add_u32_e32 v240, s43, v171
	ds_read_b32 v240, v240
	v_add_u32_e32 v241, s43, v172
	ds_read_b32 v241, v241
	v_add_u32_e32 v242, s43, v173
	ds_read_b32 v242, v242
	v_add_u32_e32 v243, s43, v174
	ds_read_b32 v243, v243
	s_waitcnt lgkmcnt(13)
	v_fmac_f32_e32 v230, 0x3e0293ee, v82
	v_cndmask_b32_e64 v229, v244, v230, s[26:27]
	v_add_u32_e32 v230, s43, v175
	ds_read_b32 v230, v230
	s_waitcnt lgkmcnt(13)
	v_fmac_f32_e32 v231, 0x3e0293ee, v66
	v_cndmask_b32_e64 v228, v244, v231, s[28:29]
	v_add_u32_e32 v231, s43, v176
	ds_read_b32 v231, v231
	s_waitcnt lgkmcnt(13)
	v_fmac_f32_e32 v232, 0x3e0293ee, v83
	v_cndmask_b32_e64 v82, v244, v232, s[30:31]
	v_add_u32_e32 v232, s43, v177
	ds_read_b32 v232, v232
	s_waitcnt lgkmcnt(13)
	v_fmac_f32_e32 v233, 0x3e0293ee, v67
	v_cndmask_b32_e64 v66, v244, v233, s[82:83]
	v_add_u32_e32 v233, s43, v190
	ds_read_b32 v233, v233
	s_waitcnt lgkmcnt(13)
	v_fmac_f32_e32 v234, 0x3e0293ee, v84
	v_cndmask_b32_e64 v83, v244, v234, s[84:85]
	v_add_u32_e32 v234, s43, v191
	ds_read_b32 v234, v234
	s_waitcnt lgkmcnt(13)
	v_fmac_f32_e32 v235, 0x3e0293ee, v68
	v_cndmask_b32_e64 v67, v244, v235, s[86:87]
	v_add_u32_e32 v235, s43, v192
	ds_read_b32 v235, v235
	s_waitcnt lgkmcnt(13)
	v_fmac_f32_e32 v236, 0x3e0293ee, v85
	v_cndmask_b32_e64 v84, v244, v236, s[88:89]
	v_add_u32_e32 v236, s43, v193
	ds_read_b32 v236, v236
	s_waitcnt lgkmcnt(13)
	v_fmac_f32_e32 v237, 0x3e0293ee, v69
	v_cndmask_b32_e64 v68, v244, v237, s[90:91]
	v_add_u32_e32 v237, s43, v194
	ds_read_b32 v237, v237
	s_waitcnt lgkmcnt(13)
	v_fmac_f32_e32 v238, 0x3e0293ee, v86
	v_cndmask_b32_e64 v85, v244, v238, s[92:93]
	v_add_u32_e32 v238, s43, v195
	ds_read_b32 v238, v238
	s_waitcnt lgkmcnt(13)
	v_fmac_f32_e32 v239, 0x3e0293ee, v70
	v_cndmask_b32_e64 v69, v244, v239, s[94:95]
	v_add_u32_e32 v239, s43, v196
	ds_read_b32 v239, v239
	s_waitcnt lgkmcnt(13)
	v_fmac_f32_e32 v240, 0x3e0293ee, v87
	v_cndmask_b32_e64 v86, v244, v240, s[96:97]
	v_add_u32_e32 v240, s43, v197
	ds_read_b32 v240, v240
	s_waitcnt lgkmcnt(13)
	v_fmac_f32_e32 v241, 0x3e0293ee, v71
	v_cndmask_b32_e64 v70, v244, v241, s[60:61]
	v_add_u32_e32 v241, s43, v207
	ds_read_b32 v241, v241
	s_waitcnt lgkmcnt(13)
	v_fmac_f32_e32 v242, 0x3e0293ee, v88
	v_cndmask_b32_e64 v87, v244, v242, s[38:39]
	v_add_u32_e32 v242, s43, v208
	ds_read_b32 v242, v242
	s_waitcnt lgkmcnt(13)
	v_fmac_f32_e32 v243, 0x3e0293ee, v72
	v_cndmask_b32_e64 v71, v244, v243, s[74:75]
	v_add_u32_e32 v243, s43, v209
	ds_read_b32 v243, v243
	s_waitcnt lgkmcnt(13)
	v_fmac_f32_e32 v230, 0x3e0293ee, v89
	v_cndmask_b32_e64 v88, v244, v230, s[36:37]
	v_add_u32_e32 v230, s43, v210
	ds_read_b32 v230, v230
	s_waitcnt lgkmcnt(13)
	v_fmac_f32_e32 v231, 0x3e0293ee, v73
	v_cndmask_b32_e64 v72, v244, v231, s[78:79]
	v_add_u32_e32 v231, s43, v211
	ds_read_b32 v231, v231
	s_waitcnt lgkmcnt(13)
; __device__ __forceinline__ int crow(int r, int hi) { return (r & 3) + 8 * (r >> 2) + 4 * hi; }
; __device__ __forceinline__ void na_item(const int g_wave, int b, int r, int hp, const bf16* __restrict__ proj, const float* __restrict__ rpb, bf16* __restrict__ cat, char* lds) {
;     ...
;     for (int q = 0; q < 16; ++q) {
;       const int j0 = crow(q, hi), j1 = 32 + j0;
;       { const bool ok = (j0 >= cs) && (j0 < cs + 16); int dc = j0 - c + 15; dc = dc < 0 ? 0 : (dc > 30 ? 30 : dc);
;         const float bv = bp[dc]; p0[q] = ok ? fmaf(p0[q], C, bv) : NEG; tmax = fmaxf(tmax, p0[q]); }
;       { const bool ok = (j1 >= cs) && (j1 < cs + 16); int dc = j1 - c + 15; dc = dc < 0 ? 0 : (dc > 30 ? 30 : dc);
;         const float bv = bp[dc]; p1[q] = ok ? fmaf(p1[q], C, bv) : NEG; tmax = fmaxf(tmax, p1[q]); }
;     }
;     { auto rr = __builtin_amdgcn_permlane32_swap(__float_as_uint(tmax), __float_as_uint(tmax), false, false);
;       tmax = fmaxf(__uint_as_float(rr[0]), __uint_as_float(rr[1])); }
;     const float mn = fmaxf(m_reg, tmax); const float alpha = __builtin_amdgcn_exp2f(m_reg - mn); m_reg = mn;
;     float ps = 0.f;
; #pragma unroll
;     for (int q = 0; q < 16; ++q) { p0[q] = __builtin_amdgcn_exp2f(p0[q] - mn); p1[q] = __builtin_amdgcn_exp2f(p1[q] - mn); ps += p0[q] + p1[q]; }
;     { auto rr = __builtin_amdgcn_permlane32_swap(__float_as_uint(ps), __float_as_uint(ps), false, false);
;       ps = __uint_as_float(rr[0]) + __uint_as_float(rr[1]); }
;     l_reg = l_reg * alpha + ps;
;     bf16x8 pa0, pa1, pa2, pa3;
;     PK4(p0, 0, pa0); PK4(p0, 8, pa1); PK4(p1, 0, pa2); PK4(p1, 8, pa3);
;     if (hi == 0) al_l[r32] = alpha; asm volatile("s_waitcnt lgkmcnt(0)" ::: "memory");
	v_fmac_f32_e32 v232, 0x3e0293ee, v90
	v_cndmask_b32_e64 v89, v244, v232, s[4:5]
	v_add_u32_e32 v232, s43, v212
	ds_read_b32 v232, v232
	s_waitcnt lgkmcnt(13)
	v_fmac_f32_e32 v233, 0x3e0293ee, v74
	v_cndmask_b32_e64 v73, v244, v233, s[14:15]
	v_add_u32_e32 v233, s43, v213
	ds_read_b32 v233, v233
	s_waitcnt lgkmcnt(13)
	v_fmac_f32_e32 v234, 0x3e0293ee, v91
	v_cndmask_b32_e64 v90, v244, v234, s[70:71]
	s_waitcnt lgkmcnt(12)
	v_fmac_f32_e32 v235, 0x3e0293ee, v75
	v_cndmask_b32_e64 v74, v244, v235, s[76:77]
	s_waitcnt lgkmcnt(11)
	v_fmac_f32_e32 v236, 0x3e0293ee, v92
	v_cndmask_b32_e64 v91, v244, v236, s[12:13]
	s_waitcnt lgkmcnt(10)
	v_fmac_f32_e32 v237, 0x3e0293ee, v76
	v_cndmask_b32_e64 v75, v244, v237, s[48:49]
	s_waitcnt lgkmcnt(9)
	v_fmac_f32_e32 v238, 0x3e0293ee, v93
	v_cndmask_b32_e64 v92, v244, v238, s[46:47]
	s_waitcnt lgkmcnt(8)
	v_fmac_f32_e32 v239, 0x3e0293ee, v77
	v_cndmask_b32_e64 v76, v244, v239, s[2:3]
	s_waitcnt lgkmcnt(7)
	v_fmac_f32_e32 v240, 0x3e0293ee, v94
	v_cndmask_b32_e64 v93, v244, v240, s[50:51]
	s_waitcnt lgkmcnt(6)
	v_fmac_f32_e32 v241, 0x3e0293ee, v78
	v_cndmask_b32_e64 v77, v244, v241, s[56:57]
	s_waitcnt lgkmcnt(5)
	v_fmac_f32_e32 v242, 0x3e0293ee, v95
	v_cndmask_b32_e64 v94, v244, v242, s[58:59]
	s_waitcnt lgkmcnt(4)
	v_fmac_f32_e32 v243, 0x3e0293ee, v79
	v_cndmask_b32_e64 v78, v244, v243, s[44:45]
	s_waitcnt lgkmcnt(3)
	v_fmac_f32_e32 v230, 0x3e0293ee, v96
	v_cndmask_b32_e64 v95, v244, v230, s[80:81]
	s_waitcnt lgkmcnt(2)
	v_fmac_f32_e32 v231, 0x3e0293ee, v80
	v_cndmask_b32_e64 v79, v244, v231, s[34:35]
	s_waitcnt lgkmcnt(1)
	v_fmac_f32_e32 v232, 0x3e0293ee, v97
	v_cndmask_b32_e64 v96, v244, v232, s[72:73]
	s_waitcnt lgkmcnt(0)
	v_fmac_f32_e32 v233, 0x3e0293ee, v81
	v_cndmask_b32_e64 v80, v244, v233, s[8:9]
	s_mov_b32 s33, 0xf149f2ca
	v_max3_f32 v0, v229, s33, v228
	v_max3_f32 v0, v0, v82, v66
	v_max3_f32 v0, v0, v83, v67
	v_max3_f32 v0, v0, v84, v68
	v_max3_f32 v0, v0, v85, v69
	v_max3_f32 v0, v0, v86, v70
	v_max3_f32 v0, v0, v87, v71
	v_max3_f32 v0, v0, v88, v72
	v_max3_f32 v0, v0, v89, v73
	v_max3_f32 v0, v0, v90, v74
	v_max3_f32 v0, v0, v91, v75
	v_max3_f32 v0, v0, v92, v76
	v_max3_f32 v0, v0, v93, v77
	v_max3_f32 v0, v0, v94, v78
	v_max3_f32 v0, v0, v95, v79
	v_max3_f32 v0, v0, v96, v80
	v_mov_b32_e32 v81, v0
	s_nop 1
	v_permlane32_swap_b32_e32 v0, v81
	v_max3_f32 v0, v227, v0, v81
	v_sub_f32_e32 v81, v229, v0
	v_sub_f32_e32 v97, v228, v0
	v_exp_f32_e32 v81, v81
	v_exp_f32_e32 v97, v97
	v_sub_f32_e32 v82, v82, v0
	v_sub_f32_e32 v66, v66, v0
	v_exp_f32_e32 v186, v82
	v_exp_f32_e32 v187, v66
	v_sub_f32_e32 v83, v83, v0
	v_sub_f32_e32 v67, v67, v0
	v_sub_f32_e32 v66, v227, v0
	v_exp_f32_e32 v189, v83
	v_exp_f32_e32 v227, v67
	v_sub_f32_e32 v67, v84, v0
	v_sub_f32_e32 v68, v68, v0
	v_exp_f32_e32 v67, v67
	v_exp_f32_e32 v228, v68
	v_add_f32_e32 v82, v81, v97
	v_add_f32_e32 v82, 0, v82
	v_add_f32_e32 v188, v186, v187
	v_add_f32_e32 v68, v188, v82
	v_add_f32_e32 v82, v189, v227
	v_sub_f32_e32 v83, v85, v0
	v_sub_f32_e32 v69, v69, v0
	v_add_f32_e32 v68, v82, v68
	v_add_f32_e32 v82, v67, v228
	v_exp_f32_e32 v85, v83
	v_exp_f32_e32 v188, v69
	v_sub_f32_e32 v69, v86, v0
	v_sub_f32_e32 v70, v70, v0
	v_exp_f32_e32 v69, v69
	v_exp_f32_e32 v86, v70
	v_add_f32_e32 v68, v82, v68
	v_sub_f32_e32 v82, v87, v0
	v_sub_f32_e32 v71, v71, v0
	v_exp_f32_e32 v87, v82
	v_exp_f32_e32 v229, v71
	v_sub_f32_e32 v71, v88, v0
	v_sub_f32_e32 v72, v72, v0
	v_exp_f32_e32 v71, v71
	v_exp_f32_e32 v88, v72
	v_sub_f32_e32 v72, v89, v0
	v_sub_f32_e32 v73, v73, v0
	v_add_f32_e32 v70, v85, v188
	v_exp_f32_e32 v72, v72
	v_exp_f32_e32 v89, v73
	v_sub_f32_e32 v73, v90, v0
	v_sub_f32_e32 v74, v74, v0
	v_add_f32_e32 v68, v70, v68
	v_add_f32_e32 v70, v69, v86
	v_exp_f32_e32 v73, v73
	v_exp_f32_e32 v90, v74
	v_sub_f32_e32 v74, v91, v0
	v_sub_f32_e32 v75, v75, v0
	v_add_f32_e32 v68, v70, v68
	v_add_f32_e32 v70, v87, v229
	v_exp_f32_e32 v74, v74
	v_exp_f32_e32 v91, v75
	v_sub_f32_e32 v75, v92, v0
	v_sub_f32_e32 v76, v76, v0
	v_add_f32_e32 v68, v70, v68
	v_add_f32_e32 v70, v71, v88
	v_exp_f32_e32 v75, v75
	v_exp_f32_e32 v92, v76
	v_sub_f32_e32 v76, v93, v0
	v_sub_f32_e32 v77, v77, v0
	v_add_f32_e32 v68, v70, v68
	v_add_f32_e32 v70, v72, v89
	v_exp_f32_e32 v76, v76
	v_exp_f32_e32 v93, v77
	v_sub_f32_e32 v77, v94, v0
	v_sub_f32_e32 v78, v78, v0
	v_add_f32_e32 v68, v70, v68
	v_add_f32_e32 v70, v73, v90
	v_exp_f32_e32 v77, v77
	v_exp_f32_e32 v94, v78
	v_sub_f32_e32 v78, v95, v0
	v_sub_f32_e32 v79, v79, v0
	v_add_f32_e32 v68, v70, v68
	v_add_f32_e32 v70, v74, v91
	v_exp_f32_e32 v78, v78
	v_exp_f32_e32 v95, v79
	v_sub_f32_e32 v79, v96, v0
	v_sub_f32_e32 v80, v80, v0
	v_add_f32_e32 v68, v70, v68
	v_add_f32_e32 v70, v75, v92
	v_exp_f32_e32 v79, v79
	v_exp_f32_e32 v96, v80
	v_add_f32_e32 v68, v70, v68
	v_add_f32_e32 v70, v76, v93
	v_add_f32_e32 v68, v70, v68
	v_add_f32_e32 v70, v77, v94
	v_add_f32_e32 v68, v70, v68
	v_add_f32_e32 v70, v78, v95
	v_add_f32_e32 v68, v70, v68
	v_add_f32_e32 v70, v79, v96
	v_exp_f32_e32 v82, v66
	v_add_f32_e32 v83, v70, v68
	v_mov_b32_e32 v84, v83
	v_cvt_pk_bf16_f32 v66, v81, v186
	v_cvt_pk_bf16_f32 v67, v189, v67
	v_cvt_pk_bf16_f32 v68, v85, v69
	v_cvt_pk_bf16_f32 v69, v87, v71
	v_cvt_pk_bf16_f32 v70, v72, v73
	v_cvt_pk_bf16_f32 v71, v74, v75
	v_cvt_pk_bf16_f32 v72, v76, v77
	v_cvt_pk_bf16_f32 v73, v78, v79
	v_cvt_pk_bf16_f32 v74, v97, v187
	v_cvt_pk_bf16_f32 v75, v227, v228
	v_cvt_pk_bf16_f32 v76, v188, v86
	v_cvt_pk_bf16_f32 v77, v229, v88
	v_cvt_pk_bf16_f32 v78, v89, v90
	v_cvt_pk_bf16_f32 v79, v91, v92
	v_cvt_pk_bf16_f32 v80, v93, v94
	v_cvt_pk_bf16_f32 v81, v95, v96
	s_nop 1
	v_permlane32_swap_b32_e32 v83, v84
	v_permlane32_swap_b32_e32 v66, v68
	v_permlane32_swap_b32_e32 v67, v69
	v_permlane32_swap_b32_e32 v70, v72
	v_permlane32_swap_b32_e32 v71, v73
	v_permlane32_swap_b32_e32 v74, v76
	v_permlane32_swap_b32_e32 v75, v77
	v_permlane32_swap_b32_e32 v78, v80
	v_permlane32_swap_b32_e32 v79, v81
	s_and_saveexec_b64 s[68:69], s[6:7]
	ds_write_b32 v147, v82 offset:128
	s_or_b64 exec, exec, s[68:69]
	v_add_f32_e32 v186, v83, v84
	s_waitcnt lgkmcnt(0)
; __device__ __forceinline__ int crow(int r, int hi) { return (r & 3) + 8 * (r >> 2) + 4 * hi; }
; __device__ __forceinline__ void na_item(const int g_wave, int b, int r, int hp, const bf16* __restrict__ proj, const float* __restrict__ rpb, bf16* __restrict__ cat, char* lds) {
;     ...
;   for (int i = 0; i < 8; ++i) {
;     const int kr = rs + i;
;     const bf16* krow0 = proj + ((long)b * 4096 + kr * 64 + sr) * 4608 + sc + hp * 256;
;     const bf16* krow1 = krow0 + 32 * 4608;
;     bf16x8 stg[2][4];
; #pragma unroll
;     for (int j = 0; j < 2; ++j) { stg[j][0] = ld8(krow0 + 512 + j * 128); stg[j][1] = ld8(krow1 + 512 + j * 128); stg[j][2] = ld8(krow0 + 1024 + j * 128); stg[j][3] = ld8(krow1 + 1024 + j * 128); }
;     ...
;     if (hi == 0) al_l[r32] = alpha; asm volatile("s_waitcnt lgkmcnt(0)" ::: "memory");
; #pragma unroll
;     for (int d = 0; d < 4; ++d)
; #pragma unroll
;       for (int q = 0; q < 16; ++q) o[d][q] *= al_l[crow(q, hi)];
;     pv_d0(o, vb, pa0, pa1, pa2, pa3);
	v_add_u32_e32 v94, s42, v135
	v_fmac_f32_e32 v186, v226, v82
	ds_read_b128 v[82:85], v94 offset:128
	ds_read_b128 v[86:89], v94 offset:160
	ds_read_b128 v[90:93], v94 offset:192
	ds_read_b128 v[94:97], v94 offset:224
	s_waitcnt lgkmcnt(3)
	v_pk_mul_f32 v[50:51], v[50:51], v[82:83]
	v_pk_mul_f32 v[34:35], v[34:35], v[82:83]
	v_pk_mul_f32 v[18:19], v[18:19], v[82:83]
	v_pk_mul_f32 v[2:3], v[2:3], v[82:83]
	ds_read_b64_tr_b16 v[82:83], v133 offset:0
	v_pk_mul_f32 v[52:53], v[52:53], v[84:85]
	v_pk_mul_f32 v[36:37], v[36:37], v[84:85]
	v_pk_mul_f32 v[20:21], v[20:21], v[84:85]
	v_pk_mul_f32 v[4:5], v[4:5], v[84:85]
	ds_read_b64_tr_b16 v[84:85], v133 offset:0x800
	s_waitcnt lgkmcnt(2)
	v_pk_mul_f32 v[54:55], v[54:55], v[86:87]
	v_pk_mul_f32 v[38:39], v[38:39], v[86:87]
	v_pk_mul_f32 v[22:23], v[22:23], v[86:87]
	v_pk_mul_f32 v[6:7], v[6:7], v[86:87]
	ds_read_b64_tr_b16 v[86:87], v133 offset:0x1000
	v_pk_mul_f32 v[56:57], v[56:57], v[88:89]
	v_pk_mul_f32 v[40:41], v[40:41], v[88:89]
	v_pk_mul_f32 v[24:25], v[24:25], v[88:89]
	v_pk_mul_f32 v[8:9], v[8:9], v[88:89]
	ds_read_b64_tr_b16 v[88:89], v133 offset:0x1800
	s_waitcnt lgkmcnt(1)
	v_pk_mul_f32 v[58:59], v[58:59], v[90:91]
	v_pk_mul_f32 v[42:43], v[42:43], v[90:91]
	v_pk_mul_f32 v[26:27], v[26:27], v[90:91]
	v_pk_mul_f32 v[10:11], v[10:11], v[90:91]
	ds_read_b64_tr_b16 v[90:91], v133 offset:0x2000
	v_pk_mul_f32 v[60:61], v[60:61], v[92:93]
	v_pk_mul_f32 v[44:45], v[44:45], v[92:93]
	v_pk_mul_f32 v[28:29], v[28:29], v[92:93]
	v_pk_mul_f32 v[12:13], v[12:13], v[92:93]
	ds_read_b64_tr_b16 v[92:93], v133 offset:0x2800
	s_waitcnt lgkmcnt(0)
	v_pk_mul_f32 v[62:63], v[62:63], v[94:95]
	v_pk_mul_f32 v[46:47], v[46:47], v[94:95]
	v_pk_mul_f32 v[30:31], v[30:31], v[94:95]
	v_pk_mul_f32 v[14:15], v[14:15], v[94:95]
	ds_read_b64_tr_b16 v[94:95], v133 offset:0x3000
	v_pk_mul_f32 v[64:65], v[64:65], v[96:97]
	v_pk_mul_f32 v[48:49], v[48:49], v[96:97]
	v_pk_mul_f32 v[32:33], v[32:33], v[96:97]
	v_pk_mul_f32 v[16:17], v[16:17], v[96:97]
	ds_read_b64_tr_b16 v[96:97], v133 offset:0x3800
	s_waitcnt lgkmcnt(0)
	v_mfma_f32_32x32x16_bf16 v[50:65], v[66:69], v[82:85], v[50:65]
	ds_read_b64_tr_b16 v[82:83], v133 offset:0x200
	ds_read_b64_tr_b16 v[84:85], v133 offset:0xa00
	v_mfma_f32_32x32x16_bf16 v[50:65], v[70:73], v[86:89], v[50:65]
	ds_read_b64_tr_b16 v[86:87], v133 offset:0x1200
	ds_read_b64_tr_b16 v[88:89], v133 offset:0x1a00
	v_mfma_f32_32x32x16_bf16 v[50:65], v[74:77], v[90:93], v[50:65]
	ds_read_b64_tr_b16 v[90:91], v133 offset:0x2200
	ds_read_b64_tr_b16 v[92:93], v133 offset:0x2a00
	v_mfma_f32_32x32x16_bf16 v[50:65], v[78:81], v[94:97], v[50:65]
	ds_read_b64_tr_b16 v[94:95], v133 offset:0x3200
	ds_read_b64_tr_b16 v[96:97], v133 offset:0x3a00
	s_waitcnt lgkmcnt(0)
	v_mfma_f32_32x32x16_bf16 v[34:49], v[66:69], v[82:85], v[34:49]
	ds_read_b64_tr_b16 v[82:83], v133 offset:0x400
	ds_read_b64_tr_b16 v[84:85], v133 offset:0xc00
	v_mfma_f32_32x32x16_bf16 v[34:49], v[70:73], v[86:89], v[34:49]
	ds_read_b64_tr_b16 v[86:87], v133 offset:0x1400
	ds_read_b64_tr_b16 v[88:89], v133 offset:0x1c00
	v_mfma_f32_32x32x16_bf16 v[34:49], v[74:77], v[90:93], v[34:49]
	ds_read_b64_tr_b16 v[90:91], v133 offset:0x2400
	ds_read_b64_tr_b16 v[92:93], v133 offset:0x2c00
	v_mfma_f32_32x32x16_bf16 v[34:49], v[78:81], v[94:97], v[34:49]
	ds_read_b64_tr_b16 v[94:95], v133 offset:0x3400
	ds_read_b64_tr_b16 v[96:97], v133 offset:0x3c00
	s_waitcnt lgkmcnt(0)
	v_mfma_f32_32x32x16_bf16 v[18:33], v[66:69], v[82:85], v[18:33]
	ds_read_b64_tr_b16 v[82:83], v133 offset:0x600
	ds_read_b64_tr_b16 v[84:85], v133 offset:0xe00
	v_mfma_f32_32x32x16_bf16 v[18:33], v[70:73], v[86:89], v[18:33]
	ds_read_b64_tr_b16 v[86:87], v133 offset:0x1600
	ds_read_b64_tr_b16 v[88:89], v133 offset:0x1e00
	v_mfma_f32_32x32x16_bf16 v[18:33], v[74:77], v[90:93], v[18:33]
	ds_read_b64_tr_b16 v[90:91], v133 offset:0x2600
	ds_read_b64_tr_b16 v[92:93], v133 offset:0x2e00
	v_mfma_f32_32x32x16_bf16 v[18:33], v[78:81], v[94:97], v[18:33]
	ds_read_b64_tr_b16 v[94:95], v133 offset:0x3600
	ds_read_b64_tr_b16 v[96:97], v133 offset:0x3e00
	s_waitcnt lgkmcnt(0)
	v_mfma_f32_32x32x16_bf16 v[2:17], v[66:69], v[82:85], v[2:17]
	v_mov_b32_e32 v226, v186
	v_mfma_f32_32x32x16_bf16 v[2:17], v[70:73], v[86:89], v[2:17]
	v_mfma_f32_32x32x16_bf16 v[2:17], v[74:77], v[90:93], v[2:17]
	v_mfma_f32_32x32x16_bf16 v[2:17], v[78:81], v[94:97], v[2:17]
	s_addk_i32 s43, 0x7c
	s_cmpk_eq_i32 s43, 0x3e0
	v_lshl_add_u64 v[162:163], v[162:163], 0, s[54:55]
	s_cbranch_scc0 .LBB0_1145
	s_branch .LBB0_1146
.LBB0_1144:
	v_mov_b32_e32 v0, v227
	s_addk_i32 s43, 0x7c
	s_cmpk_eq_i32 s43, 0x3e0
	v_lshl_add_u64 v[162:163], v[162:163], 0, s[54:55]
	s_cbranch_scc1 .LBB0_1146
	v_add_co_u32_e32 v68, vcc, 0xfffdc000, v162
	s_nop 1
	v_addc_co_u32_e32 v69, vcc, -1, v163, vcc
	v_add_co_u32_e32 v70, vcc, 0x24000, v162
	s_nop 1
	v_addc_co_u32_e32 v71, vcc, 0, v163, vcc
	v_add_co_u32_e32 v72, vcc, 0x48000, v162
	s_nop 1
	v_addc_co_u32_e32 v73, vcc, 0, v163, vcc
	global_load_dwordx4 v[2:5], v[68:69], off
	global_load_dwordx4 v[6:9], v[68:69], off offset:1024
	global_load_dwordx4 v[10:13], v[68:69], off offset:256
	global_load_dwordx4 v[14:17], v[68:69], off offset:1280
	global_load_dwordx4 v[18:21], v[162:163], off
	global_load_dwordx4 v[22:25], v[162:163], off offset:1024
	global_load_dwordx4 v[26:29], v[162:163], off offset:256
	global_load_dwordx4 v[30:33], v[162:163], off offset:1280
	global_load_dwordx4 v[34:37], v[70:71], off
	global_load_dwordx4 v[38:41], v[70:71], off offset:1024
	global_load_dwordx4 v[42:45], v[70:71], off offset:256
	global_load_dwordx4 v[46:49], v[70:71], off offset:1280
	global_load_dwordx4 v[50:53], v[72:73], off
	global_load_dwordx4 v[54:57], v[72:73], off offset:1024
	global_load_dwordx4 v[58:61], v[72:73], off offset:256
	global_load_dwordx4 v[62:65], v[72:73], off offset:1280
